# v26 plus non-temporal hint on streaming GEMM epilogue stores (SwiGLU hid output, f32 residual output)
# speedup vs baseline: 1.0056x; 1.0056x over previous
; #define LAS __attribute__((address_space(3)))
; DEVI u32x4 pack8(const float* f) { u32x4 u; u.x = pk_bf16(f[0], f[1]); u.y = pk_bf16(f[2], f[3]); u.z = pk_bf16(f[4], f[5]); u.w = pk_bf16(f[6], f[7]); return u; }
; DEVI float row_rstd(const LAS float* rsl, int r) { return rsqrtf((rsl[r] + rsl[256 + r]) * (1.0f / DM) + 1e-6f); }
;     DEVI void operator()(const f32x4 (&acc)[2][2][4][2], const Unit& u, int wr, int wc, int fr, int fq, const LAS float* rsl) const {
;         bf16_t* const O = O_; const int ldc = ldc_; const float* const rs = rs_; const int rsn = rsn_;
;         const int row0 = u.pm * BM + wr * 64 + fr, col0 = u.pn * HALF + wc * 32 + 8 * fq;
; #pragma unroll
;         for (int ai = 0; ai < 2; ++ai)
; #pragma unroll
;             for (int m = 0; m < 4; ++m) { bf16_t* rowp = O + (size_t)(row0 + ai * HALF + m * 16) * ldc + col0;
;                 const float sc = row_rstd(rsl, wr * 64 + fr + ai * HALF + m * 16);
;                 const float k1 = -1.4426950408889634f * sc, k2 = sc * sc;
;                 float h[8], tt[8];
;                 const f32x4 guk0 = (acc[ai][0][m][0] * acc[ai][1][m][0]) * k2, guk1 = (acc[ai][0][m][1] * acc[ai][1][m][1]) * k2;
;                 const f32x4 ta = acc[ai][0][m][0] * k1, tb = acc[ai][0][m][1] * k1;
; #pragma unroll
;                 for (int j = 0; j < 4; ++j) { tt[j] = __builtin_amdgcn_exp2f(ta[j]); tt[4 + j] = __builtin_amdgcn_exp2f(tb[j]); }
;                 __builtin_amdgcn_sched_barrier(0);
; #pragma unroll
;                 for (int j = 0; j < 8; ++j) tt[j] = __builtin_amdgcn_rcpf(1.0f + tt[j]);
;                 __builtin_amdgcn_sched_barrier(0);
; #pragma unroll
;                 for (int j = 0; j < 4; ++j) { h[j] = guk0[j] * tt[j]; h[4 + j] = guk1[j] * tt[4 + j]; }
;                 *(u32x4*)rowp = pack8(h); }
.LBB0_260:
	s_lshl_b32 s24, s76, 11
	s_and_b32 s24, s24, 0x800
	v_add_u32_e32 v168, s24, v148
	ds_read2st64_b32 v[144:145], v168 offset1:4
	v_readlane_b32 s76, v239, 0
	v_lshl_add_u32 v157, s75, 8, v147
	v_readlane_b32 s82, v239, 6
	v_readlane_b32 s83, v239, 7
	s_waitcnt lgkmcnt(0)
	v_add_f32_e32 v144, v144, v145
	v_fmamk_f32 v144, v144, 0x3a000000, v156
	v_mul_f32_e32 v145, 0x4b800000, v144
	v_cmp_gt_f32_e32 vcc, s16, v144
	v_readlane_b32 s80, v239, 4
	v_readlane_b32 s81, v239, 5
	v_cndmask_b32_e32 v144, v144, v145, vcc
	v_rsq_f32_e32 v158, v144
	v_lshl_or_b32 v144, s74, 7, v150
	v_ashrrev_i32_e32 v145, 31, v144
	v_lshl_add_u64 v[144:145], v[144:145], 1, s[82:83]
	v_mul_f32_e32 v159, 0x45800000, v158
	v_cndmask_b32_e32 v159, v158, v159, vcc
	v_mul_f32_e32 v158, 0xbfb8aa3b, v159
	v_pk_mul_f32 v[160:161], v[122:123], v[158:159] op_sel_hi:[1,0]
	v_pk_mul_f32 v[162:163], v[120:121], v[158:159] op_sel_hi:[1,0]
	v_pk_mul_f32 v[166:167], v[116:117], v[158:159] op_sel_hi:[1,0]
	v_pk_mul_f32 v[164:165], v[118:119], v[158:159] op_sel_hi:[1,0]
	v_exp_f32_e32 v158, v162
	v_exp_f32_e32 v162, v166
	v_exp_f32_e32 v166, v167
	v_exp_f32_e32 v167, v160
	v_exp_f32_e32 v169, v161
	v_mad_i64_i32 v[160:161], s[24:25], v157, s38, 0
	v_readlane_b32 s77, v239, 1
	v_readlane_b32 s78, v239, 2
	v_readlane_b32 s79, v239, 3
	v_exp_f32_e32 v163, v163
	v_exp_f32_e32 v164, v164
	v_exp_f32_e32 v165, v165
	v_lshl_add_u64 v[160:161], v[160:161], 1, v[144:145]
	v_add_f32_e32 v158, 1.0, v158
	v_rcp_f32_e32 v170, v158
	v_add_f32_e32 v158, 1.0, v163
	v_rcp_f32_e32 v163, v158
	v_add_f32_e32 v158, 1.0, v167
	v_rcp_f32_e32 v167, v158
	v_add_f32_e32 v158, 1.0, v169
	v_rcp_f32_e32 v169, v158
	v_add_f32_e32 v158, 1.0, v162
	v_rcp_f32_e32 v162, v158
	v_add_f32_e32 v158, 1.0, v166
	v_rcp_f32_e32 v166, v158
	v_add_f32_e32 v158, 1.0, v164
	v_rcp_f32_e32 v164, v158
	v_add_f32_e32 v158, 1.0, v165
	v_rcp_f32_e32 v165, v158
	v_mul_f32_e32 v116, v112, v116
	v_mul_f32_e32 v117, v113, v117
	v_mov_b32_e32 v158, v114
	v_mov_b32_e32 v112, v118
	v_mov_b32_e32 v113, v159
	v_pk_mul_f32 v[112:113], v[158:159], v[112:113]
	v_mul_f32_e32 v121, v125, v121
	v_mul_f32_e32 v116, v116, v113
	v_mul_f32_e32 v120, v124, v120
	v_mul_f32_e32 v118, v116, v162
	v_mul_f32_e32 v116, v121, v113
	v_mul_f32_e32 v122, v126, v122
	v_mul_f32_e32 v114, v120, v113
	v_mul_f32_e32 v120, v116, v163
	v_mul_f32_e32 v116, v117, v113
	v_mul_f32_e32 v121, v116, v166
	v_mul_f32_e32 v116, v122, v113
	v_add_u32_e32 v125, 64, v168
	v_mul_f32_e32 v122, v116, v167
	ds_read2st64_b32 v[116:117], v125 offset1:4
	v_mul_f32_e32 v112, v112, v113
	v_mul_f32_e32 v124, v112, v164
	v_mul_f32_e32 v112, v127, v123
	v_mul_f32_e32 v112, v112, v113
	s_waitcnt lgkmcnt(0)
	v_add_f32_e32 v116, v116, v117
	v_fmamk_f32 v116, v116, 0x3a000000, v156
	v_mul_f32_e32 v117, 0x4b800000, v116
	v_cmp_gt_f32_e32 vcc, s16, v116
	v_mul_f32_e32 v123, v112, v169
	v_mul_f32_e32 v112, v115, v119
	v_cndmask_b32_e32 v116, v116, v117, vcc
	v_rsq_f32_e32 v116, v116
	v_mul_f32_e32 v112, v112, v113
	v_mul_f32_e32 v114, v114, v170
	v_mul_f32_e32 v115, v112, v165
	v_cvt_pk_bf16_f32 v112, v114, v120
	v_cvt_pk_bf16_f32 v113, v122, v123
	v_cvt_pk_bf16_f32 v114, v118, v121
	v_cvt_pk_bf16_f32 v115, v124, v115
	global_store_dwordx4 v[160:161], v[112:115], off nt
	v_or_b32_e32 v122, 16, v157
	s_nop 0
	v_mul_f32_e32 v112, 0x45800000, v116
	v_cndmask_b32_e32 v113, v116, v112, vcc
	v_mul_f32_e32 v112, 0xbfb8aa3b, v113
	v_pk_mul_f32 v[114:115], v[110:111], v[112:113] op_sel_hi:[1,0]
	v_pk_mul_f32 v[116:117], v[108:109], v[112:113] op_sel_hi:[1,0]
	v_pk_mul_f32 v[120:121], v[100:101], v[112:113] op_sel_hi:[1,0]
	v_pk_mul_f32 v[118:119], v[102:103], v[112:113] op_sel_hi:[1,0]
	v_exp_f32_e32 v112, v116
	v_exp_f32_e32 v116, v120
	v_exp_f32_e32 v120, v121
	v_exp_f32_e32 v121, v114
	v_exp_f32_e32 v123, v115
	v_mad_i64_i32 v[114:115], s[24:25], v122, s38, 0
	v_exp_f32_e32 v117, v117
	v_exp_f32_e32 v118, v118
	v_exp_f32_e32 v119, v119
	v_lshl_add_u64 v[114:115], v[114:115], 1, v[144:145]
	v_add_f32_e32 v112, 1.0, v112
	v_rcp_f32_e32 v122, v112
	v_add_f32_e32 v112, 1.0, v117
	v_rcp_f32_e32 v117, v112
	v_add_f32_e32 v112, 1.0, v121
	v_rcp_f32_e32 v121, v112
	v_add_f32_e32 v112, 1.0, v123
	v_rcp_f32_e32 v123, v112
	v_add_f32_e32 v112, 1.0, v116
	v_rcp_f32_e32 v116, v112
	v_add_f32_e32 v112, 1.0, v120
	v_rcp_f32_e32 v120, v112
	v_add_f32_e32 v112, 1.0, v118
	v_rcp_f32_e32 v118, v112
	v_add_f32_e32 v112, 1.0, v119
	v_rcp_f32_e32 v119, v112
	v_mul_f32_e32 v100, v96, v100
	v_mul_f32_e32 v101, v97, v101
	v_mov_b32_e32 v112, v98
	v_mov_b32_e32 v96, v102
	v_mov_b32_e32 v97, v113
	v_pk_mul_f32 v[96:97], v[112:113], v[96:97]
	v_mul_f32_e32 v105, v105, v109
	v_mul_f32_e32 v100, v100, v97
	v_mul_f32_e32 v104, v104, v108
	v_mul_f32_e32 v102, v100, v116
	v_mul_f32_e32 v100, v105, v97
	v_mul_f32_e32 v106, v106, v110
	v_mul_f32_e32 v98, v104, v97
	v_mul_f32_e32 v104, v100, v117
	v_mul_f32_e32 v100, v101, v97
	v_mul_f32_e32 v105, v100, v120
	v_mul_f32_e32 v100, v106, v97
	v_add_u32_e32 v109, 0x80, v168
	v_mul_f32_e32 v106, v100, v121
	ds_read2st64_b32 v[100:101], v109 offset1:4
	v_mul_f32_e32 v96, v96, v97
	v_mul_f32_e32 v108, v96, v118
	v_mul_f32_e32 v96, v107, v111
	v_mul_f32_e32 v96, v96, v97
	s_waitcnt lgkmcnt(0)
; #define LAS __attribute__((address_space(3)))
; DEVI u32x4 pack8(const float* f) { u32x4 u; u.x = pk_bf16(f[0], f[1]); u.y = pk_bf16(f[2], f[3]); u.z = pk_bf16(f[4], f[5]); u.w = pk_bf16(f[6], f[7]); return u; }
; DEVI float row_rstd(const LAS float* rsl, int r) { return rsqrtf((rsl[r] + rsl[256 + r]) * (1.0f / DM) + 1e-6f); }
;     DEVI void operator()(const f32x4 (&acc)[2][2][4][2], const Unit& u, int wr, int wc, int fr, int fq, const LAS float* rsl) const {
;         bf16_t* const O = O_; const int ldc = ldc_; const float* const rs = rs_; const int rsn = rsn_;
;         const int row0 = u.pm * BM + wr * 64 + fr, col0 = u.pn * HALF + wc * 32 + 8 * fq;
; #pragma unroll
;         for (int ai = 0; ai < 2; ++ai)
; #pragma unroll
;             for (int m = 0; m < 4; ++m) { bf16_t* rowp = O + (size_t)(row0 + ai * HALF + m * 16) * ldc + col0;
;                 const float sc = row_rstd(rsl, wr * 64 + fr + ai * HALF + m * 16);
;                 const float k1 = -1.4426950408889634f * sc, k2 = sc * sc;
;                 float h[8], tt[8];
;                 const f32x4 guk0 = (acc[ai][0][m][0] * acc[ai][1][m][0]) * k2, guk1 = (acc[ai][0][m][1] * acc[ai][1][m][1]) * k2;
;                 const f32x4 ta = acc[ai][0][m][0] * k1, tb = acc[ai][0][m][1] * k1;
; #pragma unroll
;                 for (int j = 0; j < 4; ++j) { tt[j] = __builtin_amdgcn_exp2f(ta[j]); tt[4 + j] = __builtin_amdgcn_exp2f(tb[j]); }
;                 __builtin_amdgcn_sched_barrier(0);
; #pragma unroll
;                 for (int j = 0; j < 8; ++j) tt[j] = __builtin_amdgcn_rcpf(1.0f + tt[j]);
;                 __builtin_amdgcn_sched_barrier(0);
; #pragma unroll
;                 for (int j = 0; j < 4; ++j) { h[j] = guk0[j] * tt[j]; h[4 + j] = guk1[j] * tt[4 + j]; }
;                 *(u32x4*)rowp = pack8(h); }
	v_add_f32_e32 v100, v100, v101
	v_fmamk_f32 v100, v100, 0x3a000000, v156
	v_mul_f32_e32 v101, 0x4b800000, v100
	v_cmp_gt_f32_e32 vcc, s16, v100
	v_mul_f32_e32 v107, v96, v123
	v_mul_f32_e32 v96, v99, v103
	v_cndmask_b32_e32 v100, v100, v101, vcc
	v_rsq_f32_e32 v100, v100
	v_mul_f32_e32 v96, v96, v97
	v_mul_f32_e32 v98, v98, v122
	v_mul_f32_e32 v99, v96, v119
	v_cvt_pk_bf16_f32 v96, v98, v104
	v_cvt_pk_bf16_f32 v97, v106, v107
	v_cvt_pk_bf16_f32 v98, v102, v105
	v_cvt_pk_bf16_f32 v99, v108, v99
	global_store_dwordx4 v[114:115], v[96:99], off nt
	v_or_b32_e32 v106, 32, v157
	s_nop 0
	v_mul_f32_e32 v96, 0x45800000, v100
	v_cndmask_b32_e32 v97, v100, v96, vcc
	v_mul_f32_e32 v96, 0xbfb8aa3b, v97
	v_pk_mul_f32 v[98:99], v[94:95], v[96:97] op_sel_hi:[1,0]
	v_pk_mul_f32 v[100:101], v[92:93], v[96:97] op_sel_hi:[1,0]
	v_pk_mul_f32 v[104:105], v[84:85], v[96:97] op_sel_hi:[1,0]
	v_pk_mul_f32 v[102:103], v[86:87], v[96:97] op_sel_hi:[1,0]
	v_exp_f32_e32 v96, v100
	v_exp_f32_e32 v100, v104
	v_exp_f32_e32 v104, v105
	v_exp_f32_e32 v105, v98
	v_exp_f32_e32 v107, v99
	v_mad_i64_i32 v[98:99], s[24:25], v106, s38, 0
	v_exp_f32_e32 v101, v101
	v_exp_f32_e32 v102, v102
	v_exp_f32_e32 v103, v103
	v_lshl_add_u64 v[98:99], v[98:99], 1, v[144:145]
	v_add_f32_e32 v96, 1.0, v96
	v_rcp_f32_e32 v106, v96
	v_add_f32_e32 v96, 1.0, v101
	v_rcp_f32_e32 v101, v96
	v_add_f32_e32 v96, 1.0, v105
	v_rcp_f32_e32 v105, v96
	v_add_f32_e32 v96, 1.0, v107
	v_rcp_f32_e32 v107, v96
	v_add_f32_e32 v96, 1.0, v100
	v_rcp_f32_e32 v100, v96
	v_add_f32_e32 v96, 1.0, v104
	v_rcp_f32_e32 v104, v96
	v_add_f32_e32 v96, 1.0, v102
	v_rcp_f32_e32 v102, v96
	v_add_f32_e32 v96, 1.0, v103
	v_rcp_f32_e32 v103, v96
	v_mul_f32_e32 v84, v80, v84
	v_mul_f32_e32 v85, v81, v85
	v_mov_b32_e32 v96, v82
	v_mov_b32_e32 v80, v86
	v_mov_b32_e32 v81, v97
	v_pk_mul_f32 v[80:81], v[96:97], v[80:81]
	v_mul_f32_e32 v89, v89, v93
	v_mul_f32_e32 v84, v84, v81
	v_mul_f32_e32 v88, v88, v92
	v_mul_f32_e32 v86, v84, v100
	v_mul_f32_e32 v84, v89, v81
	v_mul_f32_e32 v90, v90, v94
	v_mul_f32_e32 v82, v88, v81
	v_mul_f32_e32 v88, v84, v101
	v_mul_f32_e32 v84, v85, v81
	v_mul_f32_e32 v89, v84, v104
	v_mul_f32_e32 v84, v90, v81
	v_add_u32_e32 v93, 0xc0, v168
	v_mul_f32_e32 v90, v84, v105
	ds_read2st64_b32 v[84:85], v93 offset1:4
	v_mul_f32_e32 v80, v80, v81
	v_mul_f32_e32 v92, v80, v102
	v_mul_f32_e32 v80, v91, v95
	v_mul_f32_e32 v80, v80, v81
	s_waitcnt lgkmcnt(0)
	v_add_f32_e32 v84, v84, v85
	v_fmamk_f32 v84, v84, 0x3a000000, v156
	v_mul_f32_e32 v85, 0x4b800000, v84
	v_cmp_gt_f32_e32 vcc, s16, v84
	v_mul_f32_e32 v91, v80, v107
	v_mul_f32_e32 v80, v83, v87
	v_cndmask_b32_e32 v84, v84, v85, vcc
	v_rsq_f32_e32 v84, v84
	v_mul_f32_e32 v80, v80, v81
	v_mul_f32_e32 v82, v82, v106
	v_mul_f32_e32 v83, v80, v103
	v_cvt_pk_bf16_f32 v80, v82, v88
	v_cvt_pk_bf16_f32 v81, v90, v91
	v_cvt_pk_bf16_f32 v82, v86, v89
	v_cvt_pk_bf16_f32 v83, v92, v83
	global_store_dwordx4 v[98:99], v[80:83], off nt
	v_or_b32_e32 v90, 48, v157
	s_nop 0
	v_mul_f32_e32 v80, 0x45800000, v84
	v_cndmask_b32_e32 v81, v84, v80, vcc
	v_mul_f32_e32 v80, 0xbfb8aa3b, v81
	v_pk_mul_f32 v[82:83], v[78:79], v[80:81] op_sel_hi:[1,0]
	v_pk_mul_f32 v[84:85], v[76:77], v[80:81] op_sel_hi:[1,0]
	v_pk_mul_f32 v[88:89], v[68:69], v[80:81] op_sel_hi:[1,0]
	v_pk_mul_f32 v[86:87], v[70:71], v[80:81] op_sel_hi:[1,0]
	v_exp_f32_e32 v80, v84
	v_exp_f32_e32 v84, v88
	v_exp_f32_e32 v88, v89
	v_exp_f32_e32 v89, v82
	v_exp_f32_e32 v91, v83
	v_mad_i64_i32 v[82:83], s[24:25], v90, s38, 0
	v_exp_f32_e32 v85, v85
	v_exp_f32_e32 v86, v86
	v_exp_f32_e32 v87, v87
	v_lshl_add_u64 v[82:83], v[82:83], 1, v[144:145]
	v_add_f32_e32 v80, 1.0, v80
	v_rcp_f32_e32 v90, v80
	v_add_f32_e32 v80, 1.0, v85
	v_rcp_f32_e32 v85, v80
	v_add_f32_e32 v80, 1.0, v89
	v_rcp_f32_e32 v89, v80
	v_add_f32_e32 v80, 1.0, v91
	v_rcp_f32_e32 v91, v80
	v_add_f32_e32 v80, 1.0, v84
	v_rcp_f32_e32 v84, v80
	v_add_f32_e32 v80, 1.0, v88
	v_rcp_f32_e32 v88, v80
	v_add_f32_e32 v80, 1.0, v86
	v_rcp_f32_e32 v86, v80
	v_add_f32_e32 v80, 1.0, v87
	v_rcp_f32_e32 v87, v80
	v_mul_f32_e32 v68, v64, v68
	v_mul_f32_e32 v69, v65, v69
	v_mov_b32_e32 v80, v66
	v_mov_b32_e32 v64, v70
	v_mov_b32_e32 v65, v81
	v_pk_mul_f32 v[64:65], v[80:81], v[64:65]
	v_mul_f32_e32 v73, v73, v77
	v_mul_f32_e32 v68, v68, v65
	v_mul_f32_e32 v72, v72, v76
	v_mul_f32_e32 v70, v68, v84
	v_mul_f32_e32 v68, v73, v65
	v_mul_f32_e32 v74, v74, v78
	v_mul_f32_e32 v66, v72, v65
	v_mul_f32_e32 v72, v68, v85
	v_mul_f32_e32 v68, v69, v65
	v_mul_f32_e32 v73, v68, v88
	v_mul_f32_e32 v68, v74, v65
	v_mul_f32_e32 v74, v68, v89
	ds_read2st64_b32 v[68:69], v168 offset0:2 offset1:6
	v_mul_f32_e32 v64, v64, v65
	v_mul_f32_e32 v76, v64, v86
	v_mul_f32_e32 v64, v75, v79
	v_mul_f32_e32 v64, v64, v65
	s_waitcnt lgkmcnt(0)
; #define LAS __attribute__((address_space(3)))
; DEVI u32x4 pack8(const float* f) { u32x4 u; u.x = pk_bf16(f[0], f[1]); u.y = pk_bf16(f[2], f[3]); u.z = pk_bf16(f[4], f[5]); u.w = pk_bf16(f[6], f[7]); return u; }
; DEVI float row_rstd(const LAS float* rsl, int r) { return rsqrtf((rsl[r] + rsl[256 + r]) * (1.0f / DM) + 1e-6f); }
;     DEVI void operator()(const f32x4 (&acc)[2][2][4][2], const Unit& u, int wr, int wc, int fr, int fq, const LAS float* rsl) const {
;         bf16_t* const O = O_; const int ldc = ldc_; const float* const rs = rs_; const int rsn = rsn_;
;         const int row0 = u.pm * BM + wr * 64 + fr, col0 = u.pn * HALF + wc * 32 + 8 * fq;
; #pragma unroll
;         for (int ai = 0; ai < 2; ++ai)
; #pragma unroll
;             for (int m = 0; m < 4; ++m) { bf16_t* rowp = O + (size_t)(row0 + ai * HALF + m * 16) * ldc + col0;
;                 const float sc = row_rstd(rsl, wr * 64 + fr + ai * HALF + m * 16);
;                 const float k1 = -1.4426950408889634f * sc, k2 = sc * sc;
;                 float h[8], tt[8];
;                 const f32x4 guk0 = (acc[ai][0][m][0] * acc[ai][1][m][0]) * k2, guk1 = (acc[ai][0][m][1] * acc[ai][1][m][1]) * k2;
;                 const f32x4 ta = acc[ai][0][m][0] * k1, tb = acc[ai][0][m][1] * k1;
; #pragma unroll
;                 for (int j = 0; j < 4; ++j) { tt[j] = __builtin_amdgcn_exp2f(ta[j]); tt[4 + j] = __builtin_amdgcn_exp2f(tb[j]); }
;                 __builtin_amdgcn_sched_barrier(0);
; #pragma unroll
;                 for (int j = 0; j < 8; ++j) tt[j] = __builtin_amdgcn_rcpf(1.0f + tt[j]);
;                 __builtin_amdgcn_sched_barrier(0);
; #pragma unroll
;                 for (int j = 0; j < 4; ++j) { h[j] = guk0[j] * tt[j]; h[4 + j] = guk1[j] * tt[4 + j]; }
;                 *(u32x4*)rowp = pack8(h); }
	v_add_f32_e32 v68, v68, v69
	v_fmamk_f32 v68, v68, 0x3a000000, v156
	v_mul_f32_e32 v69, 0x4b800000, v68
	v_cmp_gt_f32_e32 vcc, s16, v68
	v_mul_f32_e32 v75, v64, v91
	v_mul_f32_e32 v64, v67, v71
	v_cndmask_b32_e32 v68, v68, v69, vcc
	v_rsq_f32_e32 v68, v68
	v_mul_f32_e32 v64, v64, v65
	v_mul_f32_e32 v66, v66, v90
	v_mul_f32_e32 v67, v64, v87
	v_cvt_pk_bf16_f32 v64, v66, v72
	v_cvt_pk_bf16_f32 v65, v74, v75
	v_cvt_pk_bf16_f32 v66, v70, v73
	v_cvt_pk_bf16_f32 v67, v76, v67
	global_store_dwordx4 v[82:83], v[64:67], off nt
	v_add_u32_e32 v74, 0x80, v157
	s_nop 0
	v_mul_f32_e32 v64, 0x45800000, v68
	v_cndmask_b32_e32 v65, v68, v64, vcc
	v_mul_f32_e32 v64, 0xbfb8aa3b, v65
	v_pk_mul_f32 v[66:67], v[62:63], v[64:65] op_sel_hi:[1,0]
	v_pk_mul_f32 v[68:69], v[60:61], v[64:65] op_sel_hi:[1,0]
	v_pk_mul_f32 v[72:73], v[56:57], v[64:65] op_sel_hi:[1,0]
	v_pk_mul_f32 v[70:71], v[58:59], v[64:65] op_sel_hi:[1,0]
	v_exp_f32_e32 v64, v68
	v_exp_f32_e32 v68, v72
	v_exp_f32_e32 v72, v73
	v_exp_f32_e32 v73, v66
	v_exp_f32_e32 v75, v67
	v_mad_i64_i32 v[66:67], s[24:25], v74, s38, 0
	v_exp_f32_e32 v69, v69
	v_exp_f32_e32 v70, v70
	v_exp_f32_e32 v71, v71
	v_lshl_add_u64 v[66:67], v[66:67], 1, v[144:145]
	v_add_f32_e32 v64, 1.0, v64
	v_rcp_f32_e32 v74, v64
	v_add_f32_e32 v64, 1.0, v69
	v_rcp_f32_e32 v69, v64
	v_add_f32_e32 v64, 1.0, v73
	v_rcp_f32_e32 v73, v64
	v_add_f32_e32 v64, 1.0, v75
	v_rcp_f32_e32 v75, v64
	v_add_f32_e32 v64, 1.0, v68
	v_rcp_f32_e32 v68, v64
	v_add_f32_e32 v64, 1.0, v72
	v_rcp_f32_e32 v72, v64
	v_add_f32_e32 v64, 1.0, v70
	v_rcp_f32_e32 v70, v64
	v_add_f32_e32 v64, 1.0, v71
	v_rcp_f32_e32 v71, v64
	v_mul_f32_e32 v56, v48, v56
	v_mul_f32_e32 v57, v49, v57
	v_mov_b32_e32 v64, v50
	v_mov_b32_e32 v48, v58
	v_mov_b32_e32 v49, v65
	v_mul_f32_e32 v52, v52, v60
	v_pk_mul_f32 v[48:49], v[64:65], v[48:49]
	v_mul_f32_e32 v53, v53, v61
	v_mul_f32_e32 v50, v52, v49
	v_mul_f32_e32 v52, v56, v49
	v_mul_f32_e32 v56, v52, v68
	v_mul_f32_e32 v52, v53, v49
	v_mul_f32_e32 v54, v54, v62
	v_mul_f32_e32 v58, v52, v69
	v_mul_f32_e32 v52, v57, v49
	v_mul_f32_e32 v57, v52, v72
	v_mul_f32_e32 v52, v54, v49
	v_mul_f32_e32 v54, v52, v73
	ds_read2st64_b32 v[52:53], v125 offset0:2 offset1:6
	v_mul_f32_e32 v48, v48, v49
	v_mul_f32_e32 v60, v48, v70
	v_mul_f32_e32 v48, v55, v63
	v_mul_f32_e32 v48, v48, v49
	s_waitcnt lgkmcnt(0)
	v_add_f32_e32 v52, v52, v53
	v_fmamk_f32 v52, v52, 0x3a000000, v156
	v_mul_f32_e32 v53, 0x4b800000, v52
	v_cmp_gt_f32_e32 vcc, s16, v52
	v_mul_f32_e32 v55, v48, v75
	v_mul_f32_e32 v48, v51, v59
	v_cndmask_b32_e32 v52, v52, v53, vcc
	v_rsq_f32_e32 v52, v52
	v_mul_f32_e32 v48, v48, v49
	v_mul_f32_e32 v50, v50, v74
	v_mul_f32_e32 v51, v48, v71
	v_cvt_pk_bf16_f32 v48, v50, v58
	v_cvt_pk_bf16_f32 v49, v54, v55
	v_cvt_pk_bf16_f32 v50, v56, v57
	v_cvt_pk_bf16_f32 v51, v60, v51
	global_store_dwordx4 v[66:67], v[48:51], off nt
	v_add_u32_e32 v58, 0x90, v157
	s_nop 0
	v_mul_f32_e32 v48, 0x45800000, v52
	v_cndmask_b32_e32 v49, v52, v48, vcc
	v_mul_f32_e32 v48, 0xbfb8aa3b, v49
	v_pk_mul_f32 v[50:51], v[46:47], v[48:49] op_sel_hi:[1,0]
	v_pk_mul_f32 v[52:53], v[44:45], v[48:49] op_sel_hi:[1,0]
	v_pk_mul_f32 v[56:57], v[40:41], v[48:49] op_sel_hi:[1,0]
	v_pk_mul_f32 v[54:55], v[42:43], v[48:49] op_sel_hi:[1,0]
	v_exp_f32_e32 v48, v52
	v_exp_f32_e32 v52, v56
	v_exp_f32_e32 v56, v57
	v_exp_f32_e32 v57, v50
	v_exp_f32_e32 v59, v51
	v_mad_i64_i32 v[50:51], s[24:25], v58, s38, 0
	v_exp_f32_e32 v53, v53
	v_exp_f32_e32 v54, v54
	v_exp_f32_e32 v55, v55
	v_lshl_add_u64 v[50:51], v[50:51], 1, v[144:145]
	v_add_f32_e32 v48, 1.0, v48
	v_rcp_f32_e32 v58, v48
	v_add_f32_e32 v48, 1.0, v53
	v_rcp_f32_e32 v53, v48
	v_add_f32_e32 v48, 1.0, v57
	v_rcp_f32_e32 v57, v48
	v_add_f32_e32 v48, 1.0, v59
	v_rcp_f32_e32 v59, v48
	v_add_f32_e32 v48, 1.0, v52
	v_rcp_f32_e32 v52, v48
	v_add_f32_e32 v48, 1.0, v56
	v_rcp_f32_e32 v56, v48
	v_add_f32_e32 v48, 1.0, v54
	v_rcp_f32_e32 v54, v48
	v_add_f32_e32 v48, 1.0, v55
	v_rcp_f32_e32 v55, v48
	v_mul_f32_e32 v40, v32, v40
	v_mul_f32_e32 v41, v33, v41
	v_mov_b32_e32 v48, v34
	v_mov_b32_e32 v32, v42
	v_mov_b32_e32 v33, v49
	v_mul_f32_e32 v36, v36, v44
	v_pk_mul_f32 v[32:33], v[48:49], v[32:33]
	v_mul_f32_e32 v37, v37, v45
	v_mul_f32_e32 v34, v36, v33
	v_mul_f32_e32 v36, v40, v33
	v_mul_f32_e32 v40, v36, v52
	v_mul_f32_e32 v36, v37, v33
	v_mul_f32_e32 v38, v38, v46
	v_mul_f32_e32 v42, v36, v53
	v_mul_f32_e32 v36, v41, v33
	v_mul_f32_e32 v41, v36, v56
	v_mul_f32_e32 v36, v38, v33
	v_mul_f32_e32 v38, v36, v57
	ds_read2st64_b32 v[36:37], v109 offset0:2 offset1:6
	v_mul_f32_e32 v32, v32, v33
	v_mul_f32_e32 v44, v32, v54
	v_mul_f32_e32 v32, v39, v47
	v_mul_f32_e32 v32, v32, v33
	s_waitcnt lgkmcnt(0)
;     DEVI void operator()(const f32x4 (&acc)[2][2][4][2], const Unit& u, int wr, int wc, int fr, int fq, const LAS float* rsl) const {
;         bf16_t* const O = O_; const int ldc = ldc_; const float* const rs = rs_; const int rsn = rsn_;
;         const int row0 = u.pm * BM + wr * 64 + fr, col0 = u.pn * HALF + wc * 32 + 8 * fq;
; #pragma unroll
;         for (int ai = 0; ai < 2; ++ai)
; #pragma unroll
;             for (int m = 0; m < 4; ++m) { bf16_t* rowp = O + (size_t)(row0 + ai * HALF + m * 16) * ldc + col0;
;                 const float sc = row_rstd(rsl, wr * 64 + fr + ai * HALF + m * 16);
;                 const float k1 = -1.4426950408889634f * sc, k2 = sc * sc;
;                 float h[8], tt[8];
;                 const f32x4 guk0 = (acc[ai][0][m][0] * acc[ai][1][m][0]) * k2, guk1 = (acc[ai][0][m][1] * acc[ai][1][m][1]) * k2;
;                 const f32x4 ta = acc[ai][0][m][0] * k1, tb = acc[ai][0][m][1] * k1;
; #pragma unroll
;                 for (int j = 0; j < 4; ++j) { tt[j] = __builtin_amdgcn_exp2f(ta[j]); tt[4 + j] = __builtin_amdgcn_exp2f(tb[j]); }
;                 __builtin_amdgcn_sched_barrier(0);
; #pragma unroll
;                 for (int j = 0; j < 8; ++j) tt[j] = __builtin_amdgcn_rcpf(1.0f + tt[j]);
;                 __builtin_amdgcn_sched_barrier(0);
; #pragma unroll
;                 for (int j = 0; j < 4; ++j) { h[j] = guk0[j] * tt[j]; h[4 + j] = guk1[j] * tt[4 + j]; }
;                 *(u32x4*)rowp = pack8(h); }
; template <class Epi>
; DEVI void gemm_phase(LAS unsigned char* lds, const bf16_t* gA, const bf16_t* gBt, const int lda, const int ldb, const int K, const StaticOrder S_, const Epi E) {
;     ...
;     auto rs_prefetch = [&](const Unit& u, int par) {
;         if constexpr (Epi::HAS_RS) { if (E.rs_) {
;             const int r = tid & 255, hf = tid >> 8; float s = 0.f;
;             const float* base = E.rs_ + (size_t)(u.pm * BM + r) * 32 + hf * 16;
;             if (E.rsn_ == 32) {
;                 const f32x4 a = *(const f32x4*)base, b = *(const f32x4*)(base + 4), c = *(const f32x4*)(base + 8), d = *(const f32x4*)(base + 12);
;                 s = ((a[0] + a[1]) + (a[2] + a[3])) + ((b[0] + b[1]) + (b[2] + b[3])) + ((c[0] + c[1]) + (c[2] + c[3])) + ((d[0] + d[1]) + (d[2] + d[3]));
;             } else if (hf == 0) s = base[0];
;             *(LAS float*)(lds + STAGE_BYTES + par * 2048 + hf * 1024 + r * 4) = s; } }
	v_add_f32_e32 v36, v36, v37
	v_fmamk_f32 v36, v36, 0x3a000000, v156
	v_mul_f32_e32 v37, 0x4b800000, v36
	v_cmp_gt_f32_e32 vcc, s16, v36
	v_mul_f32_e32 v39, v32, v59
	v_mul_f32_e32 v32, v35, v43
	v_cndmask_b32_e32 v36, v36, v37, vcc
	v_rsq_f32_e32 v36, v36
	v_mul_f32_e32 v32, v32, v33
	v_mul_f32_e32 v34, v34, v58
	v_mul_f32_e32 v35, v32, v55
	v_cvt_pk_bf16_f32 v32, v34, v42
	v_cvt_pk_bf16_f32 v33, v38, v39
	v_cvt_pk_bf16_f32 v34, v40, v41
	v_cvt_pk_bf16_f32 v35, v44, v35
	global_store_dwordx4 v[50:51], v[32:35], off nt
	v_add_u32_e32 v42, 0xa0, v157
	s_nop 0
	v_mul_f32_e32 v32, 0x45800000, v36
	v_cndmask_b32_e32 v33, v36, v32, vcc
	v_mul_f32_e32 v32, 0xbfb8aa3b, v33
	v_pk_mul_f32 v[34:35], v[30:31], v[32:33] op_sel_hi:[1,0]
	v_pk_mul_f32 v[36:37], v[28:29], v[32:33] op_sel_hi:[1,0]
	v_pk_mul_f32 v[40:41], v[24:25], v[32:33] op_sel_hi:[1,0]
	v_pk_mul_f32 v[38:39], v[26:27], v[32:33] op_sel_hi:[1,0]
	v_exp_f32_e32 v32, v36
	v_exp_f32_e32 v36, v40
	v_exp_f32_e32 v40, v41
	v_exp_f32_e32 v41, v34
	v_exp_f32_e32 v43, v35
	v_mad_i64_i32 v[34:35], s[24:25], v42, s38, 0
	v_exp_f32_e32 v37, v37
	v_exp_f32_e32 v38, v38
	v_exp_f32_e32 v39, v39
	v_lshl_add_u64 v[34:35], v[34:35], 1, v[144:145]
	v_add_f32_e32 v32, 1.0, v32
	v_rcp_f32_e32 v42, v32
	v_add_f32_e32 v32, 1.0, v37
	v_rcp_f32_e32 v37, v32
	v_add_f32_e32 v32, 1.0, v41
	v_rcp_f32_e32 v41, v32
	v_add_f32_e32 v32, 1.0, v43
	v_rcp_f32_e32 v43, v32
	v_add_f32_e32 v32, 1.0, v36
	v_rcp_f32_e32 v36, v32
	v_add_f32_e32 v32, 1.0, v40
	v_rcp_f32_e32 v40, v32
	v_add_f32_e32 v32, 1.0, v38
	v_rcp_f32_e32 v38, v32
	v_add_f32_e32 v32, 1.0, v39
	v_rcp_f32_e32 v39, v32
	v_mul_f32_e32 v24, v16, v24
	v_mul_f32_e32 v25, v17, v25
	v_mov_b32_e32 v32, v18
	v_mov_b32_e32 v16, v26
	v_mov_b32_e32 v17, v33
	v_mul_f32_e32 v20, v20, v28
	v_pk_mul_f32 v[16:17], v[32:33], v[16:17]
	v_mul_f32_e32 v21, v21, v29
	v_mul_f32_e32 v18, v20, v17
	v_mul_f32_e32 v20, v24, v17
	v_mul_f32_e32 v24, v20, v36
	v_mul_f32_e32 v20, v21, v17
	v_mul_f32_e32 v22, v22, v30
	v_mul_f32_e32 v26, v20, v37
	v_mul_f32_e32 v20, v25, v17
	v_mul_f32_e32 v25, v20, v40
	v_mul_f32_e32 v20, v22, v17
	v_mul_f32_e32 v22, v20, v41
	ds_read2st64_b32 v[20:21], v93 offset0:2 offset1:6
	v_mul_f32_e32 v16, v16, v17
	v_mul_f32_e32 v28, v16, v38
	v_mul_f32_e32 v16, v23, v31
	v_mul_f32_e32 v16, v16, v17
	s_waitcnt lgkmcnt(0)
	v_add_f32_e32 v20, v20, v21
	v_fmamk_f32 v20, v20, 0x3a000000, v156
	v_mul_f32_e32 v21, 0x4b800000, v20
	v_cmp_gt_f32_e32 vcc, s16, v20
	v_mul_f32_e32 v23, v16, v43
	v_mul_f32_e32 v16, v19, v27
	v_cndmask_b32_e32 v20, v20, v21, vcc
	v_rsq_f32_e32 v20, v20
	v_mul_f32_e32 v16, v16, v17
	v_mul_f32_e32 v18, v18, v42
	v_mul_f32_e32 v19, v16, v39
	v_cvt_pk_bf16_f32 v16, v18, v26
	v_cvt_pk_bf16_f32 v17, v22, v23
	v_cvt_pk_bf16_f32 v18, v24, v25
	v_cvt_pk_bf16_f32 v19, v28, v19
	global_store_dwordx4 v[34:35], v[16:19], off nt
	v_add_u32_e32 v26, 0xb0, v157
	s_nop 0
	v_mul_f32_e32 v16, 0x45800000, v20
	v_cndmask_b32_e32 v17, v20, v16, vcc
	v_mul_f32_e32 v16, 0xbfb8aa3b, v17
	v_pk_mul_f32 v[18:19], v[14:15], v[16:17] op_sel_hi:[1,0]
	v_pk_mul_f32 v[20:21], v[12:13], v[16:17] op_sel_hi:[1,0]
	v_pk_mul_f32 v[24:25], v[8:9], v[16:17] op_sel_hi:[1,0]
	v_pk_mul_f32 v[22:23], v[10:11], v[16:17] op_sel_hi:[1,0]
	v_exp_f32_e32 v16, v20
	v_exp_f32_e32 v20, v24
	v_exp_f32_e32 v24, v25
	v_exp_f32_e32 v25, v18
	v_exp_f32_e32 v27, v19
	v_mad_i64_i32 v[18:19], s[24:25], v26, s38, 0
	v_exp_f32_e32 v21, v21
	v_exp_f32_e32 v22, v22
	v_exp_f32_e32 v23, v23
	v_lshl_add_u64 v[18:19], v[18:19], 1, v[144:145]
	v_add_f32_e32 v16, 1.0, v16
	v_rcp_f32_e32 v26, v16
	v_add_f32_e32 v16, 1.0, v21
	v_rcp_f32_e32 v21, v16
	v_add_f32_e32 v16, 1.0, v25
	v_rcp_f32_e32 v25, v16
	v_add_f32_e32 v16, 1.0, v27
	v_rcp_f32_e32 v27, v16
	v_add_f32_e32 v16, 1.0, v20
	v_rcp_f32_e32 v20, v16
	v_add_f32_e32 v16, 1.0, v24
	v_rcp_f32_e32 v24, v16
	v_add_f32_e32 v16, 1.0, v22
	v_rcp_f32_e32 v22, v16
	v_add_f32_e32 v16, 1.0, v23
	v_rcp_f32_e32 v23, v16
	v_mul_f32_e32 v8, v0, v8
	v_mul_f32_e32 v9, v1, v9
	v_mov_b32_e32 v16, v2
	v_mov_b32_e32 v0, v10
	v_mov_b32_e32 v1, v17
	v_pk_mul_f32 v[0:1], v[16:17], v[0:1]
	v_mul_f32_e32 v4, v4, v12
	v_mul_f32_e32 v0, v0, v1
	v_mul_f32_e32 v2, v4, v1
	v_mul_f32_e32 v4, v8, v1
	v_mul_f32_e32 v8, v9, v1
	v_mul_f32_e32 v9, v0, v22
	v_mul_f32_e32 v0, v7, v15
	v_mul_f32_e32 v0, v0, v1
	v_mul_f32_e32 v7, v0, v27
	v_mul_f32_e32 v0, v3, v11
	v_mul_f32_e32 v5, v5, v13
	v_mul_f32_e32 v6, v6, v14
	v_mul_f32_e32 v0, v0, v1
	v_readlane_b32 s80, v237, 2
	v_mul_f32_e32 v2, v2, v26
	v_mul_f32_e32 v5, v5, v1
	v_mul_f32_e32 v6, v6, v1
	v_mul_f32_e32 v3, v0, v23
	s_and_b64 vcc, exec, s[6:7]
	s_mov_b64 s[6:7], -1
	v_readlane_b32 s81, v237, 3
	v_readlane_b32 s82, v237, 4
	v_readlane_b32 s83, v237, 5
	v_mul_f32_e32 v4, v4, v20
	v_mul_f32_e32 v5, v5, v21
	v_mul_f32_e32 v8, v8, v24
	v_mul_f32_e32 v6, v6, v25
	v_cvt_pk_bf16_f32 v0, v2, v5
	v_cvt_pk_bf16_f32 v1, v6, v7
	v_cvt_pk_bf16_f32 v2, v4, v8
	v_cvt_pk_bf16_f32 v3, v9, v3
	global_store_dwordx4 v[18:19], v[0:3], off nt
	s_cbranch_vccnz .LBB0_250
	s_and_b64 vcc, exec, s[14:15]
	s_cbranch_vccz .LBB0_249
	v_lshl_or_b32 v0, s73, 8, v146
	v_ashrrev_i32_e32 v1, 31, v0
	v_readlane_b32 s24, v237, 8
	v_lshlrev_b64 v[0:1], 7, v[0:1]
	v_readlane_b32 s25, v237, 9
	v_lshl_add_u64 v[0:1], v[136:137], 0, v[0:1]
	s_and_b64 vcc, exec, s[24:25]
	s_cbranch_vccz .LBB0_266
	v_mov_b32_e32 v2, 0
	s_mov_b64 s[6:7], exec
	v_readlane_b32 s24, v237, 20
	v_readlane_b32 s25, v237, 21
	s_and_b64 s[24:25], s[6:7], s[24:25]
	s_mov_b64 exec, s[24:25]
	s_cbranch_execz .LBB0_265
	global_load_dword v2, v[0:1], off

; #define LAS __attribute__((address_space(3)))
; DEVI unsigned pk_bf16(float lo, float hi) { unsigned r; asm("v_cvt_pk_bf16_f32 %0, %1, %2" : "=v"(r) : "v"(lo), "v"(hi)); return r; }
;     DEVI void operator()(const f32x4 (&acc)[2][2][4][2], const Unit& u, int wr, int wc, int fr, int fq, const LAS float*) const {
;         float* const C = C_; const float* const R = R_; const int ldc = ldc_; bf16_t* const HB = HB_; float* const RS = RS_;
;         float scale = scale_; asm volatile("" : "+v"(scale));
;         const int row0 = u.pm * BM + wr * 64 + fr, col0 = u.pn * BM + wc * 32 + 4 * fq;
;         f32x4 cur[2][2], nxt[2][2];
;         { const size_t ro = (size_t)row0 * ldc + col0;
; #pragma unroll
;           for (int bj = 0; bj < 2; ++bj)
; #pragma unroll
;               for (int n = 0; n < 2; ++n) cur[bj][n] = *(const f32x4*)(R + ro + bj * HALF + n * 16); }
; #pragma unroll
;         for (int idx = 0; idx < 8; ++idx) {
;             const int ai = idx >> 2, m = idx & 3;
;             const size_t ro = (size_t)(row0 + ai * HALF + m * 16) * ldc + col0;
;             if (idx + 1 < 8) { const int ai2 = (idx + 1) >> 2, m2 = (idx + 1) & 3; const size_t ro2 = (size_t)(row0 + ai2 * HALF + m2 * 16) * ldc + col0;
; #pragma unroll
;                 for (int bj = 0; bj < 2; ++bj)
; #pragma unroll
;                     for (int n = 0; n < 2; ++n) nxt[bj][n] = *(const f32x4*)(R + ro2 + bj * HALF + n * 16); }
;             float ss = 0.f;
; #pragma unroll
;             for (int bj = 0; bj < 2; ++bj)
; #pragma unroll
;                 for (int n = 0; n < 2; ++n) {
;                     const f32x4 hn = cur[bj][n] + acc[ai][bj][m][n] * scale;
;                     *(f32x4*)(C + ro + bj * HALF + n * 16) = hn;
;                     if (HB) { u32x2 w; w.x = pk_bf16(hn[0], hn[1]); w.y = pk_bf16(hn[2], hn[3]); *(u32x2*)(HB + ro + bj * HALF + n * 16) = w;
;                         ss += hn[0] * hn[0] + hn[1] * hn[1] + hn[2] * hn[2] + hn[3] * hn[3]; } }
;             if (HB) { ss += __shfl_xor(ss, 16); ss += __shfl_xor(ss, 32); if (fq == 0) RS[(size_t)(row0 + ai * HALF + m * 16) * 32 + u.pn * 4 + wc] = ss; }
.LBB0_389:
	v_lshl_add_u32 v188, s35, 8, v198
	v_lshl_or_b32 v182, s31, 8, v200
	v_mad_i64_i32 v[128:129], s[14:15], v188, s46, 0
	v_ashrrev_i32_e32 v183, 31, v182
	v_lshl_add_u64 v[128:129], v[128:129], 2, s[94:95]
	v_lshlrev_b64 v[130:131], 2, v[182:183]
	v_or_b32_e32 v190, 16, v188
	v_mov_b32_e32 v180, v204
	v_lshl_add_u64 v[128:129], v[128:129], 0, v[130:131]
	v_lshl_add_u64 v[186:187], s[94:95], 0, v[130:131]
	v_mad_i64_i32 v[192:193], s[16:17], v190, s46, 0
	global_load_dwordx4 v[160:163], v[128:129], off
	global_load_dwordx4 v[152:155], v[128:129], off offset:64
	global_load_dwordx4 v[148:151], v[128:129], off offset:512
	global_load_dwordx4 v[140:143], v[128:129], off offset:576
	v_lshl_add_u64 v[128:129], v[192:193], 2, v[186:187]
	global_load_dwordx4 v[144:147], v[128:129], off
	global_load_dwordx4 v[136:139], v[128:129], off offset:64
	global_load_dwordx4 v[132:135], v[128:129], off offset:512
	s_nop 0
	global_load_dwordx4 v[128:131], v[128:129], off offset:576
	s_lshl_b32 s14, s31, 2
	s_ashr_i32 s15, s14, 31
	s_lshl_b64 s[14:15], s[14:15], 2
	v_mov_b32_e32 v184, v180
	v_mov_b32_e32 v185, v180
	s_add_u32 s14, s4, s14
	v_mad_i64_i32 v[158:159], s[16:17], v188, s46, v[182:183]
	v_ashrrev_i32_e32 v189, 31, v188
	s_addc_u32 s15, s5, s15
	v_lshl_add_u64 v[194:195], v[158:159], 2, s[92:93]
	s_andn2_b64 vcc, exec, s[8:9]
	s_waitcnt vmcnt(0)
	v_pk_fma_f32 v[164:165], v[126:127], v[180:181], v[162:163] op_sel_hi:[1,0,1]
	v_pk_fma_f32 v[162:163], v[124:125], v[180:181], v[160:161] op_sel_hi:[1,0,1]
	v_cndmask_b32_e64 v124, 0, 1, s[8:9]
	v_cmp_ne_u32_e64 s[40:41], 1, v124
	v_pk_fma_f32 v[160:161], v[120:121], v[184:185], v[152:153]
	v_pk_fma_f32 v[156:157], v[116:117], v[184:185], v[148:149]
	v_pk_fma_f32 v[124:125], v[112:113], v[184:185], v[140:141]
	global_store_dwordx4 v[194:195], v[162:165], off nt
	s_cbranch_vccnz .LBB0_428
	v_readlane_b32 s72, v240, 54
	v_readlane_b32 s74, v240, 56
	v_readlane_b32 s75, v240, 57
	v_cvt_pk_bf16_f32 v116, v162, v163
	v_mul_f32_e32 v120, v163, v163
	v_mov_b32_e32 v181, v180
	v_lshl_add_u64 v[112:113], v[158:159], 1, s[74:75]
	v_cvt_pk_bf16_f32 v117, v164, v165
	global_store_dwordx2 v[112:113], v[116:117], off
	v_fmac_f32_e32 v120, v162, v162
	v_pk_fma_f32 v[162:163], v[122:123], v[180:181], v[154:155]
	v_cvt_pk_bf16_f32 v116, v160, v161
	global_store_dwordx4 v[194:195], v[160:163], off offset:64 nt
	v_cvt_pk_bf16_f32 v117, v162, v163
	global_store_dwordx2 v[112:113], v[116:117], off offset:32
	v_mul_f32_e32 v116, v161, v161
	v_fmac_f32_e32 v116, v160, v160
	v_fmac_f32_e32 v120, v164, v164
	v_fmac_f32_e32 v116, v162, v162
	v_fmac_f32_e32 v120, v165, v165
	v_fmac_f32_e32 v116, v163, v163
	v_add_f32_e32 v120, v120, v116
	v_pk_fma_f32 v[158:159], v[118:119], v[180:181], v[150:151]
	v_cvt_pk_bf16_f32 v116, v156, v157
	global_store_dwordx4 v[194:195], v[156:159], off offset:512 nt
	v_cvt_pk_bf16_f32 v117, v158, v159
	global_store_dwordx2 v[112:113], v[116:117], off offset:256
	v_mul_f32_e32 v116, v157, v157
	v_fmac_f32_e32 v116, v156, v156
	v_fmac_f32_e32 v116, v158, v158
	v_fmac_f32_e32 v116, v159, v159
	v_add_f32_e32 v120, v116, v120
	v_pk_fma_f32 v[126:127], v[114:115], v[180:181], v[142:143]
	v_cvt_pk_bf16_f32 v116, v124, v125
	global_store_dwordx4 v[194:195], v[124:127], off offset:576 nt
	v_cvt_pk_bf16_f32 v117, v126, v127
	global_store_dwordx2 v[112:113], v[116:117], off offset:288
	v_mul_f32_e32 v112, v125, v125
	v_and_b32_e32 v116, 64, v205
	v_fmac_f32_e32 v112, v124, v124
	v_xor_b32_e32 v113, 16, v205
	v_add_u32_e32 v116, 64, v116
	v_fmac_f32_e32 v112, v126, v126
	v_cmp_lt_i32_e32 vcc, v113, v116
	v_fmac_f32_e32 v112, v127, v127
	v_add_f32_e32 v112, v112, v120
	v_cndmask_b32_e32 v113, v205, v113, vcc
	v_lshlrev_b32_e32 v113, 2, v113
	ds_bpermute_b32 v113, v113, v112
	v_readlane_b32 s73, v240, 55
	s_waitcnt lgkmcnt(0)
	v_add_f32_e32 v112, v112, v113
	v_xor_b32_e32 v113, 32, v205
	v_cmp_lt_i32_e32 vcc, v113, v116
	s_nop 1
	v_cndmask_b32_e32 v113, v205, v113, vcc
	v_lshlrev_b32_e32 v113, 2, v113
	ds_bpermute_b32 v113, v113, v112
	s_and_saveexec_b64 s[16:17], s[36:37]
	s_cbranch_execz .LBB0_392
	s_waitcnt lgkmcnt(0)
	v_add_f32_e32 v116, v112, v113
	v_lshlrev_b64 v[112:113], 7, v[188:189]
	v_lshl_add_u64 v[112:113], s[14:15], 0, v[112:113]
	global_store_dword v[112:113], v116, off

; DEVI unsigned pk_bf16(float lo, float hi) { unsigned r; asm("v_cvt_pk_bf16_f32 %0, %1, %2" : "=v"(r) : "v"(lo), "v"(hi)); return r; }
;     DEVI void operator()(const f32x4 (&acc)[2][2][4][2], const Unit& u, int wr, int wc, int fr, int fq, const LAS float*) const {
;     ...
;         for (int idx = 0; idx < 8; ++idx) {
;             const int ai = idx >> 2, m = idx & 3;
;             const size_t ro = (size_t)(row0 + ai * HALF + m * 16) * ldc + col0;
;             if (idx + 1 < 8) { const int ai2 = (idx + 1) >> 2, m2 = (idx + 1) & 3; const size_t ro2 = (size_t)(row0 + ai2 * HALF + m2 * 16) * ldc + col0;
; #pragma unroll
;                 for (int bj = 0; bj < 2; ++bj)
; #pragma unroll
;                     for (int n = 0; n < 2; ++n) nxt[bj][n] = *(const f32x4*)(R + ro2 + bj * HALF + n * 16); }
;             float ss = 0.f;
; #pragma unroll
;             for (int bj = 0; bj < 2; ++bj)
; #pragma unroll
;                 for (int n = 0; n < 2; ++n) {
;                     const f32x4 hn = cur[bj][n] + acc[ai][bj][m][n] * scale;
;                     *(f32x4*)(C + ro + bj * HALF + n * 16) = hn;
;                     if (HB) { u32x2 w; w.x = pk_bf16(hn[0], hn[1]); w.y = pk_bf16(hn[2], hn[3]); *(u32x2*)(HB + ro + bj * HALF + n * 16) = w;
;                         ss += hn[0] * hn[0] + hn[1] * hn[1] + hn[2] * hn[2] + hn[3] * hn[3]; } }
;             if (HB) { ss += __shfl_xor(ss, 16); ss += __shfl_xor(ss, 32); if (fq == 0) RS[(size_t)(row0 + ai * HALF + m * 16) * 32 + u.pn * 4 + wc] = ss; }
.LBB0_393:
	v_mov_b32_e32 v181, v180
	v_pk_fma_f32 v[162:163], v[122:123], v[180:181], v[154:155]
	v_pk_fma_f32 v[158:159], v[118:119], v[180:181], v[150:151]
	v_pk_fma_f32 v[126:127], v[114:115], v[180:181], v[142:143]
	global_store_dwordx4 v[194:195], v[160:163], off offset:64 nt
	global_store_dwordx4 v[194:195], v[156:159], off offset:512 nt
	global_store_dwordx4 v[194:195], v[124:127], off offset:576 nt
.LBB0_394:
	v_or_b32_e32 v150, 32, v188
	v_mad_i64_i32 v[152:153], s[16:17], v150, s46, 0
	s_waitcnt lgkmcnt(0)
	v_lshl_add_u64 v[112:113], v[152:153], 2, v[186:187]
	global_load_dwordx4 v[124:127], v[112:113], off
	global_load_dwordx4 v[120:123], v[112:113], off offset:64
	global_load_dwordx4 v[116:119], v[112:113], off offset:512
	s_nop 0
	global_load_dwordx4 v[112:115], v[112:113], off offset:576
	v_lshl_add_u64 v[142:143], v[192:193], 0, v[182:183]
	v_mov_b32_e32 v181, v180
	v_lshl_add_u64 v[154:155], v[142:143], 2, s[92:93]
	v_pk_fma_f32 v[148:149], v[110:111], v[180:181], v[146:147]
	v_pk_fma_f32 v[146:147], v[108:109], v[184:185], v[144:145]
	s_and_b64 vcc, exec, s[40:41]
	v_pk_fma_f32 v[144:145], v[104:105], v[184:185], v[136:137]
	v_pk_fma_f32 v[140:141], v[100:101], v[184:185], v[132:133]
	v_pk_fma_f32 v[108:109], v[96:97], v[184:185], v[128:129]
	global_store_dwordx4 v[154:155], v[146:149], off nt
	s_cbranch_vccnz .LBB0_429
	v_readlane_b32 s72, v240, 54
	v_readlane_b32 s74, v240, 56
	v_readlane_b32 s75, v240, 57
	v_cvt_pk_bf16_f32 v100, v146, v147
	v_mul_f32_e32 v104, v147, v147
	v_cvt_pk_bf16_f32 v101, v148, v149
	v_fmac_f32_e32 v104, v146, v146
	v_lshl_add_u64 v[96:97], v[142:143], 1, s[74:75]
	global_store_dwordx2 v[96:97], v[100:101], off
	v_pk_fma_f32 v[146:147], v[106:107], v[180:181], v[138:139]
	v_cvt_pk_bf16_f32 v100, v144, v145
	global_store_dwordx4 v[154:155], v[144:147], off offset:64 nt
	v_cvt_pk_bf16_f32 v101, v146, v147
	global_store_dwordx2 v[96:97], v[100:101], off offset:32
	v_mul_f32_e32 v100, v145, v145
	v_fmac_f32_e32 v100, v144, v144
	v_fmac_f32_e32 v104, v148, v148
	v_fmac_f32_e32 v100, v146, v146
	v_fmac_f32_e32 v104, v149, v149
	v_fmac_f32_e32 v100, v147, v147
	v_add_f32_e32 v104, v104, v100
	v_pk_fma_f32 v[142:143], v[102:103], v[180:181], v[134:135]
	v_cvt_pk_bf16_f32 v100, v140, v141
	global_store_dwordx4 v[154:155], v[140:143], off offset:512 nt
	v_cvt_pk_bf16_f32 v101, v142, v143
	global_store_dwordx2 v[96:97], v[100:101], off offset:256
	v_mul_f32_e32 v100, v141, v141
	v_fmac_f32_e32 v100, v140, v140
	v_fmac_f32_e32 v100, v142, v142
	v_fmac_f32_e32 v100, v143, v143
	v_add_f32_e32 v104, v104, v100
	v_pk_fma_f32 v[110:111], v[98:99], v[180:181], v[130:131]
	v_cvt_pk_bf16_f32 v100, v108, v109
	global_store_dwordx4 v[154:155], v[108:111], off offset:576 nt
	v_cvt_pk_bf16_f32 v101, v110, v111
	global_store_dwordx2 v[96:97], v[100:101], off offset:288
	v_mul_f32_e32 v96, v109, v109
	v_and_b32_e32 v100, 64, v205
	v_fmac_f32_e32 v96, v108, v108
	v_xor_b32_e32 v97, 16, v205
	v_add_u32_e32 v100, 64, v100
	v_fmac_f32_e32 v96, v110, v110
	v_cmp_lt_i32_e32 vcc, v97, v100
	v_fmac_f32_e32 v96, v111, v111
	v_add_f32_e32 v96, v104, v96
	v_cndmask_b32_e32 v97, v205, v97, vcc
	v_lshlrev_b32_e32 v97, 2, v97
	ds_bpermute_b32 v97, v97, v96
	v_readlane_b32 s73, v240, 55
	s_waitcnt lgkmcnt(0)
	v_add_f32_e32 v96, v96, v97
	v_xor_b32_e32 v97, 32, v205
	v_cmp_lt_i32_e32 vcc, v97, v100
	s_nop 1
	v_cndmask_b32_e32 v97, v205, v97, vcc
	v_lshlrev_b32_e32 v97, 2, v97
	ds_bpermute_b32 v97, v97, v96
	s_and_saveexec_b64 s[16:17], s[36:37]
	s_cbranch_execz .LBB0_397
	v_ashrrev_i32_e32 v191, 31, v190
	s_waitcnt lgkmcnt(0)
	v_add_f32_e32 v100, v96, v97
	v_lshlrev_b64 v[96:97], 7, v[190:191]
	v_lshl_add_u64 v[96:97], s[14:15], 0, v[96:97]
	global_store_dword v[96:97], v100, off

; DEVI unsigned pk_bf16(float lo, float hi) { unsigned r; asm("v_cvt_pk_bf16_f32 %0, %1, %2" : "=v"(r) : "v"(lo), "v"(hi)); return r; }
;     DEVI void operator()(const f32x4 (&acc)[2][2][4][2], const Unit& u, int wr, int wc, int fr, int fq, const LAS float*) const {
;     ...
;         for (int idx = 0; idx < 8; ++idx) {
;             const int ai = idx >> 2, m = idx & 3;
;             const size_t ro = (size_t)(row0 + ai * HALF + m * 16) * ldc + col0;
;             if (idx + 1 < 8) { const int ai2 = (idx + 1) >> 2, m2 = (idx + 1) & 3; const size_t ro2 = (size_t)(row0 + ai2 * HALF + m2 * 16) * ldc + col0;
; #pragma unroll
;                 for (int bj = 0; bj < 2; ++bj)
; #pragma unroll
;                     for (int n = 0; n < 2; ++n) nxt[bj][n] = *(const f32x4*)(R + ro2 + bj * HALF + n * 16); }
;             float ss = 0.f;
; #pragma unroll
;             for (int bj = 0; bj < 2; ++bj)
; #pragma unroll
;                 for (int n = 0; n < 2; ++n) {
;                     const f32x4 hn = cur[bj][n] + acc[ai][bj][m][n] * scale;
;                     *(f32x4*)(C + ro + bj * HALF + n * 16) = hn;
;                     if (HB) { u32x2 w; w.x = pk_bf16(hn[0], hn[1]); w.y = pk_bf16(hn[2], hn[3]); *(u32x2*)(HB + ro + bj * HALF + n * 16) = w;
;                         ss += hn[0] * hn[0] + hn[1] * hn[1] + hn[2] * hn[2] + hn[3] * hn[3]; } }
;             if (HB) { ss += __shfl_xor(ss, 16); ss += __shfl_xor(ss, 32); if (fq == 0) RS[(size_t)(row0 + ai * HALF + m * 16) * 32 + u.pn * 4 + wc] = ss; }
.LBB0_398:
	v_mov_b32_e32 v181, v180
	v_pk_fma_f32 v[146:147], v[106:107], v[180:181], v[138:139]
	v_pk_fma_f32 v[142:143], v[102:103], v[180:181], v[134:135]
	v_pk_fma_f32 v[110:111], v[98:99], v[180:181], v[130:131]
	global_store_dwordx4 v[154:155], v[144:147], off offset:64 nt
	global_store_dwordx4 v[154:155], v[140:143], off offset:512 nt
	global_store_dwordx4 v[154:155], v[108:111], off offset:576 nt
.LBB0_399:
	v_or_b32_e32 v134, 48, v188
	v_mad_i64_i32 v[136:137], s[16:17], v134, s46, 0
	s_waitcnt lgkmcnt(0)
	v_lshl_add_u64 v[96:97], v[136:137], 2, v[186:187]
	global_load_dwordx4 v[108:111], v[96:97], off
	global_load_dwordx4 v[104:107], v[96:97], off offset:64
	global_load_dwordx4 v[100:103], v[96:97], off offset:512
	s_nop 0
	global_load_dwordx4 v[96:99], v[96:97], off offset:576
	v_lshl_add_u64 v[140:141], v[152:153], 0, v[182:183]
	v_mov_b32_e32 v181, v180
	v_lshl_add_u64 v[138:139], v[140:141], 2, s[92:93]
	s_waitcnt vmcnt(8)
	v_pk_fma_f32 v[132:133], v[94:95], v[180:181], v[126:127]
	v_pk_fma_f32 v[130:131], v[92:93], v[184:185], v[124:125]
	s_and_b64 vcc, exec, s[40:41]
	s_waitcnt vmcnt(7)
	v_pk_fma_f32 v[128:129], v[88:89], v[184:185], v[120:121]
	s_waitcnt vmcnt(6)
	v_pk_fma_f32 v[124:125], v[84:85], v[184:185], v[116:117]
	s_waitcnt vmcnt(5)
	v_pk_fma_f32 v[92:93], v[80:81], v[184:185], v[112:113]
	global_store_dwordx4 v[138:139], v[130:133], off nt
	s_cbranch_vccnz .LBB0_430
	v_readlane_b32 s72, v240, 54
	v_readlane_b32 s74, v240, 56
	v_readlane_b32 s75, v240, 57
	v_cvt_pk_bf16_f32 v84, v130, v131
	v_mul_f32_e32 v88, v131, v131
	v_cvt_pk_bf16_f32 v85, v132, v133
	v_fmac_f32_e32 v88, v130, v130
	v_lshl_add_u64 v[80:81], v[140:141], 1, s[74:75]
	global_store_dwordx2 v[80:81], v[84:85], off
	v_pk_fma_f32 v[130:131], v[90:91], v[180:181], v[122:123]
	v_cvt_pk_bf16_f32 v84, v128, v129
	global_store_dwordx4 v[138:139], v[128:131], off offset:64 nt
	v_cvt_pk_bf16_f32 v85, v130, v131
	global_store_dwordx2 v[80:81], v[84:85], off offset:32
	v_mul_f32_e32 v84, v129, v129
	v_fmac_f32_e32 v84, v128, v128
	v_fmac_f32_e32 v88, v132, v132
	v_fmac_f32_e32 v84, v130, v130
	v_fmac_f32_e32 v88, v133, v133
	v_fmac_f32_e32 v84, v131, v131
	v_add_f32_e32 v88, v88, v84
	v_pk_fma_f32 v[126:127], v[86:87], v[180:181], v[118:119]
	v_cvt_pk_bf16_f32 v84, v124, v125
	global_store_dwordx4 v[138:139], v[124:127], off offset:512 nt
	v_cvt_pk_bf16_f32 v85, v126, v127
	global_store_dwordx2 v[80:81], v[84:85], off offset:256
	v_mul_f32_e32 v84, v125, v125
	v_fmac_f32_e32 v84, v124, v124
	v_fmac_f32_e32 v84, v126, v126
	v_fmac_f32_e32 v84, v127, v127
	v_add_f32_e32 v88, v88, v84
	v_pk_fma_f32 v[94:95], v[82:83], v[180:181], v[114:115]
	v_cvt_pk_bf16_f32 v84, v92, v93
	global_store_dwordx4 v[138:139], v[92:95], off offset:576 nt
	v_cvt_pk_bf16_f32 v85, v94, v95
	global_store_dwordx2 v[80:81], v[84:85], off offset:288
	v_mul_f32_e32 v80, v93, v93
	v_and_b32_e32 v84, 64, v205
	v_fmac_f32_e32 v80, v92, v92
	v_xor_b32_e32 v81, 16, v205
	v_add_u32_e32 v84, 64, v84
	v_fmac_f32_e32 v80, v94, v94
	v_cmp_lt_i32_e32 vcc, v81, v84
	v_fmac_f32_e32 v80, v95, v95
	v_add_f32_e32 v80, v88, v80
	v_cndmask_b32_e32 v81, v205, v81, vcc
	v_lshlrev_b32_e32 v81, 2, v81
	ds_bpermute_b32 v81, v81, v80
	v_readlane_b32 s73, v240, 55
	s_waitcnt lgkmcnt(0)
	v_add_f32_e32 v80, v80, v81
	v_xor_b32_e32 v81, 32, v205
	v_cmp_lt_i32_e32 vcc, v81, v84
	s_nop 1
	v_cndmask_b32_e32 v81, v205, v81, vcc
	v_lshlrev_b32_e32 v81, 2, v81
	ds_bpermute_b32 v81, v81, v80
	s_and_saveexec_b64 s[16:17], s[36:37]
	s_cbranch_execz .LBB0_402
	v_ashrrev_i32_e32 v151, 31, v150
	s_waitcnt lgkmcnt(0)
	v_add_f32_e32 v84, v80, v81
	v_lshlrev_b64 v[80:81], 7, v[150:151]
	v_lshl_add_u64 v[80:81], s[14:15], 0, v[80:81]
	global_store_dword v[80:81], v84, off

; DEVI unsigned pk_bf16(float lo, float hi) { unsigned r; asm("v_cvt_pk_bf16_f32 %0, %1, %2" : "=v"(r) : "v"(lo), "v"(hi)); return r; }
;     DEVI void operator()(const f32x4 (&acc)[2][2][4][2], const Unit& u, int wr, int wc, int fr, int fq, const LAS float*) const {
;     ...
;         for (int idx = 0; idx < 8; ++idx) {
;             const int ai = idx >> 2, m = idx & 3;
;             const size_t ro = (size_t)(row0 + ai * HALF + m * 16) * ldc + col0;
;             if (idx + 1 < 8) { const int ai2 = (idx + 1) >> 2, m2 = (idx + 1) & 3; const size_t ro2 = (size_t)(row0 + ai2 * HALF + m2 * 16) * ldc + col0;
; #pragma unroll
;                 for (int bj = 0; bj < 2; ++bj)
; #pragma unroll
;                     for (int n = 0; n < 2; ++n) nxt[bj][n] = *(const f32x4*)(R + ro2 + bj * HALF + n * 16); }
;             float ss = 0.f;
; #pragma unroll
;             for (int bj = 0; bj < 2; ++bj)
; #pragma unroll
;                 for (int n = 0; n < 2; ++n) {
;                     const f32x4 hn = cur[bj][n] + acc[ai][bj][m][n] * scale;
;                     *(f32x4*)(C + ro + bj * HALF + n * 16) = hn;
;                     if (HB) { u32x2 w; w.x = pk_bf16(hn[0], hn[1]); w.y = pk_bf16(hn[2], hn[3]); *(u32x2*)(HB + ro + bj * HALF + n * 16) = w;
;                         ss += hn[0] * hn[0] + hn[1] * hn[1] + hn[2] * hn[2] + hn[3] * hn[3]; } }
;             if (HB) { ss += __shfl_xor(ss, 16); ss += __shfl_xor(ss, 32); if (fq == 0) RS[(size_t)(row0 + ai * HALF + m * 16) * 32 + u.pn * 4 + wc] = ss; }
.LBB0_403:
	v_mov_b32_e32 v181, v180
	v_pk_fma_f32 v[130:131], v[90:91], v[180:181], v[122:123]
	v_pk_fma_f32 v[126:127], v[86:87], v[180:181], v[118:119]
	v_pk_fma_f32 v[94:95], v[82:83], v[180:181], v[114:115]
	global_store_dwordx4 v[138:139], v[128:131], off offset:64 nt
	global_store_dwordx4 v[138:139], v[124:127], off offset:512 nt
	global_store_dwordx4 v[138:139], v[92:95], off offset:576 nt
.LBB0_404:
	v_add_u32_e32 v118, 0x80, v188
	v_mad_i64_i32 v[120:121], s[16:17], v118, s46, 0
	s_waitcnt lgkmcnt(0)
	v_lshl_add_u64 v[80:81], v[120:121], 2, v[186:187]
	global_load_dwordx4 v[92:95], v[80:81], off
	global_load_dwordx4 v[88:91], v[80:81], off offset:64
	global_load_dwordx4 v[84:87], v[80:81], off offset:512
	s_nop 0
	global_load_dwordx4 v[80:83], v[80:81], off offset:576
	v_lshl_add_u64 v[124:125], v[136:137], 0, v[182:183]
	v_mov_b32_e32 v181, v180
	v_lshl_add_u64 v[122:123], v[124:125], 2, s[92:93]
	s_waitcnt vmcnt(8)
	v_pk_fma_f32 v[116:117], v[78:79], v[180:181], v[110:111]
	v_pk_fma_f32 v[114:115], v[76:77], v[184:185], v[108:109]
	s_and_b64 vcc, exec, s[40:41]
	s_waitcnt vmcnt(7)
	v_pk_fma_f32 v[112:113], v[72:73], v[184:185], v[104:105]
	s_waitcnt vmcnt(6)
	v_pk_fma_f32 v[108:109], v[68:69], v[184:185], v[100:101]
	s_waitcnt vmcnt(5)
	v_pk_fma_f32 v[76:77], v[64:65], v[184:185], v[96:97]
	global_store_dwordx4 v[122:123], v[114:117], off nt
	s_cbranch_vccnz .LBB0_431
	v_readlane_b32 s72, v240, 54
	v_readlane_b32 s74, v240, 56
	v_readlane_b32 s75, v240, 57
	v_cvt_pk_bf16_f32 v68, v114, v115
	v_mul_f32_e32 v72, v115, v115
	v_cvt_pk_bf16_f32 v69, v116, v117
	v_fmac_f32_e32 v72, v114, v114
	v_lshl_add_u64 v[64:65], v[124:125], 1, s[74:75]
	global_store_dwordx2 v[64:65], v[68:69], off
	v_pk_fma_f32 v[114:115], v[74:75], v[180:181], v[106:107]
	v_cvt_pk_bf16_f32 v68, v112, v113
	global_store_dwordx4 v[122:123], v[112:115], off offset:64 nt
	v_cvt_pk_bf16_f32 v69, v114, v115
	global_store_dwordx2 v[64:65], v[68:69], off offset:32
	v_mul_f32_e32 v68, v113, v113
	v_fmac_f32_e32 v68, v112, v112
	v_fmac_f32_e32 v72, v116, v116
	v_fmac_f32_e32 v68, v114, v114
	v_fmac_f32_e32 v72, v117, v117
	v_fmac_f32_e32 v68, v115, v115
	v_add_f32_e32 v72, v72, v68
	v_pk_fma_f32 v[110:111], v[70:71], v[180:181], v[102:103]
	v_cvt_pk_bf16_f32 v68, v108, v109
	global_store_dwordx4 v[122:123], v[108:111], off offset:512 nt
	v_cvt_pk_bf16_f32 v69, v110, v111
	global_store_dwordx2 v[64:65], v[68:69], off offset:256
	v_mul_f32_e32 v68, v109, v109
	v_fmac_f32_e32 v68, v108, v108
	v_fmac_f32_e32 v68, v110, v110
	v_fmac_f32_e32 v68, v111, v111
	v_add_f32_e32 v72, v72, v68
	v_pk_fma_f32 v[78:79], v[66:67], v[180:181], v[98:99]
	v_cvt_pk_bf16_f32 v68, v76, v77
	global_store_dwordx4 v[122:123], v[76:79], off offset:576 nt
	v_cvt_pk_bf16_f32 v69, v78, v79
	global_store_dwordx2 v[64:65], v[68:69], off offset:288
	v_mul_f32_e32 v64, v77, v77
	v_and_b32_e32 v68, 64, v205
	v_fmac_f32_e32 v64, v76, v76
	v_xor_b32_e32 v65, 16, v205
	v_add_u32_e32 v68, 64, v68
	v_fmac_f32_e32 v64, v78, v78
	v_cmp_lt_i32_e32 vcc, v65, v68
	v_fmac_f32_e32 v64, v79, v79
	v_add_f32_e32 v64, v72, v64
	v_cndmask_b32_e32 v65, v205, v65, vcc
	v_lshlrev_b32_e32 v65, 2, v65
	ds_bpermute_b32 v65, v65, v64
	v_readlane_b32 s73, v240, 55
	s_waitcnt lgkmcnt(0)
	v_add_f32_e32 v64, v64, v65
	v_xor_b32_e32 v65, 32, v205
	v_cmp_lt_i32_e32 vcc, v65, v68
	s_nop 1
	v_cndmask_b32_e32 v65, v205, v65, vcc
	v_lshlrev_b32_e32 v65, 2, v65
	ds_bpermute_b32 v65, v65, v64
	s_and_saveexec_b64 s[16:17], s[36:37]
	s_cbranch_execz .LBB0_407
	v_ashrrev_i32_e32 v135, 31, v134
	s_waitcnt lgkmcnt(0)
	v_add_f32_e32 v68, v64, v65
	v_lshlrev_b64 v[64:65], 7, v[134:135]
	v_lshl_add_u64 v[64:65], s[14:15], 0, v[64:65]
	global_store_dword v[64:65], v68, off

; DEVI unsigned pk_bf16(float lo, float hi) { unsigned r; asm("v_cvt_pk_bf16_f32 %0, %1, %2" : "=v"(r) : "v"(lo), "v"(hi)); return r; }
;     DEVI void operator()(const f32x4 (&acc)[2][2][4][2], const Unit& u, int wr, int wc, int fr, int fq, const LAS float*) const {
;     ...
;         for (int idx = 0; idx < 8; ++idx) {
;             const int ai = idx >> 2, m = idx & 3;
;             const size_t ro = (size_t)(row0 + ai * HALF + m * 16) * ldc + col0;
;             if (idx + 1 < 8) { const int ai2 = (idx + 1) >> 2, m2 = (idx + 1) & 3; const size_t ro2 = (size_t)(row0 + ai2 * HALF + m2 * 16) * ldc + col0;
; #pragma unroll
;                 for (int bj = 0; bj < 2; ++bj)
; #pragma unroll
;                     for (int n = 0; n < 2; ++n) nxt[bj][n] = *(const f32x4*)(R + ro2 + bj * HALF + n * 16); }
;             float ss = 0.f;
; #pragma unroll
;             for (int bj = 0; bj < 2; ++bj)
; #pragma unroll
;                 for (int n = 0; n < 2; ++n) {
;                     const f32x4 hn = cur[bj][n] + acc[ai][bj][m][n] * scale;
;                     *(f32x4*)(C + ro + bj * HALF + n * 16) = hn;
;                     if (HB) { u32x2 w; w.x = pk_bf16(hn[0], hn[1]); w.y = pk_bf16(hn[2], hn[3]); *(u32x2*)(HB + ro + bj * HALF + n * 16) = w;
;                         ss += hn[0] * hn[0] + hn[1] * hn[1] + hn[2] * hn[2] + hn[3] * hn[3]; } }
;             if (HB) { ss += __shfl_xor(ss, 16); ss += __shfl_xor(ss, 32); if (fq == 0) RS[(size_t)(row0 + ai * HALF + m * 16) * 32 + u.pn * 4 + wc] = ss; }
.LBB0_408:
	v_mov_b32_e32 v181, v180
	v_pk_fma_f32 v[114:115], v[74:75], v[180:181], v[106:107]
	v_pk_fma_f32 v[110:111], v[70:71], v[180:181], v[102:103]
	v_pk_fma_f32 v[78:79], v[66:67], v[180:181], v[98:99]
	global_store_dwordx4 v[122:123], v[112:115], off offset:64 nt
	global_store_dwordx4 v[122:123], v[108:111], off offset:512 nt
	global_store_dwordx4 v[122:123], v[76:79], off offset:576 nt
.LBB0_409:
	v_or_b32_e32 v102, 16, v118
	v_mad_i64_i32 v[104:105], s[16:17], v102, s46, 0
	s_waitcnt lgkmcnt(0)
	v_lshl_add_u64 v[64:65], v[104:105], 2, v[186:187]
	global_load_dwordx4 v[76:79], v[64:65], off
	global_load_dwordx4 v[72:75], v[64:65], off offset:64
	global_load_dwordx4 v[68:71], v[64:65], off offset:512
	s_nop 0
	global_load_dwordx4 v[64:67], v[64:65], off offset:576
	v_lshl_add_u64 v[108:109], v[120:121], 0, v[182:183]
	v_mov_b32_e32 v181, v180
	v_ashrrev_i32_e32 v119, 31, v118
	v_lshl_add_u64 v[106:107], v[108:109], 2, s[92:93]
	s_waitcnt vmcnt(8)
	v_pk_fma_f32 v[100:101], v[62:63], v[180:181], v[94:95]
	v_pk_fma_f32 v[98:99], v[60:61], v[184:185], v[92:93]
	s_and_b64 vcc, exec, s[40:41]
	s_waitcnt vmcnt(7)
	v_pk_fma_f32 v[96:97], v[56:57], v[184:185], v[88:89]
	s_waitcnt vmcnt(6)
	v_pk_fma_f32 v[92:93], v[52:53], v[184:185], v[84:85]
	s_waitcnt vmcnt(5)
	v_pk_fma_f32 v[60:61], v[48:49], v[184:185], v[80:81]
	global_store_dwordx4 v[106:107], v[98:101], off nt
	s_cbranch_vccnz .LBB0_432
	v_readlane_b32 s72, v240, 54
	v_readlane_b32 s74, v240, 56
	v_readlane_b32 s75, v240, 57
	v_cvt_pk_bf16_f32 v52, v98, v99
	v_mul_f32_e32 v56, v99, v99
	v_cvt_pk_bf16_f32 v53, v100, v101
	v_fmac_f32_e32 v56, v98, v98
	v_lshl_add_u64 v[48:49], v[108:109], 1, s[74:75]
	global_store_dwordx2 v[48:49], v[52:53], off
	v_pk_fma_f32 v[98:99], v[58:59], v[180:181], v[90:91]
	v_cvt_pk_bf16_f32 v52, v96, v97
	global_store_dwordx4 v[106:107], v[96:99], off offset:64 nt
	v_cvt_pk_bf16_f32 v53, v98, v99
	global_store_dwordx2 v[48:49], v[52:53], off offset:32
	v_mul_f32_e32 v52, v97, v97
	v_fmac_f32_e32 v52, v96, v96
	v_fmac_f32_e32 v56, v100, v100
	v_fmac_f32_e32 v52, v98, v98
	v_fmac_f32_e32 v56, v101, v101
	v_fmac_f32_e32 v52, v99, v99
	v_add_f32_e32 v56, v56, v52
	v_pk_fma_f32 v[94:95], v[54:55], v[180:181], v[86:87]
	v_cvt_pk_bf16_f32 v52, v92, v93
	global_store_dwordx4 v[106:107], v[92:95], off offset:512 nt
	v_cvt_pk_bf16_f32 v53, v94, v95
	global_store_dwordx2 v[48:49], v[52:53], off offset:256
	v_mul_f32_e32 v52, v93, v93
	v_fmac_f32_e32 v52, v92, v92
	v_fmac_f32_e32 v52, v94, v94
	v_fmac_f32_e32 v52, v95, v95
	v_add_f32_e32 v56, v56, v52
	v_pk_fma_f32 v[62:63], v[50:51], v[180:181], v[82:83]
	v_cvt_pk_bf16_f32 v52, v60, v61
	global_store_dwordx4 v[106:107], v[60:63], off offset:576 nt
	v_cvt_pk_bf16_f32 v53, v62, v63
	global_store_dwordx2 v[48:49], v[52:53], off offset:288
	v_mul_f32_e32 v48, v61, v61
	v_and_b32_e32 v52, 64, v205
	v_fmac_f32_e32 v48, v60, v60
	v_xor_b32_e32 v49, 16, v205
	v_add_u32_e32 v52, 64, v52
	v_fmac_f32_e32 v48, v62, v62
	v_cmp_lt_i32_e32 vcc, v49, v52
	v_fmac_f32_e32 v48, v63, v63
	v_add_f32_e32 v48, v56, v48
	v_cndmask_b32_e32 v49, v205, v49, vcc
	v_lshlrev_b32_e32 v49, 2, v49
	ds_bpermute_b32 v49, v49, v48
	v_readlane_b32 s73, v240, 55
	s_waitcnt lgkmcnt(0)
	v_add_f32_e32 v48, v48, v49
	v_xor_b32_e32 v49, 32, v205
	v_cmp_lt_i32_e32 vcc, v49, v52
	s_nop 1
	v_cndmask_b32_e32 v49, v205, v49, vcc
	v_lshlrev_b32_e32 v49, 2, v49
	ds_bpermute_b32 v49, v49, v48
	s_and_saveexec_b64 s[16:17], s[36:37]
	s_cbranch_execz .LBB0_412
	s_waitcnt lgkmcnt(0)
	v_add_f32_e32 v52, v48, v49
	v_lshlrev_b64 v[48:49], 7, v[118:119]
	v_lshl_add_u64 v[48:49], s[14:15], 0, v[48:49]
	global_store_dword v[48:49], v52, off

; DEVI unsigned pk_bf16(float lo, float hi) { unsigned r; asm("v_cvt_pk_bf16_f32 %0, %1, %2" : "=v"(r) : "v"(lo), "v"(hi)); return r; }
;     DEVI void operator()(const f32x4 (&acc)[2][2][4][2], const Unit& u, int wr, int wc, int fr, int fq, const LAS float*) const {
;     ...
;         for (int idx = 0; idx < 8; ++idx) {
;             const int ai = idx >> 2, m = idx & 3;
;             const size_t ro = (size_t)(row0 + ai * HALF + m * 16) * ldc + col0;
;             if (idx + 1 < 8) { const int ai2 = (idx + 1) >> 2, m2 = (idx + 1) & 3; const size_t ro2 = (size_t)(row0 + ai2 * HALF + m2 * 16) * ldc + col0;
; #pragma unroll
;                 for (int bj = 0; bj < 2; ++bj)
; #pragma unroll
;                     for (int n = 0; n < 2; ++n) nxt[bj][n] = *(const f32x4*)(R + ro2 + bj * HALF + n * 16); }
;             float ss = 0.f;
; #pragma unroll
;             for (int bj = 0; bj < 2; ++bj)
; #pragma unroll
;                 for (int n = 0; n < 2; ++n) {
;                     const f32x4 hn = cur[bj][n] + acc[ai][bj][m][n] * scale;
;                     *(f32x4*)(C + ro + bj * HALF + n * 16) = hn;
;                     if (HB) { u32x2 w; w.x = pk_bf16(hn[0], hn[1]); w.y = pk_bf16(hn[2], hn[3]); *(u32x2*)(HB + ro + bj * HALF + n * 16) = w;
;                         ss += hn[0] * hn[0] + hn[1] * hn[1] + hn[2] * hn[2] + hn[3] * hn[3]; } }
;             if (HB) { ss += __shfl_xor(ss, 16); ss += __shfl_xor(ss, 32); if (fq == 0) RS[(size_t)(row0 + ai * HALF + m * 16) * 32 + u.pn * 4 + wc] = ss; }
.LBB0_413:
	v_mov_b32_e32 v181, v180
	v_pk_fma_f32 v[98:99], v[58:59], v[180:181], v[90:91]
	v_pk_fma_f32 v[94:95], v[54:55], v[180:181], v[86:87]
	v_pk_fma_f32 v[62:63], v[50:51], v[180:181], v[82:83]
	global_store_dwordx4 v[106:107], v[96:99], off offset:64 nt
	global_store_dwordx4 v[106:107], v[92:95], off offset:512 nt
	global_store_dwordx4 v[106:107], v[60:63], off offset:576 nt
.LBB0_414:
	v_or_b32_e32 v86, 32, v118
	v_mad_i64_i32 v[88:89], s[16:17], v86, s46, 0
	s_waitcnt lgkmcnt(0)
	v_lshl_add_u64 v[48:49], v[88:89], 2, v[186:187]
	global_load_dwordx4 v[60:63], v[48:49], off
	global_load_dwordx4 v[56:59], v[48:49], off offset:64
	global_load_dwordx4 v[52:55], v[48:49], off offset:512
	s_nop 0
	global_load_dwordx4 v[48:51], v[48:49], off offset:576
	v_lshl_add_u64 v[92:93], v[104:105], 0, v[182:183]
	v_mov_b32_e32 v181, v180
	v_lshl_add_u64 v[90:91], v[92:93], 2, s[92:93]
	s_waitcnt vmcnt(8)
	v_pk_fma_f32 v[84:85], v[46:47], v[180:181], v[78:79]
	v_pk_fma_f32 v[82:83], v[44:45], v[184:185], v[76:77]
	s_and_b64 vcc, exec, s[40:41]
	s_waitcnt vmcnt(7)
	v_pk_fma_f32 v[80:81], v[40:41], v[184:185], v[72:73]
	s_waitcnt vmcnt(6)
	v_pk_fma_f32 v[76:77], v[36:37], v[184:185], v[68:69]
	s_waitcnt vmcnt(5)
	v_pk_fma_f32 v[44:45], v[32:33], v[184:185], v[64:65]
	global_store_dwordx4 v[90:91], v[82:85], off nt
	s_cbranch_vccnz .LBB0_433
	v_readlane_b32 s72, v240, 54
	v_readlane_b32 s74, v240, 56
	v_readlane_b32 s75, v240, 57
	v_cvt_pk_bf16_f32 v36, v82, v83
	v_mul_f32_e32 v40, v83, v83
	v_cvt_pk_bf16_f32 v37, v84, v85
	v_fmac_f32_e32 v40, v82, v82
	v_lshl_add_u64 v[32:33], v[92:93], 1, s[74:75]
	global_store_dwordx2 v[32:33], v[36:37], off
	v_pk_fma_f32 v[82:83], v[42:43], v[180:181], v[74:75]
	v_cvt_pk_bf16_f32 v36, v80, v81
	global_store_dwordx4 v[90:91], v[80:83], off offset:64 nt
	v_cvt_pk_bf16_f32 v37, v82, v83
	global_store_dwordx2 v[32:33], v[36:37], off offset:32
	v_mul_f32_e32 v36, v81, v81
	v_fmac_f32_e32 v36, v80, v80
	v_fmac_f32_e32 v40, v84, v84
	v_fmac_f32_e32 v36, v82, v82
	v_fmac_f32_e32 v40, v85, v85
	v_fmac_f32_e32 v36, v83, v83
	v_add_f32_e32 v40, v40, v36
	v_pk_fma_f32 v[78:79], v[38:39], v[180:181], v[70:71]
	v_cvt_pk_bf16_f32 v36, v76, v77
	global_store_dwordx4 v[90:91], v[76:79], off offset:512 nt
	v_cvt_pk_bf16_f32 v37, v78, v79
	global_store_dwordx2 v[32:33], v[36:37], off offset:256
	v_mul_f32_e32 v36, v77, v77
	v_fmac_f32_e32 v36, v76, v76
	v_fmac_f32_e32 v36, v78, v78
	v_fmac_f32_e32 v36, v79, v79
	v_add_f32_e32 v40, v40, v36
	v_pk_fma_f32 v[46:47], v[34:35], v[180:181], v[66:67]
	v_cvt_pk_bf16_f32 v36, v44, v45
	global_store_dwordx4 v[90:91], v[44:47], off offset:576 nt
	v_cvt_pk_bf16_f32 v37, v46, v47
	global_store_dwordx2 v[32:33], v[36:37], off offset:288
	v_mul_f32_e32 v32, v45, v45
	v_and_b32_e32 v36, 64, v205
	v_fmac_f32_e32 v32, v44, v44
	v_xor_b32_e32 v33, 16, v205
	v_add_u32_e32 v36, 64, v36
	v_fmac_f32_e32 v32, v46, v46
	v_cmp_lt_i32_e32 vcc, v33, v36
	v_fmac_f32_e32 v32, v47, v47
	v_add_f32_e32 v32, v40, v32
	v_cndmask_b32_e32 v33, v205, v33, vcc
	v_lshlrev_b32_e32 v33, 2, v33
	ds_bpermute_b32 v33, v33, v32
	v_readlane_b32 s73, v240, 55
	s_waitcnt lgkmcnt(0)
	v_add_f32_e32 v32, v32, v33
	v_xor_b32_e32 v33, 32, v205
	v_cmp_lt_i32_e32 vcc, v33, v36
	s_nop 1
	v_cndmask_b32_e32 v33, v205, v33, vcc
	v_lshlrev_b32_e32 v33, 2, v33
	ds_bpermute_b32 v33, v33, v32
	s_and_saveexec_b64 s[16:17], s[36:37]
	s_cbranch_execz .LBB0_417
	v_ashrrev_i32_e32 v103, 31, v102
	s_waitcnt lgkmcnt(0)
	v_add_f32_e32 v36, v32, v33
	v_lshlrev_b64 v[32:33], 7, v[102:103]
	v_lshl_add_u64 v[32:33], s[14:15], 0, v[32:33]
	global_store_dword v[32:33], v36, off

; DEVI unsigned pk_bf16(float lo, float hi) { unsigned r; asm("v_cvt_pk_bf16_f32 %0, %1, %2" : "=v"(r) : "v"(lo), "v"(hi)); return r; }
;     DEVI void operator()(const f32x4 (&acc)[2][2][4][2], const Unit& u, int wr, int wc, int fr, int fq, const LAS float*) const {
;     ...
;         for (int idx = 0; idx < 8; ++idx) {
;             const int ai = idx >> 2, m = idx & 3;
;             const size_t ro = (size_t)(row0 + ai * HALF + m * 16) * ldc + col0;
;             if (idx + 1 < 8) { const int ai2 = (idx + 1) >> 2, m2 = (idx + 1) & 3; const size_t ro2 = (size_t)(row0 + ai2 * HALF + m2 * 16) * ldc + col0;
; #pragma unroll
;                 for (int bj = 0; bj < 2; ++bj)
; #pragma unroll
;                     for (int n = 0; n < 2; ++n) nxt[bj][n] = *(const f32x4*)(R + ro2 + bj * HALF + n * 16); }
;             float ss = 0.f;
; #pragma unroll
;             for (int bj = 0; bj < 2; ++bj)
; #pragma unroll
;                 for (int n = 0; n < 2; ++n) {
;                     const f32x4 hn = cur[bj][n] + acc[ai][bj][m][n] * scale;
;                     *(f32x4*)(C + ro + bj * HALF + n * 16) = hn;
;                     if (HB) { u32x2 w; w.x = pk_bf16(hn[0], hn[1]); w.y = pk_bf16(hn[2], hn[3]); *(u32x2*)(HB + ro + bj * HALF + n * 16) = w;
;                         ss += hn[0] * hn[0] + hn[1] * hn[1] + hn[2] * hn[2] + hn[3] * hn[3]; } }
;             if (HB) { ss += __shfl_xor(ss, 16); ss += __shfl_xor(ss, 32); if (fq == 0) RS[(size_t)(row0 + ai * HALF + m * 16) * 32 + u.pn * 4 + wc] = ss; }
.LBB0_418:
	v_mov_b32_e32 v181, v180
	v_pk_fma_f32 v[82:83], v[42:43], v[180:181], v[74:75]
	v_pk_fma_f32 v[78:79], v[38:39], v[180:181], v[70:71]
	v_pk_fma_f32 v[46:47], v[34:35], v[180:181], v[66:67]
	global_store_dwordx4 v[90:91], v[80:83], off offset:64 nt
	global_store_dwordx4 v[90:91], v[76:79], off offset:512 nt
	global_store_dwordx4 v[90:91], v[44:47], off offset:576 nt
.LBB0_419:
	v_or_b32_e32 v70, 48, v118
	v_mad_i64_i32 v[72:73], s[16:17], v70, s46, 0
	s_waitcnt lgkmcnt(0)
	v_lshl_add_u64 v[32:33], v[72:73], 2, v[186:187]
	global_load_dwordx4 v[44:47], v[32:33], off
	global_load_dwordx4 v[40:43], v[32:33], off offset:64
	global_load_dwordx4 v[36:39], v[32:33], off offset:512
	s_nop 0
	global_load_dwordx4 v[32:35], v[32:33], off offset:576
	v_lshl_add_u64 v[76:77], v[88:89], 0, v[182:183]
	v_mov_b32_e32 v181, v180
	v_lshl_add_u64 v[74:75], v[76:77], 2, s[92:93]
	s_waitcnt vmcnt(8)
	v_pk_fma_f32 v[68:69], v[30:31], v[180:181], v[62:63]
	v_pk_fma_f32 v[66:67], v[28:29], v[184:185], v[60:61]
	s_and_b64 vcc, exec, s[40:41]
	s_waitcnt vmcnt(7)
	v_pk_fma_f32 v[64:65], v[24:25], v[184:185], v[56:57]
	s_waitcnt vmcnt(6)
	v_pk_fma_f32 v[60:61], v[20:21], v[184:185], v[52:53]
	s_waitcnt vmcnt(5)
	v_pk_fma_f32 v[28:29], v[16:17], v[184:185], v[48:49]
	global_store_dwordx4 v[74:75], v[66:69], off nt
	s_cbranch_vccnz .LBB0_434
	v_readlane_b32 s72, v240, 54
	v_readlane_b32 s74, v240, 56
	v_readlane_b32 s75, v240, 57
	v_cvt_pk_bf16_f32 v20, v66, v67
	v_mul_f32_e32 v24, v67, v67
	v_cvt_pk_bf16_f32 v21, v68, v69
	v_fmac_f32_e32 v24, v66, v66
	v_lshl_add_u64 v[16:17], v[76:77], 1, s[74:75]
	global_store_dwordx2 v[16:17], v[20:21], off
	v_pk_fma_f32 v[66:67], v[26:27], v[180:181], v[58:59]
	v_cvt_pk_bf16_f32 v20, v64, v65
	global_store_dwordx4 v[74:75], v[64:67], off offset:64 nt
	v_cvt_pk_bf16_f32 v21, v66, v67
	global_store_dwordx2 v[16:17], v[20:21], off offset:32
	v_mul_f32_e32 v20, v65, v65
	v_fmac_f32_e32 v20, v64, v64
	v_fmac_f32_e32 v24, v68, v68
	v_fmac_f32_e32 v20, v66, v66
	v_fmac_f32_e32 v24, v69, v69
	v_fmac_f32_e32 v20, v67, v67
	v_add_f32_e32 v24, v24, v20
	v_pk_fma_f32 v[62:63], v[22:23], v[180:181], v[54:55]
	v_cvt_pk_bf16_f32 v20, v60, v61
	global_store_dwordx4 v[74:75], v[60:63], off offset:512 nt
	v_cvt_pk_bf16_f32 v21, v62, v63
	global_store_dwordx2 v[16:17], v[20:21], off offset:256
	v_mul_f32_e32 v20, v61, v61
	v_fmac_f32_e32 v20, v60, v60
	v_fmac_f32_e32 v20, v62, v62
	v_fmac_f32_e32 v20, v63, v63
	v_add_f32_e32 v24, v24, v20
	v_pk_fma_f32 v[30:31], v[18:19], v[180:181], v[50:51]
	v_cvt_pk_bf16_f32 v20, v28, v29
	global_store_dwordx4 v[74:75], v[28:31], off offset:576 nt
	v_cvt_pk_bf16_f32 v21, v30, v31
	global_store_dwordx2 v[16:17], v[20:21], off offset:288
	v_mul_f32_e32 v16, v29, v29
	v_and_b32_e32 v20, 64, v205
	v_fmac_f32_e32 v16, v28, v28
	v_xor_b32_e32 v17, 16, v205
	v_add_u32_e32 v20, 64, v20
	v_fmac_f32_e32 v16, v30, v30
	v_cmp_lt_i32_e32 vcc, v17, v20
	v_fmac_f32_e32 v16, v31, v31
	v_add_f32_e32 v16, v24, v16
	v_cndmask_b32_e32 v17, v205, v17, vcc
	v_lshlrev_b32_e32 v17, 2, v17
	ds_bpermute_b32 v17, v17, v16
	v_readlane_b32 s73, v240, 55
	s_waitcnt lgkmcnt(0)
	v_add_f32_e32 v16, v16, v17
	v_xor_b32_e32 v17, 32, v205
	v_cmp_lt_i32_e32 vcc, v17, v20
	s_nop 1
	v_cndmask_b32_e32 v17, v205, v17, vcc
	v_lshlrev_b32_e32 v17, 2, v17
	ds_bpermute_b32 v17, v17, v16
	s_and_saveexec_b64 s[16:17], s[36:37]
	s_cbranch_execz .LBB0_422
	v_ashrrev_i32_e32 v87, 31, v86
	s_waitcnt lgkmcnt(0)
	v_add_f32_e32 v20, v16, v17
	v_lshlrev_b64 v[16:17], 7, v[86:87]
	v_lshl_add_u64 v[16:17], s[14:15], 0, v[16:17]
	global_store_dword v[16:17], v20, off

; DEVI unsigned pk_bf16(float lo, float hi) { unsigned r; asm("v_cvt_pk_bf16_f32 %0, %1, %2" : "=v"(r) : "v"(lo), "v"(hi)); return r; }
;     DEVI void operator()(const f32x4 (&acc)[2][2][4][2], const Unit& u, int wr, int wc, int fr, int fq, const LAS float*) const {
;     ...
;         for (int idx = 0; idx < 8; ++idx) {
;             const int ai = idx >> 2, m = idx & 3;
;             const size_t ro = (size_t)(row0 + ai * HALF + m * 16) * ldc + col0;
;             if (idx + 1 < 8) { const int ai2 = (idx + 1) >> 2, m2 = (idx + 1) & 3; const size_t ro2 = (size_t)(row0 + ai2 * HALF + m2 * 16) * ldc + col0;
; #pragma unroll
;                 for (int bj = 0; bj < 2; ++bj)
; #pragma unroll
;                     for (int n = 0; n < 2; ++n) nxt[bj][n] = *(const f32x4*)(R + ro2 + bj * HALF + n * 16); }
;             float ss = 0.f;
; #pragma unroll
;             for (int bj = 0; bj < 2; ++bj)
; #pragma unroll
;                 for (int n = 0; n < 2; ++n) {
;                     const f32x4 hn = cur[bj][n] + acc[ai][bj][m][n] * scale;
;                     *(f32x4*)(C + ro + bj * HALF + n * 16) = hn;
;                     if (HB) { u32x2 w; w.x = pk_bf16(hn[0], hn[1]); w.y = pk_bf16(hn[2], hn[3]); *(u32x2*)(HB + ro + bj * HALF + n * 16) = w;
;                         ss += hn[0] * hn[0] + hn[1] * hn[1] + hn[2] * hn[2] + hn[3] * hn[3]; } }
;             if (HB) { ss += __shfl_xor(ss, 16); ss += __shfl_xor(ss, 32); if (fq == 0) RS[(size_t)(row0 + ai * HALF + m * 16) * 32 + u.pn * 4 + wc] = ss; }
.LBB0_423:
	v_mov_b32_e32 v181, v180
	v_pk_fma_f32 v[66:67], v[26:27], v[180:181], v[58:59]
	v_pk_fma_f32 v[62:63], v[22:23], v[180:181], v[54:55]
	v_pk_fma_f32 v[30:31], v[18:19], v[180:181], v[50:51]
	global_store_dwordx4 v[74:75], v[64:67], off offset:64 nt
	global_store_dwordx4 v[74:75], v[60:63], off offset:512 nt
	global_store_dwordx4 v[74:75], v[28:31], off offset:576 nt
.LBB0_424:
	v_lshl_add_u64 v[18:19], v[72:73], 0, v[182:183]
	v_mov_b32_e32 v181, v180
	v_lshl_add_u64 v[26:27], v[18:19], 2, s[92:93]
	s_waitcnt vmcnt(4)
	v_pk_fma_f32 v[24:25], v[14:15], v[180:181], v[46:47]
	v_pk_fma_f32 v[22:23], v[12:13], v[184:185], v[44:45]
	s_and_b64 vcc, exec, s[40:41]
	s_waitcnt vmcnt(3)
	v_pk_fma_f32 v[20:21], v[8:9], v[184:185], v[40:41]
	s_waitcnt vmcnt(2) lgkmcnt(0)
	v_pk_fma_f32 v[16:17], v[4:5], v[184:185], v[36:37]
	s_waitcnt vmcnt(1)
	v_pk_fma_f32 v[12:13], v[0:1], v[184:185], v[32:33]
	global_store_dwordx4 v[26:27], v[22:25], off nt
	s_cbranch_vccnz .LBB0_435
	v_readlane_b32 s72, v240, 54
	v_readlane_b32 s74, v240, 56
	v_readlane_b32 s75, v240, 57
	v_cvt_pk_bf16_f32 v4, v22, v23
	v_mul_f32_e32 v8, v23, v23
	v_cvt_pk_bf16_f32 v5, v24, v25
	v_fmac_f32_e32 v8, v22, v22
	v_lshl_add_u64 v[0:1], v[18:19], 1, s[74:75]
	global_store_dwordx2 v[0:1], v[4:5], off
	v_pk_fma_f32 v[22:23], v[10:11], v[180:181], v[42:43]
	v_cvt_pk_bf16_f32 v4, v20, v21
	global_store_dwordx4 v[26:27], v[20:23], off offset:64 nt
	v_cvt_pk_bf16_f32 v5, v22, v23
	global_store_dwordx2 v[0:1], v[4:5], off offset:32
	v_mul_f32_e32 v4, v21, v21
	v_fmac_f32_e32 v4, v20, v20
	v_fmac_f32_e32 v8, v24, v24
	v_fmac_f32_e32 v4, v22, v22
	v_fmac_f32_e32 v8, v25, v25
	v_fmac_f32_e32 v4, v23, v23
	v_add_f32_e32 v8, v8, v4
	v_pk_fma_f32 v[18:19], v[6:7], v[180:181], v[38:39]
	v_cvt_pk_bf16_f32 v4, v16, v17
	global_store_dwordx4 v[26:27], v[16:19], off offset:512 nt
	v_cvt_pk_bf16_f32 v5, v18, v19
	global_store_dwordx2 v[0:1], v[4:5], off offset:256
	v_mul_f32_e32 v4, v17, v17
	v_fmac_f32_e32 v4, v16, v16
	v_fmac_f32_e32 v4, v18, v18
	v_fmac_f32_e32 v4, v19, v19
	v_add_f32_e32 v8, v8, v4
	v_pk_fma_f32 v[14:15], v[2:3], v[180:181], v[34:35]
	v_cvt_pk_bf16_f32 v4, v12, v13
	global_store_dwordx4 v[26:27], v[12:15], off offset:576 nt
	v_cvt_pk_bf16_f32 v5, v14, v15
	global_store_dwordx2 v[0:1], v[4:5], off offset:288
	v_mul_f32_e32 v0, v13, v13
	v_and_b32_e32 v4, 64, v205
	v_fmac_f32_e32 v0, v12, v12
	v_xor_b32_e32 v1, 16, v205
	v_add_u32_e32 v4, 64, v4
	v_fmac_f32_e32 v0, v14, v14
	v_cmp_lt_i32_e32 vcc, v1, v4
	v_fmac_f32_e32 v0, v15, v15
	v_add_f32_e32 v0, v8, v0
	v_cndmask_b32_e32 v1, v205, v1, vcc
	v_lshlrev_b32_e32 v1, 2, v1
	ds_bpermute_b32 v1, v1, v0
	v_readlane_b32 s73, v240, 55
	s_waitcnt lgkmcnt(0)
	v_add_f32_e32 v0, v0, v1
	v_xor_b32_e32 v1, 32, v205
	v_cmp_lt_i32_e32 vcc, v1, v4
	s_nop 1
	v_cndmask_b32_e32 v1, v205, v1, vcc
	v_lshlrev_b32_e32 v1, 2, v1
	ds_bpermute_b32 v1, v1, v0
	s_and_saveexec_b64 s[16:17], s[36:37]
	s_cbranch_execz .LBB0_427
	v_ashrrev_i32_e32 v71, 31, v70
	s_waitcnt lgkmcnt(0)
	v_add_f32_e32 v4, v0, v1
	v_lshlrev_b64 v[0:1], 7, v[70:71]
	v_lshl_add_u64 v[0:1], s[14:15], 0, v[0:1]
	global_store_dword v[0:1], v4, off

;     DEVI void operator()(const f32x4 (&acc)[2][2][4][2], const Unit& u, int wr, int wc, int fr, int fq, const LAS float*) const {
;     ...
;                     const f32x4 hn = cur[bj][n] + acc[ai][bj][m][n] * scale;
;                     *(f32x4*)(C + ro + bj * HALF + n * 16) = hn;
.LBB0_435:
.LBB0_436:
	v_mov_b32_e32 v181, v180
	v_pk_fma_f32 v[22:23], v[10:11], v[180:181], v[42:43]
	v_pk_fma_f32 v[18:19], v[6:7], v[180:181], v[38:39]
	v_pk_fma_f32 v[14:15], v[2:3], v[180:181], v[34:35]
	global_store_dwordx4 v[26:27], v[20:23], off offset:64 nt
	global_store_dwordx4 v[26:27], v[16:19], off offset:512 nt
	global_store_dwordx4 v[26:27], v[12:15], off offset:576 nt
	s_branch .LBB0_379

; DEVI unsigned pk_bf16(float lo, float hi) { unsigned r; asm("v_cvt_pk_bf16_f32 %0, %1, %2" : "=v"(r) : "v"(lo), "v"(hi)); return r; }
;     DEVI void operator()(const f32x4 (&acc)[2][2][4][2], const Unit& u, int wr, int wc, int fr, int fq, const LAS float*) const {
;     ...
;         const int row0 = u.pm * BM + wr * 64 + fr, col0 = u.pn * BM + wc * 32 + 4 * fq;
;         f32x4 cur[2][2], nxt[2][2];
;         { const size_t ro = (size_t)row0 * ldc + col0;
; #pragma unroll
;           for (int bj = 0; bj < 2; ++bj)
; #pragma unroll
;               for (int n = 0; n < 2; ++n) cur[bj][n] = *(const f32x4*)(R + ro + bj * HALF + n * 16); }
; #pragma unroll
;         for (int idx = 0; idx < 8; ++idx) {
;             const int ai = idx >> 2, m = idx & 3;
;             const size_t ro = (size_t)(row0 + ai * HALF + m * 16) * ldc + col0;
;             if (idx + 1 < 8) { const int ai2 = (idx + 1) >> 2, m2 = (idx + 1) & 3; const size_t ro2 = (size_t)(row0 + ai2 * HALF + m2 * 16) * ldc + col0;
; #pragma unroll
;                 for (int bj = 0; bj < 2; ++bj)
; #pragma unroll
;                     for (int n = 0; n < 2; ++n) nxt[bj][n] = *(const f32x4*)(R + ro2 + bj * HALF + n * 16); }
;             float ss = 0.f;
; #pragma unroll
;             for (int bj = 0; bj < 2; ++bj)
; #pragma unroll
;                 for (int n = 0; n < 2; ++n) {
;                     const f32x4 hn = cur[bj][n] + acc[ai][bj][m][n] * scale;
;                     *(f32x4*)(C + ro + bj * HALF + n * 16) = hn;
;                     if (HB) { u32x2 w; w.x = pk_bf16(hn[0], hn[1]); w.y = pk_bf16(hn[2], hn[3]); *(u32x2*)(HB + ro + bj * HALF + n * 16) = w;
;                         ss += hn[0] * hn[0] + hn[1] * hn[1] + hn[2] * hn[2] + hn[3] * hn[3]; } }
;             if (HB) { ss += __shfl_xor(ss, 16); ss += __shfl_xor(ss, 32); if (fq == 0) RS[(size_t)(row0 + ai * HALF + m * 16) * 32 + u.pn * 4 + wc] = ss; }
.LBB0_1302:
	v_readlane_b32 s72, v239, 34
	v_readlane_b32 s73, v239, 35
	v_readlane_b32 s74, v239, 36
	v_readlane_b32 s75, v239, 37
	v_lshl_add_u32 v188, s35, 8, v198
	v_lshl_or_b32 v182, s31, 8, v200
	s_mov_b32 s70, s74
	v_readlane_b32 s72, v240, 62
	v_mad_i64_i32 v[128:129], s[14:15], v188, s70, 0
	v_ashrrev_i32_e32 v183, 31, v182
	v_readlane_b32 s78, v238, 4
	v_readlane_b32 s79, v238, 5
	v_lshlrev_b64 v[130:131], 2, v[182:183]
	v_or_b32_e32 v190, 16, v188
	v_lshl_add_u64 v[128:129], v[128:129], 2, s[78:79]
	v_mov_b32_e32 v180, v204
	v_lshl_add_u64 v[128:129], v[128:129], 0, v[130:131]
	v_lshl_add_u64 v[186:187], s[78:79], 0, v[130:131]
	v_mad_i64_i32 v[192:193], s[16:17], v190, s70, 0
	global_load_dwordx4 v[160:163], v[128:129], off
	global_load_dwordx4 v[152:155], v[128:129], off offset:64
	global_load_dwordx4 v[148:151], v[128:129], off offset:512
	global_load_dwordx4 v[144:147], v[128:129], off offset:576
	v_lshl_add_u64 v[128:129], v[192:193], 2, v[186:187]
	global_load_dwordx4 v[140:143], v[128:129], off
	global_load_dwordx4 v[136:139], v[128:129], off offset:64
	global_load_dwordx4 v[132:135], v[128:129], off offset:512
	s_nop 0
	global_load_dwordx4 v[128:131], v[128:129], off offset:576
	s_lshl_b32 s14, s31, 2
	s_ashr_i32 s15, s14, 31
	s_lshl_b64 s[14:15], s[14:15], 2
	v_readlane_b32 s76, v238, 2
	v_readlane_b32 s77, v238, 3
	v_mov_b32_e32 v184, v180
	v_mov_b32_e32 v185, v180
	s_add_u32 s14, s4, s14
	v_mad_i64_i32 v[158:159], s[16:17], v188, s70, v[182:183]
	v_ashrrev_i32_e32 v189, 31, v188
	s_addc_u32 s15, s5, s15
	v_lshl_add_u64 v[194:195], v[158:159], 2, s[76:77]
	s_andn2_b64 vcc, exec, s[66:67]
	v_readlane_b32 s73, v240, 63
	v_readlane_b32 s74, v238, 0
	v_readlane_b32 s75, v238, 1
	s_waitcnt vmcnt(0)
	v_pk_fma_f32 v[164:165], v[126:127], v[180:181], v[162:163] op_sel_hi:[1,0,1]
	v_pk_fma_f32 v[162:163], v[124:125], v[180:181], v[160:161] op_sel_hi:[1,0,1]
	v_cndmask_b32_e64 v124, 0, 1, s[66:67]
	v_cmp_ne_u32_e64 s[40:41], 1, v124
	v_pk_fma_f32 v[160:161], v[120:121], v[184:185], v[152:153]
	v_pk_fma_f32 v[156:157], v[116:117], v[184:185], v[148:149]
	v_pk_fma_f32 v[124:125], v[112:113], v[184:185], v[144:145]
	global_store_dwordx4 v[194:195], v[162:165], off nt
	s_cbranch_vccnz .LBB0_1341
	v_readlane_b32 s72, v238, 6
	v_readlane_b32 s74, v238, 8
	v_readlane_b32 s75, v238, 9
	v_cvt_pk_bf16_f32 v116, v162, v163
	v_mul_f32_e32 v120, v163, v163
	v_mov_b32_e32 v181, v180
	v_lshl_add_u64 v[112:113], v[158:159], 1, s[74:75]
	v_cvt_pk_bf16_f32 v117, v164, v165
	global_store_dwordx2 v[112:113], v[116:117], off
	v_fmac_f32_e32 v120, v162, v162
	v_pk_fma_f32 v[162:163], v[122:123], v[180:181], v[154:155]
	v_cvt_pk_bf16_f32 v116, v160, v161
	global_store_dwordx4 v[194:195], v[160:163], off offset:64 nt
	v_cvt_pk_bf16_f32 v117, v162, v163
	global_store_dwordx2 v[112:113], v[116:117], off offset:32
	v_mul_f32_e32 v116, v161, v161
	v_fmac_f32_e32 v116, v160, v160
	v_fmac_f32_e32 v120, v164, v164
	v_fmac_f32_e32 v116, v162, v162
	v_fmac_f32_e32 v120, v165, v165
	v_fmac_f32_e32 v116, v163, v163
	v_add_f32_e32 v120, v120, v116
	v_pk_fma_f32 v[158:159], v[118:119], v[180:181], v[150:151]
	v_cvt_pk_bf16_f32 v116, v156, v157
	global_store_dwordx4 v[194:195], v[156:159], off offset:512 nt
	v_cvt_pk_bf16_f32 v117, v158, v159
	global_store_dwordx2 v[112:113], v[116:117], off offset:256
	v_mul_f32_e32 v116, v157, v157
	v_fmac_f32_e32 v116, v156, v156
	v_fmac_f32_e32 v116, v158, v158
	v_fmac_f32_e32 v116, v159, v159
	v_add_f32_e32 v120, v116, v120
	v_pk_fma_f32 v[126:127], v[114:115], v[180:181], v[146:147]
	v_cvt_pk_bf16_f32 v116, v124, v125
	global_store_dwordx4 v[194:195], v[124:127], off offset:576 nt
	v_cvt_pk_bf16_f32 v117, v126, v127
	global_store_dwordx2 v[112:113], v[116:117], off offset:288
	v_mul_f32_e32 v112, v125, v125
	v_and_b32_e32 v116, 64, v197
	v_fmac_f32_e32 v112, v124, v124
	v_xor_b32_e32 v113, 16, v197
	v_add_u32_e32 v116, 64, v116
	v_fmac_f32_e32 v112, v126, v126
	v_cmp_lt_i32_e32 vcc, v113, v116
	v_fmac_f32_e32 v112, v127, v127
	v_add_f32_e32 v112, v112, v120
	v_cndmask_b32_e32 v113, v197, v113, vcc
	v_lshlrev_b32_e32 v113, 2, v113
	ds_bpermute_b32 v113, v113, v112
	v_readlane_b32 s73, v238, 7
	s_waitcnt lgkmcnt(0)
	v_add_f32_e32 v112, v112, v113
	v_xor_b32_e32 v113, 32, v197
	v_cmp_lt_i32_e32 vcc, v113, v116
	s_nop 1
	v_cndmask_b32_e32 v113, v197, v113, vcc
	v_lshlrev_b32_e32 v113, 2, v113
	ds_bpermute_b32 v113, v113, v112
	s_and_saveexec_b64 s[16:17], s[36:37]
	s_cbranch_execz .LBB0_1305
	s_waitcnt lgkmcnt(0)
	v_add_f32_e32 v116, v112, v113
	v_lshlrev_b64 v[112:113], 7, v[188:189]
	v_lshl_add_u64 v[112:113], s[14:15], 0, v[112:113]
	global_store_dword v[112:113], v116, off

; DEVI unsigned pk_bf16(float lo, float hi) { unsigned r; asm("v_cvt_pk_bf16_f32 %0, %1, %2" : "=v"(r) : "v"(lo), "v"(hi)); return r; }
;     DEVI void operator()(const f32x4 (&acc)[2][2][4][2], const Unit& u, int wr, int wc, int fr, int fq, const LAS float*) const {
;     ...
;         for (int idx = 0; idx < 8; ++idx) {
;             const int ai = idx >> 2, m = idx & 3;
;             const size_t ro = (size_t)(row0 + ai * HALF + m * 16) * ldc + col0;
;             if (idx + 1 < 8) { const int ai2 = (idx + 1) >> 2, m2 = (idx + 1) & 3; const size_t ro2 = (size_t)(row0 + ai2 * HALF + m2 * 16) * ldc + col0;
; #pragma unroll
;                 for (int bj = 0; bj < 2; ++bj)
; #pragma unroll
;                     for (int n = 0; n < 2; ++n) nxt[bj][n] = *(const f32x4*)(R + ro2 + bj * HALF + n * 16); }
;             float ss = 0.f;
; #pragma unroll
;             for (int bj = 0; bj < 2; ++bj)
; #pragma unroll
;                 for (int n = 0; n < 2; ++n) {
;                     const f32x4 hn = cur[bj][n] + acc[ai][bj][m][n] * scale;
;                     *(f32x4*)(C + ro + bj * HALF + n * 16) = hn;
;                     if (HB) { u32x2 w; w.x = pk_bf16(hn[0], hn[1]); w.y = pk_bf16(hn[2], hn[3]); *(u32x2*)(HB + ro + bj * HALF + n * 16) = w;
;                         ss += hn[0] * hn[0] + hn[1] * hn[1] + hn[2] * hn[2] + hn[3] * hn[3]; } }
;             if (HB) { ss += __shfl_xor(ss, 16); ss += __shfl_xor(ss, 32); if (fq == 0) RS[(size_t)(row0 + ai * HALF + m * 16) * 32 + u.pn * 4 + wc] = ss; }
.LBB0_1306:
	v_mov_b32_e32 v181, v180
	v_pk_fma_f32 v[162:163], v[122:123], v[180:181], v[154:155]
	v_pk_fma_f32 v[158:159], v[118:119], v[180:181], v[150:151]
	v_pk_fma_f32 v[126:127], v[114:115], v[180:181], v[146:147]
	global_store_dwordx4 v[194:195], v[160:163], off offset:64 nt
	global_store_dwordx4 v[194:195], v[156:159], off offset:512 nt
	global_store_dwordx4 v[194:195], v[124:127], off offset:576 nt
.LBB0_1307:
	v_readlane_b32 s72, v239, 34
	v_or_b32_e32 v150, 32, v188
	v_readlane_b32 s74, v239, 36
	v_readlane_b32 s73, v239, 35
	v_readlane_b32 s75, v239, 37
	v_mad_i64_i32 v[152:153], s[16:17], v150, s74, 0
	s_waitcnt lgkmcnt(0)
	v_lshl_add_u64 v[112:113], v[152:153], 2, v[186:187]
	global_load_dwordx4 v[124:127], v[112:113], off
	global_load_dwordx4 v[120:123], v[112:113], off offset:64
	global_load_dwordx4 v[116:119], v[112:113], off offset:512
	s_nop 0
	global_load_dwordx4 v[112:115], v[112:113], off offset:576
	v_readlane_b32 s72, v240, 62
	v_lshl_add_u64 v[156:157], v[192:193], 0, v[182:183]
	v_readlane_b32 s76, v238, 2
	v_readlane_b32 s77, v238, 3
	v_mov_b32_e32 v181, v180
	v_pk_fma_f32 v[148:149], v[110:111], v[180:181], v[142:143]
	v_lshl_add_u64 v[154:155], v[156:157], 2, s[76:77]
	v_pk_fma_f32 v[146:147], v[108:109], v[184:185], v[140:141]
	s_and_b64 vcc, exec, s[40:41]
	v_pk_fma_f32 v[144:145], v[104:105], v[184:185], v[136:137]
	v_pk_fma_f32 v[140:141], v[100:101], v[184:185], v[132:133]
	v_pk_fma_f32 v[108:109], v[96:97], v[184:185], v[128:129]
	v_readlane_b32 s73, v240, 63
	v_readlane_b32 s74, v238, 0
	v_readlane_b32 s75, v238, 1
	v_readlane_b32 s78, v238, 4
	v_readlane_b32 s79, v238, 5
	global_store_dwordx4 v[154:155], v[146:149], off nt
	s_cbranch_vccnz .LBB0_1342
	v_readlane_b32 s72, v238, 6
	v_readlane_b32 s74, v238, 8
	v_readlane_b32 s75, v238, 9
	v_cvt_pk_bf16_f32 v100, v146, v147
	v_mul_f32_e32 v104, v147, v147
	v_cvt_pk_bf16_f32 v101, v148, v149
	v_fmac_f32_e32 v104, v146, v146
	v_lshl_add_u64 v[96:97], v[156:157], 1, s[74:75]
	global_store_dwordx2 v[96:97], v[100:101], off
	v_pk_fma_f32 v[146:147], v[106:107], v[180:181], v[138:139]
	v_cvt_pk_bf16_f32 v100, v144, v145
	global_store_dwordx4 v[154:155], v[144:147], off offset:64 nt
	v_cvt_pk_bf16_f32 v101, v146, v147
	global_store_dwordx2 v[96:97], v[100:101], off offset:32
	v_mul_f32_e32 v100, v145, v145
	v_fmac_f32_e32 v100, v144, v144
	v_fmac_f32_e32 v104, v148, v148
	v_fmac_f32_e32 v100, v146, v146
	v_fmac_f32_e32 v104, v149, v149
	v_fmac_f32_e32 v100, v147, v147
	v_add_f32_e32 v104, v104, v100
	v_pk_fma_f32 v[142:143], v[102:103], v[180:181], v[134:135]
	v_cvt_pk_bf16_f32 v100, v140, v141
	global_store_dwordx4 v[154:155], v[140:143], off offset:512 nt
	v_cvt_pk_bf16_f32 v101, v142, v143
	global_store_dwordx2 v[96:97], v[100:101], off offset:256
	v_mul_f32_e32 v100, v141, v141
	v_fmac_f32_e32 v100, v140, v140
	v_fmac_f32_e32 v100, v142, v142
	v_fmac_f32_e32 v100, v143, v143
	v_add_f32_e32 v104, v104, v100
	v_pk_fma_f32 v[110:111], v[98:99], v[180:181], v[130:131]
	v_cvt_pk_bf16_f32 v100, v108, v109
	global_store_dwordx4 v[154:155], v[108:111], off offset:576 nt
	v_cvt_pk_bf16_f32 v101, v110, v111
	global_store_dwordx2 v[96:97], v[100:101], off offset:288
	v_mul_f32_e32 v96, v109, v109
	v_and_b32_e32 v100, 64, v197
	v_fmac_f32_e32 v96, v108, v108
	v_xor_b32_e32 v97, 16, v197
	v_add_u32_e32 v100, 64, v100
	v_fmac_f32_e32 v96, v110, v110
	v_cmp_lt_i32_e32 vcc, v97, v100
	v_fmac_f32_e32 v96, v111, v111
	v_add_f32_e32 v96, v104, v96
	v_cndmask_b32_e32 v97, v197, v97, vcc
	v_lshlrev_b32_e32 v97, 2, v97
	ds_bpermute_b32 v97, v97, v96
	v_readlane_b32 s73, v238, 7
	s_waitcnt lgkmcnt(0)
	v_add_f32_e32 v96, v96, v97
	v_xor_b32_e32 v97, 32, v197
	v_cmp_lt_i32_e32 vcc, v97, v100
	s_nop 1
	v_cndmask_b32_e32 v97, v197, v97, vcc
	v_lshlrev_b32_e32 v97, 2, v97
	ds_bpermute_b32 v97, v97, v96
	s_and_saveexec_b64 s[16:17], s[36:37]
	s_cbranch_execz .LBB0_1310
	v_ashrrev_i32_e32 v191, 31, v190
	s_waitcnt lgkmcnt(0)
	v_add_f32_e32 v100, v96, v97
	v_lshlrev_b64 v[96:97], 7, v[190:191]
	v_lshl_add_u64 v[96:97], s[14:15], 0, v[96:97]
	global_store_dword v[96:97], v100, off

; DEVI unsigned pk_bf16(float lo, float hi) { unsigned r; asm("v_cvt_pk_bf16_f32 %0, %1, %2" : "=v"(r) : "v"(lo), "v"(hi)); return r; }
;     DEVI void operator()(const f32x4 (&acc)[2][2][4][2], const Unit& u, int wr, int wc, int fr, int fq, const LAS float*) const {
;     ...
;         for (int idx = 0; idx < 8; ++idx) {
;             const int ai = idx >> 2, m = idx & 3;
;             const size_t ro = (size_t)(row0 + ai * HALF + m * 16) * ldc + col0;
;             if (idx + 1 < 8) { const int ai2 = (idx + 1) >> 2, m2 = (idx + 1) & 3; const size_t ro2 = (size_t)(row0 + ai2 * HALF + m2 * 16) * ldc + col0;
; #pragma unroll
;                 for (int bj = 0; bj < 2; ++bj)
; #pragma unroll
;                     for (int n = 0; n < 2; ++n) nxt[bj][n] = *(const f32x4*)(R + ro2 + bj * HALF + n * 16); }
;             float ss = 0.f;
; #pragma unroll
;             for (int bj = 0; bj < 2; ++bj)
; #pragma unroll
;                 for (int n = 0; n < 2; ++n) {
;                     const f32x4 hn = cur[bj][n] + acc[ai][bj][m][n] * scale;
;                     *(f32x4*)(C + ro + bj * HALF + n * 16) = hn;
;                     if (HB) { u32x2 w; w.x = pk_bf16(hn[0], hn[1]); w.y = pk_bf16(hn[2], hn[3]); *(u32x2*)(HB + ro + bj * HALF + n * 16) = w;
;                         ss += hn[0] * hn[0] + hn[1] * hn[1] + hn[2] * hn[2] + hn[3] * hn[3]; } }
;             if (HB) { ss += __shfl_xor(ss, 16); ss += __shfl_xor(ss, 32); if (fq == 0) RS[(size_t)(row0 + ai * HALF + m * 16) * 32 + u.pn * 4 + wc] = ss; }
.LBB0_1312:
	v_readlane_b32 s72, v239, 34
	v_or_b32_e32 v134, 48, v188
	v_readlane_b32 s74, v239, 36
	v_readlane_b32 s73, v239, 35
	v_readlane_b32 s75, v239, 37
	v_mad_i64_i32 v[136:137], s[16:17], v134, s74, 0
	s_waitcnt lgkmcnt(0)
	v_lshl_add_u64 v[96:97], v[136:137], 2, v[186:187]
	global_load_dwordx4 v[108:111], v[96:97], off
	global_load_dwordx4 v[104:107], v[96:97], off offset:64
	global_load_dwordx4 v[100:103], v[96:97], off offset:512
	s_nop 0
	global_load_dwordx4 v[96:99], v[96:97], off offset:576
	v_readlane_b32 s72, v240, 62
	v_lshl_add_u64 v[140:141], v[152:153], 0, v[182:183]
	v_readlane_b32 s76, v238, 2
	v_readlane_b32 s77, v238, 3
	v_mov_b32_e32 v181, v180
	s_waitcnt vmcnt(8)
	v_pk_fma_f32 v[132:133], v[94:95], v[180:181], v[126:127]
	v_lshl_add_u64 v[138:139], v[140:141], 2, s[76:77]
	v_pk_fma_f32 v[130:131], v[92:93], v[184:185], v[124:125]
	s_and_b64 vcc, exec, s[40:41]
	s_waitcnt vmcnt(7)
	v_pk_fma_f32 v[128:129], v[88:89], v[184:185], v[120:121]
	s_waitcnt vmcnt(6)
	v_pk_fma_f32 v[124:125], v[84:85], v[184:185], v[116:117]
	s_waitcnt vmcnt(5)
	v_pk_fma_f32 v[92:93], v[80:81], v[184:185], v[112:113]
	v_readlane_b32 s73, v240, 63
	v_readlane_b32 s74, v238, 0
	v_readlane_b32 s75, v238, 1
	v_readlane_b32 s78, v238, 4
	v_readlane_b32 s79, v238, 5
	global_store_dwordx4 v[138:139], v[130:133], off nt
	s_cbranch_vccnz .LBB0_1343
	v_readlane_b32 s72, v238, 6
	v_readlane_b32 s74, v238, 8
	v_readlane_b32 s75, v238, 9
	v_cvt_pk_bf16_f32 v84, v130, v131
	v_mul_f32_e32 v88, v131, v131
	v_cvt_pk_bf16_f32 v85, v132, v133
	v_fmac_f32_e32 v88, v130, v130
	v_lshl_add_u64 v[80:81], v[140:141], 1, s[74:75]
	global_store_dwordx2 v[80:81], v[84:85], off
	v_pk_fma_f32 v[130:131], v[90:91], v[180:181], v[122:123]
	v_cvt_pk_bf16_f32 v84, v128, v129
	global_store_dwordx4 v[138:139], v[128:131], off offset:64 nt
	v_cvt_pk_bf16_f32 v85, v130, v131
	global_store_dwordx2 v[80:81], v[84:85], off offset:32
	v_mul_f32_e32 v84, v129, v129
	v_fmac_f32_e32 v84, v128, v128
	v_fmac_f32_e32 v88, v132, v132
	v_fmac_f32_e32 v84, v130, v130
	v_fmac_f32_e32 v88, v133, v133
	v_fmac_f32_e32 v84, v131, v131
	v_add_f32_e32 v88, v88, v84
	v_pk_fma_f32 v[126:127], v[86:87], v[180:181], v[118:119]
	v_cvt_pk_bf16_f32 v84, v124, v125
	global_store_dwordx4 v[138:139], v[124:127], off offset:512 nt
	v_cvt_pk_bf16_f32 v85, v126, v127
	global_store_dwordx2 v[80:81], v[84:85], off offset:256
	v_mul_f32_e32 v84, v125, v125
	v_fmac_f32_e32 v84, v124, v124
	v_fmac_f32_e32 v84, v126, v126
	v_fmac_f32_e32 v84, v127, v127
	v_add_f32_e32 v88, v88, v84
	v_pk_fma_f32 v[94:95], v[82:83], v[180:181], v[114:115]
	v_cvt_pk_bf16_f32 v84, v92, v93
	global_store_dwordx4 v[138:139], v[92:95], off offset:576 nt
	v_cvt_pk_bf16_f32 v85, v94, v95
	global_store_dwordx2 v[80:81], v[84:85], off offset:288
	v_mul_f32_e32 v80, v93, v93
	v_and_b32_e32 v84, 64, v197
	v_fmac_f32_e32 v80, v92, v92
	v_xor_b32_e32 v81, 16, v197
	v_add_u32_e32 v84, 64, v84
	v_fmac_f32_e32 v80, v94, v94
	v_cmp_lt_i32_e32 vcc, v81, v84
	v_fmac_f32_e32 v80, v95, v95
	v_add_f32_e32 v80, v88, v80
	v_cndmask_b32_e32 v81, v197, v81, vcc
	v_lshlrev_b32_e32 v81, 2, v81
	ds_bpermute_b32 v81, v81, v80
	v_readlane_b32 s73, v238, 7
	s_waitcnt lgkmcnt(0)
	v_add_f32_e32 v80, v80, v81
	v_xor_b32_e32 v81, 32, v197
	v_cmp_lt_i32_e32 vcc, v81, v84
	s_nop 1
	v_cndmask_b32_e32 v81, v197, v81, vcc
	v_lshlrev_b32_e32 v81, 2, v81
	ds_bpermute_b32 v81, v81, v80
	s_and_saveexec_b64 s[16:17], s[36:37]
	s_cbranch_execz .LBB0_1315
	v_ashrrev_i32_e32 v151, 31, v150
	s_waitcnt lgkmcnt(0)
	v_add_f32_e32 v84, v80, v81
	v_lshlrev_b64 v[80:81], 7, v[150:151]
	v_lshl_add_u64 v[80:81], s[14:15], 0, v[80:81]
	global_store_dword v[80:81], v84, off

; DEVI unsigned pk_bf16(float lo, float hi) { unsigned r; asm("v_cvt_pk_bf16_f32 %0, %1, %2" : "=v"(r) : "v"(lo), "v"(hi)); return r; }
;     DEVI void operator()(const f32x4 (&acc)[2][2][4][2], const Unit& u, int wr, int wc, int fr, int fq, const LAS float*) const {
;     ...
;         for (int idx = 0; idx < 8; ++idx) {
;             const int ai = idx >> 2, m = idx & 3;
;             const size_t ro = (size_t)(row0 + ai * HALF + m * 16) * ldc + col0;
;             if (idx + 1 < 8) { const int ai2 = (idx + 1) >> 2, m2 = (idx + 1) & 3; const size_t ro2 = (size_t)(row0 + ai2 * HALF + m2 * 16) * ldc + col0;
; #pragma unroll
;                 for (int bj = 0; bj < 2; ++bj)
; #pragma unroll
;                     for (int n = 0; n < 2; ++n) nxt[bj][n] = *(const f32x4*)(R + ro2 + bj * HALF + n * 16); }
;             float ss = 0.f;
; #pragma unroll
;             for (int bj = 0; bj < 2; ++bj)
; #pragma unroll
;                 for (int n = 0; n < 2; ++n) {
;                     const f32x4 hn = cur[bj][n] + acc[ai][bj][m][n] * scale;
;                     *(f32x4*)(C + ro + bj * HALF + n * 16) = hn;
;                     if (HB) { u32x2 w; w.x = pk_bf16(hn[0], hn[1]); w.y = pk_bf16(hn[2], hn[3]); *(u32x2*)(HB + ro + bj * HALF + n * 16) = w;
;                         ss += hn[0] * hn[0] + hn[1] * hn[1] + hn[2] * hn[2] + hn[3] * hn[3]; } }
;             if (HB) { ss += __shfl_xor(ss, 16); ss += __shfl_xor(ss, 32); if (fq == 0) RS[(size_t)(row0 + ai * HALF + m * 16) * 32 + u.pn * 4 + wc] = ss; }
.LBB0_1317:
	v_readlane_b32 s72, v239, 34
	v_add_u32_e32 v118, 0x80, v188
	v_readlane_b32 s74, v239, 36
	v_readlane_b32 s73, v239, 35
	v_readlane_b32 s75, v239, 37
	v_mad_i64_i32 v[120:121], s[16:17], v118, s74, 0
	s_waitcnt lgkmcnt(0)
	v_lshl_add_u64 v[80:81], v[120:121], 2, v[186:187]
	global_load_dwordx4 v[92:95], v[80:81], off
	global_load_dwordx4 v[88:91], v[80:81], off offset:64
	global_load_dwordx4 v[84:87], v[80:81], off offset:512
	s_nop 0
	global_load_dwordx4 v[80:83], v[80:81], off offset:576
	v_readlane_b32 s72, v240, 62
	v_lshl_add_u64 v[124:125], v[136:137], 0, v[182:183]
	v_readlane_b32 s76, v238, 2
	v_readlane_b32 s77, v238, 3
	v_mov_b32_e32 v181, v180
	s_waitcnt vmcnt(8)
	v_pk_fma_f32 v[116:117], v[78:79], v[180:181], v[110:111]
	v_lshl_add_u64 v[122:123], v[124:125], 2, s[76:77]
	v_pk_fma_f32 v[114:115], v[76:77], v[184:185], v[108:109]
	s_and_b64 vcc, exec, s[40:41]
	s_waitcnt vmcnt(7)
	v_pk_fma_f32 v[112:113], v[72:73], v[184:185], v[104:105]
	s_waitcnt vmcnt(6)
	v_pk_fma_f32 v[108:109], v[68:69], v[184:185], v[100:101]
	s_waitcnt vmcnt(5)
	v_pk_fma_f32 v[76:77], v[64:65], v[184:185], v[96:97]
	v_readlane_b32 s73, v240, 63
	v_readlane_b32 s74, v238, 0
	v_readlane_b32 s75, v238, 1
	v_readlane_b32 s78, v238, 4
	v_readlane_b32 s79, v238, 5
	global_store_dwordx4 v[122:123], v[114:117], off nt
	s_cbranch_vccnz .LBB0_1344
	v_readlane_b32 s72, v238, 6
	v_readlane_b32 s74, v238, 8
	v_readlane_b32 s75, v238, 9
	v_cvt_pk_bf16_f32 v68, v114, v115
	v_mul_f32_e32 v72, v115, v115
	v_cvt_pk_bf16_f32 v69, v116, v117
	v_fmac_f32_e32 v72, v114, v114
	v_lshl_add_u64 v[64:65], v[124:125], 1, s[74:75]
	global_store_dwordx2 v[64:65], v[68:69], off
	v_pk_fma_f32 v[114:115], v[74:75], v[180:181], v[106:107]
	v_cvt_pk_bf16_f32 v68, v112, v113
	global_store_dwordx4 v[122:123], v[112:115], off offset:64 nt
	v_cvt_pk_bf16_f32 v69, v114, v115
	global_store_dwordx2 v[64:65], v[68:69], off offset:32
	v_mul_f32_e32 v68, v113, v113
	v_fmac_f32_e32 v68, v112, v112
	v_fmac_f32_e32 v72, v116, v116
	v_fmac_f32_e32 v68, v114, v114
	v_fmac_f32_e32 v72, v117, v117
	v_fmac_f32_e32 v68, v115, v115
	v_add_f32_e32 v72, v72, v68
	v_pk_fma_f32 v[110:111], v[70:71], v[180:181], v[102:103]
	v_cvt_pk_bf16_f32 v68, v108, v109
	global_store_dwordx4 v[122:123], v[108:111], off offset:512 nt
	v_cvt_pk_bf16_f32 v69, v110, v111
	global_store_dwordx2 v[64:65], v[68:69], off offset:256
	v_mul_f32_e32 v68, v109, v109
	v_fmac_f32_e32 v68, v108, v108
	v_fmac_f32_e32 v68, v110, v110
	v_fmac_f32_e32 v68, v111, v111
	v_add_f32_e32 v72, v72, v68
	v_pk_fma_f32 v[78:79], v[66:67], v[180:181], v[98:99]
	v_cvt_pk_bf16_f32 v68, v76, v77
	global_store_dwordx4 v[122:123], v[76:79], off offset:576 nt
	v_cvt_pk_bf16_f32 v69, v78, v79
	global_store_dwordx2 v[64:65], v[68:69], off offset:288
	v_mul_f32_e32 v64, v77, v77
	v_and_b32_e32 v68, 64, v197
	v_fmac_f32_e32 v64, v76, v76
	v_xor_b32_e32 v65, 16, v197
	v_add_u32_e32 v68, 64, v68
	v_fmac_f32_e32 v64, v78, v78
	v_cmp_lt_i32_e32 vcc, v65, v68
	v_fmac_f32_e32 v64, v79, v79
	v_add_f32_e32 v64, v72, v64
	v_cndmask_b32_e32 v65, v197, v65, vcc
	v_lshlrev_b32_e32 v65, 2, v65
	ds_bpermute_b32 v65, v65, v64
	v_readlane_b32 s73, v238, 7
	s_waitcnt lgkmcnt(0)
	v_add_f32_e32 v64, v64, v65
	v_xor_b32_e32 v65, 32, v197
	v_cmp_lt_i32_e32 vcc, v65, v68
	s_nop 1
	v_cndmask_b32_e32 v65, v197, v65, vcc
	v_lshlrev_b32_e32 v65, 2, v65
	ds_bpermute_b32 v65, v65, v64
	s_and_saveexec_b64 s[16:17], s[36:37]
	s_cbranch_execz .LBB0_1320
	v_ashrrev_i32_e32 v135, 31, v134
	s_waitcnt lgkmcnt(0)
	v_add_f32_e32 v68, v64, v65
	v_lshlrev_b64 v[64:65], 7, v[134:135]
	v_lshl_add_u64 v[64:65], s[14:15], 0, v[64:65]
	global_store_dword v[64:65], v68, off

; DEVI unsigned pk_bf16(float lo, float hi) { unsigned r; asm("v_cvt_pk_bf16_f32 %0, %1, %2" : "=v"(r) : "v"(lo), "v"(hi)); return r; }
;     DEVI void operator()(const f32x4 (&acc)[2][2][4][2], const Unit& u, int wr, int wc, int fr, int fq, const LAS float*) const {
;     ...
;         for (int idx = 0; idx < 8; ++idx) {
;             const int ai = idx >> 2, m = idx & 3;
;             const size_t ro = (size_t)(row0 + ai * HALF + m * 16) * ldc + col0;
;             if (idx + 1 < 8) { const int ai2 = (idx + 1) >> 2, m2 = (idx + 1) & 3; const size_t ro2 = (size_t)(row0 + ai2 * HALF + m2 * 16) * ldc + col0;
; #pragma unroll
;                 for (int bj = 0; bj < 2; ++bj)
; #pragma unroll
;                     for (int n = 0; n < 2; ++n) nxt[bj][n] = *(const f32x4*)(R + ro2 + bj * HALF + n * 16); }
;             float ss = 0.f;
; #pragma unroll
;             for (int bj = 0; bj < 2; ++bj)
; #pragma unroll
;                 for (int n = 0; n < 2; ++n) {
;                     const f32x4 hn = cur[bj][n] + acc[ai][bj][m][n] * scale;
;                     *(f32x4*)(C + ro + bj * HALF + n * 16) = hn;
;                     if (HB) { u32x2 w; w.x = pk_bf16(hn[0], hn[1]); w.y = pk_bf16(hn[2], hn[3]); *(u32x2*)(HB + ro + bj * HALF + n * 16) = w;
;                         ss += hn[0] * hn[0] + hn[1] * hn[1] + hn[2] * hn[2] + hn[3] * hn[3]; } }
;             if (HB) { ss += __shfl_xor(ss, 16); ss += __shfl_xor(ss, 32); if (fq == 0) RS[(size_t)(row0 + ai * HALF + m * 16) * 32 + u.pn * 4 + wc] = ss; }
.LBB0_1322:
	v_readlane_b32 s72, v239, 34
	v_or_b32_e32 v102, 16, v118
	v_readlane_b32 s74, v239, 36
	v_readlane_b32 s73, v239, 35
	v_readlane_b32 s75, v239, 37
	v_mad_i64_i32 v[104:105], s[16:17], v102, s74, 0
	s_waitcnt lgkmcnt(0)
	v_lshl_add_u64 v[64:65], v[104:105], 2, v[186:187]
	global_load_dwordx4 v[76:79], v[64:65], off
	global_load_dwordx4 v[72:75], v[64:65], off offset:64
	global_load_dwordx4 v[68:71], v[64:65], off offset:512
	s_nop 0
	global_load_dwordx4 v[64:67], v[64:65], off offset:576
	v_readlane_b32 s72, v240, 62
	v_lshl_add_u64 v[108:109], v[120:121], 0, v[182:183]
	v_readlane_b32 s76, v238, 2
	v_readlane_b32 s77, v238, 3
	v_mov_b32_e32 v181, v180
	v_ashrrev_i32_e32 v119, 31, v118
	v_lshl_add_u64 v[106:107], v[108:109], 2, s[76:77]
	s_waitcnt vmcnt(8)
	v_pk_fma_f32 v[100:101], v[62:63], v[180:181], v[94:95]
	v_pk_fma_f32 v[98:99], v[60:61], v[184:185], v[92:93]
	s_and_b64 vcc, exec, s[40:41]
	s_waitcnt vmcnt(7)
	v_pk_fma_f32 v[96:97], v[56:57], v[184:185], v[88:89]
	s_waitcnt vmcnt(6)
	v_pk_fma_f32 v[92:93], v[52:53], v[184:185], v[84:85]
	s_waitcnt vmcnt(5)
	v_pk_fma_f32 v[60:61], v[48:49], v[184:185], v[80:81]
	v_readlane_b32 s73, v240, 63
	v_readlane_b32 s74, v238, 0
	v_readlane_b32 s75, v238, 1
	v_readlane_b32 s78, v238, 4
	v_readlane_b32 s79, v238, 5
	global_store_dwordx4 v[106:107], v[98:101], off nt
	s_cbranch_vccnz .LBB0_1345
	v_readlane_b32 s72, v238, 6
	v_readlane_b32 s74, v238, 8
	v_readlane_b32 s75, v238, 9
	v_cvt_pk_bf16_f32 v52, v98, v99
	v_mul_f32_e32 v56, v99, v99
	v_cvt_pk_bf16_f32 v53, v100, v101
	v_fmac_f32_e32 v56, v98, v98
	v_lshl_add_u64 v[48:49], v[108:109], 1, s[74:75]
	global_store_dwordx2 v[48:49], v[52:53], off
	v_pk_fma_f32 v[98:99], v[58:59], v[180:181], v[90:91]
	v_cvt_pk_bf16_f32 v52, v96, v97
	global_store_dwordx4 v[106:107], v[96:99], off offset:64 nt
	v_cvt_pk_bf16_f32 v53, v98, v99
	global_store_dwordx2 v[48:49], v[52:53], off offset:32
	v_mul_f32_e32 v52, v97, v97
	v_fmac_f32_e32 v52, v96, v96
	v_fmac_f32_e32 v56, v100, v100
	v_fmac_f32_e32 v52, v98, v98
	v_fmac_f32_e32 v56, v101, v101
	v_fmac_f32_e32 v52, v99, v99
	v_add_f32_e32 v56, v56, v52
	v_pk_fma_f32 v[94:95], v[54:55], v[180:181], v[86:87]
	v_cvt_pk_bf16_f32 v52, v92, v93
	global_store_dwordx4 v[106:107], v[92:95], off offset:512 nt
	v_cvt_pk_bf16_f32 v53, v94, v95
	global_store_dwordx2 v[48:49], v[52:53], off offset:256
	v_mul_f32_e32 v52, v93, v93
	v_fmac_f32_e32 v52, v92, v92
	v_fmac_f32_e32 v52, v94, v94
	v_fmac_f32_e32 v52, v95, v95
	v_add_f32_e32 v56, v56, v52
	v_pk_fma_f32 v[62:63], v[50:51], v[180:181], v[82:83]
	v_cvt_pk_bf16_f32 v52, v60, v61
	global_store_dwordx4 v[106:107], v[60:63], off offset:576 nt
	v_cvt_pk_bf16_f32 v53, v62, v63
	global_store_dwordx2 v[48:49], v[52:53], off offset:288
	v_mul_f32_e32 v48, v61, v61
	v_and_b32_e32 v52, 64, v197
	v_fmac_f32_e32 v48, v60, v60
	v_xor_b32_e32 v49, 16, v197
	v_add_u32_e32 v52, 64, v52
	v_fmac_f32_e32 v48, v62, v62
	v_cmp_lt_i32_e32 vcc, v49, v52
	v_fmac_f32_e32 v48, v63, v63
	v_add_f32_e32 v48, v56, v48
	v_cndmask_b32_e32 v49, v197, v49, vcc
	v_lshlrev_b32_e32 v49, 2, v49
	ds_bpermute_b32 v49, v49, v48
	v_readlane_b32 s73, v238, 7
	s_waitcnt lgkmcnt(0)
	v_add_f32_e32 v48, v48, v49
	v_xor_b32_e32 v49, 32, v197
	v_cmp_lt_i32_e32 vcc, v49, v52
	s_nop 1
	v_cndmask_b32_e32 v49, v197, v49, vcc
	v_lshlrev_b32_e32 v49, 2, v49
	ds_bpermute_b32 v49, v49, v48
	s_and_saveexec_b64 s[16:17], s[36:37]
	s_cbranch_execz .LBB0_1325
	s_waitcnt lgkmcnt(0)
	v_add_f32_e32 v52, v48, v49
	v_lshlrev_b64 v[48:49], 7, v[118:119]
	v_lshl_add_u64 v[48:49], s[14:15], 0, v[48:49]
	global_store_dword v[48:49], v52, off

; DEVI unsigned pk_bf16(float lo, float hi) { unsigned r; asm("v_cvt_pk_bf16_f32 %0, %1, %2" : "=v"(r) : "v"(lo), "v"(hi)); return r; }
;     DEVI void operator()(const f32x4 (&acc)[2][2][4][2], const Unit& u, int wr, int wc, int fr, int fq, const LAS float*) const {
;     ...
;         for (int idx = 0; idx < 8; ++idx) {
;             const int ai = idx >> 2, m = idx & 3;
;             const size_t ro = (size_t)(row0 + ai * HALF + m * 16) * ldc + col0;
;             if (idx + 1 < 8) { const int ai2 = (idx + 1) >> 2, m2 = (idx + 1) & 3; const size_t ro2 = (size_t)(row0 + ai2 * HALF + m2 * 16) * ldc + col0;
; #pragma unroll
;                 for (int bj = 0; bj < 2; ++bj)
; #pragma unroll
;                     for (int n = 0; n < 2; ++n) nxt[bj][n] = *(const f32x4*)(R + ro2 + bj * HALF + n * 16); }
;             float ss = 0.f;
; #pragma unroll
;             for (int bj = 0; bj < 2; ++bj)
; #pragma unroll
;                 for (int n = 0; n < 2; ++n) {
;                     const f32x4 hn = cur[bj][n] + acc[ai][bj][m][n] * scale;
;                     *(f32x4*)(C + ro + bj * HALF + n * 16) = hn;
;                     if (HB) { u32x2 w; w.x = pk_bf16(hn[0], hn[1]); w.y = pk_bf16(hn[2], hn[3]); *(u32x2*)(HB + ro + bj * HALF + n * 16) = w;
;                         ss += hn[0] * hn[0] + hn[1] * hn[1] + hn[2] * hn[2] + hn[3] * hn[3]; } }
;             if (HB) { ss += __shfl_xor(ss, 16); ss += __shfl_xor(ss, 32); if (fq == 0) RS[(size_t)(row0 + ai * HALF + m * 16) * 32 + u.pn * 4 + wc] = ss; }
.LBB0_1327:
	v_readlane_b32 s72, v239, 34
	v_or_b32_e32 v86, 32, v118
	v_readlane_b32 s74, v239, 36
	v_readlane_b32 s73, v239, 35
	v_readlane_b32 s75, v239, 37
	v_mad_i64_i32 v[88:89], s[16:17], v86, s74, 0
	s_waitcnt lgkmcnt(0)
	v_lshl_add_u64 v[48:49], v[88:89], 2, v[186:187]
	global_load_dwordx4 v[60:63], v[48:49], off
	global_load_dwordx4 v[56:59], v[48:49], off offset:64
	global_load_dwordx4 v[52:55], v[48:49], off offset:512
	s_nop 0
	global_load_dwordx4 v[48:51], v[48:49], off offset:576
	v_readlane_b32 s72, v240, 62
	v_lshl_add_u64 v[92:93], v[104:105], 0, v[182:183]
	v_readlane_b32 s76, v238, 2
	v_readlane_b32 s77, v238, 3
	v_mov_b32_e32 v181, v180
	s_waitcnt vmcnt(8)
	v_pk_fma_f32 v[84:85], v[46:47], v[180:181], v[78:79]
	v_lshl_add_u64 v[90:91], v[92:93], 2, s[76:77]
	v_pk_fma_f32 v[82:83], v[44:45], v[184:185], v[76:77]
	s_and_b64 vcc, exec, s[40:41]
	s_waitcnt vmcnt(7)
	v_pk_fma_f32 v[80:81], v[40:41], v[184:185], v[72:73]
	s_waitcnt vmcnt(6)
	v_pk_fma_f32 v[76:77], v[36:37], v[184:185], v[68:69]
	s_waitcnt vmcnt(5)
	v_pk_fma_f32 v[44:45], v[32:33], v[184:185], v[64:65]
	v_readlane_b32 s73, v240, 63
	v_readlane_b32 s74, v238, 0
	v_readlane_b32 s75, v238, 1
	v_readlane_b32 s78, v238, 4
	v_readlane_b32 s79, v238, 5
	global_store_dwordx4 v[90:91], v[82:85], off nt
	s_cbranch_vccnz .LBB0_1346
	v_readlane_b32 s72, v238, 6
	v_readlane_b32 s74, v238, 8
	v_readlane_b32 s75, v238, 9
	v_cvt_pk_bf16_f32 v36, v82, v83
	v_mul_f32_e32 v40, v83, v83
	v_cvt_pk_bf16_f32 v37, v84, v85
	v_fmac_f32_e32 v40, v82, v82
	v_lshl_add_u64 v[32:33], v[92:93], 1, s[74:75]
	global_store_dwordx2 v[32:33], v[36:37], off
	v_pk_fma_f32 v[82:83], v[42:43], v[180:181], v[74:75]
	v_cvt_pk_bf16_f32 v36, v80, v81
	global_store_dwordx4 v[90:91], v[80:83], off offset:64 nt
	v_cvt_pk_bf16_f32 v37, v82, v83
	global_store_dwordx2 v[32:33], v[36:37], off offset:32
	v_mul_f32_e32 v36, v81, v81
	v_fmac_f32_e32 v36, v80, v80
	v_fmac_f32_e32 v40, v84, v84
	v_fmac_f32_e32 v36, v82, v82
	v_fmac_f32_e32 v40, v85, v85
	v_fmac_f32_e32 v36, v83, v83
	v_add_f32_e32 v40, v40, v36
	v_pk_fma_f32 v[78:79], v[38:39], v[180:181], v[70:71]
	v_cvt_pk_bf16_f32 v36, v76, v77
	global_store_dwordx4 v[90:91], v[76:79], off offset:512 nt
	v_cvt_pk_bf16_f32 v37, v78, v79
	global_store_dwordx2 v[32:33], v[36:37], off offset:256
	v_mul_f32_e32 v36, v77, v77
	v_fmac_f32_e32 v36, v76, v76
	v_fmac_f32_e32 v36, v78, v78
	v_fmac_f32_e32 v36, v79, v79
	v_add_f32_e32 v40, v40, v36
	v_pk_fma_f32 v[46:47], v[34:35], v[180:181], v[66:67]
	v_cvt_pk_bf16_f32 v36, v44, v45
	global_store_dwordx4 v[90:91], v[44:47], off offset:576 nt
	v_cvt_pk_bf16_f32 v37, v46, v47
	global_store_dwordx2 v[32:33], v[36:37], off offset:288
	v_mul_f32_e32 v32, v45, v45
	v_and_b32_e32 v36, 64, v197
	v_fmac_f32_e32 v32, v44, v44
	v_xor_b32_e32 v33, 16, v197
	v_add_u32_e32 v36, 64, v36
	v_fmac_f32_e32 v32, v46, v46
	v_cmp_lt_i32_e32 vcc, v33, v36
	v_fmac_f32_e32 v32, v47, v47
	v_add_f32_e32 v32, v40, v32
	v_cndmask_b32_e32 v33, v197, v33, vcc
	v_lshlrev_b32_e32 v33, 2, v33
	ds_bpermute_b32 v33, v33, v32
	v_readlane_b32 s73, v238, 7
	s_waitcnt lgkmcnt(0)
	v_add_f32_e32 v32, v32, v33
	v_xor_b32_e32 v33, 32, v197
	v_cmp_lt_i32_e32 vcc, v33, v36
	s_nop 1
	v_cndmask_b32_e32 v33, v197, v33, vcc
	v_lshlrev_b32_e32 v33, 2, v33
	ds_bpermute_b32 v33, v33, v32
	s_and_saveexec_b64 s[16:17], s[36:37]
	s_cbranch_execz .LBB0_1330
	v_ashrrev_i32_e32 v103, 31, v102
	s_waitcnt lgkmcnt(0)
	v_add_f32_e32 v36, v32, v33
	v_lshlrev_b64 v[32:33], 7, v[102:103]
	v_lshl_add_u64 v[32:33], s[14:15], 0, v[32:33]
	global_store_dword v[32:33], v36, off

; DEVI unsigned pk_bf16(float lo, float hi) { unsigned r; asm("v_cvt_pk_bf16_f32 %0, %1, %2" : "=v"(r) : "v"(lo), "v"(hi)); return r; }
;     DEVI void operator()(const f32x4 (&acc)[2][2][4][2], const Unit& u, int wr, int wc, int fr, int fq, const LAS float*) const {
;     ...
;         for (int idx = 0; idx < 8; ++idx) {
;             const int ai = idx >> 2, m = idx & 3;
;             const size_t ro = (size_t)(row0 + ai * HALF + m * 16) * ldc + col0;
;             if (idx + 1 < 8) { const int ai2 = (idx + 1) >> 2, m2 = (idx + 1) & 3; const size_t ro2 = (size_t)(row0 + ai2 * HALF + m2 * 16) * ldc + col0;
; #pragma unroll
;                 for (int bj = 0; bj < 2; ++bj)
; #pragma unroll
;                     for (int n = 0; n < 2; ++n) nxt[bj][n] = *(const f32x4*)(R + ro2 + bj * HALF + n * 16); }
;             float ss = 0.f;
; #pragma unroll
;             for (int bj = 0; bj < 2; ++bj)
; #pragma unroll
;                 for (int n = 0; n < 2; ++n) {
;                     const f32x4 hn = cur[bj][n] + acc[ai][bj][m][n] * scale;
;                     *(f32x4*)(C + ro + bj * HALF + n * 16) = hn;
;                     if (HB) { u32x2 w; w.x = pk_bf16(hn[0], hn[1]); w.y = pk_bf16(hn[2], hn[3]); *(u32x2*)(HB + ro + bj * HALF + n * 16) = w;
;                         ss += hn[0] * hn[0] + hn[1] * hn[1] + hn[2] * hn[2] + hn[3] * hn[3]; } }
;             if (HB) { ss += __shfl_xor(ss, 16); ss += __shfl_xor(ss, 32); if (fq == 0) RS[(size_t)(row0 + ai * HALF + m * 16) * 32 + u.pn * 4 + wc] = ss; }
.LBB0_1332:
	v_readlane_b32 s72, v239, 34
	v_or_b32_e32 v70, 48, v118
	v_readlane_b32 s74, v239, 36
	v_readlane_b32 s73, v239, 35
	v_readlane_b32 s75, v239, 37
	v_mad_i64_i32 v[72:73], s[16:17], v70, s74, 0
	s_waitcnt lgkmcnt(0)
	v_lshl_add_u64 v[32:33], v[72:73], 2, v[186:187]
	global_load_dwordx4 v[44:47], v[32:33], off
	global_load_dwordx4 v[40:43], v[32:33], off offset:64
	global_load_dwordx4 v[36:39], v[32:33], off offset:512
	s_nop 0
	global_load_dwordx4 v[32:35], v[32:33], off offset:576
	v_readlane_b32 s72, v240, 62
	v_lshl_add_u64 v[76:77], v[88:89], 0, v[182:183]
	v_readlane_b32 s76, v238, 2
	v_readlane_b32 s77, v238, 3
	v_mov_b32_e32 v181, v180
	s_waitcnt vmcnt(8)
	v_pk_fma_f32 v[68:69], v[30:31], v[180:181], v[62:63]
	v_lshl_add_u64 v[74:75], v[76:77], 2, s[76:77]
	v_pk_fma_f32 v[66:67], v[28:29], v[184:185], v[60:61]
	s_and_b64 vcc, exec, s[40:41]
	s_waitcnt vmcnt(7)
	v_pk_fma_f32 v[64:65], v[24:25], v[184:185], v[56:57]
	s_waitcnt vmcnt(6)
	v_pk_fma_f32 v[60:61], v[20:21], v[184:185], v[52:53]
	s_waitcnt vmcnt(5)
	v_pk_fma_f32 v[28:29], v[16:17], v[184:185], v[48:49]
	v_readlane_b32 s73, v240, 63
	v_readlane_b32 s74, v238, 0
	v_readlane_b32 s75, v238, 1
	v_readlane_b32 s78, v238, 4
	v_readlane_b32 s79, v238, 5
	global_store_dwordx4 v[74:75], v[66:69], off nt
	s_cbranch_vccnz .LBB0_1347
	v_readlane_b32 s72, v238, 6
	v_readlane_b32 s74, v238, 8
	v_readlane_b32 s75, v238, 9
	v_cvt_pk_bf16_f32 v20, v66, v67
	v_mul_f32_e32 v24, v67, v67
	v_cvt_pk_bf16_f32 v21, v68, v69
	v_fmac_f32_e32 v24, v66, v66
	v_lshl_add_u64 v[16:17], v[76:77], 1, s[74:75]
	global_store_dwordx2 v[16:17], v[20:21], off
	v_pk_fma_f32 v[66:67], v[26:27], v[180:181], v[58:59]
	v_cvt_pk_bf16_f32 v20, v64, v65
	global_store_dwordx4 v[74:75], v[64:67], off offset:64 nt
	v_cvt_pk_bf16_f32 v21, v66, v67
	global_store_dwordx2 v[16:17], v[20:21], off offset:32
	v_mul_f32_e32 v20, v65, v65
	v_fmac_f32_e32 v20, v64, v64
	v_fmac_f32_e32 v24, v68, v68
	v_fmac_f32_e32 v20, v66, v66
	v_fmac_f32_e32 v24, v69, v69
	v_fmac_f32_e32 v20, v67, v67
	v_add_f32_e32 v24, v24, v20
	v_pk_fma_f32 v[62:63], v[22:23], v[180:181], v[54:55]
	v_cvt_pk_bf16_f32 v20, v60, v61
	global_store_dwordx4 v[74:75], v[60:63], off offset:512 nt
	v_cvt_pk_bf16_f32 v21, v62, v63
	global_store_dwordx2 v[16:17], v[20:21], off offset:256
	v_mul_f32_e32 v20, v61, v61
	v_fmac_f32_e32 v20, v60, v60
	v_fmac_f32_e32 v20, v62, v62
	v_fmac_f32_e32 v20, v63, v63
	v_add_f32_e32 v24, v24, v20
	v_pk_fma_f32 v[30:31], v[18:19], v[180:181], v[50:51]
	v_cvt_pk_bf16_f32 v20, v28, v29
	global_store_dwordx4 v[74:75], v[28:31], off offset:576 nt
	v_cvt_pk_bf16_f32 v21, v30, v31
	global_store_dwordx2 v[16:17], v[20:21], off offset:288
	v_mul_f32_e32 v16, v29, v29
	v_and_b32_e32 v20, 64, v197
	v_fmac_f32_e32 v16, v28, v28
	v_xor_b32_e32 v17, 16, v197
	v_add_u32_e32 v20, 64, v20
	v_fmac_f32_e32 v16, v30, v30
	v_cmp_lt_i32_e32 vcc, v17, v20
	v_fmac_f32_e32 v16, v31, v31
	v_add_f32_e32 v16, v24, v16
	v_cndmask_b32_e32 v17, v197, v17, vcc
	v_lshlrev_b32_e32 v17, 2, v17
	ds_bpermute_b32 v17, v17, v16
	v_readlane_b32 s73, v238, 7
	s_waitcnt lgkmcnt(0)
	v_add_f32_e32 v16, v16, v17
	v_xor_b32_e32 v17, 32, v197
	v_cmp_lt_i32_e32 vcc, v17, v20
	s_nop 1
	v_cndmask_b32_e32 v17, v197, v17, vcc
	v_lshlrev_b32_e32 v17, 2, v17
	ds_bpermute_b32 v17, v17, v16
	s_and_saveexec_b64 s[16:17], s[36:37]
	s_cbranch_execz .LBB0_1335
	v_ashrrev_i32_e32 v87, 31, v86
	s_waitcnt lgkmcnt(0)
	v_add_f32_e32 v20, v16, v17
	v_lshlrev_b64 v[16:17], 7, v[86:87]
	v_lshl_add_u64 v[16:17], s[14:15], 0, v[16:17]
	global_store_dword v[16:17], v20, off

; DEVI unsigned pk_bf16(float lo, float hi) { unsigned r; asm("v_cvt_pk_bf16_f32 %0, %1, %2" : "=v"(r) : "v"(lo), "v"(hi)); return r; }
;     DEVI void operator()(const f32x4 (&acc)[2][2][4][2], const Unit& u, int wr, int wc, int fr, int fq, const LAS float*) const {
;     ...
;         for (int idx = 0; idx < 8; ++idx) {
;             const int ai = idx >> 2, m = idx & 3;
;             const size_t ro = (size_t)(row0 + ai * HALF + m * 16) * ldc + col0;
;             if (idx + 1 < 8) { const int ai2 = (idx + 1) >> 2, m2 = (idx + 1) & 3; const size_t ro2 = (size_t)(row0 + ai2 * HALF + m2 * 16) * ldc + col0;
; #pragma unroll
;                 for (int bj = 0; bj < 2; ++bj)
; #pragma unroll
;                     for (int n = 0; n < 2; ++n) nxt[bj][n] = *(const f32x4*)(R + ro2 + bj * HALF + n * 16); }
;             float ss = 0.f;
; #pragma unroll
;             for (int bj = 0; bj < 2; ++bj)
; #pragma unroll
;                 for (int n = 0; n < 2; ++n) {
;                     const f32x4 hn = cur[bj][n] + acc[ai][bj][m][n] * scale;
;                     *(f32x4*)(C + ro + bj * HALF + n * 16) = hn;
;                     if (HB) { u32x2 w; w.x = pk_bf16(hn[0], hn[1]); w.y = pk_bf16(hn[2], hn[3]); *(u32x2*)(HB + ro + bj * HALF + n * 16) = w;
;                         ss += hn[0] * hn[0] + hn[1] * hn[1] + hn[2] * hn[2] + hn[3] * hn[3]; } }
;             if (HB) { ss += __shfl_xor(ss, 16); ss += __shfl_xor(ss, 32); if (fq == 0) RS[(size_t)(row0 + ai * HALF + m * 16) * 32 + u.pn * 4 + wc] = ss; }
.LBB0_1337:
	v_readlane_b32 s72, v240, 62
	v_lshl_add_u64 v[18:19], v[72:73], 0, v[182:183]
	v_readlane_b32 s76, v238, 2
	v_readlane_b32 s77, v238, 3
	v_mov_b32_e32 v181, v180
	s_waitcnt vmcnt(4)
	v_pk_fma_f32 v[24:25], v[14:15], v[180:181], v[46:47]
	v_lshl_add_u64 v[26:27], v[18:19], 2, s[76:77]
	v_pk_fma_f32 v[22:23], v[12:13], v[184:185], v[44:45]
	s_and_b64 vcc, exec, s[40:41]
	s_waitcnt vmcnt(3)
	v_pk_fma_f32 v[20:21], v[8:9], v[184:185], v[40:41]
	s_waitcnt vmcnt(2) lgkmcnt(0)
	v_pk_fma_f32 v[16:17], v[4:5], v[184:185], v[36:37]
	s_waitcnt vmcnt(1)
	v_pk_fma_f32 v[12:13], v[0:1], v[184:185], v[32:33]
	v_readlane_b32 s73, v240, 63
	v_readlane_b32 s74, v238, 0
	v_readlane_b32 s75, v238, 1
	v_readlane_b32 s78, v238, 4
	v_readlane_b32 s79, v238, 5
	global_store_dwordx4 v[26:27], v[22:25], off nt
	s_cbranch_vccnz .LBB0_1348
	v_readlane_b32 s72, v238, 6
	v_readlane_b32 s74, v238, 8
	v_readlane_b32 s75, v238, 9
	v_cvt_pk_bf16_f32 v4, v22, v23
	v_mul_f32_e32 v8, v23, v23
	v_cvt_pk_bf16_f32 v5, v24, v25
	v_fmac_f32_e32 v8, v22, v22
	v_lshl_add_u64 v[0:1], v[18:19], 1, s[74:75]
	global_store_dwordx2 v[0:1], v[4:5], off
	v_pk_fma_f32 v[22:23], v[10:11], v[180:181], v[42:43]
	v_cvt_pk_bf16_f32 v4, v20, v21
	global_store_dwordx4 v[26:27], v[20:23], off offset:64 nt
	v_cvt_pk_bf16_f32 v5, v22, v23
	global_store_dwordx2 v[0:1], v[4:5], off offset:32
	v_mul_f32_e32 v4, v21, v21
	v_fmac_f32_e32 v4, v20, v20
	v_fmac_f32_e32 v8, v24, v24
	v_fmac_f32_e32 v4, v22, v22
	v_fmac_f32_e32 v8, v25, v25
	v_fmac_f32_e32 v4, v23, v23
	v_add_f32_e32 v8, v8, v4
	v_pk_fma_f32 v[18:19], v[6:7], v[180:181], v[38:39]
	v_cvt_pk_bf16_f32 v4, v16, v17
	global_store_dwordx4 v[26:27], v[16:19], off offset:512 nt
	v_cvt_pk_bf16_f32 v5, v18, v19
	global_store_dwordx2 v[0:1], v[4:5], off offset:256
	v_mul_f32_e32 v4, v17, v17
	v_fmac_f32_e32 v4, v16, v16
	v_fmac_f32_e32 v4, v18, v18
	v_fmac_f32_e32 v4, v19, v19
	v_add_f32_e32 v8, v8, v4
	v_pk_fma_f32 v[14:15], v[2:3], v[180:181], v[34:35]
	v_cvt_pk_bf16_f32 v4, v12, v13
	global_store_dwordx4 v[26:27], v[12:15], off offset:576 nt
	v_cvt_pk_bf16_f32 v5, v14, v15
	global_store_dwordx2 v[0:1], v[4:5], off offset:288
	v_mul_f32_e32 v0, v13, v13
	v_and_b32_e32 v4, 64, v197
	v_fmac_f32_e32 v0, v12, v12
	v_xor_b32_e32 v1, 16, v197
	v_add_u32_e32 v4, 64, v4
	v_fmac_f32_e32 v0, v14, v14
	v_cmp_lt_i32_e32 vcc, v1, v4
	v_fmac_f32_e32 v0, v15, v15
	v_add_f32_e32 v0, v8, v0
	v_cndmask_b32_e32 v1, v197, v1, vcc
	v_lshlrev_b32_e32 v1, 2, v1
	ds_bpermute_b32 v1, v1, v0
	v_readlane_b32 s73, v238, 7
	s_waitcnt lgkmcnt(0)
	v_add_f32_e32 v0, v0, v1
	v_xor_b32_e32 v1, 32, v197
	v_cmp_lt_i32_e32 vcc, v1, v4
	s_nop 1
	v_cndmask_b32_e32 v1, v197, v1, vcc
	v_lshlrev_b32_e32 v1, 2, v1
	ds_bpermute_b32 v1, v1, v0
	s_and_saveexec_b64 s[16:17], s[36:37]
	s_cbranch_execz .LBB0_1340
	v_ashrrev_i32_e32 v71, 31, v70
	s_waitcnt lgkmcnt(0)
	v_add_f32_e32 v4, v0, v1
	v_lshlrev_b64 v[0:1], 7, v[70:71]
	v_lshl_add_u64 v[0:1], s[14:15], 0, v[0:1]
	global_store_dword v[0:1], v4, off

; #define LAS __attribute__((address_space(3)))
; DEVI u32x4 pack8(const float* f) { u32x4 u; u.x = pk_bf16(f[0], f[1]); u.y = pk_bf16(f[2], f[3]); u.z = pk_bf16(f[4], f[5]); u.w = pk_bf16(f[6], f[7]); return u; }
; DEVI float row_rstd(const LAS float* rsl, int r) { return rsqrtf((rsl[r] + rsl[256 + r]) * (1.0f / DM) + 1e-6f); }
;     DEVI void operator()(const f32x4 (&acc)[2][2][4][2], const Unit& u, int wr, int wc, int fr, int fq, const LAS float* rsl) const {
;     ...
;             for (int m = 0; m < 4; ++m) { bf16_t* rowp = O + (size_t)(row0 + ai * HALF + m * 16) * ldc + col0;
;                 const float sc = row_rstd(rsl, wr * 64 + fr + ai * HALF + m * 16);
;                 const float k1 = -1.4426950408889634f * sc, k2 = sc * sc;
;                 float h[8], tt[8];
;                 const f32x4 guk0 = (acc[ai][0][m][0] * acc[ai][1][m][0]) * k2, guk1 = (acc[ai][0][m][1] * acc[ai][1][m][1]) * k2;
;                 const f32x4 ta = acc[ai][0][m][0] * k1, tb = acc[ai][0][m][1] * k1;
; #pragma unroll
;                 for (int j = 0; j < 4; ++j) { tt[j] = __builtin_amdgcn_exp2f(ta[j]); tt[4 + j] = __builtin_amdgcn_exp2f(tb[j]); }
;                 __builtin_amdgcn_sched_barrier(0);
; #pragma unroll
;                 for (int j = 0; j < 8; ++j) tt[j] = __builtin_amdgcn_rcpf(1.0f + tt[j]);
;                 __builtin_amdgcn_sched_barrier(0);
; #pragma unroll
;                 for (int j = 0; j < 4; ++j) { h[j] = guk0[j] * tt[j]; h[4 + j] = guk1[j] * tt[4 + j]; }
;                 *(u32x4*)rowp = pack8(h); }
.LBB0_1446:
	s_lshl_b32 s14, s76, 11
	s_and_b32 s14, s14, 0x800
	v_add_u32_e32 v168, s14, v148
	ds_read2st64_b32 v[144:145], v168 offset1:4
	v_readlane_b32 s76, v239, 44
	v_readlane_b32 s14, v239, 42
	v_readlane_b32 s78, v239, 46
	v_lshl_add_u32 v157, s75, 8, v147
	s_waitcnt lgkmcnt(0)
	v_add_f32_e32 v144, v144, v145
	v_fmamk_f32 v144, v144, 0x3a000000, v156
	v_mul_f32_e32 v145, 0x4b800000, v144
	v_cmp_gt_f32_e32 vcc, s50, v144
	v_readlane_b32 s15, v239, 43
	s_mov_b32 s70, s78
	v_cndmask_b32_e32 v144, v144, v145, vcc
	v_rsq_f32_e32 v158, v144
	v_lshl_or_b32 v144, s74, 7, v150
	v_ashrrev_i32_e32 v145, 31, v144
	v_lshl_add_u64 v[144:145], v[144:145], 1, s[14:15]
	v_mul_f32_e32 v159, 0x45800000, v158
	v_cndmask_b32_e32 v159, v158, v159, vcc
	v_mul_f32_e32 v158, 0xbfb8aa3b, v159
	v_pk_mul_f32 v[160:161], v[122:123], v[158:159] op_sel_hi:[1,0]
	v_pk_mul_f32 v[162:163], v[120:121], v[158:159] op_sel_hi:[1,0]
	v_pk_mul_f32 v[166:167], v[116:117], v[158:159] op_sel_hi:[1,0]
	v_pk_mul_f32 v[164:165], v[118:119], v[158:159] op_sel_hi:[1,0]
	v_exp_f32_e32 v158, v162
	v_exp_f32_e32 v162, v166
	v_exp_f32_e32 v166, v167
	v_exp_f32_e32 v167, v160
	v_exp_f32_e32 v169, v161
	v_mad_i64_i32 v[160:161], s[14:15], v157, s70, 0
	v_exp_f32_e32 v163, v163
	v_exp_f32_e32 v164, v164
	v_exp_f32_e32 v165, v165
	v_readlane_b32 s77, v239, 45
	v_readlane_b32 s79, v239, 47
	v_lshl_add_u64 v[160:161], v[160:161], 1, v[144:145]
	v_add_f32_e32 v158, 1.0, v158
	v_rcp_f32_e32 v170, v158
	v_add_f32_e32 v158, 1.0, v163
	v_rcp_f32_e32 v163, v158
	v_add_f32_e32 v158, 1.0, v167
	v_rcp_f32_e32 v167, v158
	v_add_f32_e32 v158, 1.0, v169
	v_rcp_f32_e32 v169, v158
	v_add_f32_e32 v158, 1.0, v162
	v_rcp_f32_e32 v162, v158
	v_add_f32_e32 v158, 1.0, v166
	v_rcp_f32_e32 v166, v158
	v_add_f32_e32 v158, 1.0, v164
	v_rcp_f32_e32 v164, v158
	v_add_f32_e32 v158, 1.0, v165
	v_rcp_f32_e32 v165, v158
	v_mul_f32_e32 v116, v112, v116
	v_mul_f32_e32 v117, v113, v117
	v_mov_b32_e32 v158, v114
	v_mov_b32_e32 v112, v118
	v_mov_b32_e32 v113, v159
	v_pk_mul_f32 v[112:113], v[158:159], v[112:113]
	v_mul_f32_e32 v121, v125, v121
	v_mul_f32_e32 v116, v116, v113
	v_mul_f32_e32 v120, v124, v120
	v_mul_f32_e32 v118, v116, v162
	v_mul_f32_e32 v116, v121, v113
	v_mul_f32_e32 v122, v126, v122
	v_mul_f32_e32 v114, v120, v113
	v_mul_f32_e32 v120, v116, v163
	v_mul_f32_e32 v116, v117, v113
	v_mul_f32_e32 v121, v116, v166
	v_mul_f32_e32 v116, v122, v113
	v_add_u32_e32 v125, 64, v168
	v_mul_f32_e32 v122, v116, v167
	ds_read2st64_b32 v[116:117], v125 offset1:4
	v_mul_f32_e32 v112, v112, v113
	v_mul_f32_e32 v124, v112, v164
	v_mul_f32_e32 v112, v127, v123
	v_mul_f32_e32 v112, v112, v113
	s_waitcnt lgkmcnt(0)
	v_add_f32_e32 v116, v116, v117
	v_fmamk_f32 v116, v116, 0x3a000000, v156
	v_mul_f32_e32 v117, 0x4b800000, v116
	v_cmp_gt_f32_e32 vcc, s50, v116
	v_mul_f32_e32 v123, v112, v169
	v_mul_f32_e32 v112, v115, v119
	v_cndmask_b32_e32 v116, v116, v117, vcc
	v_rsq_f32_e32 v116, v116
	v_mul_f32_e32 v112, v112, v113
	v_mul_f32_e32 v114, v114, v170
	v_mul_f32_e32 v115, v112, v165
	v_cvt_pk_bf16_f32 v112, v114, v120
	v_cvt_pk_bf16_f32 v113, v122, v123
	v_cvt_pk_bf16_f32 v114, v118, v121
	v_cvt_pk_bf16_f32 v115, v124, v115
	global_store_dwordx4 v[160:161], v[112:115], off nt
	v_or_b32_e32 v122, 16, v157
	s_nop 0
	v_mul_f32_e32 v112, 0x45800000, v116
	v_cndmask_b32_e32 v113, v116, v112, vcc
	v_mul_f32_e32 v112, 0xbfb8aa3b, v113
	v_pk_mul_f32 v[114:115], v[110:111], v[112:113] op_sel_hi:[1,0]
	v_pk_mul_f32 v[116:117], v[108:109], v[112:113] op_sel_hi:[1,0]
	v_pk_mul_f32 v[120:121], v[100:101], v[112:113] op_sel_hi:[1,0]
	v_pk_mul_f32 v[118:119], v[102:103], v[112:113] op_sel_hi:[1,0]
	v_exp_f32_e32 v112, v116
	v_exp_f32_e32 v116, v120
	v_exp_f32_e32 v120, v121
	v_exp_f32_e32 v121, v114
	v_exp_f32_e32 v123, v115
	v_mad_i64_i32 v[114:115], s[14:15], v122, s70, 0
	v_exp_f32_e32 v117, v117
	v_exp_f32_e32 v118, v118
	v_exp_f32_e32 v119, v119
	v_lshl_add_u64 v[114:115], v[114:115], 1, v[144:145]
	v_add_f32_e32 v112, 1.0, v112
	v_rcp_f32_e32 v122, v112
	v_add_f32_e32 v112, 1.0, v117
	v_rcp_f32_e32 v117, v112
	v_add_f32_e32 v112, 1.0, v121
	v_rcp_f32_e32 v121, v112
	v_add_f32_e32 v112, 1.0, v123
	v_rcp_f32_e32 v123, v112
	v_add_f32_e32 v112, 1.0, v116
	v_rcp_f32_e32 v116, v112
	v_add_f32_e32 v112, 1.0, v120
	v_rcp_f32_e32 v120, v112
	v_add_f32_e32 v112, 1.0, v118
	v_rcp_f32_e32 v118, v112
	v_add_f32_e32 v112, 1.0, v119
	v_rcp_f32_e32 v119, v112
	v_mul_f32_e32 v100, v96, v100
	v_mul_f32_e32 v101, v97, v101
	v_mov_b32_e32 v112, v98
	v_mov_b32_e32 v96, v102
	v_mov_b32_e32 v97, v113
	v_pk_mul_f32 v[96:97], v[112:113], v[96:97]
	v_mul_f32_e32 v105, v105, v109
	v_mul_f32_e32 v100, v100, v97
	v_mul_f32_e32 v104, v104, v108
	v_mul_f32_e32 v102, v100, v116
	v_mul_f32_e32 v100, v105, v97
	v_mul_f32_e32 v106, v106, v110
	v_mul_f32_e32 v98, v104, v97
	v_mul_f32_e32 v104, v100, v117
	v_mul_f32_e32 v100, v101, v97
	v_mul_f32_e32 v105, v100, v120
	v_mul_f32_e32 v100, v106, v97
	v_add_u32_e32 v109, 0x80, v168
	v_mul_f32_e32 v106, v100, v121
	ds_read2st64_b32 v[100:101], v109 offset1:4
	v_mul_f32_e32 v96, v96, v97
	v_mul_f32_e32 v108, v96, v118
	v_mul_f32_e32 v96, v107, v111
	v_mul_f32_e32 v96, v96, v97
	s_waitcnt lgkmcnt(0)
; DEVI u32x4 pack8(const float* f) { u32x4 u; u.x = pk_bf16(f[0], f[1]); u.y = pk_bf16(f[2], f[3]); u.z = pk_bf16(f[4], f[5]); u.w = pk_bf16(f[6], f[7]); return u; }
; DEVI float row_rstd(const LAS float* rsl, int r) { return rsqrtf((rsl[r] + rsl[256 + r]) * (1.0f / DM) + 1e-6f); }
;     DEVI void operator()(const f32x4 (&acc)[2][2][4][2], const Unit& u, int wr, int wc, int fr, int fq, const LAS float* rsl) const {
;     ...
;             for (int m = 0; m < 4; ++m) { bf16_t* rowp = O + (size_t)(row0 + ai * HALF + m * 16) * ldc + col0;
;                 const float sc = row_rstd(rsl, wr * 64 + fr + ai * HALF + m * 16);
;                 const float k1 = -1.4426950408889634f * sc, k2 = sc * sc;
;                 float h[8], tt[8];
;                 const f32x4 guk0 = (acc[ai][0][m][0] * acc[ai][1][m][0]) * k2, guk1 = (acc[ai][0][m][1] * acc[ai][1][m][1]) * k2;
;                 const f32x4 ta = acc[ai][0][m][0] * k1, tb = acc[ai][0][m][1] * k1;
; #pragma unroll
;                 for (int j = 0; j < 4; ++j) { tt[j] = __builtin_amdgcn_exp2f(ta[j]); tt[4 + j] = __builtin_amdgcn_exp2f(tb[j]); }
;                 __builtin_amdgcn_sched_barrier(0);
; #pragma unroll
;                 for (int j = 0; j < 8; ++j) tt[j] = __builtin_amdgcn_rcpf(1.0f + tt[j]);
;                 __builtin_amdgcn_sched_barrier(0);
; #pragma unroll
;                 for (int j = 0; j < 4; ++j) { h[j] = guk0[j] * tt[j]; h[4 + j] = guk1[j] * tt[4 + j]; }
;                 *(u32x4*)rowp = pack8(h); }
	v_add_f32_e32 v100, v100, v101
	v_fmamk_f32 v100, v100, 0x3a000000, v156
	v_mul_f32_e32 v101, 0x4b800000, v100
	v_cmp_gt_f32_e32 vcc, s50, v100
	v_mul_f32_e32 v107, v96, v123
	v_mul_f32_e32 v96, v99, v103
	v_cndmask_b32_e32 v100, v100, v101, vcc
	v_rsq_f32_e32 v100, v100
	v_mul_f32_e32 v96, v96, v97
	v_mul_f32_e32 v98, v98, v122
	v_mul_f32_e32 v99, v96, v119
	v_cvt_pk_bf16_f32 v96, v98, v104
	v_cvt_pk_bf16_f32 v97, v106, v107
	v_cvt_pk_bf16_f32 v98, v102, v105
	v_cvt_pk_bf16_f32 v99, v108, v99
	global_store_dwordx4 v[114:115], v[96:99], off nt
	v_or_b32_e32 v106, 32, v157
	s_nop 0
	v_mul_f32_e32 v96, 0x45800000, v100
	v_cndmask_b32_e32 v97, v100, v96, vcc
	v_mul_f32_e32 v96, 0xbfb8aa3b, v97
	v_pk_mul_f32 v[98:99], v[94:95], v[96:97] op_sel_hi:[1,0]
	v_pk_mul_f32 v[100:101], v[92:93], v[96:97] op_sel_hi:[1,0]
	v_pk_mul_f32 v[104:105], v[84:85], v[96:97] op_sel_hi:[1,0]
	v_pk_mul_f32 v[102:103], v[86:87], v[96:97] op_sel_hi:[1,0]
	v_exp_f32_e32 v96, v100
	v_exp_f32_e32 v100, v104
	v_exp_f32_e32 v104, v105
	v_exp_f32_e32 v105, v98
	v_exp_f32_e32 v107, v99
	v_mad_i64_i32 v[98:99], s[14:15], v106, s70, 0
	v_exp_f32_e32 v101, v101
	v_exp_f32_e32 v102, v102
	v_exp_f32_e32 v103, v103
	v_lshl_add_u64 v[98:99], v[98:99], 1, v[144:145]
	v_add_f32_e32 v96, 1.0, v96
	v_rcp_f32_e32 v106, v96
	v_add_f32_e32 v96, 1.0, v101
	v_rcp_f32_e32 v101, v96
	v_add_f32_e32 v96, 1.0, v105
	v_rcp_f32_e32 v105, v96
	v_add_f32_e32 v96, 1.0, v107
	v_rcp_f32_e32 v107, v96
	v_add_f32_e32 v96, 1.0, v100
	v_rcp_f32_e32 v100, v96
	v_add_f32_e32 v96, 1.0, v104
	v_rcp_f32_e32 v104, v96
	v_add_f32_e32 v96, 1.0, v102
	v_rcp_f32_e32 v102, v96
	v_add_f32_e32 v96, 1.0, v103
	v_rcp_f32_e32 v103, v96
	v_mul_f32_e32 v84, v80, v84
	v_mul_f32_e32 v85, v81, v85
	v_mov_b32_e32 v96, v82
	v_mov_b32_e32 v80, v86
	v_mov_b32_e32 v81, v97
	v_pk_mul_f32 v[80:81], v[96:97], v[80:81]
	v_mul_f32_e32 v89, v89, v93
	v_mul_f32_e32 v84, v84, v81
	v_mul_f32_e32 v88, v88, v92
	v_mul_f32_e32 v86, v84, v100
	v_mul_f32_e32 v84, v89, v81
	v_mul_f32_e32 v90, v90, v94
	v_mul_f32_e32 v82, v88, v81
	v_mul_f32_e32 v88, v84, v101
	v_mul_f32_e32 v84, v85, v81
	v_mul_f32_e32 v89, v84, v104
	v_mul_f32_e32 v84, v90, v81
	v_add_u32_e32 v93, 0xc0, v168
	v_mul_f32_e32 v90, v84, v105
	ds_read2st64_b32 v[84:85], v93 offset1:4
	v_mul_f32_e32 v80, v80, v81
	v_mul_f32_e32 v92, v80, v102
	v_mul_f32_e32 v80, v91, v95
	v_mul_f32_e32 v80, v80, v81
	s_waitcnt lgkmcnt(0)
	v_add_f32_e32 v84, v84, v85
	v_fmamk_f32 v84, v84, 0x3a000000, v156
	v_mul_f32_e32 v85, 0x4b800000, v84
	v_cmp_gt_f32_e32 vcc, s50, v84
	v_mul_f32_e32 v91, v80, v107
	v_mul_f32_e32 v80, v83, v87
	v_cndmask_b32_e32 v84, v84, v85, vcc
	v_rsq_f32_e32 v84, v84
	v_mul_f32_e32 v80, v80, v81
	v_mul_f32_e32 v82, v82, v106
	v_mul_f32_e32 v83, v80, v103
	v_cvt_pk_bf16_f32 v80, v82, v88
	v_cvt_pk_bf16_f32 v81, v90, v91
	v_cvt_pk_bf16_f32 v82, v86, v89
	v_cvt_pk_bf16_f32 v83, v92, v83
	global_store_dwordx4 v[98:99], v[80:83], off nt
	v_or_b32_e32 v90, 48, v157
	s_nop 0
	v_mul_f32_e32 v80, 0x45800000, v84
	v_cndmask_b32_e32 v81, v84, v80, vcc
	v_mul_f32_e32 v80, 0xbfb8aa3b, v81
	v_pk_mul_f32 v[82:83], v[78:79], v[80:81] op_sel_hi:[1,0]
	v_pk_mul_f32 v[84:85], v[76:77], v[80:81] op_sel_hi:[1,0]
	v_pk_mul_f32 v[88:89], v[68:69], v[80:81] op_sel_hi:[1,0]
	v_pk_mul_f32 v[86:87], v[70:71], v[80:81] op_sel_hi:[1,0]
	v_exp_f32_e32 v80, v84
	v_exp_f32_e32 v84, v88
	v_exp_f32_e32 v88, v89
	v_exp_f32_e32 v89, v82
	v_exp_f32_e32 v91, v83
	v_mad_i64_i32 v[82:83], s[14:15], v90, s70, 0
	v_exp_f32_e32 v85, v85
	v_exp_f32_e32 v86, v86
	v_exp_f32_e32 v87, v87
	v_lshl_add_u64 v[82:83], v[82:83], 1, v[144:145]
	v_add_f32_e32 v80, 1.0, v80
	v_rcp_f32_e32 v90, v80
	v_add_f32_e32 v80, 1.0, v85
	v_rcp_f32_e32 v85, v80
	v_add_f32_e32 v80, 1.0, v89
	v_rcp_f32_e32 v89, v80
	v_add_f32_e32 v80, 1.0, v91
	v_rcp_f32_e32 v91, v80
	v_add_f32_e32 v80, 1.0, v84
	v_rcp_f32_e32 v84, v80
	v_add_f32_e32 v80, 1.0, v88
	v_rcp_f32_e32 v88, v80
	v_add_f32_e32 v80, 1.0, v86
	v_rcp_f32_e32 v86, v80
	v_add_f32_e32 v80, 1.0, v87
	v_rcp_f32_e32 v87, v80
	v_mul_f32_e32 v68, v64, v68
	v_mul_f32_e32 v69, v65, v69
	v_mov_b32_e32 v80, v66
	v_mov_b32_e32 v64, v70
	v_mov_b32_e32 v65, v81
	v_pk_mul_f32 v[64:65], v[80:81], v[64:65]
	v_mul_f32_e32 v73, v73, v77
	v_mul_f32_e32 v68, v68, v65
	v_mul_f32_e32 v72, v72, v76
	v_mul_f32_e32 v70, v68, v84
	v_mul_f32_e32 v68, v73, v65
	v_mul_f32_e32 v74, v74, v78
	v_mul_f32_e32 v66, v72, v65
	v_mul_f32_e32 v72, v68, v85
	v_mul_f32_e32 v68, v69, v65
	v_mul_f32_e32 v73, v68, v88
	v_mul_f32_e32 v68, v74, v65
	v_mul_f32_e32 v74, v68, v89
	ds_read2st64_b32 v[68:69], v168 offset0:2 offset1:6
	v_mul_f32_e32 v64, v64, v65
	v_mul_f32_e32 v76, v64, v86
	v_mul_f32_e32 v64, v75, v79
	v_mul_f32_e32 v64, v64, v65
	s_waitcnt lgkmcnt(0)
; DEVI u32x4 pack8(const float* f) { u32x4 u; u.x = pk_bf16(f[0], f[1]); u.y = pk_bf16(f[2], f[3]); u.z = pk_bf16(f[4], f[5]); u.w = pk_bf16(f[6], f[7]); return u; }
; DEVI float row_rstd(const LAS float* rsl, int r) { return rsqrtf((rsl[r] + rsl[256 + r]) * (1.0f / DM) + 1e-6f); }
;     DEVI void operator()(const f32x4 (&acc)[2][2][4][2], const Unit& u, int wr, int wc, int fr, int fq, const LAS float* rsl) const {
;     ...
;             for (int m = 0; m < 4; ++m) { bf16_t* rowp = O + (size_t)(row0 + ai * HALF + m * 16) * ldc + col0;
;                 const float sc = row_rstd(rsl, wr * 64 + fr + ai * HALF + m * 16);
;                 const float k1 = -1.4426950408889634f * sc, k2 = sc * sc;
;                 float h[8], tt[8];
;                 const f32x4 guk0 = (acc[ai][0][m][0] * acc[ai][1][m][0]) * k2, guk1 = (acc[ai][0][m][1] * acc[ai][1][m][1]) * k2;
;                 const f32x4 ta = acc[ai][0][m][0] * k1, tb = acc[ai][0][m][1] * k1;
; #pragma unroll
;                 for (int j = 0; j < 4; ++j) { tt[j] = __builtin_amdgcn_exp2f(ta[j]); tt[4 + j] = __builtin_amdgcn_exp2f(tb[j]); }
;                 __builtin_amdgcn_sched_barrier(0);
; #pragma unroll
;                 for (int j = 0; j < 8; ++j) tt[j] = __builtin_amdgcn_rcpf(1.0f + tt[j]);
;                 __builtin_amdgcn_sched_barrier(0);
; #pragma unroll
;                 for (int j = 0; j < 4; ++j) { h[j] = guk0[j] * tt[j]; h[4 + j] = guk1[j] * tt[4 + j]; }
;                 *(u32x4*)rowp = pack8(h); }
	v_add_f32_e32 v68, v68, v69
	v_fmamk_f32 v68, v68, 0x3a000000, v156
	v_mul_f32_e32 v69, 0x4b800000, v68
	v_cmp_gt_f32_e32 vcc, s50, v68
	v_mul_f32_e32 v75, v64, v91
	v_mul_f32_e32 v64, v67, v71
	v_cndmask_b32_e32 v68, v68, v69, vcc
	v_rsq_f32_e32 v68, v68
	v_mul_f32_e32 v64, v64, v65
	v_mul_f32_e32 v66, v66, v90
	v_mul_f32_e32 v67, v64, v87
	v_cvt_pk_bf16_f32 v64, v66, v72
	v_cvt_pk_bf16_f32 v65, v74, v75
	v_cvt_pk_bf16_f32 v66, v70, v73
	v_cvt_pk_bf16_f32 v67, v76, v67
	global_store_dwordx4 v[82:83], v[64:67], off nt
	v_add_u32_e32 v74, 0x80, v157
	s_nop 0
	v_mul_f32_e32 v64, 0x45800000, v68
	v_cndmask_b32_e32 v65, v68, v64, vcc
	v_mul_f32_e32 v64, 0xbfb8aa3b, v65
	v_pk_mul_f32 v[66:67], v[62:63], v[64:65] op_sel_hi:[1,0]
	v_pk_mul_f32 v[68:69], v[60:61], v[64:65] op_sel_hi:[1,0]
	v_pk_mul_f32 v[72:73], v[56:57], v[64:65] op_sel_hi:[1,0]
	v_pk_mul_f32 v[70:71], v[58:59], v[64:65] op_sel_hi:[1,0]
	v_exp_f32_e32 v64, v68
	v_exp_f32_e32 v68, v72
	v_exp_f32_e32 v72, v73
	v_exp_f32_e32 v73, v66
	v_exp_f32_e32 v75, v67
	v_mad_i64_i32 v[66:67], s[14:15], v74, s70, 0
	v_exp_f32_e32 v69, v69
	v_exp_f32_e32 v70, v70
	v_exp_f32_e32 v71, v71
	v_lshl_add_u64 v[66:67], v[66:67], 1, v[144:145]
	v_add_f32_e32 v64, 1.0, v64
	v_rcp_f32_e32 v74, v64
	v_add_f32_e32 v64, 1.0, v69
	v_rcp_f32_e32 v69, v64
	v_add_f32_e32 v64, 1.0, v73
	v_rcp_f32_e32 v73, v64
	v_add_f32_e32 v64, 1.0, v75
	v_rcp_f32_e32 v75, v64
	v_add_f32_e32 v64, 1.0, v68
	v_rcp_f32_e32 v68, v64
	v_add_f32_e32 v64, 1.0, v72
	v_rcp_f32_e32 v72, v64
	v_add_f32_e32 v64, 1.0, v70
	v_rcp_f32_e32 v70, v64
	v_add_f32_e32 v64, 1.0, v71
	v_rcp_f32_e32 v71, v64
	v_mul_f32_e32 v56, v48, v56
	v_mul_f32_e32 v57, v49, v57
	v_mov_b32_e32 v64, v50
	v_mov_b32_e32 v48, v58
	v_mov_b32_e32 v49, v65
	v_mul_f32_e32 v52, v52, v60
	v_pk_mul_f32 v[48:49], v[64:65], v[48:49]
	v_mul_f32_e32 v53, v53, v61
	v_mul_f32_e32 v50, v52, v49
	v_mul_f32_e32 v52, v56, v49
	v_mul_f32_e32 v56, v52, v68
	v_mul_f32_e32 v52, v53, v49
	v_mul_f32_e32 v54, v54, v62
	v_mul_f32_e32 v58, v52, v69
	v_mul_f32_e32 v52, v57, v49
	v_mul_f32_e32 v57, v52, v72
	v_mul_f32_e32 v52, v54, v49
	v_mul_f32_e32 v54, v52, v73
	ds_read2st64_b32 v[52:53], v125 offset0:2 offset1:6
	v_mul_f32_e32 v48, v48, v49
	v_mul_f32_e32 v60, v48, v70
	v_mul_f32_e32 v48, v55, v63
	v_mul_f32_e32 v48, v48, v49
	s_waitcnt lgkmcnt(0)
	v_add_f32_e32 v52, v52, v53
	v_fmamk_f32 v52, v52, 0x3a000000, v156
	v_mul_f32_e32 v53, 0x4b800000, v52
	v_cmp_gt_f32_e32 vcc, s50, v52
	v_mul_f32_e32 v55, v48, v75
	v_mul_f32_e32 v48, v51, v59
	v_cndmask_b32_e32 v52, v52, v53, vcc
	v_rsq_f32_e32 v52, v52
	v_mul_f32_e32 v48, v48, v49
	v_mul_f32_e32 v50, v50, v74
	v_mul_f32_e32 v51, v48, v71
	v_cvt_pk_bf16_f32 v48, v50, v58
	v_cvt_pk_bf16_f32 v49, v54, v55
	v_cvt_pk_bf16_f32 v50, v56, v57
	v_cvt_pk_bf16_f32 v51, v60, v51
	global_store_dwordx4 v[66:67], v[48:51], off nt
	v_add_u32_e32 v58, 0x90, v157
	s_nop 0
	v_mul_f32_e32 v48, 0x45800000, v52
	v_cndmask_b32_e32 v49, v52, v48, vcc
	v_mul_f32_e32 v48, 0xbfb8aa3b, v49
	v_pk_mul_f32 v[50:51], v[46:47], v[48:49] op_sel_hi:[1,0]
	v_pk_mul_f32 v[52:53], v[44:45], v[48:49] op_sel_hi:[1,0]
	v_pk_mul_f32 v[56:57], v[40:41], v[48:49] op_sel_hi:[1,0]
	v_pk_mul_f32 v[54:55], v[42:43], v[48:49] op_sel_hi:[1,0]
	v_exp_f32_e32 v48, v52
	v_exp_f32_e32 v52, v56
	v_exp_f32_e32 v56, v57
	v_exp_f32_e32 v57, v50
	v_exp_f32_e32 v59, v51
	v_mad_i64_i32 v[50:51], s[14:15], v58, s70, 0
	v_exp_f32_e32 v53, v53
	v_exp_f32_e32 v54, v54
	v_exp_f32_e32 v55, v55
	v_lshl_add_u64 v[50:51], v[50:51], 1, v[144:145]
	v_add_f32_e32 v48, 1.0, v48
	v_rcp_f32_e32 v58, v48
	v_add_f32_e32 v48, 1.0, v53
	v_rcp_f32_e32 v53, v48
	v_add_f32_e32 v48, 1.0, v57
	v_rcp_f32_e32 v57, v48
	v_add_f32_e32 v48, 1.0, v59
	v_rcp_f32_e32 v59, v48
	v_add_f32_e32 v48, 1.0, v52
	v_rcp_f32_e32 v52, v48
	v_add_f32_e32 v48, 1.0, v56
	v_rcp_f32_e32 v56, v48
	v_add_f32_e32 v48, 1.0, v54
	v_rcp_f32_e32 v54, v48
	v_add_f32_e32 v48, 1.0, v55
	v_rcp_f32_e32 v55, v48
	v_mul_f32_e32 v40, v32, v40
	v_mul_f32_e32 v41, v33, v41
	v_mov_b32_e32 v48, v34
	v_mov_b32_e32 v32, v42
	v_mov_b32_e32 v33, v49
	v_mul_f32_e32 v36, v36, v44
	v_pk_mul_f32 v[32:33], v[48:49], v[32:33]
	v_mul_f32_e32 v37, v37, v45
	v_mul_f32_e32 v34, v36, v33
	v_mul_f32_e32 v36, v40, v33
	v_mul_f32_e32 v40, v36, v52
	v_mul_f32_e32 v36, v37, v33
	v_mul_f32_e32 v38, v38, v46
	v_mul_f32_e32 v42, v36, v53
	v_mul_f32_e32 v36, v41, v33
	v_mul_f32_e32 v41, v36, v56
	v_mul_f32_e32 v36, v38, v33
	v_mul_f32_e32 v38, v36, v57
	ds_read2st64_b32 v[36:37], v109 offset0:2 offset1:6
	v_mul_f32_e32 v32, v32, v33
	v_mul_f32_e32 v44, v32, v54
	v_mul_f32_e32 v32, v39, v47
	v_mul_f32_e32 v32, v32, v33
	s_waitcnt lgkmcnt(0)
; DEVI u32x4 pack8(const float* f) { u32x4 u; u.x = pk_bf16(f[0], f[1]); u.y = pk_bf16(f[2], f[3]); u.z = pk_bf16(f[4], f[5]); u.w = pk_bf16(f[6], f[7]); return u; }
; DEVI float row_rstd(const LAS float* rsl, int r) { return rsqrtf((rsl[r] + rsl[256 + r]) * (1.0f / DM) + 1e-6f); }
;     DEVI void operator()(const f32x4 (&acc)[2][2][4][2], const Unit& u, int wr, int wc, int fr, int fq, const LAS float* rsl) const {
;     ...
;             for (int m = 0; m < 4; ++m) { bf16_t* rowp = O + (size_t)(row0 + ai * HALF + m * 16) * ldc + col0;
;                 const float sc = row_rstd(rsl, wr * 64 + fr + ai * HALF + m * 16);
;                 const float k1 = -1.4426950408889634f * sc, k2 = sc * sc;
;                 float h[8], tt[8];
;                 const f32x4 guk0 = (acc[ai][0][m][0] * acc[ai][1][m][0]) * k2, guk1 = (acc[ai][0][m][1] * acc[ai][1][m][1]) * k2;
;                 const f32x4 ta = acc[ai][0][m][0] * k1, tb = acc[ai][0][m][1] * k1;
; #pragma unroll
;                 for (int j = 0; j < 4; ++j) { tt[j] = __builtin_amdgcn_exp2f(ta[j]); tt[4 + j] = __builtin_amdgcn_exp2f(tb[j]); }
;                 __builtin_amdgcn_sched_barrier(0);
; #pragma unroll
;                 for (int j = 0; j < 8; ++j) tt[j] = __builtin_amdgcn_rcpf(1.0f + tt[j]);
;                 __builtin_amdgcn_sched_barrier(0);
; #pragma unroll
;                 for (int j = 0; j < 4; ++j) { h[j] = guk0[j] * tt[j]; h[4 + j] = guk1[j] * tt[4 + j]; }
;                 *(u32x4*)rowp = pack8(h); }
; template <class Epi>
; DEVI void gemm_phase(LAS unsigned char* lds, const bf16_t* gA, const bf16_t* gBt, const int lda, const int ldb, const int K, const StaticOrder S_, const Epi E) {
;     ...
;         if constexpr (Epi::HAS_RS) { if (E.rs_) {
;             const int r = tid & 255, hf = tid >> 8; float s = 0.f;
;             const float* base = E.rs_ + (size_t)(u.pm * BM + r) * 32 + hf * 16;
;             if (E.rsn_ == 32) {
;                 const f32x4 a = *(const f32x4*)base, b = *(const f32x4*)(base + 4), c = *(const f32x4*)(base + 8), d = *(const f32x4*)(base + 12);
;                 s = ((a[0] + a[1]) + (a[2] + a[3])) + ((b[0] + b[1]) + (b[2] + b[3])) + ((c[0] + c[1]) + (c[2] + c[3])) + ((d[0] + d[1]) + (d[2] + d[3]));
;             } else if (hf == 0) s = base[0];
	v_add_f32_e32 v36, v36, v37
	v_fmamk_f32 v36, v36, 0x3a000000, v156
	v_mul_f32_e32 v37, 0x4b800000, v36
	v_cmp_gt_f32_e32 vcc, s50, v36
	v_mul_f32_e32 v39, v32, v59
	v_mul_f32_e32 v32, v35, v43
	v_cndmask_b32_e32 v36, v36, v37, vcc
	v_rsq_f32_e32 v36, v36
	v_mul_f32_e32 v32, v32, v33
	v_mul_f32_e32 v34, v34, v58
	v_mul_f32_e32 v35, v32, v55
	v_cvt_pk_bf16_f32 v32, v34, v42
	v_cvt_pk_bf16_f32 v33, v38, v39
	v_cvt_pk_bf16_f32 v34, v40, v41
	v_cvt_pk_bf16_f32 v35, v44, v35
	global_store_dwordx4 v[50:51], v[32:35], off nt
	v_add_u32_e32 v42, 0xa0, v157
	s_nop 0
	v_mul_f32_e32 v32, 0x45800000, v36
	v_cndmask_b32_e32 v33, v36, v32, vcc
	v_mul_f32_e32 v32, 0xbfb8aa3b, v33
	v_pk_mul_f32 v[34:35], v[30:31], v[32:33] op_sel_hi:[1,0]
	v_pk_mul_f32 v[36:37], v[28:29], v[32:33] op_sel_hi:[1,0]
	v_pk_mul_f32 v[40:41], v[24:25], v[32:33] op_sel_hi:[1,0]
	v_pk_mul_f32 v[38:39], v[26:27], v[32:33] op_sel_hi:[1,0]
	v_exp_f32_e32 v32, v36
	v_exp_f32_e32 v36, v40
	v_exp_f32_e32 v40, v41
	v_exp_f32_e32 v41, v34
	v_exp_f32_e32 v43, v35
	v_mad_i64_i32 v[34:35], s[14:15], v42, s70, 0
	v_exp_f32_e32 v37, v37
	v_exp_f32_e32 v38, v38
	v_exp_f32_e32 v39, v39
	v_lshl_add_u64 v[34:35], v[34:35], 1, v[144:145]
	v_add_f32_e32 v32, 1.0, v32
	v_rcp_f32_e32 v42, v32
	v_add_f32_e32 v32, 1.0, v37
	v_rcp_f32_e32 v37, v32
	v_add_f32_e32 v32, 1.0, v41
	v_rcp_f32_e32 v41, v32
	v_add_f32_e32 v32, 1.0, v43
	v_rcp_f32_e32 v43, v32
	v_add_f32_e32 v32, 1.0, v36
	v_rcp_f32_e32 v36, v32
	v_add_f32_e32 v32, 1.0, v40
	v_rcp_f32_e32 v40, v32
	v_add_f32_e32 v32, 1.0, v38
	v_rcp_f32_e32 v38, v32
	v_add_f32_e32 v32, 1.0, v39
	v_rcp_f32_e32 v39, v32
	v_mul_f32_e32 v24, v16, v24
	v_mul_f32_e32 v25, v17, v25
	v_mov_b32_e32 v32, v18
	v_mov_b32_e32 v16, v26
	v_mov_b32_e32 v17, v33
	v_mul_f32_e32 v20, v20, v28
	v_pk_mul_f32 v[16:17], v[32:33], v[16:17]
	v_mul_f32_e32 v21, v21, v29
	v_mul_f32_e32 v18, v20, v17
	v_mul_f32_e32 v20, v24, v17
	v_mul_f32_e32 v24, v20, v36
	v_mul_f32_e32 v20, v21, v17
	v_mul_f32_e32 v22, v22, v30
	v_mul_f32_e32 v26, v20, v37
	v_mul_f32_e32 v20, v25, v17
	v_mul_f32_e32 v25, v20, v40
	v_mul_f32_e32 v20, v22, v17
	v_mul_f32_e32 v22, v20, v41
	ds_read2st64_b32 v[20:21], v93 offset0:2 offset1:6
	v_mul_f32_e32 v16, v16, v17
	v_mul_f32_e32 v28, v16, v38
	v_mul_f32_e32 v16, v23, v31
	v_mul_f32_e32 v16, v16, v17
	s_waitcnt lgkmcnt(0)
	v_add_f32_e32 v20, v20, v21
	v_fmamk_f32 v20, v20, 0x3a000000, v156
	v_mul_f32_e32 v21, 0x4b800000, v20
	v_cmp_gt_f32_e32 vcc, s50, v20
	v_mul_f32_e32 v23, v16, v43
	v_mul_f32_e32 v16, v19, v27
	v_cndmask_b32_e32 v20, v20, v21, vcc
	v_rsq_f32_e32 v20, v20
	v_mul_f32_e32 v16, v16, v17
	v_mul_f32_e32 v18, v18, v42
	v_mul_f32_e32 v19, v16, v39
	v_cvt_pk_bf16_f32 v16, v18, v26
	v_cvt_pk_bf16_f32 v17, v22, v23
	v_cvt_pk_bf16_f32 v18, v24, v25
	v_cvt_pk_bf16_f32 v19, v28, v19
	global_store_dwordx4 v[34:35], v[16:19], off nt
	v_add_u32_e32 v26, 0xb0, v157
	s_nop 0
	v_mul_f32_e32 v16, 0x45800000, v20
	v_cndmask_b32_e32 v17, v20, v16, vcc
	v_mul_f32_e32 v16, 0xbfb8aa3b, v17
	v_pk_mul_f32 v[18:19], v[14:15], v[16:17] op_sel_hi:[1,0]
	v_pk_mul_f32 v[20:21], v[12:13], v[16:17] op_sel_hi:[1,0]
	v_pk_mul_f32 v[24:25], v[8:9], v[16:17] op_sel_hi:[1,0]
	v_pk_mul_f32 v[22:23], v[10:11], v[16:17] op_sel_hi:[1,0]
	v_exp_f32_e32 v16, v20
	v_exp_f32_e32 v20, v24
	v_exp_f32_e32 v24, v25
	v_exp_f32_e32 v25, v18
	v_exp_f32_e32 v27, v19
	v_mad_i64_i32 v[18:19], s[14:15], v26, s70, 0
	v_exp_f32_e32 v21, v21
	v_exp_f32_e32 v22, v22
	v_exp_f32_e32 v23, v23
	v_lshl_add_u64 v[18:19], v[18:19], 1, v[144:145]
	v_add_f32_e32 v16, 1.0, v16
	v_rcp_f32_e32 v26, v16
	v_add_f32_e32 v16, 1.0, v21
	v_rcp_f32_e32 v21, v16
	v_add_f32_e32 v16, 1.0, v25
	v_rcp_f32_e32 v25, v16
	v_add_f32_e32 v16, 1.0, v27
	v_rcp_f32_e32 v27, v16
	v_add_f32_e32 v16, 1.0, v20
	v_rcp_f32_e32 v20, v16
	v_add_f32_e32 v16, 1.0, v24
	v_rcp_f32_e32 v24, v16
	v_add_f32_e32 v16, 1.0, v22
	v_rcp_f32_e32 v22, v16
	v_add_f32_e32 v16, 1.0, v23
	v_rcp_f32_e32 v23, v16
	v_mul_f32_e32 v8, v0, v8
	v_mul_f32_e32 v9, v1, v9
	v_mov_b32_e32 v16, v2
	v_mov_b32_e32 v0, v10
	v_mov_b32_e32 v1, v17
	v_pk_mul_f32 v[0:1], v[16:17], v[0:1]
	v_mul_f32_e32 v4, v4, v12
	v_mul_f32_e32 v0, v0, v1
	v_mul_f32_e32 v2, v4, v1
	v_mul_f32_e32 v4, v8, v1
	v_mul_f32_e32 v8, v9, v1
	v_mul_f32_e32 v9, v0, v22
	v_mul_f32_e32 v0, v7, v15
	v_mul_f32_e32 v0, v0, v1
	v_mul_f32_e32 v7, v0, v27
	v_mul_f32_e32 v0, v3, v11
	v_mul_f32_e32 v5, v5, v13
	v_mul_f32_e32 v6, v6, v14
	v_mul_f32_e32 v0, v0, v1
	v_mul_f32_e32 v2, v2, v26
	v_mul_f32_e32 v5, v5, v1
	v_mul_f32_e32 v6, v6, v1
	v_mul_f32_e32 v3, v0, v23
	s_and_b64 vcc, exec, s[38:39]
	s_mov_b64 s[14:15], -1
	v_mul_f32_e32 v4, v4, v20
	v_mul_f32_e32 v5, v5, v21
	v_mul_f32_e32 v8, v8, v24
	v_mul_f32_e32 v6, v6, v25
	v_cvt_pk_bf16_f32 v0, v2, v5
	v_cvt_pk_bf16_f32 v1, v6, v7
	v_cvt_pk_bf16_f32 v2, v4, v8
	v_cvt_pk_bf16_f32 v3, v9, v3
	global_store_dwordx4 v[18:19], v[0:3], off nt
	s_cbranch_vccnz .LBB0_1436
	s_and_b64 vcc, exec, s[12:13]
	s_cbranch_vccz .LBB0_1435
	v_lshl_or_b32 v0, s73, 8, v146
	v_ashrrev_i32_e32 v1, 31, v0
	v_lshlrev_b64 v[0:1], 7, v[0:1]
	v_lshl_add_u64 v[0:1], v[136:137], 0, v[0:1]
	s_and_b64 vcc, exec, s[42:43]
	s_cbranch_vccz .LBB0_1452
	v_mov_b32_e32 v2, 0
	s_and_saveexec_b64 s[14:15], s[36:37]
	s_cbranch_execz .LBB0_1451
	global_load_dword v2, v[0:1], off

; DEVI unsigned pk_bf16(float lo, float hi) { unsigned r; asm("v_cvt_pk_bf16_f32 %0, %1, %2" : "=v"(r) : "v"(lo), "v"(hi)); return r; }
;     DEVI void operator()(const f32x4 (&acc)[2][2][4][2], const Unit& u, int wr, int wc, int fr, int fq, const LAS float*) const {
;     ...
;         const int row0 = u.pm * BM + wr * 64 + fr, col0 = u.pn * BM + wc * 32 + 4 * fq;
;         f32x4 cur[2][2], nxt[2][2];
;         { const size_t ro = (size_t)row0 * ldc + col0;
; #pragma unroll
;           for (int bj = 0; bj < 2; ++bj)
; #pragma unroll
;               for (int n = 0; n < 2; ++n) cur[bj][n] = *(const f32x4*)(R + ro + bj * HALF + n * 16); }
; #pragma unroll
;         for (int idx = 0; idx < 8; ++idx) {
;             const int ai = idx >> 2, m = idx & 3;
;             const size_t ro = (size_t)(row0 + ai * HALF + m * 16) * ldc + col0;
;             if (idx + 1 < 8) { const int ai2 = (idx + 1) >> 2, m2 = (idx + 1) & 3; const size_t ro2 = (size_t)(row0 + ai2 * HALF + m2 * 16) * ldc + col0;
; #pragma unroll
;                 for (int bj = 0; bj < 2; ++bj)
; #pragma unroll
;                     for (int n = 0; n < 2; ++n) nxt[bj][n] = *(const f32x4*)(R + ro2 + bj * HALF + n * 16); }
;             float ss = 0.f;
; #pragma unroll
;             for (int bj = 0; bj < 2; ++bj)
; #pragma unroll
;                 for (int n = 0; n < 2; ++n) {
;                     const f32x4 hn = cur[bj][n] + acc[ai][bj][m][n] * scale;
;                     *(f32x4*)(C + ro + bj * HALF + n * 16) = hn;
;                     if (HB) { u32x2 w; w.x = pk_bf16(hn[0], hn[1]); w.y = pk_bf16(hn[2], hn[3]); *(u32x2*)(HB + ro + bj * HALF + n * 16) = w;
;                         ss += hn[0] * hn[0] + hn[1] * hn[1] + hn[2] * hn[2] + hn[3] * hn[3]; } }
;             if (HB) { ss += __shfl_xor(ss, 16); ss += __shfl_xor(ss, 32); if (fq == 0) RS[(size_t)(row0 + ai * HALF + m * 16) * 32 + u.pn * 4 + wc] = ss; }
.LBB0_1576:
	v_readlane_b32 s84, v239, 50
	v_readlane_b32 s85, v239, 51
	v_readlane_b32 s86, v239, 52
	v_readlane_b32 s87, v239, 53
	v_lshl_add_u32 v188, s35, 8, v198
	v_lshl_or_b32 v182, s31, 8, v200
	s_mov_b32 s70, s86
	v_readlane_b32 s84, v238, 11
	v_mad_i64_i32 v[128:129], s[14:15], v188, s70, 0
	v_ashrrev_i32_e32 v183, 31, v182
	v_readlane_b32 s90, v238, 17
	v_readlane_b32 s91, v238, 18
	v_lshlrev_b64 v[130:131], 2, v[182:183]
	v_or_b32_e32 v190, 16, v188
	v_lshl_add_u64 v[128:129], v[128:129], 2, s[90:91]
	v_mov_b32_e32 v180, v204
	v_lshl_add_u64 v[128:129], v[128:129], 0, v[130:131]
	v_lshl_add_u64 v[186:187], s[90:91], 0, v[130:131]
	v_mad_i64_i32 v[192:193], s[16:17], v190, s70, 0
	global_load_dwordx4 v[160:163], v[128:129], off
	global_load_dwordx4 v[152:155], v[128:129], off offset:64
	global_load_dwordx4 v[148:151], v[128:129], off offset:512
	global_load_dwordx4 v[144:147], v[128:129], off offset:576
	v_lshl_add_u64 v[128:129], v[192:193], 2, v[186:187]
	global_load_dwordx4 v[140:143], v[128:129], off
	global_load_dwordx4 v[136:139], v[128:129], off offset:64
	global_load_dwordx4 v[132:135], v[128:129], off offset:512
	s_nop 0
	global_load_dwordx4 v[128:131], v[128:129], off offset:576
	s_lshl_b32 s14, s31, 2
	s_ashr_i32 s15, s14, 31
	s_lshl_b64 s[14:15], s[14:15], 2
	v_readlane_b32 s88, v238, 15
	v_readlane_b32 s89, v238, 16
	v_mov_b32_e32 v184, v180
	v_mov_b32_e32 v185, v180
	s_add_u32 s14, s4, s14
	v_mad_i64_i32 v[158:159], s[16:17], v188, s70, v[182:183]
	v_ashrrev_i32_e32 v189, 31, v188
	s_addc_u32 s15, s5, s15
	v_lshl_add_u64 v[194:195], v[158:159], 2, s[88:89]
	s_andn2_b64 vcc, exec, s[66:67]
	v_readlane_b32 s85, v238, 12
	v_readlane_b32 s86, v238, 13
	v_readlane_b32 s87, v238, 14
	s_waitcnt vmcnt(0)
	v_pk_fma_f32 v[164:165], v[126:127], v[180:181], v[162:163] op_sel_hi:[1,0,1]
	v_pk_fma_f32 v[162:163], v[124:125], v[180:181], v[160:161] op_sel_hi:[1,0,1]
	v_cndmask_b32_e64 v124, 0, 1, s[66:67]
	v_cmp_ne_u32_e64 s[40:41], 1, v124
	v_pk_fma_f32 v[160:161], v[120:121], v[184:185], v[152:153]
	v_pk_fma_f32 v[156:157], v[116:117], v[184:185], v[148:149]
	v_pk_fma_f32 v[124:125], v[112:113], v[184:185], v[144:145]
	global_store_dwordx4 v[194:195], v[162:165], off nt
	s_cbranch_vccnz .LBB0_1615
	v_readlane_b32 s84, v238, 19
	v_readlane_b32 s86, v238, 21
	v_readlane_b32 s87, v238, 22
	v_cvt_pk_bf16_f32 v116, v162, v163
	v_mul_f32_e32 v120, v163, v163
	v_mov_b32_e32 v181, v180
	v_lshl_add_u64 v[112:113], v[158:159], 1, s[86:87]
	v_cvt_pk_bf16_f32 v117, v164, v165
	global_store_dwordx2 v[112:113], v[116:117], off
	v_fmac_f32_e32 v120, v162, v162
	v_pk_fma_f32 v[162:163], v[122:123], v[180:181], v[154:155]
	v_cvt_pk_bf16_f32 v116, v160, v161
	global_store_dwordx4 v[194:195], v[160:163], off offset:64 nt
	v_cvt_pk_bf16_f32 v117, v162, v163
	global_store_dwordx2 v[112:113], v[116:117], off offset:32
	v_mul_f32_e32 v116, v161, v161
	v_fmac_f32_e32 v116, v160, v160
	v_fmac_f32_e32 v120, v164, v164
	v_fmac_f32_e32 v116, v162, v162
	v_fmac_f32_e32 v120, v165, v165
	v_fmac_f32_e32 v116, v163, v163
	v_add_f32_e32 v120, v120, v116
	v_pk_fma_f32 v[158:159], v[118:119], v[180:181], v[150:151]
	v_cvt_pk_bf16_f32 v116, v156, v157
	global_store_dwordx4 v[194:195], v[156:159], off offset:512 nt
	v_cvt_pk_bf16_f32 v117, v158, v159
	global_store_dwordx2 v[112:113], v[116:117], off offset:256
	v_mul_f32_e32 v116, v157, v157
	v_fmac_f32_e32 v116, v156, v156
	v_fmac_f32_e32 v116, v158, v158
	v_fmac_f32_e32 v116, v159, v159
	v_add_f32_e32 v120, v116, v120
	v_pk_fma_f32 v[126:127], v[114:115], v[180:181], v[146:147]
	v_cvt_pk_bf16_f32 v116, v124, v125
	global_store_dwordx4 v[194:195], v[124:127], off offset:576 nt
	v_cvt_pk_bf16_f32 v117, v126, v127
	global_store_dwordx2 v[112:113], v[116:117], off offset:288
	v_mul_f32_e32 v112, v125, v125
	v_and_b32_e32 v116, 64, v197
	v_fmac_f32_e32 v112, v124, v124
	v_xor_b32_e32 v113, 16, v197
	v_add_u32_e32 v116, 64, v116
	v_fmac_f32_e32 v112, v126, v126
	v_cmp_lt_i32_e32 vcc, v113, v116
	v_fmac_f32_e32 v112, v127, v127
	v_add_f32_e32 v112, v112, v120
	v_cndmask_b32_e32 v113, v197, v113, vcc
	v_lshlrev_b32_e32 v113, 2, v113
	ds_bpermute_b32 v113, v113, v112
	v_readlane_b32 s85, v238, 20
	s_waitcnt lgkmcnt(0)
	v_add_f32_e32 v112, v112, v113
	v_xor_b32_e32 v113, 32, v197
	v_cmp_lt_i32_e32 vcc, v113, v116
	s_nop 1
	v_cndmask_b32_e32 v113, v197, v113, vcc
	v_lshlrev_b32_e32 v113, 2, v113
	ds_bpermute_b32 v113, v113, v112
	s_and_saveexec_b64 s[16:17], s[36:37]
	s_cbranch_execz .LBB0_1579
	s_waitcnt lgkmcnt(0)
	v_add_f32_e32 v116, v112, v113
	v_lshlrev_b64 v[112:113], 7, v[188:189]
	v_lshl_add_u64 v[112:113], s[14:15], 0, v[112:113]
	global_store_dword v[112:113], v116, off

; DEVI unsigned pk_bf16(float lo, float hi) { unsigned r; asm("v_cvt_pk_bf16_f32 %0, %1, %2" : "=v"(r) : "v"(lo), "v"(hi)); return r; }
;     DEVI void operator()(const f32x4 (&acc)[2][2][4][2], const Unit& u, int wr, int wc, int fr, int fq, const LAS float*) const {
;     ...
;         for (int idx = 0; idx < 8; ++idx) {
;             const int ai = idx >> 2, m = idx & 3;
;             const size_t ro = (size_t)(row0 + ai * HALF + m * 16) * ldc + col0;
;             if (idx + 1 < 8) { const int ai2 = (idx + 1) >> 2, m2 = (idx + 1) & 3; const size_t ro2 = (size_t)(row0 + ai2 * HALF + m2 * 16) * ldc + col0;
; #pragma unroll
;                 for (int bj = 0; bj < 2; ++bj)
; #pragma unroll
;                     for (int n = 0; n < 2; ++n) nxt[bj][n] = *(const f32x4*)(R + ro2 + bj * HALF + n * 16); }
;             float ss = 0.f;
; #pragma unroll
;             for (int bj = 0; bj < 2; ++bj)
; #pragma unroll
;                 for (int n = 0; n < 2; ++n) {
;                     const f32x4 hn = cur[bj][n] + acc[ai][bj][m][n] * scale;
;                     *(f32x4*)(C + ro + bj * HALF + n * 16) = hn;
;                     if (HB) { u32x2 w; w.x = pk_bf16(hn[0], hn[1]); w.y = pk_bf16(hn[2], hn[3]); *(u32x2*)(HB + ro + bj * HALF + n * 16) = w;
;                         ss += hn[0] * hn[0] + hn[1] * hn[1] + hn[2] * hn[2] + hn[3] * hn[3]; } }
;             if (HB) { ss += __shfl_xor(ss, 16); ss += __shfl_xor(ss, 32); if (fq == 0) RS[(size_t)(row0 + ai * HALF + m * 16) * 32 + u.pn * 4 + wc] = ss; }
.LBB0_1581:
	v_readlane_b32 s84, v239, 50
	v_or_b32_e32 v150, 32, v188
	v_readlane_b32 s86, v239, 52
	v_readlane_b32 s85, v239, 51
	v_readlane_b32 s87, v239, 53
	v_mad_i64_i32 v[152:153], s[16:17], v150, s86, 0
	s_waitcnt lgkmcnt(0)
	v_lshl_add_u64 v[112:113], v[152:153], 2, v[186:187]
	global_load_dwordx4 v[124:127], v[112:113], off
	global_load_dwordx4 v[120:123], v[112:113], off offset:64
	global_load_dwordx4 v[116:119], v[112:113], off offset:512
	s_nop 0
	global_load_dwordx4 v[112:115], v[112:113], off offset:576
	v_readlane_b32 s84, v238, 11
	v_lshl_add_u64 v[156:157], v[192:193], 0, v[182:183]
	v_readlane_b32 s88, v238, 15
	v_readlane_b32 s89, v238, 16
	v_mov_b32_e32 v181, v180
	v_pk_fma_f32 v[148:149], v[110:111], v[180:181], v[142:143]
	v_lshl_add_u64 v[154:155], v[156:157], 2, s[88:89]
	v_pk_fma_f32 v[146:147], v[108:109], v[184:185], v[140:141]
	s_and_b64 vcc, exec, s[40:41]
	v_pk_fma_f32 v[144:145], v[104:105], v[184:185], v[136:137]
	v_pk_fma_f32 v[140:141], v[100:101], v[184:185], v[132:133]
	v_pk_fma_f32 v[108:109], v[96:97], v[184:185], v[128:129]
	v_readlane_b32 s85, v238, 12
	v_readlane_b32 s86, v238, 13
	v_readlane_b32 s87, v238, 14
	v_readlane_b32 s90, v238, 17
	v_readlane_b32 s91, v238, 18
	global_store_dwordx4 v[154:155], v[146:149], off nt
	s_cbranch_vccnz .LBB0_1616
	v_readlane_b32 s84, v238, 19
	v_readlane_b32 s86, v238, 21
	v_readlane_b32 s87, v238, 22
	v_cvt_pk_bf16_f32 v100, v146, v147
	v_mul_f32_e32 v104, v147, v147
	v_cvt_pk_bf16_f32 v101, v148, v149
	v_fmac_f32_e32 v104, v146, v146
	v_lshl_add_u64 v[96:97], v[156:157], 1, s[86:87]
	global_store_dwordx2 v[96:97], v[100:101], off
	v_pk_fma_f32 v[146:147], v[106:107], v[180:181], v[138:139]
	v_cvt_pk_bf16_f32 v100, v144, v145
	global_store_dwordx4 v[154:155], v[144:147], off offset:64 nt
	v_cvt_pk_bf16_f32 v101, v146, v147
	global_store_dwordx2 v[96:97], v[100:101], off offset:32
	v_mul_f32_e32 v100, v145, v145
	v_fmac_f32_e32 v100, v144, v144
	v_fmac_f32_e32 v104, v148, v148
	v_fmac_f32_e32 v100, v146, v146
	v_fmac_f32_e32 v104, v149, v149
	v_fmac_f32_e32 v100, v147, v147
	v_add_f32_e32 v104, v104, v100
	v_pk_fma_f32 v[142:143], v[102:103], v[180:181], v[134:135]
	v_cvt_pk_bf16_f32 v100, v140, v141
	global_store_dwordx4 v[154:155], v[140:143], off offset:512 nt
	v_cvt_pk_bf16_f32 v101, v142, v143
	global_store_dwordx2 v[96:97], v[100:101], off offset:256
	v_mul_f32_e32 v100, v141, v141
	v_fmac_f32_e32 v100, v140, v140
	v_fmac_f32_e32 v100, v142, v142
	v_fmac_f32_e32 v100, v143, v143
	v_add_f32_e32 v104, v104, v100
	v_pk_fma_f32 v[110:111], v[98:99], v[180:181], v[130:131]
	v_cvt_pk_bf16_f32 v100, v108, v109
	global_store_dwordx4 v[154:155], v[108:111], off offset:576 nt
	v_cvt_pk_bf16_f32 v101, v110, v111
	global_store_dwordx2 v[96:97], v[100:101], off offset:288
	v_mul_f32_e32 v96, v109, v109
	v_and_b32_e32 v100, 64, v197
	v_fmac_f32_e32 v96, v108, v108
	v_xor_b32_e32 v97, 16, v197
	v_add_u32_e32 v100, 64, v100
	v_fmac_f32_e32 v96, v110, v110
	v_cmp_lt_i32_e32 vcc, v97, v100
	v_fmac_f32_e32 v96, v111, v111
	v_add_f32_e32 v96, v104, v96
	v_cndmask_b32_e32 v97, v197, v97, vcc
	v_lshlrev_b32_e32 v97, 2, v97
	ds_bpermute_b32 v97, v97, v96
	v_readlane_b32 s85, v238, 20
	s_waitcnt lgkmcnt(0)
	v_add_f32_e32 v96, v96, v97
	v_xor_b32_e32 v97, 32, v197
	v_cmp_lt_i32_e32 vcc, v97, v100
	s_nop 1
	v_cndmask_b32_e32 v97, v197, v97, vcc
	v_lshlrev_b32_e32 v97, 2, v97
	ds_bpermute_b32 v97, v97, v96
	s_and_saveexec_b64 s[16:17], s[36:37]
	s_cbranch_execz .LBB0_1584
	v_ashrrev_i32_e32 v191, 31, v190
	s_waitcnt lgkmcnt(0)
	v_add_f32_e32 v100, v96, v97
	v_lshlrev_b64 v[96:97], 7, v[190:191]
	v_lshl_add_u64 v[96:97], s[14:15], 0, v[96:97]
	global_store_dword v[96:97], v100, off

; DEVI unsigned pk_bf16(float lo, float hi) { unsigned r; asm("v_cvt_pk_bf16_f32 %0, %1, %2" : "=v"(r) : "v"(lo), "v"(hi)); return r; }
;     DEVI void operator()(const f32x4 (&acc)[2][2][4][2], const Unit& u, int wr, int wc, int fr, int fq, const LAS float*) const {
;     ...
;         for (int idx = 0; idx < 8; ++idx) {
;             const int ai = idx >> 2, m = idx & 3;
;             const size_t ro = (size_t)(row0 + ai * HALF + m * 16) * ldc + col0;
;             if (idx + 1 < 8) { const int ai2 = (idx + 1) >> 2, m2 = (idx + 1) & 3; const size_t ro2 = (size_t)(row0 + ai2 * HALF + m2 * 16) * ldc + col0;
; #pragma unroll
;                 for (int bj = 0; bj < 2; ++bj)
; #pragma unroll
;                     for (int n = 0; n < 2; ++n) nxt[bj][n] = *(const f32x4*)(R + ro2 + bj * HALF + n * 16); }
;             float ss = 0.f;
; #pragma unroll
;             for (int bj = 0; bj < 2; ++bj)
; #pragma unroll
;                 for (int n = 0; n < 2; ++n) {
;                     const f32x4 hn = cur[bj][n] + acc[ai][bj][m][n] * scale;
;                     *(f32x4*)(C + ro + bj * HALF + n * 16) = hn;
;                     if (HB) { u32x2 w; w.x = pk_bf16(hn[0], hn[1]); w.y = pk_bf16(hn[2], hn[3]); *(u32x2*)(HB + ro + bj * HALF + n * 16) = w;
;                         ss += hn[0] * hn[0] + hn[1] * hn[1] + hn[2] * hn[2] + hn[3] * hn[3]; } }
;             if (HB) { ss += __shfl_xor(ss, 16); ss += __shfl_xor(ss, 32); if (fq == 0) RS[(size_t)(row0 + ai * HALF + m * 16) * 32 + u.pn * 4 + wc] = ss; }
.LBB0_1586:
	v_readlane_b32 s84, v239, 50
	v_or_b32_e32 v134, 48, v188
	v_readlane_b32 s86, v239, 52
	v_readlane_b32 s85, v239, 51
	v_readlane_b32 s87, v239, 53
	v_mad_i64_i32 v[136:137], s[16:17], v134, s86, 0
	s_waitcnt lgkmcnt(0)
	v_lshl_add_u64 v[96:97], v[136:137], 2, v[186:187]
	global_load_dwordx4 v[108:111], v[96:97], off
	global_load_dwordx4 v[104:107], v[96:97], off offset:64
	global_load_dwordx4 v[100:103], v[96:97], off offset:512
	s_nop 0
	global_load_dwordx4 v[96:99], v[96:97], off offset:576
	v_readlane_b32 s84, v238, 11
	v_lshl_add_u64 v[140:141], v[152:153], 0, v[182:183]
	v_readlane_b32 s88, v238, 15
	v_readlane_b32 s89, v238, 16
	v_mov_b32_e32 v181, v180
	s_waitcnt vmcnt(8)
	v_pk_fma_f32 v[132:133], v[94:95], v[180:181], v[126:127]
	v_lshl_add_u64 v[138:139], v[140:141], 2, s[88:89]
	v_pk_fma_f32 v[130:131], v[92:93], v[184:185], v[124:125]
	s_and_b64 vcc, exec, s[40:41]
	s_waitcnt vmcnt(7)
	v_pk_fma_f32 v[128:129], v[88:89], v[184:185], v[120:121]
	s_waitcnt vmcnt(6)
	v_pk_fma_f32 v[124:125], v[84:85], v[184:185], v[116:117]
	s_waitcnt vmcnt(5)
	v_pk_fma_f32 v[92:93], v[80:81], v[184:185], v[112:113]
	v_readlane_b32 s85, v238, 12
	v_readlane_b32 s86, v238, 13
	v_readlane_b32 s87, v238, 14
	v_readlane_b32 s90, v238, 17
	v_readlane_b32 s91, v238, 18
	global_store_dwordx4 v[138:139], v[130:133], off nt
	s_cbranch_vccnz .LBB0_1617
	v_readlane_b32 s84, v238, 19
	v_readlane_b32 s86, v238, 21
	v_readlane_b32 s87, v238, 22
	v_cvt_pk_bf16_f32 v84, v130, v131
	v_mul_f32_e32 v88, v131, v131
	v_cvt_pk_bf16_f32 v85, v132, v133
	v_fmac_f32_e32 v88, v130, v130
	v_lshl_add_u64 v[80:81], v[140:141], 1, s[86:87]
	global_store_dwordx2 v[80:81], v[84:85], off
	v_pk_fma_f32 v[130:131], v[90:91], v[180:181], v[122:123]
	v_cvt_pk_bf16_f32 v84, v128, v129
	global_store_dwordx4 v[138:139], v[128:131], off offset:64 nt
	v_cvt_pk_bf16_f32 v85, v130, v131
	global_store_dwordx2 v[80:81], v[84:85], off offset:32
	v_mul_f32_e32 v84, v129, v129
	v_fmac_f32_e32 v84, v128, v128
	v_fmac_f32_e32 v88, v132, v132
	v_fmac_f32_e32 v84, v130, v130
	v_fmac_f32_e32 v88, v133, v133
	v_fmac_f32_e32 v84, v131, v131
	v_add_f32_e32 v88, v88, v84
	v_pk_fma_f32 v[126:127], v[86:87], v[180:181], v[118:119]
	v_cvt_pk_bf16_f32 v84, v124, v125
	global_store_dwordx4 v[138:139], v[124:127], off offset:512 nt
	v_cvt_pk_bf16_f32 v85, v126, v127
	global_store_dwordx2 v[80:81], v[84:85], off offset:256
	v_mul_f32_e32 v84, v125, v125
	v_fmac_f32_e32 v84, v124, v124
	v_fmac_f32_e32 v84, v126, v126
	v_fmac_f32_e32 v84, v127, v127
	v_add_f32_e32 v88, v88, v84
	v_pk_fma_f32 v[94:95], v[82:83], v[180:181], v[114:115]
	v_cvt_pk_bf16_f32 v84, v92, v93
	global_store_dwordx4 v[138:139], v[92:95], off offset:576 nt
	v_cvt_pk_bf16_f32 v85, v94, v95
	global_store_dwordx2 v[80:81], v[84:85], off offset:288
	v_mul_f32_e32 v80, v93, v93
	v_and_b32_e32 v84, 64, v197
	v_fmac_f32_e32 v80, v92, v92
	v_xor_b32_e32 v81, 16, v197
	v_add_u32_e32 v84, 64, v84
	v_fmac_f32_e32 v80, v94, v94
	v_cmp_lt_i32_e32 vcc, v81, v84
	v_fmac_f32_e32 v80, v95, v95
	v_add_f32_e32 v80, v88, v80
	v_cndmask_b32_e32 v81, v197, v81, vcc
	v_lshlrev_b32_e32 v81, 2, v81
	ds_bpermute_b32 v81, v81, v80
	v_readlane_b32 s85, v238, 20
	s_waitcnt lgkmcnt(0)
	v_add_f32_e32 v80, v80, v81
	v_xor_b32_e32 v81, 32, v197
	v_cmp_lt_i32_e32 vcc, v81, v84
	s_nop 1
	v_cndmask_b32_e32 v81, v197, v81, vcc
	v_lshlrev_b32_e32 v81, 2, v81
	ds_bpermute_b32 v81, v81, v80
	s_and_saveexec_b64 s[16:17], s[36:37]
	s_cbranch_execz .LBB0_1589
	v_ashrrev_i32_e32 v151, 31, v150
	s_waitcnt lgkmcnt(0)
	v_add_f32_e32 v84, v80, v81
	v_lshlrev_b64 v[80:81], 7, v[150:151]
	v_lshl_add_u64 v[80:81], s[14:15], 0, v[80:81]
	global_store_dword v[80:81], v84, off

; DEVI unsigned pk_bf16(float lo, float hi) { unsigned r; asm("v_cvt_pk_bf16_f32 %0, %1, %2" : "=v"(r) : "v"(lo), "v"(hi)); return r; }
;     DEVI void operator()(const f32x4 (&acc)[2][2][4][2], const Unit& u, int wr, int wc, int fr, int fq, const LAS float*) const {
;     ...
;         for (int idx = 0; idx < 8; ++idx) {
;             const int ai = idx >> 2, m = idx & 3;
;             const size_t ro = (size_t)(row0 + ai * HALF + m * 16) * ldc + col0;
;             if (idx + 1 < 8) { const int ai2 = (idx + 1) >> 2, m2 = (idx + 1) & 3; const size_t ro2 = (size_t)(row0 + ai2 * HALF + m2 * 16) * ldc + col0;
; #pragma unroll
;                 for (int bj = 0; bj < 2; ++bj)
; #pragma unroll
;                     for (int n = 0; n < 2; ++n) nxt[bj][n] = *(const f32x4*)(R + ro2 + bj * HALF + n * 16); }
;             float ss = 0.f;
; #pragma unroll
;             for (int bj = 0; bj < 2; ++bj)
; #pragma unroll
;                 for (int n = 0; n < 2; ++n) {
;                     const f32x4 hn = cur[bj][n] + acc[ai][bj][m][n] * scale;
;                     *(f32x4*)(C + ro + bj * HALF + n * 16) = hn;
;                     if (HB) { u32x2 w; w.x = pk_bf16(hn[0], hn[1]); w.y = pk_bf16(hn[2], hn[3]); *(u32x2*)(HB + ro + bj * HALF + n * 16) = w;
;                         ss += hn[0] * hn[0] + hn[1] * hn[1] + hn[2] * hn[2] + hn[3] * hn[3]; } }
;             if (HB) { ss += __shfl_xor(ss, 16); ss += __shfl_xor(ss, 32); if (fq == 0) RS[(size_t)(row0 + ai * HALF + m * 16) * 32 + u.pn * 4 + wc] = ss; }
.LBB0_1591:
	v_readlane_b32 s84, v239, 50
	v_add_u32_e32 v118, 0x80, v188
	v_readlane_b32 s86, v239, 52
	v_readlane_b32 s85, v239, 51
	v_readlane_b32 s87, v239, 53
	v_mad_i64_i32 v[120:121], s[16:17], v118, s86, 0
	s_waitcnt lgkmcnt(0)
	v_lshl_add_u64 v[80:81], v[120:121], 2, v[186:187]
	global_load_dwordx4 v[92:95], v[80:81], off
	global_load_dwordx4 v[88:91], v[80:81], off offset:64
	global_load_dwordx4 v[84:87], v[80:81], off offset:512
	s_nop 0
	global_load_dwordx4 v[80:83], v[80:81], off offset:576
	v_readlane_b32 s84, v238, 11
	v_lshl_add_u64 v[124:125], v[136:137], 0, v[182:183]
	v_readlane_b32 s88, v238, 15
	v_readlane_b32 s89, v238, 16
	v_mov_b32_e32 v181, v180
	s_waitcnt vmcnt(8)
	v_pk_fma_f32 v[116:117], v[78:79], v[180:181], v[110:111]
	v_lshl_add_u64 v[122:123], v[124:125], 2, s[88:89]
	v_pk_fma_f32 v[114:115], v[76:77], v[184:185], v[108:109]
	s_and_b64 vcc, exec, s[40:41]
	s_waitcnt vmcnt(7)
	v_pk_fma_f32 v[112:113], v[72:73], v[184:185], v[104:105]
	s_waitcnt vmcnt(6)
	v_pk_fma_f32 v[108:109], v[68:69], v[184:185], v[100:101]
	s_waitcnt vmcnt(5)
	v_pk_fma_f32 v[76:77], v[64:65], v[184:185], v[96:97]
	v_readlane_b32 s85, v238, 12
	v_readlane_b32 s86, v238, 13
	v_readlane_b32 s87, v238, 14
	v_readlane_b32 s90, v238, 17
	v_readlane_b32 s91, v238, 18
	global_store_dwordx4 v[122:123], v[114:117], off nt
	s_cbranch_vccnz .LBB0_1618
	v_readlane_b32 s84, v238, 19
	v_readlane_b32 s86, v238, 21
	v_readlane_b32 s87, v238, 22
	v_cvt_pk_bf16_f32 v68, v114, v115
	v_mul_f32_e32 v72, v115, v115
	v_cvt_pk_bf16_f32 v69, v116, v117
	v_fmac_f32_e32 v72, v114, v114
	v_lshl_add_u64 v[64:65], v[124:125], 1, s[86:87]
	global_store_dwordx2 v[64:65], v[68:69], off
	v_pk_fma_f32 v[114:115], v[74:75], v[180:181], v[106:107]
	v_cvt_pk_bf16_f32 v68, v112, v113
	global_store_dwordx4 v[122:123], v[112:115], off offset:64 nt
	v_cvt_pk_bf16_f32 v69, v114, v115
	global_store_dwordx2 v[64:65], v[68:69], off offset:32
	v_mul_f32_e32 v68, v113, v113
	v_fmac_f32_e32 v68, v112, v112
	v_fmac_f32_e32 v72, v116, v116
	v_fmac_f32_e32 v68, v114, v114
	v_fmac_f32_e32 v72, v117, v117
	v_fmac_f32_e32 v68, v115, v115
	v_add_f32_e32 v72, v72, v68
	v_pk_fma_f32 v[110:111], v[70:71], v[180:181], v[102:103]
	v_cvt_pk_bf16_f32 v68, v108, v109
	global_store_dwordx4 v[122:123], v[108:111], off offset:512 nt
	v_cvt_pk_bf16_f32 v69, v110, v111
	global_store_dwordx2 v[64:65], v[68:69], off offset:256
	v_mul_f32_e32 v68, v109, v109
	v_fmac_f32_e32 v68, v108, v108
	v_fmac_f32_e32 v68, v110, v110
	v_fmac_f32_e32 v68, v111, v111
	v_add_f32_e32 v72, v72, v68
	v_pk_fma_f32 v[78:79], v[66:67], v[180:181], v[98:99]
	v_cvt_pk_bf16_f32 v68, v76, v77
	global_store_dwordx4 v[122:123], v[76:79], off offset:576 nt
	v_cvt_pk_bf16_f32 v69, v78, v79
	global_store_dwordx2 v[64:65], v[68:69], off offset:288
	v_mul_f32_e32 v64, v77, v77
	v_and_b32_e32 v68, 64, v197
	v_fmac_f32_e32 v64, v76, v76
	v_xor_b32_e32 v65, 16, v197
	v_add_u32_e32 v68, 64, v68
	v_fmac_f32_e32 v64, v78, v78
	v_cmp_lt_i32_e32 vcc, v65, v68
	v_fmac_f32_e32 v64, v79, v79
	v_add_f32_e32 v64, v72, v64
	v_cndmask_b32_e32 v65, v197, v65, vcc
	v_lshlrev_b32_e32 v65, 2, v65
	ds_bpermute_b32 v65, v65, v64
	v_readlane_b32 s85, v238, 20
	s_waitcnt lgkmcnt(0)
	v_add_f32_e32 v64, v64, v65
	v_xor_b32_e32 v65, 32, v197
	v_cmp_lt_i32_e32 vcc, v65, v68
	s_nop 1
	v_cndmask_b32_e32 v65, v197, v65, vcc
	v_lshlrev_b32_e32 v65, 2, v65
	ds_bpermute_b32 v65, v65, v64
	s_and_saveexec_b64 s[16:17], s[36:37]
	s_cbranch_execz .LBB0_1594
	v_ashrrev_i32_e32 v135, 31, v134
	s_waitcnt lgkmcnt(0)
	v_add_f32_e32 v68, v64, v65
	v_lshlrev_b64 v[64:65], 7, v[134:135]
	v_lshl_add_u64 v[64:65], s[14:15], 0, v[64:65]
	global_store_dword v[64:65], v68, off

; DEVI unsigned pk_bf16(float lo, float hi) { unsigned r; asm("v_cvt_pk_bf16_f32 %0, %1, %2" : "=v"(r) : "v"(lo), "v"(hi)); return r; }
;     DEVI void operator()(const f32x4 (&acc)[2][2][4][2], const Unit& u, int wr, int wc, int fr, int fq, const LAS float*) const {
;     ...
;         for (int idx = 0; idx < 8; ++idx) {
;             const int ai = idx >> 2, m = idx & 3;
;             const size_t ro = (size_t)(row0 + ai * HALF + m * 16) * ldc + col0;
;             if (idx + 1 < 8) { const int ai2 = (idx + 1) >> 2, m2 = (idx + 1) & 3; const size_t ro2 = (size_t)(row0 + ai2 * HALF + m2 * 16) * ldc + col0;
; #pragma unroll
;                 for (int bj = 0; bj < 2; ++bj)
; #pragma unroll
;                     for (int n = 0; n < 2; ++n) nxt[bj][n] = *(const f32x4*)(R + ro2 + bj * HALF + n * 16); }
;             float ss = 0.f;
; #pragma unroll
;             for (int bj = 0; bj < 2; ++bj)
; #pragma unroll
;                 for (int n = 0; n < 2; ++n) {
;                     const f32x4 hn = cur[bj][n] + acc[ai][bj][m][n] * scale;
;                     *(f32x4*)(C + ro + bj * HALF + n * 16) = hn;
;                     if (HB) { u32x2 w; w.x = pk_bf16(hn[0], hn[1]); w.y = pk_bf16(hn[2], hn[3]); *(u32x2*)(HB + ro + bj * HALF + n * 16) = w;
;                         ss += hn[0] * hn[0] + hn[1] * hn[1] + hn[2] * hn[2] + hn[3] * hn[3]; } }
;             if (HB) { ss += __shfl_xor(ss, 16); ss += __shfl_xor(ss, 32); if (fq == 0) RS[(size_t)(row0 + ai * HALF + m * 16) * 32 + u.pn * 4 + wc] = ss; }
.LBB0_1596:
	v_readlane_b32 s84, v239, 50
	v_or_b32_e32 v102, 16, v118
	v_readlane_b32 s86, v239, 52
	v_readlane_b32 s85, v239, 51
	v_readlane_b32 s87, v239, 53
	v_mad_i64_i32 v[104:105], s[16:17], v102, s86, 0
	s_waitcnt lgkmcnt(0)
	v_lshl_add_u64 v[64:65], v[104:105], 2, v[186:187]
	global_load_dwordx4 v[76:79], v[64:65], off
	global_load_dwordx4 v[72:75], v[64:65], off offset:64
	global_load_dwordx4 v[68:71], v[64:65], off offset:512
	s_nop 0
	global_load_dwordx4 v[64:67], v[64:65], off offset:576
	v_readlane_b32 s84, v238, 11
	v_lshl_add_u64 v[108:109], v[120:121], 0, v[182:183]
	v_readlane_b32 s88, v238, 15
	v_readlane_b32 s89, v238, 16
	v_mov_b32_e32 v181, v180
	v_ashrrev_i32_e32 v119, 31, v118
	v_lshl_add_u64 v[106:107], v[108:109], 2, s[88:89]
	s_waitcnt vmcnt(8)
	v_pk_fma_f32 v[100:101], v[62:63], v[180:181], v[94:95]
	v_pk_fma_f32 v[98:99], v[60:61], v[184:185], v[92:93]
	s_and_b64 vcc, exec, s[40:41]
	s_waitcnt vmcnt(7)
	v_pk_fma_f32 v[96:97], v[56:57], v[184:185], v[88:89]
	s_waitcnt vmcnt(6)
	v_pk_fma_f32 v[92:93], v[52:53], v[184:185], v[84:85]
	s_waitcnt vmcnt(5)
	v_pk_fma_f32 v[60:61], v[48:49], v[184:185], v[80:81]
	v_readlane_b32 s85, v238, 12
	v_readlane_b32 s86, v238, 13
	v_readlane_b32 s87, v238, 14
	v_readlane_b32 s90, v238, 17
	v_readlane_b32 s91, v238, 18
	global_store_dwordx4 v[106:107], v[98:101], off nt
	s_cbranch_vccnz .LBB0_1619
	v_readlane_b32 s84, v238, 19
	v_readlane_b32 s86, v238, 21
	v_readlane_b32 s87, v238, 22
	v_cvt_pk_bf16_f32 v52, v98, v99
	v_mul_f32_e32 v56, v99, v99
	v_cvt_pk_bf16_f32 v53, v100, v101
	v_fmac_f32_e32 v56, v98, v98
	v_lshl_add_u64 v[48:49], v[108:109], 1, s[86:87]
	global_store_dwordx2 v[48:49], v[52:53], off
	v_pk_fma_f32 v[98:99], v[58:59], v[180:181], v[90:91]
	v_cvt_pk_bf16_f32 v52, v96, v97
	global_store_dwordx4 v[106:107], v[96:99], off offset:64 nt
	v_cvt_pk_bf16_f32 v53, v98, v99
	global_store_dwordx2 v[48:49], v[52:53], off offset:32
	v_mul_f32_e32 v52, v97, v97
	v_fmac_f32_e32 v52, v96, v96
	v_fmac_f32_e32 v56, v100, v100
	v_fmac_f32_e32 v52, v98, v98
	v_fmac_f32_e32 v56, v101, v101
	v_fmac_f32_e32 v52, v99, v99
	v_add_f32_e32 v56, v56, v52
	v_pk_fma_f32 v[94:95], v[54:55], v[180:181], v[86:87]
	v_cvt_pk_bf16_f32 v52, v92, v93
	global_store_dwordx4 v[106:107], v[92:95], off offset:512 nt
	v_cvt_pk_bf16_f32 v53, v94, v95
	global_store_dwordx2 v[48:49], v[52:53], off offset:256
	v_mul_f32_e32 v52, v93, v93
	v_fmac_f32_e32 v52, v92, v92
	v_fmac_f32_e32 v52, v94, v94
	v_fmac_f32_e32 v52, v95, v95
	v_add_f32_e32 v56, v56, v52
	v_pk_fma_f32 v[62:63], v[50:51], v[180:181], v[82:83]
	v_cvt_pk_bf16_f32 v52, v60, v61
	global_store_dwordx4 v[106:107], v[60:63], off offset:576 nt
	v_cvt_pk_bf16_f32 v53, v62, v63
	global_store_dwordx2 v[48:49], v[52:53], off offset:288
	v_mul_f32_e32 v48, v61, v61
	v_and_b32_e32 v52, 64, v197
	v_fmac_f32_e32 v48, v60, v60
	v_xor_b32_e32 v49, 16, v197
	v_add_u32_e32 v52, 64, v52
	v_fmac_f32_e32 v48, v62, v62
	v_cmp_lt_i32_e32 vcc, v49, v52
	v_fmac_f32_e32 v48, v63, v63
	v_add_f32_e32 v48, v56, v48
	v_cndmask_b32_e32 v49, v197, v49, vcc
	v_lshlrev_b32_e32 v49, 2, v49
	ds_bpermute_b32 v49, v49, v48
	v_readlane_b32 s85, v238, 20
	s_waitcnt lgkmcnt(0)
	v_add_f32_e32 v48, v48, v49
	v_xor_b32_e32 v49, 32, v197
	v_cmp_lt_i32_e32 vcc, v49, v52
	s_nop 1
	v_cndmask_b32_e32 v49, v197, v49, vcc
	v_lshlrev_b32_e32 v49, 2, v49
	ds_bpermute_b32 v49, v49, v48
	s_and_saveexec_b64 s[16:17], s[36:37]
	s_cbranch_execz .LBB0_1599
	s_waitcnt lgkmcnt(0)
	v_add_f32_e32 v52, v48, v49
	v_lshlrev_b64 v[48:49], 7, v[118:119]
	v_lshl_add_u64 v[48:49], s[14:15], 0, v[48:49]
	global_store_dword v[48:49], v52, off

; DEVI unsigned pk_bf16(float lo, float hi) { unsigned r; asm("v_cvt_pk_bf16_f32 %0, %1, %2" : "=v"(r) : "v"(lo), "v"(hi)); return r; }
;     DEVI void operator()(const f32x4 (&acc)[2][2][4][2], const Unit& u, int wr, int wc, int fr, int fq, const LAS float*) const {
;     ...
;         for (int idx = 0; idx < 8; ++idx) {
;             const int ai = idx >> 2, m = idx & 3;
;             const size_t ro = (size_t)(row0 + ai * HALF + m * 16) * ldc + col0;
;             if (idx + 1 < 8) { const int ai2 = (idx + 1) >> 2, m2 = (idx + 1) & 3; const size_t ro2 = (size_t)(row0 + ai2 * HALF + m2 * 16) * ldc + col0;
; #pragma unroll
;                 for (int bj = 0; bj < 2; ++bj)
; #pragma unroll
;                     for (int n = 0; n < 2; ++n) nxt[bj][n] = *(const f32x4*)(R + ro2 + bj * HALF + n * 16); }
;             float ss = 0.f;
; #pragma unroll
;             for (int bj = 0; bj < 2; ++bj)
; #pragma unroll
;                 for (int n = 0; n < 2; ++n) {
;                     const f32x4 hn = cur[bj][n] + acc[ai][bj][m][n] * scale;
;                     *(f32x4*)(C + ro + bj * HALF + n * 16) = hn;
;                     if (HB) { u32x2 w; w.x = pk_bf16(hn[0], hn[1]); w.y = pk_bf16(hn[2], hn[3]); *(u32x2*)(HB + ro + bj * HALF + n * 16) = w;
;                         ss += hn[0] * hn[0] + hn[1] * hn[1] + hn[2] * hn[2] + hn[3] * hn[3]; } }
;             if (HB) { ss += __shfl_xor(ss, 16); ss += __shfl_xor(ss, 32); if (fq == 0) RS[(size_t)(row0 + ai * HALF + m * 16) * 32 + u.pn * 4 + wc] = ss; }
.LBB0_1601:
	v_readlane_b32 s84, v239, 50
	v_or_b32_e32 v86, 32, v118
	v_readlane_b32 s86, v239, 52
	v_readlane_b32 s85, v239, 51
	v_readlane_b32 s87, v239, 53
	v_mad_i64_i32 v[88:89], s[16:17], v86, s86, 0
	s_waitcnt lgkmcnt(0)
	v_lshl_add_u64 v[48:49], v[88:89], 2, v[186:187]
	global_load_dwordx4 v[60:63], v[48:49], off
	global_load_dwordx4 v[56:59], v[48:49], off offset:64
	global_load_dwordx4 v[52:55], v[48:49], off offset:512
	s_nop 0
	global_load_dwordx4 v[48:51], v[48:49], off offset:576
	v_readlane_b32 s84, v238, 11
	v_lshl_add_u64 v[92:93], v[104:105], 0, v[182:183]
	v_readlane_b32 s88, v238, 15
	v_readlane_b32 s89, v238, 16
	v_mov_b32_e32 v181, v180
	s_waitcnt vmcnt(8)
	v_pk_fma_f32 v[84:85], v[46:47], v[180:181], v[78:79]
	v_lshl_add_u64 v[90:91], v[92:93], 2, s[88:89]
	v_pk_fma_f32 v[82:83], v[44:45], v[184:185], v[76:77]
	s_and_b64 vcc, exec, s[40:41]
	s_waitcnt vmcnt(7)
	v_pk_fma_f32 v[80:81], v[40:41], v[184:185], v[72:73]
	s_waitcnt vmcnt(6)
	v_pk_fma_f32 v[76:77], v[36:37], v[184:185], v[68:69]
	s_waitcnt vmcnt(5)
	v_pk_fma_f32 v[44:45], v[32:33], v[184:185], v[64:65]
	v_readlane_b32 s85, v238, 12
	v_readlane_b32 s86, v238, 13
	v_readlane_b32 s87, v238, 14
	v_readlane_b32 s90, v238, 17
	v_readlane_b32 s91, v238, 18
	global_store_dwordx4 v[90:91], v[82:85], off nt
	s_cbranch_vccnz .LBB0_1620
	v_readlane_b32 s84, v238, 19
	v_readlane_b32 s86, v238, 21
	v_readlane_b32 s87, v238, 22
	v_cvt_pk_bf16_f32 v36, v82, v83
	v_mul_f32_e32 v40, v83, v83
	v_cvt_pk_bf16_f32 v37, v84, v85
	v_fmac_f32_e32 v40, v82, v82
	v_lshl_add_u64 v[32:33], v[92:93], 1, s[86:87]
	global_store_dwordx2 v[32:33], v[36:37], off
	v_pk_fma_f32 v[82:83], v[42:43], v[180:181], v[74:75]
	v_cvt_pk_bf16_f32 v36, v80, v81
	global_store_dwordx4 v[90:91], v[80:83], off offset:64 nt
	v_cvt_pk_bf16_f32 v37, v82, v83
	global_store_dwordx2 v[32:33], v[36:37], off offset:32
	v_mul_f32_e32 v36, v81, v81
	v_fmac_f32_e32 v36, v80, v80
	v_fmac_f32_e32 v40, v84, v84
	v_fmac_f32_e32 v36, v82, v82
	v_fmac_f32_e32 v40, v85, v85
	v_fmac_f32_e32 v36, v83, v83
	v_add_f32_e32 v40, v40, v36
	v_pk_fma_f32 v[78:79], v[38:39], v[180:181], v[70:71]
	v_cvt_pk_bf16_f32 v36, v76, v77
	global_store_dwordx4 v[90:91], v[76:79], off offset:512 nt
	v_cvt_pk_bf16_f32 v37, v78, v79
	global_store_dwordx2 v[32:33], v[36:37], off offset:256
	v_mul_f32_e32 v36, v77, v77
	v_fmac_f32_e32 v36, v76, v76
	v_fmac_f32_e32 v36, v78, v78
	v_fmac_f32_e32 v36, v79, v79
	v_add_f32_e32 v40, v40, v36
	v_pk_fma_f32 v[46:47], v[34:35], v[180:181], v[66:67]
	v_cvt_pk_bf16_f32 v36, v44, v45
	global_store_dwordx4 v[90:91], v[44:47], off offset:576 nt
	v_cvt_pk_bf16_f32 v37, v46, v47
	global_store_dwordx2 v[32:33], v[36:37], off offset:288
	v_mul_f32_e32 v32, v45, v45
	v_and_b32_e32 v36, 64, v197
	v_fmac_f32_e32 v32, v44, v44
	v_xor_b32_e32 v33, 16, v197
	v_add_u32_e32 v36, 64, v36
	v_fmac_f32_e32 v32, v46, v46
	v_cmp_lt_i32_e32 vcc, v33, v36
	v_fmac_f32_e32 v32, v47, v47
	v_add_f32_e32 v32, v40, v32
	v_cndmask_b32_e32 v33, v197, v33, vcc
	v_lshlrev_b32_e32 v33, 2, v33
	ds_bpermute_b32 v33, v33, v32
	v_readlane_b32 s85, v238, 20
	s_waitcnt lgkmcnt(0)
	v_add_f32_e32 v32, v32, v33
	v_xor_b32_e32 v33, 32, v197
	v_cmp_lt_i32_e32 vcc, v33, v36
	s_nop 1
	v_cndmask_b32_e32 v33, v197, v33, vcc
	v_lshlrev_b32_e32 v33, 2, v33
	ds_bpermute_b32 v33, v33, v32
	s_and_saveexec_b64 s[16:17], s[36:37]
	s_cbranch_execz .LBB0_1604
	v_ashrrev_i32_e32 v103, 31, v102
	s_waitcnt lgkmcnt(0)
	v_add_f32_e32 v36, v32, v33
	v_lshlrev_b64 v[32:33], 7, v[102:103]
	v_lshl_add_u64 v[32:33], s[14:15], 0, v[32:33]
	global_store_dword v[32:33], v36, off

; DEVI unsigned pk_bf16(float lo, float hi) { unsigned r; asm("v_cvt_pk_bf16_f32 %0, %1, %2" : "=v"(r) : "v"(lo), "v"(hi)); return r; }
;     DEVI void operator()(const f32x4 (&acc)[2][2][4][2], const Unit& u, int wr, int wc, int fr, int fq, const LAS float*) const {
;     ...
;         for (int idx = 0; idx < 8; ++idx) {
;             const int ai = idx >> 2, m = idx & 3;
;             const size_t ro = (size_t)(row0 + ai * HALF + m * 16) * ldc + col0;
;             if (idx + 1 < 8) { const int ai2 = (idx + 1) >> 2, m2 = (idx + 1) & 3; const size_t ro2 = (size_t)(row0 + ai2 * HALF + m2 * 16) * ldc + col0;
; #pragma unroll
;                 for (int bj = 0; bj < 2; ++bj)
; #pragma unroll
;                     for (int n = 0; n < 2; ++n) nxt[bj][n] = *(const f32x4*)(R + ro2 + bj * HALF + n * 16); }
;             float ss = 0.f;
; #pragma unroll
;             for (int bj = 0; bj < 2; ++bj)
; #pragma unroll
;                 for (int n = 0; n < 2; ++n) {
;                     const f32x4 hn = cur[bj][n] + acc[ai][bj][m][n] * scale;
;                     *(f32x4*)(C + ro + bj * HALF + n * 16) = hn;
;                     if (HB) { u32x2 w; w.x = pk_bf16(hn[0], hn[1]); w.y = pk_bf16(hn[2], hn[3]); *(u32x2*)(HB + ro + bj * HALF + n * 16) = w;
;                         ss += hn[0] * hn[0] + hn[1] * hn[1] + hn[2] * hn[2] + hn[3] * hn[3]; } }
;             if (HB) { ss += __shfl_xor(ss, 16); ss += __shfl_xor(ss, 32); if (fq == 0) RS[(size_t)(row0 + ai * HALF + m * 16) * 32 + u.pn * 4 + wc] = ss; }
.LBB0_1606:
	v_readlane_b32 s84, v239, 50
	v_or_b32_e32 v70, 48, v118
	v_readlane_b32 s86, v239, 52
	v_readlane_b32 s85, v239, 51
	v_readlane_b32 s87, v239, 53
	v_mad_i64_i32 v[72:73], s[16:17], v70, s86, 0
	s_waitcnt lgkmcnt(0)
	v_lshl_add_u64 v[32:33], v[72:73], 2, v[186:187]
	global_load_dwordx4 v[44:47], v[32:33], off
	global_load_dwordx4 v[40:43], v[32:33], off offset:64
	global_load_dwordx4 v[36:39], v[32:33], off offset:512
	s_nop 0
	global_load_dwordx4 v[32:35], v[32:33], off offset:576
	v_readlane_b32 s84, v238, 11
	v_lshl_add_u64 v[76:77], v[88:89], 0, v[182:183]
	v_readlane_b32 s88, v238, 15
	v_readlane_b32 s89, v238, 16
	v_mov_b32_e32 v181, v180
	s_waitcnt vmcnt(8)
	v_pk_fma_f32 v[68:69], v[30:31], v[180:181], v[62:63]
	v_lshl_add_u64 v[74:75], v[76:77], 2, s[88:89]
	v_pk_fma_f32 v[66:67], v[28:29], v[184:185], v[60:61]
	s_and_b64 vcc, exec, s[40:41]
	s_waitcnt vmcnt(7)
	v_pk_fma_f32 v[64:65], v[24:25], v[184:185], v[56:57]
	s_waitcnt vmcnt(6)
	v_pk_fma_f32 v[60:61], v[20:21], v[184:185], v[52:53]
	s_waitcnt vmcnt(5)
	v_pk_fma_f32 v[28:29], v[16:17], v[184:185], v[48:49]
	v_readlane_b32 s85, v238, 12
	v_readlane_b32 s86, v238, 13
	v_readlane_b32 s87, v238, 14
	v_readlane_b32 s90, v238, 17
	v_readlane_b32 s91, v238, 18
	global_store_dwordx4 v[74:75], v[66:69], off nt
	s_cbranch_vccnz .LBB0_1621
	v_readlane_b32 s84, v238, 19
	v_readlane_b32 s86, v238, 21
	v_readlane_b32 s87, v238, 22
	v_cvt_pk_bf16_f32 v20, v66, v67
	v_mul_f32_e32 v24, v67, v67
	v_cvt_pk_bf16_f32 v21, v68, v69
	v_fmac_f32_e32 v24, v66, v66
	v_lshl_add_u64 v[16:17], v[76:77], 1, s[86:87]
	global_store_dwordx2 v[16:17], v[20:21], off
	v_pk_fma_f32 v[66:67], v[26:27], v[180:181], v[58:59]
	v_cvt_pk_bf16_f32 v20, v64, v65
	global_store_dwordx4 v[74:75], v[64:67], off offset:64 nt
	v_cvt_pk_bf16_f32 v21, v66, v67
	global_store_dwordx2 v[16:17], v[20:21], off offset:32
	v_mul_f32_e32 v20, v65, v65
	v_fmac_f32_e32 v20, v64, v64
	v_fmac_f32_e32 v24, v68, v68
	v_fmac_f32_e32 v20, v66, v66
	v_fmac_f32_e32 v24, v69, v69
	v_fmac_f32_e32 v20, v67, v67
	v_add_f32_e32 v24, v24, v20
	v_pk_fma_f32 v[62:63], v[22:23], v[180:181], v[54:55]
	v_cvt_pk_bf16_f32 v20, v60, v61
	global_store_dwordx4 v[74:75], v[60:63], off offset:512 nt
	v_cvt_pk_bf16_f32 v21, v62, v63
	global_store_dwordx2 v[16:17], v[20:21], off offset:256
	v_mul_f32_e32 v20, v61, v61
	v_fmac_f32_e32 v20, v60, v60
	v_fmac_f32_e32 v20, v62, v62
	v_fmac_f32_e32 v20, v63, v63
	v_add_f32_e32 v24, v24, v20
	v_pk_fma_f32 v[30:31], v[18:19], v[180:181], v[50:51]
	v_cvt_pk_bf16_f32 v20, v28, v29
	global_store_dwordx4 v[74:75], v[28:31], off offset:576 nt
	v_cvt_pk_bf16_f32 v21, v30, v31
	global_store_dwordx2 v[16:17], v[20:21], off offset:288
	v_mul_f32_e32 v16, v29, v29
	v_and_b32_e32 v20, 64, v197
	v_fmac_f32_e32 v16, v28, v28
	v_xor_b32_e32 v17, 16, v197
	v_add_u32_e32 v20, 64, v20
	v_fmac_f32_e32 v16, v30, v30
	v_cmp_lt_i32_e32 vcc, v17, v20
	v_fmac_f32_e32 v16, v31, v31
	v_add_f32_e32 v16, v24, v16
	v_cndmask_b32_e32 v17, v197, v17, vcc
	v_lshlrev_b32_e32 v17, 2, v17
	ds_bpermute_b32 v17, v17, v16
	v_readlane_b32 s85, v238, 20
	s_waitcnt lgkmcnt(0)
	v_add_f32_e32 v16, v16, v17
	v_xor_b32_e32 v17, 32, v197
	v_cmp_lt_i32_e32 vcc, v17, v20
	s_nop 1
	v_cndmask_b32_e32 v17, v197, v17, vcc
	v_lshlrev_b32_e32 v17, 2, v17
	ds_bpermute_b32 v17, v17, v16
	s_and_saveexec_b64 s[16:17], s[36:37]
	s_cbranch_execz .LBB0_1609
	v_ashrrev_i32_e32 v87, 31, v86
	s_waitcnt lgkmcnt(0)
	v_add_f32_e32 v20, v16, v17
	v_lshlrev_b64 v[16:17], 7, v[86:87]
	v_lshl_add_u64 v[16:17], s[14:15], 0, v[16:17]
	global_store_dword v[16:17], v20, off

; DEVI unsigned pk_bf16(float lo, float hi) { unsigned r; asm("v_cvt_pk_bf16_f32 %0, %1, %2" : "=v"(r) : "v"(lo), "v"(hi)); return r; }
;     DEVI void operator()(const f32x4 (&acc)[2][2][4][2], const Unit& u, int wr, int wc, int fr, int fq, const LAS float*) const {
;     ...
;         for (int idx = 0; idx < 8; ++idx) {
;             const int ai = idx >> 2, m = idx & 3;
;             const size_t ro = (size_t)(row0 + ai * HALF + m * 16) * ldc + col0;
;             if (idx + 1 < 8) { const int ai2 = (idx + 1) >> 2, m2 = (idx + 1) & 3; const size_t ro2 = (size_t)(row0 + ai2 * HALF + m2 * 16) * ldc + col0;
; #pragma unroll
;                 for (int bj = 0; bj < 2; ++bj)
; #pragma unroll
;                     for (int n = 0; n < 2; ++n) nxt[bj][n] = *(const f32x4*)(R + ro2 + bj * HALF + n * 16); }
;             float ss = 0.f;
; #pragma unroll
;             for (int bj = 0; bj < 2; ++bj)
; #pragma unroll
;                 for (int n = 0; n < 2; ++n) {
;                     const f32x4 hn = cur[bj][n] + acc[ai][bj][m][n] * scale;
;                     *(f32x4*)(C + ro + bj * HALF + n * 16) = hn;
;                     if (HB) { u32x2 w; w.x = pk_bf16(hn[0], hn[1]); w.y = pk_bf16(hn[2], hn[3]); *(u32x2*)(HB + ro + bj * HALF + n * 16) = w;
;                         ss += hn[0] * hn[0] + hn[1] * hn[1] + hn[2] * hn[2] + hn[3] * hn[3]; } }
;             if (HB) { ss += __shfl_xor(ss, 16); ss += __shfl_xor(ss, 32); if (fq == 0) RS[(size_t)(row0 + ai * HALF + m * 16) * 32 + u.pn * 4 + wc] = ss; }
.LBB0_1611:
	v_readlane_b32 s84, v238, 11
	v_lshl_add_u64 v[18:19], v[72:73], 0, v[182:183]
	v_readlane_b32 s88, v238, 15
	v_readlane_b32 s89, v238, 16
	v_mov_b32_e32 v181, v180
	s_waitcnt vmcnt(4)
	v_pk_fma_f32 v[24:25], v[14:15], v[180:181], v[46:47]
	v_lshl_add_u64 v[26:27], v[18:19], 2, s[88:89]
	v_pk_fma_f32 v[22:23], v[12:13], v[184:185], v[44:45]
	s_and_b64 vcc, exec, s[40:41]
	s_waitcnt vmcnt(3)
	v_pk_fma_f32 v[20:21], v[8:9], v[184:185], v[40:41]
	s_waitcnt vmcnt(2) lgkmcnt(0)
	v_pk_fma_f32 v[16:17], v[4:5], v[184:185], v[36:37]
	s_waitcnt vmcnt(1)
	v_pk_fma_f32 v[12:13], v[0:1], v[184:185], v[32:33]
	v_readlane_b32 s85, v238, 12
	v_readlane_b32 s86, v238, 13
	v_readlane_b32 s87, v238, 14
	v_readlane_b32 s90, v238, 17
	v_readlane_b32 s91, v238, 18
	global_store_dwordx4 v[26:27], v[22:25], off nt
	s_cbranch_vccnz .LBB0_1622
	v_readlane_b32 s84, v238, 19
	v_readlane_b32 s86, v238, 21
	v_readlane_b32 s87, v238, 22
	v_cvt_pk_bf16_f32 v4, v22, v23
	v_mul_f32_e32 v8, v23, v23
	v_cvt_pk_bf16_f32 v5, v24, v25
	v_fmac_f32_e32 v8, v22, v22
	v_lshl_add_u64 v[0:1], v[18:19], 1, s[86:87]
	global_store_dwordx2 v[0:1], v[4:5], off
	v_pk_fma_f32 v[22:23], v[10:11], v[180:181], v[42:43]
	v_cvt_pk_bf16_f32 v4, v20, v21
	global_store_dwordx4 v[26:27], v[20:23], off offset:64 nt
	v_cvt_pk_bf16_f32 v5, v22, v23
	global_store_dwordx2 v[0:1], v[4:5], off offset:32
	v_mul_f32_e32 v4, v21, v21
	v_fmac_f32_e32 v4, v20, v20
	v_fmac_f32_e32 v8, v24, v24
	v_fmac_f32_e32 v4, v22, v22
	v_fmac_f32_e32 v8, v25, v25
	v_fmac_f32_e32 v4, v23, v23
	v_add_f32_e32 v8, v8, v4
	v_pk_fma_f32 v[18:19], v[6:7], v[180:181], v[38:39]
	v_cvt_pk_bf16_f32 v4, v16, v17
	global_store_dwordx4 v[26:27], v[16:19], off offset:512 nt
	v_cvt_pk_bf16_f32 v5, v18, v19
	global_store_dwordx2 v[0:1], v[4:5], off offset:256
	v_mul_f32_e32 v4, v17, v17
	v_fmac_f32_e32 v4, v16, v16
	v_fmac_f32_e32 v4, v18, v18
	v_fmac_f32_e32 v4, v19, v19
	v_add_f32_e32 v8, v8, v4
	v_pk_fma_f32 v[14:15], v[2:3], v[180:181], v[34:35]
	v_cvt_pk_bf16_f32 v4, v12, v13
	global_store_dwordx4 v[26:27], v[12:15], off offset:576 nt
	v_cvt_pk_bf16_f32 v5, v14, v15
	global_store_dwordx2 v[0:1], v[4:5], off offset:288
	v_mul_f32_e32 v0, v13, v13
	v_and_b32_e32 v4, 64, v197
	v_fmac_f32_e32 v0, v12, v12
	v_xor_b32_e32 v1, 16, v197
	v_add_u32_e32 v4, 64, v4
	v_fmac_f32_e32 v0, v14, v14
	v_cmp_lt_i32_e32 vcc, v1, v4
	v_fmac_f32_e32 v0, v15, v15
	v_add_f32_e32 v0, v8, v0
	v_cndmask_b32_e32 v1, v197, v1, vcc
	v_lshlrev_b32_e32 v1, 2, v1
	ds_bpermute_b32 v1, v1, v0
	v_readlane_b32 s85, v238, 20
	s_waitcnt lgkmcnt(0)
	v_add_f32_e32 v0, v0, v1
	v_xor_b32_e32 v1, 32, v197
	v_cmp_lt_i32_e32 vcc, v1, v4
	s_nop 1
	v_cndmask_b32_e32 v1, v197, v1, vcc
	v_lshlrev_b32_e32 v1, 2, v1
	ds_bpermute_b32 v1, v1, v0
	s_and_saveexec_b64 s[16:17], s[36:37]
	s_cbranch_execz .LBB0_1614
	v_ashrrev_i32_e32 v71, 31, v70
	s_waitcnt lgkmcnt(0)
	v_add_f32_e32 v4, v0, v1
	v_lshlrev_b64 v[0:1], 7, v[70:71]
	v_lshl_add_u64 v[0:1], s[14:15], 0, v[0:1]
	global_store_dword v[0:1], v4, off

; #define LAS __attribute__((address_space(3)))
; DEVI u32x4 pack8(const float* f) { u32x4 u; u.x = pk_bf16(f[0], f[1]); u.y = pk_bf16(f[2], f[3]); u.z = pk_bf16(f[4], f[5]); u.w = pk_bf16(f[6], f[7]); return u; }
; DEVI float row_rstd(const LAS float* rsl, int r) { return rsqrtf((rsl[r] + rsl[256 + r]) * (1.0f / DM) + 1e-6f); }
;     DEVI void operator()(const f32x4 (&acc)[2][2][4][2], const Unit& u, int wr, int wc, int fr, int fq, const LAS float* rsl) const {
;     ...
;             for (int m = 0; m < 4; ++m) { bf16_t* rowp = O + (size_t)(row0 + ai * HALF + m * 16) * ldc + col0;
;                 const float sc = row_rstd(rsl, wr * 64 + fr + ai * HALF + m * 16);
;                 const float k1 = -1.4426950408889634f * sc, k2 = sc * sc;
;                 float h[8], tt[8];
;                 const f32x4 guk0 = (acc[ai][0][m][0] * acc[ai][1][m][0]) * k2, guk1 = (acc[ai][0][m][1] * acc[ai][1][m][1]) * k2;
;                 const f32x4 ta = acc[ai][0][m][0] * k1, tb = acc[ai][0][m][1] * k1;
; #pragma unroll
;                 for (int j = 0; j < 4; ++j) { tt[j] = __builtin_amdgcn_exp2f(ta[j]); tt[4 + j] = __builtin_amdgcn_exp2f(tb[j]); }
;                 __builtin_amdgcn_sched_barrier(0);
; #pragma unroll
;                 for (int j = 0; j < 8; ++j) tt[j] = __builtin_amdgcn_rcpf(1.0f + tt[j]);
;                 __builtin_amdgcn_sched_barrier(0);
; #pragma unroll
;                 for (int j = 0; j < 4; ++j) { h[j] = guk0[j] * tt[j]; h[4 + j] = guk1[j] * tt[4 + j]; }
;                 *(u32x4*)rowp = pack8(h); }
.LBB0_1720:
	s_lshl_b32 s14, s76, 11
	s_and_b32 s14, s14, 0x800
	v_add_u32_e32 v168, s14, v148
	ds_read2st64_b32 v[144:145], v168 offset1:4
	v_readlane_b32 s76, v239, 60
	v_readlane_b32 s14, v239, 58
	v_readlane_b32 s78, v239, 62
	v_lshl_add_u32 v157, s75, 8, v147
	s_waitcnt lgkmcnt(0)
	v_add_f32_e32 v144, v144, v145
	v_fmamk_f32 v144, v144, 0x3a000000, v156
	v_mul_f32_e32 v145, 0x4b800000, v144
	v_cmp_gt_f32_e32 vcc, s50, v144
	v_readlane_b32 s15, v239, 59
	s_mov_b32 s70, s78
	v_cndmask_b32_e32 v144, v144, v145, vcc
	v_rsq_f32_e32 v158, v144
	v_lshl_or_b32 v144, s74, 7, v150
	v_ashrrev_i32_e32 v145, 31, v144
	v_lshl_add_u64 v[144:145], v[144:145], 1, s[14:15]
	v_mul_f32_e32 v159, 0x45800000, v158
	v_cndmask_b32_e32 v159, v158, v159, vcc
	v_mul_f32_e32 v158, 0xbfb8aa3b, v159
	v_pk_mul_f32 v[160:161], v[122:123], v[158:159] op_sel_hi:[1,0]
	v_pk_mul_f32 v[162:163], v[120:121], v[158:159] op_sel_hi:[1,0]
	v_pk_mul_f32 v[166:167], v[116:117], v[158:159] op_sel_hi:[1,0]
	v_pk_mul_f32 v[164:165], v[118:119], v[158:159] op_sel_hi:[1,0]
	v_exp_f32_e32 v158, v162
	v_exp_f32_e32 v162, v166
	v_exp_f32_e32 v166, v167
	v_exp_f32_e32 v167, v160
	v_exp_f32_e32 v169, v161
	v_mad_i64_i32 v[160:161], s[14:15], v157, s70, 0
	v_exp_f32_e32 v163, v163
	v_exp_f32_e32 v164, v164
	v_exp_f32_e32 v165, v165
	v_readlane_b32 s77, v239, 61
	v_readlane_b32 s79, v239, 63
	v_lshl_add_u64 v[160:161], v[160:161], 1, v[144:145]
	v_add_f32_e32 v158, 1.0, v158
	v_rcp_f32_e32 v170, v158
	v_add_f32_e32 v158, 1.0, v163
	v_rcp_f32_e32 v163, v158
	v_add_f32_e32 v158, 1.0, v167
	v_rcp_f32_e32 v167, v158
	v_add_f32_e32 v158, 1.0, v169
	v_rcp_f32_e32 v169, v158
	v_add_f32_e32 v158, 1.0, v162
	v_rcp_f32_e32 v162, v158
	v_add_f32_e32 v158, 1.0, v166
	v_rcp_f32_e32 v166, v158
	v_add_f32_e32 v158, 1.0, v164
	v_rcp_f32_e32 v164, v158
	v_add_f32_e32 v158, 1.0, v165
	v_rcp_f32_e32 v165, v158
	v_mul_f32_e32 v116, v112, v116
	v_mul_f32_e32 v117, v113, v117
	v_mov_b32_e32 v158, v114
	v_mov_b32_e32 v112, v118
	v_mov_b32_e32 v113, v159
	v_pk_mul_f32 v[112:113], v[158:159], v[112:113]
	v_mul_f32_e32 v121, v125, v121
	v_mul_f32_e32 v116, v116, v113
	v_mul_f32_e32 v120, v124, v120
	v_mul_f32_e32 v118, v116, v162
	v_mul_f32_e32 v116, v121, v113
	v_mul_f32_e32 v122, v126, v122
	v_mul_f32_e32 v114, v120, v113
	v_mul_f32_e32 v120, v116, v163
	v_mul_f32_e32 v116, v117, v113
	v_mul_f32_e32 v121, v116, v166
	v_mul_f32_e32 v116, v122, v113
	v_add_u32_e32 v125, 64, v168
	v_mul_f32_e32 v122, v116, v167
	ds_read2st64_b32 v[116:117], v125 offset1:4
	v_mul_f32_e32 v112, v112, v113
	v_mul_f32_e32 v124, v112, v164
	v_mul_f32_e32 v112, v127, v123
	v_mul_f32_e32 v112, v112, v113
	s_waitcnt lgkmcnt(0)
	v_add_f32_e32 v116, v116, v117
	v_fmamk_f32 v116, v116, 0x3a000000, v156
	v_mul_f32_e32 v117, 0x4b800000, v116
	v_cmp_gt_f32_e32 vcc, s50, v116
	v_mul_f32_e32 v123, v112, v169
	v_mul_f32_e32 v112, v115, v119
	v_cndmask_b32_e32 v116, v116, v117, vcc
	v_rsq_f32_e32 v116, v116
	v_mul_f32_e32 v112, v112, v113
	v_mul_f32_e32 v114, v114, v170
	v_mul_f32_e32 v115, v112, v165
	v_cvt_pk_bf16_f32 v112, v114, v120
	v_cvt_pk_bf16_f32 v113, v122, v123
	v_cvt_pk_bf16_f32 v114, v118, v121
	v_cvt_pk_bf16_f32 v115, v124, v115
	global_store_dwordx4 v[160:161], v[112:115], off nt
	v_or_b32_e32 v122, 16, v157
	s_nop 0
	v_mul_f32_e32 v112, 0x45800000, v116
	v_cndmask_b32_e32 v113, v116, v112, vcc
	v_mul_f32_e32 v112, 0xbfb8aa3b, v113
	v_pk_mul_f32 v[114:115], v[110:111], v[112:113] op_sel_hi:[1,0]
	v_pk_mul_f32 v[116:117], v[108:109], v[112:113] op_sel_hi:[1,0]
	v_pk_mul_f32 v[120:121], v[100:101], v[112:113] op_sel_hi:[1,0]
	v_pk_mul_f32 v[118:119], v[102:103], v[112:113] op_sel_hi:[1,0]
	v_exp_f32_e32 v112, v116
	v_exp_f32_e32 v116, v120
	v_exp_f32_e32 v120, v121
	v_exp_f32_e32 v121, v114
	v_exp_f32_e32 v123, v115
	v_mad_i64_i32 v[114:115], s[14:15], v122, s70, 0
	v_exp_f32_e32 v117, v117
	v_exp_f32_e32 v118, v118
	v_exp_f32_e32 v119, v119
	v_lshl_add_u64 v[114:115], v[114:115], 1, v[144:145]
	v_add_f32_e32 v112, 1.0, v112
	v_rcp_f32_e32 v122, v112
	v_add_f32_e32 v112, 1.0, v117
	v_rcp_f32_e32 v117, v112
	v_add_f32_e32 v112, 1.0, v121
	v_rcp_f32_e32 v121, v112
	v_add_f32_e32 v112, 1.0, v123
	v_rcp_f32_e32 v123, v112
	v_add_f32_e32 v112, 1.0, v116
	v_rcp_f32_e32 v116, v112
	v_add_f32_e32 v112, 1.0, v120
	v_rcp_f32_e32 v120, v112
	v_add_f32_e32 v112, 1.0, v118
	v_rcp_f32_e32 v118, v112
	v_add_f32_e32 v112, 1.0, v119
	v_rcp_f32_e32 v119, v112
	v_mul_f32_e32 v100, v96, v100
	v_mul_f32_e32 v101, v97, v101
	v_mov_b32_e32 v112, v98
	v_mov_b32_e32 v96, v102
	v_mov_b32_e32 v97, v113
	v_pk_mul_f32 v[96:97], v[112:113], v[96:97]
	v_mul_f32_e32 v105, v105, v109
	v_mul_f32_e32 v100, v100, v97
	v_mul_f32_e32 v104, v104, v108
	v_mul_f32_e32 v102, v100, v116
	v_mul_f32_e32 v100, v105, v97
	v_mul_f32_e32 v106, v106, v110
	v_mul_f32_e32 v98, v104, v97
	v_mul_f32_e32 v104, v100, v117
	v_mul_f32_e32 v100, v101, v97
	v_mul_f32_e32 v105, v100, v120
	v_mul_f32_e32 v100, v106, v97
	v_add_u32_e32 v109, 0x80, v168
	v_mul_f32_e32 v106, v100, v121
	ds_read2st64_b32 v[100:101], v109 offset1:4
	v_mul_f32_e32 v96, v96, v97
	v_mul_f32_e32 v108, v96, v118
	v_mul_f32_e32 v96, v107, v111
	v_mul_f32_e32 v96, v96, v97
	s_waitcnt lgkmcnt(0)
; DEVI u32x4 pack8(const float* f) { u32x4 u; u.x = pk_bf16(f[0], f[1]); u.y = pk_bf16(f[2], f[3]); u.z = pk_bf16(f[4], f[5]); u.w = pk_bf16(f[6], f[7]); return u; }
; DEVI float row_rstd(const LAS float* rsl, int r) { return rsqrtf((rsl[r] + rsl[256 + r]) * (1.0f / DM) + 1e-6f); }
;     DEVI void operator()(const f32x4 (&acc)[2][2][4][2], const Unit& u, int wr, int wc, int fr, int fq, const LAS float* rsl) const {
;     ...
;             for (int m = 0; m < 4; ++m) { bf16_t* rowp = O + (size_t)(row0 + ai * HALF + m * 16) * ldc + col0;
;                 const float sc = row_rstd(rsl, wr * 64 + fr + ai * HALF + m * 16);
;                 const float k1 = -1.4426950408889634f * sc, k2 = sc * sc;
;                 float h[8], tt[8];
;                 const f32x4 guk0 = (acc[ai][0][m][0] * acc[ai][1][m][0]) * k2, guk1 = (acc[ai][0][m][1] * acc[ai][1][m][1]) * k2;
;                 const f32x4 ta = acc[ai][0][m][0] * k1, tb = acc[ai][0][m][1] * k1;
; #pragma unroll
;                 for (int j = 0; j < 4; ++j) { tt[j] = __builtin_amdgcn_exp2f(ta[j]); tt[4 + j] = __builtin_amdgcn_exp2f(tb[j]); }
;                 __builtin_amdgcn_sched_barrier(0);
; #pragma unroll
;                 for (int j = 0; j < 8; ++j) tt[j] = __builtin_amdgcn_rcpf(1.0f + tt[j]);
;                 __builtin_amdgcn_sched_barrier(0);
; #pragma unroll
;                 for (int j = 0; j < 4; ++j) { h[j] = guk0[j] * tt[j]; h[4 + j] = guk1[j] * tt[4 + j]; }
;                 *(u32x4*)rowp = pack8(h); }
	v_add_f32_e32 v100, v100, v101
	v_fmamk_f32 v100, v100, 0x3a000000, v156
	v_mul_f32_e32 v101, 0x4b800000, v100
	v_cmp_gt_f32_e32 vcc, s50, v100
	v_mul_f32_e32 v107, v96, v123
	v_mul_f32_e32 v96, v99, v103
	v_cndmask_b32_e32 v100, v100, v101, vcc
	v_rsq_f32_e32 v100, v100
	v_mul_f32_e32 v96, v96, v97
	v_mul_f32_e32 v98, v98, v122
	v_mul_f32_e32 v99, v96, v119
	v_cvt_pk_bf16_f32 v96, v98, v104
	v_cvt_pk_bf16_f32 v97, v106, v107
	v_cvt_pk_bf16_f32 v98, v102, v105
	v_cvt_pk_bf16_f32 v99, v108, v99
	global_store_dwordx4 v[114:115], v[96:99], off nt
	v_or_b32_e32 v106, 32, v157
	s_nop 0
	v_mul_f32_e32 v96, 0x45800000, v100
	v_cndmask_b32_e32 v97, v100, v96, vcc
	v_mul_f32_e32 v96, 0xbfb8aa3b, v97
	v_pk_mul_f32 v[98:99], v[94:95], v[96:97] op_sel_hi:[1,0]
	v_pk_mul_f32 v[100:101], v[92:93], v[96:97] op_sel_hi:[1,0]
	v_pk_mul_f32 v[104:105], v[84:85], v[96:97] op_sel_hi:[1,0]
	v_pk_mul_f32 v[102:103], v[86:87], v[96:97] op_sel_hi:[1,0]
	v_exp_f32_e32 v96, v100
	v_exp_f32_e32 v100, v104
	v_exp_f32_e32 v104, v105
	v_exp_f32_e32 v105, v98
	v_exp_f32_e32 v107, v99
	v_mad_i64_i32 v[98:99], s[14:15], v106, s70, 0
	v_exp_f32_e32 v101, v101
	v_exp_f32_e32 v102, v102
	v_exp_f32_e32 v103, v103
	v_lshl_add_u64 v[98:99], v[98:99], 1, v[144:145]
	v_add_f32_e32 v96, 1.0, v96
	v_rcp_f32_e32 v106, v96
	v_add_f32_e32 v96, 1.0, v101
	v_rcp_f32_e32 v101, v96
	v_add_f32_e32 v96, 1.0, v105
	v_rcp_f32_e32 v105, v96
	v_add_f32_e32 v96, 1.0, v107
	v_rcp_f32_e32 v107, v96
	v_add_f32_e32 v96, 1.0, v100
	v_rcp_f32_e32 v100, v96
	v_add_f32_e32 v96, 1.0, v104
	v_rcp_f32_e32 v104, v96
	v_add_f32_e32 v96, 1.0, v102
	v_rcp_f32_e32 v102, v96
	v_add_f32_e32 v96, 1.0, v103
	v_rcp_f32_e32 v103, v96
	v_mul_f32_e32 v84, v80, v84
	v_mul_f32_e32 v85, v81, v85
	v_mov_b32_e32 v96, v82
	v_mov_b32_e32 v80, v86
	v_mov_b32_e32 v81, v97
	v_pk_mul_f32 v[80:81], v[96:97], v[80:81]
	v_mul_f32_e32 v89, v89, v93
	v_mul_f32_e32 v84, v84, v81
	v_mul_f32_e32 v88, v88, v92
	v_mul_f32_e32 v86, v84, v100
	v_mul_f32_e32 v84, v89, v81
	v_mul_f32_e32 v90, v90, v94
	v_mul_f32_e32 v82, v88, v81
	v_mul_f32_e32 v88, v84, v101
	v_mul_f32_e32 v84, v85, v81
	v_mul_f32_e32 v89, v84, v104
	v_mul_f32_e32 v84, v90, v81
	v_add_u32_e32 v93, 0xc0, v168
	v_mul_f32_e32 v90, v84, v105
	ds_read2st64_b32 v[84:85], v93 offset1:4
	v_mul_f32_e32 v80, v80, v81
	v_mul_f32_e32 v92, v80, v102
	v_mul_f32_e32 v80, v91, v95
	v_mul_f32_e32 v80, v80, v81
	s_waitcnt lgkmcnt(0)
	v_add_f32_e32 v84, v84, v85
	v_fmamk_f32 v84, v84, 0x3a000000, v156
	v_mul_f32_e32 v85, 0x4b800000, v84
	v_cmp_gt_f32_e32 vcc, s50, v84
	v_mul_f32_e32 v91, v80, v107
	v_mul_f32_e32 v80, v83, v87
	v_cndmask_b32_e32 v84, v84, v85, vcc
	v_rsq_f32_e32 v84, v84
	v_mul_f32_e32 v80, v80, v81
	v_mul_f32_e32 v82, v82, v106
	v_mul_f32_e32 v83, v80, v103
	v_cvt_pk_bf16_f32 v80, v82, v88
	v_cvt_pk_bf16_f32 v81, v90, v91
	v_cvt_pk_bf16_f32 v82, v86, v89
	v_cvt_pk_bf16_f32 v83, v92, v83
	global_store_dwordx4 v[98:99], v[80:83], off nt
	v_or_b32_e32 v90, 48, v157
	s_nop 0
	v_mul_f32_e32 v80, 0x45800000, v84
	v_cndmask_b32_e32 v81, v84, v80, vcc
	v_mul_f32_e32 v80, 0xbfb8aa3b, v81
	v_pk_mul_f32 v[82:83], v[78:79], v[80:81] op_sel_hi:[1,0]
	v_pk_mul_f32 v[84:85], v[76:77], v[80:81] op_sel_hi:[1,0]
	v_pk_mul_f32 v[88:89], v[68:69], v[80:81] op_sel_hi:[1,0]
	v_pk_mul_f32 v[86:87], v[70:71], v[80:81] op_sel_hi:[1,0]
	v_exp_f32_e32 v80, v84
	v_exp_f32_e32 v84, v88
	v_exp_f32_e32 v88, v89
	v_exp_f32_e32 v89, v82
	v_exp_f32_e32 v91, v83
	v_mad_i64_i32 v[82:83], s[14:15], v90, s70, 0
	v_exp_f32_e32 v85, v85
	v_exp_f32_e32 v86, v86
	v_exp_f32_e32 v87, v87
	v_lshl_add_u64 v[82:83], v[82:83], 1, v[144:145]
	v_add_f32_e32 v80, 1.0, v80
	v_rcp_f32_e32 v90, v80
	v_add_f32_e32 v80, 1.0, v85
	v_rcp_f32_e32 v85, v80
	v_add_f32_e32 v80, 1.0, v89
	v_rcp_f32_e32 v89, v80
	v_add_f32_e32 v80, 1.0, v91
	v_rcp_f32_e32 v91, v80
	v_add_f32_e32 v80, 1.0, v84
	v_rcp_f32_e32 v84, v80
	v_add_f32_e32 v80, 1.0, v88
	v_rcp_f32_e32 v88, v80
	v_add_f32_e32 v80, 1.0, v86
	v_rcp_f32_e32 v86, v80
	v_add_f32_e32 v80, 1.0, v87
	v_rcp_f32_e32 v87, v80
	v_mul_f32_e32 v68, v64, v68
	v_mul_f32_e32 v69, v65, v69
	v_mov_b32_e32 v80, v66
	v_mov_b32_e32 v64, v70
	v_mov_b32_e32 v65, v81
	v_pk_mul_f32 v[64:65], v[80:81], v[64:65]
	v_mul_f32_e32 v73, v73, v77
	v_mul_f32_e32 v68, v68, v65
	v_mul_f32_e32 v72, v72, v76
	v_mul_f32_e32 v70, v68, v84
	v_mul_f32_e32 v68, v73, v65
	v_mul_f32_e32 v74, v74, v78
	v_mul_f32_e32 v66, v72, v65
	v_mul_f32_e32 v72, v68, v85
	v_mul_f32_e32 v68, v69, v65
	v_mul_f32_e32 v73, v68, v88
	v_mul_f32_e32 v68, v74, v65
	v_mul_f32_e32 v74, v68, v89
	ds_read2st64_b32 v[68:69], v168 offset0:2 offset1:6
	v_mul_f32_e32 v64, v64, v65
	v_mul_f32_e32 v76, v64, v86
	v_mul_f32_e32 v64, v75, v79
	v_mul_f32_e32 v64, v64, v65
	s_waitcnt lgkmcnt(0)
; DEVI u32x4 pack8(const float* f) { u32x4 u; u.x = pk_bf16(f[0], f[1]); u.y = pk_bf16(f[2], f[3]); u.z = pk_bf16(f[4], f[5]); u.w = pk_bf16(f[6], f[7]); return u; }
; DEVI float row_rstd(const LAS float* rsl, int r) { return rsqrtf((rsl[r] + rsl[256 + r]) * (1.0f / DM) + 1e-6f); }
;     DEVI void operator()(const f32x4 (&acc)[2][2][4][2], const Unit& u, int wr, int wc, int fr, int fq, const LAS float* rsl) const {
;     ...
;             for (int m = 0; m < 4; ++m) { bf16_t* rowp = O + (size_t)(row0 + ai * HALF + m * 16) * ldc + col0;
;                 const float sc = row_rstd(rsl, wr * 64 + fr + ai * HALF + m * 16);
;                 const float k1 = -1.4426950408889634f * sc, k2 = sc * sc;
;                 float h[8], tt[8];
;                 const f32x4 guk0 = (acc[ai][0][m][0] * acc[ai][1][m][0]) * k2, guk1 = (acc[ai][0][m][1] * acc[ai][1][m][1]) * k2;
;                 const f32x4 ta = acc[ai][0][m][0] * k1, tb = acc[ai][0][m][1] * k1;
; #pragma unroll
;                 for (int j = 0; j < 4; ++j) { tt[j] = __builtin_amdgcn_exp2f(ta[j]); tt[4 + j] = __builtin_amdgcn_exp2f(tb[j]); }
;                 __builtin_amdgcn_sched_barrier(0);
; #pragma unroll
;                 for (int j = 0; j < 8; ++j) tt[j] = __builtin_amdgcn_rcpf(1.0f + tt[j]);
;                 __builtin_amdgcn_sched_barrier(0);
; #pragma unroll
;                 for (int j = 0; j < 4; ++j) { h[j] = guk0[j] * tt[j]; h[4 + j] = guk1[j] * tt[4 + j]; }
;                 *(u32x4*)rowp = pack8(h); }
	v_add_f32_e32 v68, v68, v69
	v_fmamk_f32 v68, v68, 0x3a000000, v156
	v_mul_f32_e32 v69, 0x4b800000, v68
	v_cmp_gt_f32_e32 vcc, s50, v68
	v_mul_f32_e32 v75, v64, v91
	v_mul_f32_e32 v64, v67, v71
	v_cndmask_b32_e32 v68, v68, v69, vcc
	v_rsq_f32_e32 v68, v68
	v_mul_f32_e32 v64, v64, v65
	v_mul_f32_e32 v66, v66, v90
	v_mul_f32_e32 v67, v64, v87
	v_cvt_pk_bf16_f32 v64, v66, v72
	v_cvt_pk_bf16_f32 v65, v74, v75
	v_cvt_pk_bf16_f32 v66, v70, v73
	v_cvt_pk_bf16_f32 v67, v76, v67
	global_store_dwordx4 v[82:83], v[64:67], off nt
	v_add_u32_e32 v74, 0x80, v157
	s_nop 0
	v_mul_f32_e32 v64, 0x45800000, v68
	v_cndmask_b32_e32 v65, v68, v64, vcc
	v_mul_f32_e32 v64, 0xbfb8aa3b, v65
	v_pk_mul_f32 v[66:67], v[62:63], v[64:65] op_sel_hi:[1,0]
	v_pk_mul_f32 v[68:69], v[60:61], v[64:65] op_sel_hi:[1,0]
	v_pk_mul_f32 v[72:73], v[56:57], v[64:65] op_sel_hi:[1,0]
	v_pk_mul_f32 v[70:71], v[58:59], v[64:65] op_sel_hi:[1,0]
	v_exp_f32_e32 v64, v68
	v_exp_f32_e32 v68, v72
	v_exp_f32_e32 v72, v73
	v_exp_f32_e32 v73, v66
	v_exp_f32_e32 v75, v67
	v_mad_i64_i32 v[66:67], s[14:15], v74, s70, 0
	v_exp_f32_e32 v69, v69
	v_exp_f32_e32 v70, v70
	v_exp_f32_e32 v71, v71
	v_lshl_add_u64 v[66:67], v[66:67], 1, v[144:145]
	v_add_f32_e32 v64, 1.0, v64
	v_rcp_f32_e32 v74, v64
	v_add_f32_e32 v64, 1.0, v69
	v_rcp_f32_e32 v69, v64
	v_add_f32_e32 v64, 1.0, v73
	v_rcp_f32_e32 v73, v64
	v_add_f32_e32 v64, 1.0, v75
	v_rcp_f32_e32 v75, v64
	v_add_f32_e32 v64, 1.0, v68
	v_rcp_f32_e32 v68, v64
	v_add_f32_e32 v64, 1.0, v72
	v_rcp_f32_e32 v72, v64
	v_add_f32_e32 v64, 1.0, v70
	v_rcp_f32_e32 v70, v64
	v_add_f32_e32 v64, 1.0, v71
	v_rcp_f32_e32 v71, v64
	v_mul_f32_e32 v56, v48, v56
	v_mul_f32_e32 v57, v49, v57
	v_mov_b32_e32 v64, v50
	v_mov_b32_e32 v48, v58
	v_mov_b32_e32 v49, v65
	v_mul_f32_e32 v52, v52, v60
	v_pk_mul_f32 v[48:49], v[64:65], v[48:49]
	v_mul_f32_e32 v53, v53, v61
	v_mul_f32_e32 v50, v52, v49
	v_mul_f32_e32 v52, v56, v49
	v_mul_f32_e32 v56, v52, v68
	v_mul_f32_e32 v52, v53, v49
	v_mul_f32_e32 v54, v54, v62
	v_mul_f32_e32 v58, v52, v69
	v_mul_f32_e32 v52, v57, v49
	v_mul_f32_e32 v57, v52, v72
	v_mul_f32_e32 v52, v54, v49
	v_mul_f32_e32 v54, v52, v73
	ds_read2st64_b32 v[52:53], v125 offset0:2 offset1:6
	v_mul_f32_e32 v48, v48, v49
	v_mul_f32_e32 v60, v48, v70
	v_mul_f32_e32 v48, v55, v63
	v_mul_f32_e32 v48, v48, v49
	s_waitcnt lgkmcnt(0)
	v_add_f32_e32 v52, v52, v53
	v_fmamk_f32 v52, v52, 0x3a000000, v156
	v_mul_f32_e32 v53, 0x4b800000, v52
	v_cmp_gt_f32_e32 vcc, s50, v52
	v_mul_f32_e32 v55, v48, v75
	v_mul_f32_e32 v48, v51, v59
	v_cndmask_b32_e32 v52, v52, v53, vcc
	v_rsq_f32_e32 v52, v52
	v_mul_f32_e32 v48, v48, v49
	v_mul_f32_e32 v50, v50, v74
	v_mul_f32_e32 v51, v48, v71
	v_cvt_pk_bf16_f32 v48, v50, v58
	v_cvt_pk_bf16_f32 v49, v54, v55
	v_cvt_pk_bf16_f32 v50, v56, v57
	v_cvt_pk_bf16_f32 v51, v60, v51
	global_store_dwordx4 v[66:67], v[48:51], off nt
	v_add_u32_e32 v58, 0x90, v157
	s_nop 0
	v_mul_f32_e32 v48, 0x45800000, v52
	v_cndmask_b32_e32 v49, v52, v48, vcc
	v_mul_f32_e32 v48, 0xbfb8aa3b, v49
	v_pk_mul_f32 v[50:51], v[46:47], v[48:49] op_sel_hi:[1,0]
	v_pk_mul_f32 v[52:53], v[44:45], v[48:49] op_sel_hi:[1,0]
	v_pk_mul_f32 v[56:57], v[40:41], v[48:49] op_sel_hi:[1,0]
	v_pk_mul_f32 v[54:55], v[42:43], v[48:49] op_sel_hi:[1,0]
	v_exp_f32_e32 v48, v52
	v_exp_f32_e32 v52, v56
	v_exp_f32_e32 v56, v57
	v_exp_f32_e32 v57, v50
	v_exp_f32_e32 v59, v51
	v_mad_i64_i32 v[50:51], s[14:15], v58, s70, 0
	v_exp_f32_e32 v53, v53
	v_exp_f32_e32 v54, v54
	v_exp_f32_e32 v55, v55
	v_lshl_add_u64 v[50:51], v[50:51], 1, v[144:145]
	v_add_f32_e32 v48, 1.0, v48
	v_rcp_f32_e32 v58, v48
	v_add_f32_e32 v48, 1.0, v53
	v_rcp_f32_e32 v53, v48
	v_add_f32_e32 v48, 1.0, v57
	v_rcp_f32_e32 v57, v48
	v_add_f32_e32 v48, 1.0, v59
	v_rcp_f32_e32 v59, v48
	v_add_f32_e32 v48, 1.0, v52
	v_rcp_f32_e32 v52, v48
	v_add_f32_e32 v48, 1.0, v56
	v_rcp_f32_e32 v56, v48
	v_add_f32_e32 v48, 1.0, v54
	v_rcp_f32_e32 v54, v48
	v_add_f32_e32 v48, 1.0, v55
	v_rcp_f32_e32 v55, v48
	v_mul_f32_e32 v40, v32, v40
	v_mul_f32_e32 v41, v33, v41
	v_mov_b32_e32 v48, v34
	v_mov_b32_e32 v32, v42
	v_mov_b32_e32 v33, v49
	v_mul_f32_e32 v36, v36, v44
	v_pk_mul_f32 v[32:33], v[48:49], v[32:33]
	v_mul_f32_e32 v37, v37, v45
	v_mul_f32_e32 v34, v36, v33
	v_mul_f32_e32 v36, v40, v33
	v_mul_f32_e32 v40, v36, v52
	v_mul_f32_e32 v36, v37, v33
	v_mul_f32_e32 v38, v38, v46
	v_mul_f32_e32 v42, v36, v53
	v_mul_f32_e32 v36, v41, v33
	v_mul_f32_e32 v41, v36, v56
	v_mul_f32_e32 v36, v38, v33
	v_mul_f32_e32 v38, v36, v57
	ds_read2st64_b32 v[36:37], v109 offset0:2 offset1:6
	v_mul_f32_e32 v32, v32, v33
	v_mul_f32_e32 v44, v32, v54
	v_mul_f32_e32 v32, v39, v47
	v_mul_f32_e32 v32, v32, v33
	s_waitcnt lgkmcnt(0)
; DEVI u32x4 pack8(const float* f) { u32x4 u; u.x = pk_bf16(f[0], f[1]); u.y = pk_bf16(f[2], f[3]); u.z = pk_bf16(f[4], f[5]); u.w = pk_bf16(f[6], f[7]); return u; }
; DEVI float row_rstd(const LAS float* rsl, int r) { return rsqrtf((rsl[r] + rsl[256 + r]) * (1.0f / DM) + 1e-6f); }
;     DEVI void operator()(const f32x4 (&acc)[2][2][4][2], const Unit& u, int wr, int wc, int fr, int fq, const LAS float* rsl) const {
;     ...
;             for (int m = 0; m < 4; ++m) { bf16_t* rowp = O + (size_t)(row0 + ai * HALF + m * 16) * ldc + col0;
;                 const float sc = row_rstd(rsl, wr * 64 + fr + ai * HALF + m * 16);
;                 const float k1 = -1.4426950408889634f * sc, k2 = sc * sc;
;                 float h[8], tt[8];
;                 const f32x4 guk0 = (acc[ai][0][m][0] * acc[ai][1][m][0]) * k2, guk1 = (acc[ai][0][m][1] * acc[ai][1][m][1]) * k2;
;                 const f32x4 ta = acc[ai][0][m][0] * k1, tb = acc[ai][0][m][1] * k1;
; #pragma unroll
;                 for (int j = 0; j < 4; ++j) { tt[j] = __builtin_amdgcn_exp2f(ta[j]); tt[4 + j] = __builtin_amdgcn_exp2f(tb[j]); }
;                 __builtin_amdgcn_sched_barrier(0);
; #pragma unroll
;                 for (int j = 0; j < 8; ++j) tt[j] = __builtin_amdgcn_rcpf(1.0f + tt[j]);
;                 __builtin_amdgcn_sched_barrier(0);
; #pragma unroll
;                 for (int j = 0; j < 4; ++j) { h[j] = guk0[j] * tt[j]; h[4 + j] = guk1[j] * tt[4 + j]; }
;                 *(u32x4*)rowp = pack8(h); }
; template <class Epi>
; DEVI void gemm_phase(LAS unsigned char* lds, const bf16_t* gA, const bf16_t* gBt, const int lda, const int ldb, const int K, const StaticOrder S_, const Epi E) {
;     ...
;         if constexpr (Epi::HAS_RS) { if (E.rs_) {
;             const int r = tid & 255, hf = tid >> 8; float s = 0.f;
;             const float* base = E.rs_ + (size_t)(u.pm * BM + r) * 32 + hf * 16;
;             if (E.rsn_ == 32) {
;                 const f32x4 a = *(const f32x4*)base, b = *(const f32x4*)(base + 4), c = *(const f32x4*)(base + 8), d = *(const f32x4*)(base + 12);
;                 s = ((a[0] + a[1]) + (a[2] + a[3])) + ((b[0] + b[1]) + (b[2] + b[3])) + ((c[0] + c[1]) + (c[2] + c[3])) + ((d[0] + d[1]) + (d[2] + d[3]));
;             } else if (hf == 0) s = base[0];
	v_add_f32_e32 v36, v36, v37
	v_fmamk_f32 v36, v36, 0x3a000000, v156
	v_mul_f32_e32 v37, 0x4b800000, v36
	v_cmp_gt_f32_e32 vcc, s50, v36
	v_mul_f32_e32 v39, v32, v59
	v_mul_f32_e32 v32, v35, v43
	v_cndmask_b32_e32 v36, v36, v37, vcc
	v_rsq_f32_e32 v36, v36
	v_mul_f32_e32 v32, v32, v33
	v_mul_f32_e32 v34, v34, v58
	v_mul_f32_e32 v35, v32, v55
	v_cvt_pk_bf16_f32 v32, v34, v42
	v_cvt_pk_bf16_f32 v33, v38, v39
	v_cvt_pk_bf16_f32 v34, v40, v41
	v_cvt_pk_bf16_f32 v35, v44, v35
	global_store_dwordx4 v[50:51], v[32:35], off nt
	v_add_u32_e32 v42, 0xa0, v157
	s_nop 0
	v_mul_f32_e32 v32, 0x45800000, v36
	v_cndmask_b32_e32 v33, v36, v32, vcc
	v_mul_f32_e32 v32, 0xbfb8aa3b, v33
	v_pk_mul_f32 v[34:35], v[30:31], v[32:33] op_sel_hi:[1,0]
	v_pk_mul_f32 v[36:37], v[28:29], v[32:33] op_sel_hi:[1,0]
	v_pk_mul_f32 v[40:41], v[24:25], v[32:33] op_sel_hi:[1,0]
	v_pk_mul_f32 v[38:39], v[26:27], v[32:33] op_sel_hi:[1,0]
	v_exp_f32_e32 v32, v36
	v_exp_f32_e32 v36, v40
	v_exp_f32_e32 v40, v41
	v_exp_f32_e32 v41, v34
	v_exp_f32_e32 v43, v35
	v_mad_i64_i32 v[34:35], s[14:15], v42, s70, 0
	v_exp_f32_e32 v37, v37
	v_exp_f32_e32 v38, v38
	v_exp_f32_e32 v39, v39
	v_lshl_add_u64 v[34:35], v[34:35], 1, v[144:145]
	v_add_f32_e32 v32, 1.0, v32
	v_rcp_f32_e32 v42, v32
	v_add_f32_e32 v32, 1.0, v37
	v_rcp_f32_e32 v37, v32
	v_add_f32_e32 v32, 1.0, v41
	v_rcp_f32_e32 v41, v32
	v_add_f32_e32 v32, 1.0, v43
	v_rcp_f32_e32 v43, v32
	v_add_f32_e32 v32, 1.0, v36
	v_rcp_f32_e32 v36, v32
	v_add_f32_e32 v32, 1.0, v40
	v_rcp_f32_e32 v40, v32
	v_add_f32_e32 v32, 1.0, v38
	v_rcp_f32_e32 v38, v32
	v_add_f32_e32 v32, 1.0, v39
	v_rcp_f32_e32 v39, v32
	v_mul_f32_e32 v24, v16, v24
	v_mul_f32_e32 v25, v17, v25
	v_mov_b32_e32 v32, v18
	v_mov_b32_e32 v16, v26
	v_mov_b32_e32 v17, v33
	v_mul_f32_e32 v20, v20, v28
	v_pk_mul_f32 v[16:17], v[32:33], v[16:17]
	v_mul_f32_e32 v21, v21, v29
	v_mul_f32_e32 v18, v20, v17
	v_mul_f32_e32 v20, v24, v17
	v_mul_f32_e32 v24, v20, v36
	v_mul_f32_e32 v20, v21, v17
	v_mul_f32_e32 v22, v22, v30
	v_mul_f32_e32 v26, v20, v37
	v_mul_f32_e32 v20, v25, v17
	v_mul_f32_e32 v25, v20, v40
	v_mul_f32_e32 v20, v22, v17
	v_mul_f32_e32 v22, v20, v41
	ds_read2st64_b32 v[20:21], v93 offset0:2 offset1:6
	v_mul_f32_e32 v16, v16, v17
	v_mul_f32_e32 v28, v16, v38
	v_mul_f32_e32 v16, v23, v31
	v_mul_f32_e32 v16, v16, v17
	s_waitcnt lgkmcnt(0)
	v_add_f32_e32 v20, v20, v21
	v_fmamk_f32 v20, v20, 0x3a000000, v156
	v_mul_f32_e32 v21, 0x4b800000, v20
	v_cmp_gt_f32_e32 vcc, s50, v20
	v_mul_f32_e32 v23, v16, v43
	v_mul_f32_e32 v16, v19, v27
	v_cndmask_b32_e32 v20, v20, v21, vcc
	v_rsq_f32_e32 v20, v20
	v_mul_f32_e32 v16, v16, v17
	v_mul_f32_e32 v18, v18, v42
	v_mul_f32_e32 v19, v16, v39
	v_cvt_pk_bf16_f32 v16, v18, v26
	v_cvt_pk_bf16_f32 v17, v22, v23
	v_cvt_pk_bf16_f32 v18, v24, v25
	v_cvt_pk_bf16_f32 v19, v28, v19
	global_store_dwordx4 v[34:35], v[16:19], off nt
	v_add_u32_e32 v26, 0xb0, v157
	s_nop 0
	v_mul_f32_e32 v16, 0x45800000, v20
	v_cndmask_b32_e32 v17, v20, v16, vcc
	v_mul_f32_e32 v16, 0xbfb8aa3b, v17
	v_pk_mul_f32 v[18:19], v[14:15], v[16:17] op_sel_hi:[1,0]
	v_pk_mul_f32 v[20:21], v[12:13], v[16:17] op_sel_hi:[1,0]
	v_pk_mul_f32 v[24:25], v[8:9], v[16:17] op_sel_hi:[1,0]
	v_pk_mul_f32 v[22:23], v[10:11], v[16:17] op_sel_hi:[1,0]
	v_exp_f32_e32 v16, v20
	v_exp_f32_e32 v20, v24
	v_exp_f32_e32 v24, v25
	v_exp_f32_e32 v25, v18
	v_exp_f32_e32 v27, v19
	v_mad_i64_i32 v[18:19], s[14:15], v26, s70, 0
	v_exp_f32_e32 v21, v21
	v_exp_f32_e32 v22, v22
	v_exp_f32_e32 v23, v23
	v_lshl_add_u64 v[18:19], v[18:19], 1, v[144:145]
	v_add_f32_e32 v16, 1.0, v16
	v_rcp_f32_e32 v26, v16
	v_add_f32_e32 v16, 1.0, v21
	v_rcp_f32_e32 v21, v16
	v_add_f32_e32 v16, 1.0, v25
	v_rcp_f32_e32 v25, v16
	v_add_f32_e32 v16, 1.0, v27
	v_rcp_f32_e32 v27, v16
	v_add_f32_e32 v16, 1.0, v20
	v_rcp_f32_e32 v20, v16
	v_add_f32_e32 v16, 1.0, v24
	v_rcp_f32_e32 v24, v16
	v_add_f32_e32 v16, 1.0, v22
	v_rcp_f32_e32 v22, v16
	v_add_f32_e32 v16, 1.0, v23
	v_rcp_f32_e32 v23, v16
	v_mul_f32_e32 v8, v0, v8
	v_mul_f32_e32 v9, v1, v9
	v_mov_b32_e32 v16, v2
	v_mov_b32_e32 v0, v10
	v_mov_b32_e32 v1, v17
	v_pk_mul_f32 v[0:1], v[16:17], v[0:1]
	v_mul_f32_e32 v4, v4, v12
	v_mul_f32_e32 v0, v0, v1
	v_mul_f32_e32 v2, v4, v1
	v_mul_f32_e32 v4, v8, v1
	v_mul_f32_e32 v8, v9, v1
	v_mul_f32_e32 v9, v0, v22
	v_mul_f32_e32 v0, v7, v15
	v_mul_f32_e32 v0, v0, v1
	v_mul_f32_e32 v7, v0, v27
	v_mul_f32_e32 v0, v3, v11
	v_mul_f32_e32 v5, v5, v13
	v_mul_f32_e32 v6, v6, v14
	v_mul_f32_e32 v0, v0, v1
	v_mul_f32_e32 v2, v2, v26
	v_mul_f32_e32 v5, v5, v1
	v_mul_f32_e32 v6, v6, v1
	v_mul_f32_e32 v3, v0, v23
	s_and_b64 vcc, exec, s[38:39]
	s_mov_b64 s[14:15], -1
	v_mul_f32_e32 v4, v4, v20
	v_mul_f32_e32 v5, v5, v21
	v_mul_f32_e32 v8, v8, v24
	v_mul_f32_e32 v6, v6, v25
	v_cvt_pk_bf16_f32 v0, v2, v5
	v_cvt_pk_bf16_f32 v1, v6, v7
	v_cvt_pk_bf16_f32 v2, v4, v8
	v_cvt_pk_bf16_f32 v3, v9, v3
	global_store_dwordx4 v[18:19], v[0:3], off nt
	s_cbranch_vccnz .LBB0_1710
	s_and_b64 vcc, exec, s[12:13]
	s_cbranch_vccz .LBB0_1709
	v_lshl_or_b32 v0, s73, 8, v146
	v_ashrrev_i32_e32 v1, 31, v0
	v_lshlrev_b64 v[0:1], 7, v[0:1]
	v_lshl_add_u64 v[0:1], v[136:137], 0, v[0:1]
	s_and_b64 vcc, exec, s[42:43]
	s_cbranch_vccz .LBB0_1726
	v_mov_b32_e32 v2, 0
	s_and_saveexec_b64 s[14:15], s[36:37]
	s_cbranch_execz .LBB0_1725
	global_load_dword v2, v[0:1], off

; DEVI unsigned pk_bf16(float lo, float hi) { unsigned r; asm("v_cvt_pk_bf16_f32 %0, %1, %2" : "=v"(r) : "v"(lo), "v"(hi)); return r; }
;     DEVI void operator()(const f32x4 (&acc)[2][2][4][2], const Unit& u, int wr, int wc, int fr, int fq, const LAS float*) const {
;     ...
;         const int row0 = u.pm * BM + wr * 64 + fr, col0 = u.pn * BM + wc * 32 + 4 * fq;
;         f32x4 cur[2][2], nxt[2][2];
;         { const size_t ro = (size_t)row0 * ldc + col0;
; #pragma unroll
;           for (int bj = 0; bj < 2; ++bj)
; #pragma unroll
;               for (int n = 0; n < 2; ++n) cur[bj][n] = *(const f32x4*)(R + ro + bj * HALF + n * 16); }
; #pragma unroll
;         for (int idx = 0; idx < 8; ++idx) {
;             const int ai = idx >> 2, m = idx & 3;
;             const size_t ro = (size_t)(row0 + ai * HALF + m * 16) * ldc + col0;
;             if (idx + 1 < 8) { const int ai2 = (idx + 1) >> 2, m2 = (idx + 1) & 3; const size_t ro2 = (size_t)(row0 + ai2 * HALF + m2 * 16) * ldc + col0;
; #pragma unroll
;                 for (int bj = 0; bj < 2; ++bj)
; #pragma unroll
;                     for (int n = 0; n < 2; ++n) nxt[bj][n] = *(const f32x4*)(R + ro2 + bj * HALF + n * 16); }
;             float ss = 0.f;
; #pragma unroll
;             for (int bj = 0; bj < 2; ++bj)
; #pragma unroll
;                 for (int n = 0; n < 2; ++n) {
;                     const f32x4 hn = cur[bj][n] + acc[ai][bj][m][n] * scale;
;                     *(f32x4*)(C + ro + bj * HALF + n * 16) = hn;
;                     if (HB) { u32x2 w; w.x = pk_bf16(hn[0], hn[1]); w.y = pk_bf16(hn[2], hn[3]); *(u32x2*)(HB + ro + bj * HALF + n * 16) = w;
;                         ss += hn[0] * hn[0] + hn[1] * hn[1] + hn[2] * hn[2] + hn[3] * hn[3]; } }
;             if (HB) { ss += __shfl_xor(ss, 16); ss += __shfl_xor(ss, 32); if (fq == 0) RS[(size_t)(row0 + ai * HALF + m * 16) * 32 + u.pn * 4 + wc] = ss; }
.LBB0_1850:
	v_lshl_add_u32 v188, s63, 8, v198
	v_lshl_or_b32 v182, s31, 8, v200
	v_readlane_b32 s84, v238, 24
	v_mad_i64_i32 v[128:129], s[14:15], v188, s66, 0
	v_ashrrev_i32_e32 v183, 31, v182
	v_readlane_b32 s90, v238, 30
	v_readlane_b32 s91, v238, 31
	v_lshlrev_b64 v[130:131], 2, v[182:183]
	v_or_b32_e32 v190, 16, v188
	v_lshl_add_u64 v[128:129], v[128:129], 2, s[90:91]
	v_mov_b32_e32 v180, v204
	v_lshl_add_u64 v[128:129], v[128:129], 0, v[130:131]
	v_lshl_add_u64 v[186:187], s[90:91], 0, v[130:131]
	v_mad_i64_i32 v[192:193], s[16:17], v190, s66, 0
	global_load_dwordx4 v[160:163], v[128:129], off
	global_load_dwordx4 v[152:155], v[128:129], off offset:64
	global_load_dwordx4 v[148:151], v[128:129], off offset:512
	global_load_dwordx4 v[140:143], v[128:129], off offset:576
	v_lshl_add_u64 v[128:129], v[192:193], 2, v[186:187]
	global_load_dwordx4 v[144:147], v[128:129], off
	global_load_dwordx4 v[136:139], v[128:129], off offset:64
	global_load_dwordx4 v[132:135], v[128:129], off offset:512
	s_nop 0
	global_load_dwordx4 v[128:131], v[128:129], off offset:576
	s_lshl_b32 s14, s31, 2
	s_ashr_i32 s15, s14, 31
	s_lshl_b64 s[14:15], s[14:15], 2
	v_readlane_b32 s88, v238, 28
	v_readlane_b32 s89, v238, 29
	v_mov_b32_e32 v184, v180
	v_mov_b32_e32 v185, v180
	s_add_u32 s14, s4, s14
	v_mad_i64_i32 v[158:159], s[16:17], v188, s66, v[182:183]
	v_ashrrev_i32_e32 v189, 31, v188
	s_addc_u32 s15, s5, s15
	v_lshl_add_u64 v[194:195], v[158:159], 2, s[88:89]
	s_andn2_b64 vcc, exec, s[54:55]
	v_readlane_b32 s85, v238, 25
	v_readlane_b32 s86, v238, 26
	v_readlane_b32 s87, v238, 27
	s_waitcnt vmcnt(0)
	v_pk_fma_f32 v[164:165], v[126:127], v[180:181], v[162:163] op_sel_hi:[1,0,1]
	v_pk_fma_f32 v[162:163], v[124:125], v[180:181], v[160:161] op_sel_hi:[1,0,1]
	v_cndmask_b32_e64 v124, 0, 1, s[54:55]
	v_cmp_ne_u32_e64 s[38:39], 1, v124
	v_pk_fma_f32 v[160:161], v[120:121], v[184:185], v[152:153]
	v_pk_fma_f32 v[156:157], v[116:117], v[184:185], v[148:149]
	v_pk_fma_f32 v[124:125], v[112:113], v[184:185], v[140:141]
	global_store_dwordx4 v[194:195], v[162:165], off nt
	s_cbranch_vccnz .LBB0_1889
	v_readlane_b32 s84, v238, 32
	v_readlane_b32 s86, v238, 34
	v_readlane_b32 s87, v238, 35
	v_cvt_pk_bf16_f32 v116, v162, v163
	v_mul_f32_e32 v120, v163, v163
	v_mov_b32_e32 v181, v180
	v_lshl_add_u64 v[112:113], v[158:159], 1, s[86:87]
	v_cvt_pk_bf16_f32 v117, v164, v165
	global_store_dwordx2 v[112:113], v[116:117], off
	v_fmac_f32_e32 v120, v162, v162
	v_pk_fma_f32 v[162:163], v[122:123], v[180:181], v[154:155]
	v_cvt_pk_bf16_f32 v116, v160, v161
	global_store_dwordx4 v[194:195], v[160:163], off offset:64 nt
	v_cvt_pk_bf16_f32 v117, v162, v163
	global_store_dwordx2 v[112:113], v[116:117], off offset:32
	v_mul_f32_e32 v116, v161, v161
	v_fmac_f32_e32 v116, v160, v160
	v_fmac_f32_e32 v120, v164, v164
	v_fmac_f32_e32 v116, v162, v162
	v_fmac_f32_e32 v120, v165, v165
	v_fmac_f32_e32 v116, v163, v163
	v_add_f32_e32 v120, v120, v116
	v_pk_fma_f32 v[158:159], v[118:119], v[180:181], v[150:151]
	v_cvt_pk_bf16_f32 v116, v156, v157
	global_store_dwordx4 v[194:195], v[156:159], off offset:512 nt
	v_cvt_pk_bf16_f32 v117, v158, v159
	global_store_dwordx2 v[112:113], v[116:117], off offset:256
	v_mul_f32_e32 v116, v157, v157
	v_fmac_f32_e32 v116, v156, v156
	v_fmac_f32_e32 v116, v158, v158
	v_fmac_f32_e32 v116, v159, v159
	v_add_f32_e32 v120, v116, v120
	v_pk_fma_f32 v[126:127], v[114:115], v[180:181], v[142:143]
	v_cvt_pk_bf16_f32 v116, v124, v125
	global_store_dwordx4 v[194:195], v[124:127], off offset:576 nt
	v_cvt_pk_bf16_f32 v117, v126, v127
	global_store_dwordx2 v[112:113], v[116:117], off offset:288
	v_mul_f32_e32 v112, v125, v125
	v_and_b32_e32 v116, 64, v197
	v_fmac_f32_e32 v112, v124, v124
	v_xor_b32_e32 v113, 16, v197
	v_add_u32_e32 v116, 64, v116
	v_fmac_f32_e32 v112, v126, v126
	v_cmp_lt_i32_e32 vcc, v113, v116
	v_fmac_f32_e32 v112, v127, v127
	v_add_f32_e32 v112, v112, v120
	v_cndmask_b32_e32 v113, v197, v113, vcc
	v_lshlrev_b32_e32 v113, 2, v113
	ds_bpermute_b32 v113, v113, v112
	v_readlane_b32 s85, v238, 33
	s_waitcnt lgkmcnt(0)
	v_add_f32_e32 v112, v112, v113
	v_xor_b32_e32 v113, 32, v197
	v_cmp_lt_i32_e32 vcc, v113, v116
	s_nop 1
	v_cndmask_b32_e32 v113, v197, v113, vcc
	v_lshlrev_b32_e32 v113, 2, v113
	ds_bpermute_b32 v113, v113, v112
	s_and_saveexec_b64 s[16:17], s[34:35]
	s_cbranch_execz .LBB0_1853
	s_waitcnt lgkmcnt(0)
	v_add_f32_e32 v116, v112, v113
	v_lshlrev_b64 v[112:113], 7, v[188:189]
	v_lshl_add_u64 v[112:113], s[14:15], 0, v[112:113]
	global_store_dword v[112:113], v116, off

; DEVI unsigned pk_bf16(float lo, float hi) { unsigned r; asm("v_cvt_pk_bf16_f32 %0, %1, %2" : "=v"(r) : "v"(lo), "v"(hi)); return r; }
;     DEVI void operator()(const f32x4 (&acc)[2][2][4][2], const Unit& u, int wr, int wc, int fr, int fq, const LAS float*) const {
;     ...
;         for (int idx = 0; idx < 8; ++idx) {
;             const int ai = idx >> 2, m = idx & 3;
;             const size_t ro = (size_t)(row0 + ai * HALF + m * 16) * ldc + col0;
;             if (idx + 1 < 8) { const int ai2 = (idx + 1) >> 2, m2 = (idx + 1) & 3; const size_t ro2 = (size_t)(row0 + ai2 * HALF + m2 * 16) * ldc + col0;
; #pragma unroll
;                 for (int bj = 0; bj < 2; ++bj)
; #pragma unroll
;                     for (int n = 0; n < 2; ++n) nxt[bj][n] = *(const f32x4*)(R + ro2 + bj * HALF + n * 16); }
;             float ss = 0.f;
; #pragma unroll
;             for (int bj = 0; bj < 2; ++bj)
; #pragma unroll
;                 for (int n = 0; n < 2; ++n) {
;                     const f32x4 hn = cur[bj][n] + acc[ai][bj][m][n] * scale;
;                     *(f32x4*)(C + ro + bj * HALF + n * 16) = hn;
;                     if (HB) { u32x2 w; w.x = pk_bf16(hn[0], hn[1]); w.y = pk_bf16(hn[2], hn[3]); *(u32x2*)(HB + ro + bj * HALF + n * 16) = w;
;                         ss += hn[0] * hn[0] + hn[1] * hn[1] + hn[2] * hn[2] + hn[3] * hn[3]; } }
;             if (HB) { ss += __shfl_xor(ss, 16); ss += __shfl_xor(ss, 32); if (fq == 0) RS[(size_t)(row0 + ai * HALF + m * 16) * 32 + u.pn * 4 + wc] = ss; }
; #pragma unroll
;             for (int bj = 0; bj < 2; ++bj)
; #pragma unroll
;                 for (int n = 0; n < 2; ++n) cur[bj][n] = nxt[bj][n];
;         }
.LBB0_1855:
	v_or_b32_e32 v150, 32, v188
	v_mad_i64_i32 v[152:153], s[16:17], v150, s66, 0
	s_waitcnt lgkmcnt(0)
	v_lshl_add_u64 v[112:113], v[152:153], 2, v[186:187]
	global_load_dwordx4 v[124:127], v[112:113], off
	global_load_dwordx4 v[120:123], v[112:113], off offset:64
	global_load_dwordx4 v[116:119], v[112:113], off offset:512
	s_nop 0
	global_load_dwordx4 v[112:115], v[112:113], off offset:576
	v_readlane_b32 s84, v238, 24
	v_lshl_add_u64 v[142:143], v[192:193], 0, v[182:183]
	v_readlane_b32 s88, v238, 28
	v_readlane_b32 s89, v238, 29
	v_mov_b32_e32 v181, v180
	v_pk_fma_f32 v[148:149], v[110:111], v[180:181], v[146:147]
	v_lshl_add_u64 v[154:155], v[142:143], 2, s[88:89]
	v_pk_fma_f32 v[146:147], v[108:109], v[184:185], v[144:145]
	s_and_b64 vcc, exec, s[38:39]
	v_pk_fma_f32 v[144:145], v[104:105], v[184:185], v[136:137]
	v_pk_fma_f32 v[140:141], v[100:101], v[184:185], v[132:133]
	v_pk_fma_f32 v[108:109], v[96:97], v[184:185], v[128:129]
	v_readlane_b32 s85, v238, 25
	v_readlane_b32 s86, v238, 26
	v_readlane_b32 s87, v238, 27
	v_readlane_b32 s90, v238, 30
	v_readlane_b32 s91, v238, 31
	global_store_dwordx4 v[154:155], v[146:149], off nt
	s_cbranch_vccnz .LBB0_1890
	v_readlane_b32 s84, v238, 32
	v_readlane_b32 s86, v238, 34
	v_readlane_b32 s87, v238, 35
	v_cvt_pk_bf16_f32 v100, v146, v147
	v_mul_f32_e32 v104, v147, v147
	v_cvt_pk_bf16_f32 v101, v148, v149
	v_fmac_f32_e32 v104, v146, v146
	v_lshl_add_u64 v[96:97], v[142:143], 1, s[86:87]
	global_store_dwordx2 v[96:97], v[100:101], off
	v_pk_fma_f32 v[146:147], v[106:107], v[180:181], v[138:139]
	v_cvt_pk_bf16_f32 v100, v144, v145
	global_store_dwordx4 v[154:155], v[144:147], off offset:64 nt
	v_cvt_pk_bf16_f32 v101, v146, v147
	global_store_dwordx2 v[96:97], v[100:101], off offset:32
	v_mul_f32_e32 v100, v145, v145
	v_fmac_f32_e32 v100, v144, v144
	v_fmac_f32_e32 v104, v148, v148
	v_fmac_f32_e32 v100, v146, v146
	v_fmac_f32_e32 v104, v149, v149
	v_fmac_f32_e32 v100, v147, v147
	v_add_f32_e32 v104, v104, v100
	v_pk_fma_f32 v[142:143], v[102:103], v[180:181], v[134:135]
	v_cvt_pk_bf16_f32 v100, v140, v141
	global_store_dwordx4 v[154:155], v[140:143], off offset:512 nt
	v_cvt_pk_bf16_f32 v101, v142, v143
	global_store_dwordx2 v[96:97], v[100:101], off offset:256
	v_mul_f32_e32 v100, v141, v141
	v_fmac_f32_e32 v100, v140, v140
	v_fmac_f32_e32 v100, v142, v142
	v_fmac_f32_e32 v100, v143, v143
	v_add_f32_e32 v104, v104, v100
	v_pk_fma_f32 v[110:111], v[98:99], v[180:181], v[130:131]
	v_cvt_pk_bf16_f32 v100, v108, v109
	global_store_dwordx4 v[154:155], v[108:111], off offset:576 nt
	v_cvt_pk_bf16_f32 v101, v110, v111
	global_store_dwordx2 v[96:97], v[100:101], off offset:288
	v_mul_f32_e32 v96, v109, v109
	v_and_b32_e32 v100, 64, v197
	v_fmac_f32_e32 v96, v108, v108
	v_xor_b32_e32 v97, 16, v197
	v_add_u32_e32 v100, 64, v100
	v_fmac_f32_e32 v96, v110, v110
	v_cmp_lt_i32_e32 vcc, v97, v100
	v_fmac_f32_e32 v96, v111, v111
	v_add_f32_e32 v96, v104, v96
	v_cndmask_b32_e32 v97, v197, v97, vcc
	v_lshlrev_b32_e32 v97, 2, v97
	ds_bpermute_b32 v97, v97, v96
	v_readlane_b32 s85, v238, 33
	s_waitcnt lgkmcnt(0)
	v_add_f32_e32 v96, v96, v97
	v_xor_b32_e32 v97, 32, v197
	v_cmp_lt_i32_e32 vcc, v97, v100
	s_nop 1
	v_cndmask_b32_e32 v97, v197, v97, vcc
	v_lshlrev_b32_e32 v97, 2, v97
	ds_bpermute_b32 v97, v97, v96
	s_and_saveexec_b64 s[16:17], s[34:35]
	s_cbranch_execz .LBB0_1858
	v_ashrrev_i32_e32 v191, 31, v190
	s_waitcnt lgkmcnt(0)
	v_add_f32_e32 v100, v96, v97
	v_lshlrev_b64 v[96:97], 7, v[190:191]
	v_lshl_add_u64 v[96:97], s[14:15], 0, v[96:97]
	global_store_dword v[96:97], v100, off

; DEVI unsigned pk_bf16(float lo, float hi) { unsigned r; asm("v_cvt_pk_bf16_f32 %0, %1, %2" : "=v"(r) : "v"(lo), "v"(hi)); return r; }
;     DEVI void operator()(const f32x4 (&acc)[2][2][4][2], const Unit& u, int wr, int wc, int fr, int fq, const LAS float*) const {
;     ...
;         for (int idx = 0; idx < 8; ++idx) {
;             const int ai = idx >> 2, m = idx & 3;
;             const size_t ro = (size_t)(row0 + ai * HALF + m * 16) * ldc + col0;
;             if (idx + 1 < 8) { const int ai2 = (idx + 1) >> 2, m2 = (idx + 1) & 3; const size_t ro2 = (size_t)(row0 + ai2 * HALF + m2 * 16) * ldc + col0;
; #pragma unroll
;                 for (int bj = 0; bj < 2; ++bj)
; #pragma unroll
;                     for (int n = 0; n < 2; ++n) nxt[bj][n] = *(const f32x4*)(R + ro2 + bj * HALF + n * 16); }
;             float ss = 0.f;
; #pragma unroll
;             for (int bj = 0; bj < 2; ++bj)
; #pragma unroll
;                 for (int n = 0; n < 2; ++n) {
;                     const f32x4 hn = cur[bj][n] + acc[ai][bj][m][n] * scale;
;                     *(f32x4*)(C + ro + bj * HALF + n * 16) = hn;
;                     if (HB) { u32x2 w; w.x = pk_bf16(hn[0], hn[1]); w.y = pk_bf16(hn[2], hn[3]); *(u32x2*)(HB + ro + bj * HALF + n * 16) = w;
;                         ss += hn[0] * hn[0] + hn[1] * hn[1] + hn[2] * hn[2] + hn[3] * hn[3]; } }
;             if (HB) { ss += __shfl_xor(ss, 16); ss += __shfl_xor(ss, 32); if (fq == 0) RS[(size_t)(row0 + ai * HALF + m * 16) * 32 + u.pn * 4 + wc] = ss; }
; #pragma unroll
;             for (int bj = 0; bj < 2; ++bj)
; #pragma unroll
;                 for (int n = 0; n < 2; ++n) cur[bj][n] = nxt[bj][n];
;         }
.LBB0_1860:
	v_or_b32_e32 v134, 48, v188
	v_mad_i64_i32 v[136:137], s[16:17], v134, s66, 0
	s_waitcnt lgkmcnt(0)
	v_lshl_add_u64 v[96:97], v[136:137], 2, v[186:187]
	global_load_dwordx4 v[108:111], v[96:97], off
	global_load_dwordx4 v[104:107], v[96:97], off offset:64
	global_load_dwordx4 v[100:103], v[96:97], off offset:512
	s_nop 0
	global_load_dwordx4 v[96:99], v[96:97], off offset:576
	v_readlane_b32 s84, v238, 24
	v_lshl_add_u64 v[140:141], v[152:153], 0, v[182:183]
	v_readlane_b32 s88, v238, 28
	v_readlane_b32 s89, v238, 29
	v_mov_b32_e32 v181, v180
	s_waitcnt vmcnt(8)
	v_pk_fma_f32 v[132:133], v[94:95], v[180:181], v[126:127]
	v_lshl_add_u64 v[138:139], v[140:141], 2, s[88:89]
	v_pk_fma_f32 v[130:131], v[92:93], v[184:185], v[124:125]
	s_and_b64 vcc, exec, s[38:39]
	s_waitcnt vmcnt(7)
	v_pk_fma_f32 v[128:129], v[88:89], v[184:185], v[120:121]
	s_waitcnt vmcnt(6)
	v_pk_fma_f32 v[124:125], v[84:85], v[184:185], v[116:117]
	s_waitcnt vmcnt(5)
	v_pk_fma_f32 v[92:93], v[80:81], v[184:185], v[112:113]
	v_readlane_b32 s85, v238, 25
	v_readlane_b32 s86, v238, 26
	v_readlane_b32 s87, v238, 27
	v_readlane_b32 s90, v238, 30
	v_readlane_b32 s91, v238, 31
	global_store_dwordx4 v[138:139], v[130:133], off nt
	s_cbranch_vccnz .LBB0_1891
	v_readlane_b32 s84, v238, 32
	v_readlane_b32 s86, v238, 34
	v_readlane_b32 s87, v238, 35
	v_cvt_pk_bf16_f32 v84, v130, v131
	v_mul_f32_e32 v88, v131, v131
	v_cvt_pk_bf16_f32 v85, v132, v133
	v_fmac_f32_e32 v88, v130, v130
	v_lshl_add_u64 v[80:81], v[140:141], 1, s[86:87]
	global_store_dwordx2 v[80:81], v[84:85], off
	v_pk_fma_f32 v[130:131], v[90:91], v[180:181], v[122:123]
	v_cvt_pk_bf16_f32 v84, v128, v129
	global_store_dwordx4 v[138:139], v[128:131], off offset:64 nt
	v_cvt_pk_bf16_f32 v85, v130, v131
	global_store_dwordx2 v[80:81], v[84:85], off offset:32
	v_mul_f32_e32 v84, v129, v129
	v_fmac_f32_e32 v84, v128, v128
	v_fmac_f32_e32 v88, v132, v132
	v_fmac_f32_e32 v84, v130, v130
	v_fmac_f32_e32 v88, v133, v133
	v_fmac_f32_e32 v84, v131, v131
	v_add_f32_e32 v88, v88, v84
	v_pk_fma_f32 v[126:127], v[86:87], v[180:181], v[118:119]
	v_cvt_pk_bf16_f32 v84, v124, v125
	global_store_dwordx4 v[138:139], v[124:127], off offset:512 nt
	v_cvt_pk_bf16_f32 v85, v126, v127
	global_store_dwordx2 v[80:81], v[84:85], off offset:256
	v_mul_f32_e32 v84, v125, v125
	v_fmac_f32_e32 v84, v124, v124
	v_fmac_f32_e32 v84, v126, v126
	v_fmac_f32_e32 v84, v127, v127
	v_add_f32_e32 v88, v88, v84
	v_pk_fma_f32 v[94:95], v[82:83], v[180:181], v[114:115]
	v_cvt_pk_bf16_f32 v84, v92, v93
	global_store_dwordx4 v[138:139], v[92:95], off offset:576 nt
	v_cvt_pk_bf16_f32 v85, v94, v95
	global_store_dwordx2 v[80:81], v[84:85], off offset:288
	v_mul_f32_e32 v80, v93, v93
	v_and_b32_e32 v84, 64, v197
	v_fmac_f32_e32 v80, v92, v92
	v_xor_b32_e32 v81, 16, v197
	v_add_u32_e32 v84, 64, v84
	v_fmac_f32_e32 v80, v94, v94
	v_cmp_lt_i32_e32 vcc, v81, v84
	v_fmac_f32_e32 v80, v95, v95
	v_add_f32_e32 v80, v88, v80
	v_cndmask_b32_e32 v81, v197, v81, vcc
	v_lshlrev_b32_e32 v81, 2, v81
	ds_bpermute_b32 v81, v81, v80
	v_readlane_b32 s85, v238, 33
	s_waitcnt lgkmcnt(0)
	v_add_f32_e32 v80, v80, v81
	v_xor_b32_e32 v81, 32, v197
	v_cmp_lt_i32_e32 vcc, v81, v84
	s_nop 1
	v_cndmask_b32_e32 v81, v197, v81, vcc
	v_lshlrev_b32_e32 v81, 2, v81
	ds_bpermute_b32 v81, v81, v80
	s_and_saveexec_b64 s[16:17], s[34:35]
	s_cbranch_execz .LBB0_1863
	v_ashrrev_i32_e32 v151, 31, v150
	s_waitcnt lgkmcnt(0)
	v_add_f32_e32 v84, v80, v81
	v_lshlrev_b64 v[80:81], 7, v[150:151]
	v_lshl_add_u64 v[80:81], s[14:15], 0, v[80:81]
	global_store_dword v[80:81], v84, off

; DEVI unsigned pk_bf16(float lo, float hi) { unsigned r; asm("v_cvt_pk_bf16_f32 %0, %1, %2" : "=v"(r) : "v"(lo), "v"(hi)); return r; }
;     DEVI void operator()(const f32x4 (&acc)[2][2][4][2], const Unit& u, int wr, int wc, int fr, int fq, const LAS float*) const {
;     ...
;         for (int idx = 0; idx < 8; ++idx) {
;             const int ai = idx >> 2, m = idx & 3;
;             const size_t ro = (size_t)(row0 + ai * HALF + m * 16) * ldc + col0;
;             if (idx + 1 < 8) { const int ai2 = (idx + 1) >> 2, m2 = (idx + 1) & 3; const size_t ro2 = (size_t)(row0 + ai2 * HALF + m2 * 16) * ldc + col0;
; #pragma unroll
;                 for (int bj = 0; bj < 2; ++bj)
; #pragma unroll
;                     for (int n = 0; n < 2; ++n) nxt[bj][n] = *(const f32x4*)(R + ro2 + bj * HALF + n * 16); }
;             float ss = 0.f;
; #pragma unroll
;             for (int bj = 0; bj < 2; ++bj)
; #pragma unroll
;                 for (int n = 0; n < 2; ++n) {
;                     const f32x4 hn = cur[bj][n] + acc[ai][bj][m][n] * scale;
;                     *(f32x4*)(C + ro + bj * HALF + n * 16) = hn;
;                     if (HB) { u32x2 w; w.x = pk_bf16(hn[0], hn[1]); w.y = pk_bf16(hn[2], hn[3]); *(u32x2*)(HB + ro + bj * HALF + n * 16) = w;
;                         ss += hn[0] * hn[0] + hn[1] * hn[1] + hn[2] * hn[2] + hn[3] * hn[3]; } }
;             if (HB) { ss += __shfl_xor(ss, 16); ss += __shfl_xor(ss, 32); if (fq == 0) RS[(size_t)(row0 + ai * HALF + m * 16) * 32 + u.pn * 4 + wc] = ss; }
; #pragma unroll
;             for (int bj = 0; bj < 2; ++bj)
; #pragma unroll
;                 for (int n = 0; n < 2; ++n) cur[bj][n] = nxt[bj][n];
;         }
.LBB0_1865:
	v_add_u32_e32 v118, 0x80, v188
	v_mad_i64_i32 v[120:121], s[16:17], v118, s66, 0
	s_waitcnt lgkmcnt(0)
	v_lshl_add_u64 v[80:81], v[120:121], 2, v[186:187]
	global_load_dwordx4 v[92:95], v[80:81], off
	global_load_dwordx4 v[88:91], v[80:81], off offset:64
	global_load_dwordx4 v[84:87], v[80:81], off offset:512
	s_nop 0
	global_load_dwordx4 v[80:83], v[80:81], off offset:576
	v_readlane_b32 s84, v238, 24
	v_lshl_add_u64 v[124:125], v[136:137], 0, v[182:183]
	v_readlane_b32 s88, v238, 28
	v_readlane_b32 s89, v238, 29
	v_mov_b32_e32 v181, v180
	s_waitcnt vmcnt(8)
	v_pk_fma_f32 v[116:117], v[78:79], v[180:181], v[110:111]
	v_lshl_add_u64 v[122:123], v[124:125], 2, s[88:89]
	v_pk_fma_f32 v[114:115], v[76:77], v[184:185], v[108:109]
	s_and_b64 vcc, exec, s[38:39]
	s_waitcnt vmcnt(7)
	v_pk_fma_f32 v[112:113], v[72:73], v[184:185], v[104:105]
	s_waitcnt vmcnt(6)
	v_pk_fma_f32 v[108:109], v[68:69], v[184:185], v[100:101]
	s_waitcnt vmcnt(5)
	v_pk_fma_f32 v[76:77], v[64:65], v[184:185], v[96:97]
	v_readlane_b32 s85, v238, 25
	v_readlane_b32 s86, v238, 26
	v_readlane_b32 s87, v238, 27
	v_readlane_b32 s90, v238, 30
	v_readlane_b32 s91, v238, 31
	global_store_dwordx4 v[122:123], v[114:117], off nt
	s_cbranch_vccnz .LBB0_1892
	v_readlane_b32 s84, v238, 32
	v_readlane_b32 s86, v238, 34
	v_readlane_b32 s87, v238, 35
	v_cvt_pk_bf16_f32 v68, v114, v115
	v_mul_f32_e32 v72, v115, v115
	v_cvt_pk_bf16_f32 v69, v116, v117
	v_fmac_f32_e32 v72, v114, v114
	v_lshl_add_u64 v[64:65], v[124:125], 1, s[86:87]
	global_store_dwordx2 v[64:65], v[68:69], off
	v_pk_fma_f32 v[114:115], v[74:75], v[180:181], v[106:107]
	v_cvt_pk_bf16_f32 v68, v112, v113
	global_store_dwordx4 v[122:123], v[112:115], off offset:64 nt
	v_cvt_pk_bf16_f32 v69, v114, v115
	global_store_dwordx2 v[64:65], v[68:69], off offset:32
	v_mul_f32_e32 v68, v113, v113
	v_fmac_f32_e32 v68, v112, v112
	v_fmac_f32_e32 v72, v116, v116
	v_fmac_f32_e32 v68, v114, v114
	v_fmac_f32_e32 v72, v117, v117
	v_fmac_f32_e32 v68, v115, v115
	v_add_f32_e32 v72, v72, v68
	v_pk_fma_f32 v[110:111], v[70:71], v[180:181], v[102:103]
	v_cvt_pk_bf16_f32 v68, v108, v109
	global_store_dwordx4 v[122:123], v[108:111], off offset:512 nt
	v_cvt_pk_bf16_f32 v69, v110, v111
	global_store_dwordx2 v[64:65], v[68:69], off offset:256
	v_mul_f32_e32 v68, v109, v109
	v_fmac_f32_e32 v68, v108, v108
	v_fmac_f32_e32 v68, v110, v110
	v_fmac_f32_e32 v68, v111, v111
	v_add_f32_e32 v72, v72, v68
	v_pk_fma_f32 v[78:79], v[66:67], v[180:181], v[98:99]
	v_cvt_pk_bf16_f32 v68, v76, v77
	global_store_dwordx4 v[122:123], v[76:79], off offset:576 nt
	v_cvt_pk_bf16_f32 v69, v78, v79
	global_store_dwordx2 v[64:65], v[68:69], off offset:288
	v_mul_f32_e32 v64, v77, v77
	v_and_b32_e32 v68, 64, v197
	v_fmac_f32_e32 v64, v76, v76
	v_xor_b32_e32 v65, 16, v197
	v_add_u32_e32 v68, 64, v68
	v_fmac_f32_e32 v64, v78, v78
	v_cmp_lt_i32_e32 vcc, v65, v68
	v_fmac_f32_e32 v64, v79, v79
	v_add_f32_e32 v64, v72, v64
	v_cndmask_b32_e32 v65, v197, v65, vcc
	v_lshlrev_b32_e32 v65, 2, v65
	ds_bpermute_b32 v65, v65, v64
	v_readlane_b32 s85, v238, 33
	s_waitcnt lgkmcnt(0)
	v_add_f32_e32 v64, v64, v65
	v_xor_b32_e32 v65, 32, v197
	v_cmp_lt_i32_e32 vcc, v65, v68
	s_nop 1
	v_cndmask_b32_e32 v65, v197, v65, vcc
	v_lshlrev_b32_e32 v65, 2, v65
	ds_bpermute_b32 v65, v65, v64
	s_and_saveexec_b64 s[16:17], s[34:35]
	s_cbranch_execz .LBB0_1868
	v_ashrrev_i32_e32 v135, 31, v134
	s_waitcnt lgkmcnt(0)
	v_add_f32_e32 v68, v64, v65
	v_lshlrev_b64 v[64:65], 7, v[134:135]
	v_lshl_add_u64 v[64:65], s[14:15], 0, v[64:65]
	global_store_dword v[64:65], v68, off

; DEVI unsigned pk_bf16(float lo, float hi) { unsigned r; asm("v_cvt_pk_bf16_f32 %0, %1, %2" : "=v"(r) : "v"(lo), "v"(hi)); return r; }
;     DEVI void operator()(const f32x4 (&acc)[2][2][4][2], const Unit& u, int wr, int wc, int fr, int fq, const LAS float*) const {
;     ...
;         for (int idx = 0; idx < 8; ++idx) {
;             const int ai = idx >> 2, m = idx & 3;
;             const size_t ro = (size_t)(row0 + ai * HALF + m * 16) * ldc + col0;
;             if (idx + 1 < 8) { const int ai2 = (idx + 1) >> 2, m2 = (idx + 1) & 3; const size_t ro2 = (size_t)(row0 + ai2 * HALF + m2 * 16) * ldc + col0;
; #pragma unroll
;                 for (int bj = 0; bj < 2; ++bj)
; #pragma unroll
;                     for (int n = 0; n < 2; ++n) nxt[bj][n] = *(const f32x4*)(R + ro2 + bj * HALF + n * 16); }
;             float ss = 0.f;
; #pragma unroll
;             for (int bj = 0; bj < 2; ++bj)
; #pragma unroll
;                 for (int n = 0; n < 2; ++n) {
;                     const f32x4 hn = cur[bj][n] + acc[ai][bj][m][n] * scale;
;                     *(f32x4*)(C + ro + bj * HALF + n * 16) = hn;
;                     if (HB) { u32x2 w; w.x = pk_bf16(hn[0], hn[1]); w.y = pk_bf16(hn[2], hn[3]); *(u32x2*)(HB + ro + bj * HALF + n * 16) = w;
;                         ss += hn[0] * hn[0] + hn[1] * hn[1] + hn[2] * hn[2] + hn[3] * hn[3]; } }
;             if (HB) { ss += __shfl_xor(ss, 16); ss += __shfl_xor(ss, 32); if (fq == 0) RS[(size_t)(row0 + ai * HALF + m * 16) * 32 + u.pn * 4 + wc] = ss; }
; #pragma unroll
;             for (int bj = 0; bj < 2; ++bj)
; #pragma unroll
;                 for (int n = 0; n < 2; ++n) cur[bj][n] = nxt[bj][n];
;         }
.LBB0_1870:
	v_or_b32_e32 v102, 16, v118
	v_mad_i64_i32 v[104:105], s[16:17], v102, s66, 0
	s_waitcnt lgkmcnt(0)
	v_lshl_add_u64 v[64:65], v[104:105], 2, v[186:187]
	global_load_dwordx4 v[76:79], v[64:65], off
	global_load_dwordx4 v[72:75], v[64:65], off offset:64
	global_load_dwordx4 v[68:71], v[64:65], off offset:512
	s_nop 0
	global_load_dwordx4 v[64:67], v[64:65], off offset:576
	v_readlane_b32 s84, v238, 24
	v_lshl_add_u64 v[108:109], v[120:121], 0, v[182:183]
	v_readlane_b32 s88, v238, 28
	v_readlane_b32 s89, v238, 29
	v_mov_b32_e32 v181, v180
	v_ashrrev_i32_e32 v119, 31, v118
	v_lshl_add_u64 v[106:107], v[108:109], 2, s[88:89]
	s_waitcnt vmcnt(8)
	v_pk_fma_f32 v[100:101], v[62:63], v[180:181], v[94:95]
	v_pk_fma_f32 v[98:99], v[60:61], v[184:185], v[92:93]
	s_and_b64 vcc, exec, s[38:39]
	s_waitcnt vmcnt(7)
	v_pk_fma_f32 v[96:97], v[56:57], v[184:185], v[88:89]
	s_waitcnt vmcnt(6)
	v_pk_fma_f32 v[92:93], v[52:53], v[184:185], v[84:85]
	s_waitcnt vmcnt(5)
	v_pk_fma_f32 v[60:61], v[48:49], v[184:185], v[80:81]
	v_readlane_b32 s85, v238, 25
	v_readlane_b32 s86, v238, 26
	v_readlane_b32 s87, v238, 27
	v_readlane_b32 s90, v238, 30
	v_readlane_b32 s91, v238, 31
	global_store_dwordx4 v[106:107], v[98:101], off nt
	s_cbranch_vccnz .LBB0_1893
	v_readlane_b32 s84, v238, 32
	v_readlane_b32 s86, v238, 34
	v_readlane_b32 s87, v238, 35
	v_cvt_pk_bf16_f32 v52, v98, v99
	v_mul_f32_e32 v56, v99, v99
	v_cvt_pk_bf16_f32 v53, v100, v101
	v_fmac_f32_e32 v56, v98, v98
	v_lshl_add_u64 v[48:49], v[108:109], 1, s[86:87]
	global_store_dwordx2 v[48:49], v[52:53], off
	v_pk_fma_f32 v[98:99], v[58:59], v[180:181], v[90:91]
	v_cvt_pk_bf16_f32 v52, v96, v97
	global_store_dwordx4 v[106:107], v[96:99], off offset:64 nt
	v_cvt_pk_bf16_f32 v53, v98, v99
	global_store_dwordx2 v[48:49], v[52:53], off offset:32
	v_mul_f32_e32 v52, v97, v97
	v_fmac_f32_e32 v52, v96, v96
	v_fmac_f32_e32 v56, v100, v100
	v_fmac_f32_e32 v52, v98, v98
	v_fmac_f32_e32 v56, v101, v101
	v_fmac_f32_e32 v52, v99, v99
	v_add_f32_e32 v56, v56, v52
	v_pk_fma_f32 v[94:95], v[54:55], v[180:181], v[86:87]
	v_cvt_pk_bf16_f32 v52, v92, v93
	global_store_dwordx4 v[106:107], v[92:95], off offset:512 nt
	v_cvt_pk_bf16_f32 v53, v94, v95
	global_store_dwordx2 v[48:49], v[52:53], off offset:256
	v_mul_f32_e32 v52, v93, v93
	v_fmac_f32_e32 v52, v92, v92
	v_fmac_f32_e32 v52, v94, v94
	v_fmac_f32_e32 v52, v95, v95
	v_add_f32_e32 v56, v56, v52
	v_pk_fma_f32 v[62:63], v[50:51], v[180:181], v[82:83]
	v_cvt_pk_bf16_f32 v52, v60, v61
	global_store_dwordx4 v[106:107], v[60:63], off offset:576 nt
	v_cvt_pk_bf16_f32 v53, v62, v63
	global_store_dwordx2 v[48:49], v[52:53], off offset:288
	v_mul_f32_e32 v48, v61, v61
	v_and_b32_e32 v52, 64, v197
	v_fmac_f32_e32 v48, v60, v60
	v_xor_b32_e32 v49, 16, v197
	v_add_u32_e32 v52, 64, v52
	v_fmac_f32_e32 v48, v62, v62
	v_cmp_lt_i32_e32 vcc, v49, v52
	v_fmac_f32_e32 v48, v63, v63
	v_add_f32_e32 v48, v56, v48
	v_cndmask_b32_e32 v49, v197, v49, vcc
	v_lshlrev_b32_e32 v49, 2, v49
	ds_bpermute_b32 v49, v49, v48
	v_readlane_b32 s85, v238, 33
	s_waitcnt lgkmcnt(0)
	v_add_f32_e32 v48, v48, v49
	v_xor_b32_e32 v49, 32, v197
	v_cmp_lt_i32_e32 vcc, v49, v52
	s_nop 1
	v_cndmask_b32_e32 v49, v197, v49, vcc
	v_lshlrev_b32_e32 v49, 2, v49
	ds_bpermute_b32 v49, v49, v48
	s_and_saveexec_b64 s[16:17], s[34:35]
	s_cbranch_execz .LBB0_1873
	s_waitcnt lgkmcnt(0)
	v_add_f32_e32 v52, v48, v49
	v_lshlrev_b64 v[48:49], 7, v[118:119]
	v_lshl_add_u64 v[48:49], s[14:15], 0, v[48:49]
	global_store_dword v[48:49], v52, off

; DEVI unsigned pk_bf16(float lo, float hi) { unsigned r; asm("v_cvt_pk_bf16_f32 %0, %1, %2" : "=v"(r) : "v"(lo), "v"(hi)); return r; }
;     DEVI void operator()(const f32x4 (&acc)[2][2][4][2], const Unit& u, int wr, int wc, int fr, int fq, const LAS float*) const {
;     ...
;         for (int idx = 0; idx < 8; ++idx) {
;             const int ai = idx >> 2, m = idx & 3;
;             const size_t ro = (size_t)(row0 + ai * HALF + m * 16) * ldc + col0;
;             if (idx + 1 < 8) { const int ai2 = (idx + 1) >> 2, m2 = (idx + 1) & 3; const size_t ro2 = (size_t)(row0 + ai2 * HALF + m2 * 16) * ldc + col0;
; #pragma unroll
;                 for (int bj = 0; bj < 2; ++bj)
; #pragma unroll
;                     for (int n = 0; n < 2; ++n) nxt[bj][n] = *(const f32x4*)(R + ro2 + bj * HALF + n * 16); }
;             float ss = 0.f;
; #pragma unroll
;             for (int bj = 0; bj < 2; ++bj)
; #pragma unroll
;                 for (int n = 0; n < 2; ++n) {
;                     const f32x4 hn = cur[bj][n] + acc[ai][bj][m][n] * scale;
;                     *(f32x4*)(C + ro + bj * HALF + n * 16) = hn;
;                     if (HB) { u32x2 w; w.x = pk_bf16(hn[0], hn[1]); w.y = pk_bf16(hn[2], hn[3]); *(u32x2*)(HB + ro + bj * HALF + n * 16) = w;
;                         ss += hn[0] * hn[0] + hn[1] * hn[1] + hn[2] * hn[2] + hn[3] * hn[3]; } }
;             if (HB) { ss += __shfl_xor(ss, 16); ss += __shfl_xor(ss, 32); if (fq == 0) RS[(size_t)(row0 + ai * HALF + m * 16) * 32 + u.pn * 4 + wc] = ss; }
; #pragma unroll
;             for (int bj = 0; bj < 2; ++bj)
; #pragma unroll
;                 for (int n = 0; n < 2; ++n) cur[bj][n] = nxt[bj][n];
;         }
.LBB0_1875:
	v_or_b32_e32 v86, 32, v118
	v_mad_i64_i32 v[88:89], s[16:17], v86, s66, 0
	s_waitcnt lgkmcnt(0)
	v_lshl_add_u64 v[48:49], v[88:89], 2, v[186:187]
	global_load_dwordx4 v[60:63], v[48:49], off
	global_load_dwordx4 v[56:59], v[48:49], off offset:64
	global_load_dwordx4 v[52:55], v[48:49], off offset:512
	s_nop 0
	global_load_dwordx4 v[48:51], v[48:49], off offset:576
	v_readlane_b32 s84, v238, 24
	v_lshl_add_u64 v[92:93], v[104:105], 0, v[182:183]
	v_readlane_b32 s88, v238, 28
	v_readlane_b32 s89, v238, 29
	v_mov_b32_e32 v181, v180
	s_waitcnt vmcnt(8)
	v_pk_fma_f32 v[84:85], v[46:47], v[180:181], v[78:79]
	v_lshl_add_u64 v[90:91], v[92:93], 2, s[88:89]
	v_pk_fma_f32 v[82:83], v[44:45], v[184:185], v[76:77]
	s_and_b64 vcc, exec, s[38:39]
	s_waitcnt vmcnt(7)
	v_pk_fma_f32 v[80:81], v[40:41], v[184:185], v[72:73]
	s_waitcnt vmcnt(6)
	v_pk_fma_f32 v[76:77], v[36:37], v[184:185], v[68:69]
	s_waitcnt vmcnt(5)
	v_pk_fma_f32 v[44:45], v[32:33], v[184:185], v[64:65]
	v_readlane_b32 s85, v238, 25
	v_readlane_b32 s86, v238, 26
	v_readlane_b32 s87, v238, 27
	v_readlane_b32 s90, v238, 30
	v_readlane_b32 s91, v238, 31
	global_store_dwordx4 v[90:91], v[82:85], off nt
	s_cbranch_vccnz .LBB0_1894
	v_readlane_b32 s84, v238, 32
	v_readlane_b32 s86, v238, 34
	v_readlane_b32 s87, v238, 35
	v_cvt_pk_bf16_f32 v36, v82, v83
	v_mul_f32_e32 v40, v83, v83
	v_cvt_pk_bf16_f32 v37, v84, v85
	v_fmac_f32_e32 v40, v82, v82
	v_lshl_add_u64 v[32:33], v[92:93], 1, s[86:87]
	global_store_dwordx2 v[32:33], v[36:37], off
	v_pk_fma_f32 v[82:83], v[42:43], v[180:181], v[74:75]
	v_cvt_pk_bf16_f32 v36, v80, v81
	global_store_dwordx4 v[90:91], v[80:83], off offset:64 nt
	v_cvt_pk_bf16_f32 v37, v82, v83
	global_store_dwordx2 v[32:33], v[36:37], off offset:32
	v_mul_f32_e32 v36, v81, v81
	v_fmac_f32_e32 v36, v80, v80
	v_fmac_f32_e32 v40, v84, v84
	v_fmac_f32_e32 v36, v82, v82
	v_fmac_f32_e32 v40, v85, v85
	v_fmac_f32_e32 v36, v83, v83
	v_add_f32_e32 v40, v40, v36
	v_pk_fma_f32 v[78:79], v[38:39], v[180:181], v[70:71]
	v_cvt_pk_bf16_f32 v36, v76, v77
	global_store_dwordx4 v[90:91], v[76:79], off offset:512 nt
	v_cvt_pk_bf16_f32 v37, v78, v79
	global_store_dwordx2 v[32:33], v[36:37], off offset:256
	v_mul_f32_e32 v36, v77, v77
	v_fmac_f32_e32 v36, v76, v76
	v_fmac_f32_e32 v36, v78, v78
	v_fmac_f32_e32 v36, v79, v79
	v_add_f32_e32 v40, v40, v36
	v_pk_fma_f32 v[46:47], v[34:35], v[180:181], v[66:67]
	v_cvt_pk_bf16_f32 v36, v44, v45
	global_store_dwordx4 v[90:91], v[44:47], off offset:576 nt
	v_cvt_pk_bf16_f32 v37, v46, v47
	global_store_dwordx2 v[32:33], v[36:37], off offset:288
	v_mul_f32_e32 v32, v45, v45
	v_and_b32_e32 v36, 64, v197
	v_fmac_f32_e32 v32, v44, v44
	v_xor_b32_e32 v33, 16, v197
	v_add_u32_e32 v36, 64, v36
	v_fmac_f32_e32 v32, v46, v46
	v_cmp_lt_i32_e32 vcc, v33, v36
	v_fmac_f32_e32 v32, v47, v47
	v_add_f32_e32 v32, v40, v32
	v_cndmask_b32_e32 v33, v197, v33, vcc
	v_lshlrev_b32_e32 v33, 2, v33
	ds_bpermute_b32 v33, v33, v32
	v_readlane_b32 s85, v238, 33
	s_waitcnt lgkmcnt(0)
	v_add_f32_e32 v32, v32, v33
	v_xor_b32_e32 v33, 32, v197
	v_cmp_lt_i32_e32 vcc, v33, v36
	s_nop 1
	v_cndmask_b32_e32 v33, v197, v33, vcc
	v_lshlrev_b32_e32 v33, 2, v33
	ds_bpermute_b32 v33, v33, v32
	s_and_saveexec_b64 s[16:17], s[34:35]
	s_cbranch_execz .LBB0_1878
	v_ashrrev_i32_e32 v103, 31, v102
	s_waitcnt lgkmcnt(0)
	v_add_f32_e32 v36, v32, v33
	v_lshlrev_b64 v[32:33], 7, v[102:103]
	v_lshl_add_u64 v[32:33], s[14:15], 0, v[32:33]
	global_store_dword v[32:33], v36, off

; DEVI unsigned pk_bf16(float lo, float hi) { unsigned r; asm("v_cvt_pk_bf16_f32 %0, %1, %2" : "=v"(r) : "v"(lo), "v"(hi)); return r; }
;     DEVI void operator()(const f32x4 (&acc)[2][2][4][2], const Unit& u, int wr, int wc, int fr, int fq, const LAS float*) const {
;     ...
;         for (int idx = 0; idx < 8; ++idx) {
;             const int ai = idx >> 2, m = idx & 3;
;             const size_t ro = (size_t)(row0 + ai * HALF + m * 16) * ldc + col0;
;             if (idx + 1 < 8) { const int ai2 = (idx + 1) >> 2, m2 = (idx + 1) & 3; const size_t ro2 = (size_t)(row0 + ai2 * HALF + m2 * 16) * ldc + col0;
; #pragma unroll
;                 for (int bj = 0; bj < 2; ++bj)
; #pragma unroll
;                     for (int n = 0; n < 2; ++n) nxt[bj][n] = *(const f32x4*)(R + ro2 + bj * HALF + n * 16); }
;             float ss = 0.f;
; #pragma unroll
;             for (int bj = 0; bj < 2; ++bj)
; #pragma unroll
;                 for (int n = 0; n < 2; ++n) {
;                     const f32x4 hn = cur[bj][n] + acc[ai][bj][m][n] * scale;
;                     *(f32x4*)(C + ro + bj * HALF + n * 16) = hn;
;                     if (HB) { u32x2 w; w.x = pk_bf16(hn[0], hn[1]); w.y = pk_bf16(hn[2], hn[3]); *(u32x2*)(HB + ro + bj * HALF + n * 16) = w;
;                         ss += hn[0] * hn[0] + hn[1] * hn[1] + hn[2] * hn[2] + hn[3] * hn[3]; } }
;             if (HB) { ss += __shfl_xor(ss, 16); ss += __shfl_xor(ss, 32); if (fq == 0) RS[(size_t)(row0 + ai * HALF + m * 16) * 32 + u.pn * 4 + wc] = ss; }
; #pragma unroll
;             for (int bj = 0; bj < 2; ++bj)
; #pragma unroll
;                 for (int n = 0; n < 2; ++n) cur[bj][n] = nxt[bj][n];
;         }
.LBB0_1880:
	v_or_b32_e32 v70, 48, v118
	v_mad_i64_i32 v[72:73], s[16:17], v70, s66, 0
	s_waitcnt lgkmcnt(0)
	v_lshl_add_u64 v[32:33], v[72:73], 2, v[186:187]
	global_load_dwordx4 v[44:47], v[32:33], off
	global_load_dwordx4 v[40:43], v[32:33], off offset:64
	global_load_dwordx4 v[36:39], v[32:33], off offset:512
	s_nop 0
	global_load_dwordx4 v[32:35], v[32:33], off offset:576
	v_readlane_b32 s84, v238, 24
	v_lshl_add_u64 v[76:77], v[88:89], 0, v[182:183]
	v_readlane_b32 s88, v238, 28
	v_readlane_b32 s89, v238, 29
	v_mov_b32_e32 v181, v180
	s_waitcnt vmcnt(8)
	v_pk_fma_f32 v[68:69], v[30:31], v[180:181], v[62:63]
	v_lshl_add_u64 v[74:75], v[76:77], 2, s[88:89]
	v_pk_fma_f32 v[66:67], v[28:29], v[184:185], v[60:61]
	s_and_b64 vcc, exec, s[38:39]
	s_waitcnt vmcnt(7)
	v_pk_fma_f32 v[64:65], v[24:25], v[184:185], v[56:57]
	s_waitcnt vmcnt(6)
	v_pk_fma_f32 v[60:61], v[20:21], v[184:185], v[52:53]
	s_waitcnt vmcnt(5)
	v_pk_fma_f32 v[28:29], v[16:17], v[184:185], v[48:49]
	v_readlane_b32 s85, v238, 25
	v_readlane_b32 s86, v238, 26
	v_readlane_b32 s87, v238, 27
	v_readlane_b32 s90, v238, 30
	v_readlane_b32 s91, v238, 31
	global_store_dwordx4 v[74:75], v[66:69], off nt
	s_cbranch_vccnz .LBB0_1895
	v_readlane_b32 s84, v238, 32
	v_readlane_b32 s86, v238, 34
	v_readlane_b32 s87, v238, 35
	v_cvt_pk_bf16_f32 v20, v66, v67
	v_mul_f32_e32 v24, v67, v67
	v_cvt_pk_bf16_f32 v21, v68, v69
	v_fmac_f32_e32 v24, v66, v66
	v_lshl_add_u64 v[16:17], v[76:77], 1, s[86:87]
	global_store_dwordx2 v[16:17], v[20:21], off
	v_pk_fma_f32 v[66:67], v[26:27], v[180:181], v[58:59]
	v_cvt_pk_bf16_f32 v20, v64, v65
	global_store_dwordx4 v[74:75], v[64:67], off offset:64 nt
	v_cvt_pk_bf16_f32 v21, v66, v67
	global_store_dwordx2 v[16:17], v[20:21], off offset:32
	v_mul_f32_e32 v20, v65, v65
	v_fmac_f32_e32 v20, v64, v64
	v_fmac_f32_e32 v24, v68, v68
	v_fmac_f32_e32 v20, v66, v66
	v_fmac_f32_e32 v24, v69, v69
	v_fmac_f32_e32 v20, v67, v67
	v_add_f32_e32 v24, v24, v20
	v_pk_fma_f32 v[62:63], v[22:23], v[180:181], v[54:55]
	v_cvt_pk_bf16_f32 v20, v60, v61
	global_store_dwordx4 v[74:75], v[60:63], off offset:512 nt
	v_cvt_pk_bf16_f32 v21, v62, v63
	global_store_dwordx2 v[16:17], v[20:21], off offset:256
	v_mul_f32_e32 v20, v61, v61
	v_fmac_f32_e32 v20, v60, v60
	v_fmac_f32_e32 v20, v62, v62
	v_fmac_f32_e32 v20, v63, v63
	v_add_f32_e32 v24, v24, v20
	v_pk_fma_f32 v[30:31], v[18:19], v[180:181], v[50:51]
	v_cvt_pk_bf16_f32 v20, v28, v29
	global_store_dwordx4 v[74:75], v[28:31], off offset:576 nt
	v_cvt_pk_bf16_f32 v21, v30, v31
	global_store_dwordx2 v[16:17], v[20:21], off offset:288
	v_mul_f32_e32 v16, v29, v29
	v_and_b32_e32 v20, 64, v197
	v_fmac_f32_e32 v16, v28, v28
	v_xor_b32_e32 v17, 16, v197
	v_add_u32_e32 v20, 64, v20
	v_fmac_f32_e32 v16, v30, v30
	v_cmp_lt_i32_e32 vcc, v17, v20
	v_fmac_f32_e32 v16, v31, v31
	v_add_f32_e32 v16, v24, v16
	v_cndmask_b32_e32 v17, v197, v17, vcc
	v_lshlrev_b32_e32 v17, 2, v17
	ds_bpermute_b32 v17, v17, v16
	v_readlane_b32 s85, v238, 33
	s_waitcnt lgkmcnt(0)
	v_add_f32_e32 v16, v16, v17
	v_xor_b32_e32 v17, 32, v197
	v_cmp_lt_i32_e32 vcc, v17, v20
	s_nop 1
	v_cndmask_b32_e32 v17, v197, v17, vcc
	v_lshlrev_b32_e32 v17, 2, v17
	ds_bpermute_b32 v17, v17, v16
	s_and_saveexec_b64 s[16:17], s[34:35]
	s_cbranch_execz .LBB0_1883
	v_ashrrev_i32_e32 v87, 31, v86
	s_waitcnt lgkmcnt(0)
	v_add_f32_e32 v20, v16, v17
	v_lshlrev_b64 v[16:17], 7, v[86:87]
	v_lshl_add_u64 v[16:17], s[14:15], 0, v[16:17]
	global_store_dword v[16:17], v20, off

; DEVI unsigned pk_bf16(float lo, float hi) { unsigned r; asm("v_cvt_pk_bf16_f32 %0, %1, %2" : "=v"(r) : "v"(lo), "v"(hi)); return r; }
;     DEVI void operator()(const f32x4 (&acc)[2][2][4][2], const Unit& u, int wr, int wc, int fr, int fq, const LAS float*) const {
;     ...
;             float ss = 0.f;
; #pragma unroll
;             for (int bj = 0; bj < 2; ++bj)
; #pragma unroll
;                 for (int n = 0; n < 2; ++n) {
;                     const f32x4 hn = cur[bj][n] + acc[ai][bj][m][n] * scale;
;                     *(f32x4*)(C + ro + bj * HALF + n * 16) = hn;
;                     if (HB) { u32x2 w; w.x = pk_bf16(hn[0], hn[1]); w.y = pk_bf16(hn[2], hn[3]); *(u32x2*)(HB + ro + bj * HALF + n * 16) = w;
;                         ss += hn[0] * hn[0] + hn[1] * hn[1] + hn[2] * hn[2] + hn[3] * hn[3]; } }
;             if (HB) { ss += __shfl_xor(ss, 16); ss += __shfl_xor(ss, 32); if (fq == 0) RS[(size_t)(row0 + ai * HALF + m * 16) * 32 + u.pn * 4 + wc] = ss; }
; #pragma unroll
;             for (int bj = 0; bj < 2; ++bj)
; #pragma unroll
;                 for (int n = 0; n < 2; ++n) cur[bj][n] = nxt[bj][n];
;         }
.LBB0_1885:
	v_readlane_b32 s84, v238, 24
	v_lshl_add_u64 v[18:19], v[72:73], 0, v[182:183]
	v_readlane_b32 s88, v238, 28
	v_readlane_b32 s89, v238, 29
	v_mov_b32_e32 v181, v180
	s_waitcnt vmcnt(4)
	v_pk_fma_f32 v[24:25], v[14:15], v[180:181], v[46:47]
	v_lshl_add_u64 v[26:27], v[18:19], 2, s[88:89]
	v_pk_fma_f32 v[22:23], v[12:13], v[184:185], v[44:45]
	s_and_b64 vcc, exec, s[38:39]
	s_waitcnt vmcnt(3)
	v_pk_fma_f32 v[20:21], v[8:9], v[184:185], v[40:41]
	s_waitcnt vmcnt(2) lgkmcnt(0)
	v_pk_fma_f32 v[16:17], v[4:5], v[184:185], v[36:37]
	s_waitcnt vmcnt(1)
	v_pk_fma_f32 v[12:13], v[0:1], v[184:185], v[32:33]
	v_readlane_b32 s85, v238, 25
	v_readlane_b32 s86, v238, 26
	v_readlane_b32 s87, v238, 27
	v_readlane_b32 s90, v238, 30
	v_readlane_b32 s91, v238, 31
	global_store_dwordx4 v[26:27], v[22:25], off nt
	s_cbranch_vccnz .LBB0_1896
	v_readlane_b32 s84, v238, 32
	v_readlane_b32 s86, v238, 34
	v_readlane_b32 s87, v238, 35
	v_cvt_pk_bf16_f32 v4, v22, v23
	v_mul_f32_e32 v8, v23, v23
	v_cvt_pk_bf16_f32 v5, v24, v25
	v_fmac_f32_e32 v8, v22, v22
	v_lshl_add_u64 v[0:1], v[18:19], 1, s[86:87]
	global_store_dwordx2 v[0:1], v[4:5], off
	v_pk_fma_f32 v[22:23], v[10:11], v[180:181], v[42:43]
	v_cvt_pk_bf16_f32 v4, v20, v21
	global_store_dwordx4 v[26:27], v[20:23], off offset:64 nt
	v_cvt_pk_bf16_f32 v5, v22, v23
	global_store_dwordx2 v[0:1], v[4:5], off offset:32
	v_mul_f32_e32 v4, v21, v21
	v_fmac_f32_e32 v4, v20, v20
	v_fmac_f32_e32 v8, v24, v24
	v_fmac_f32_e32 v4, v22, v22
	v_fmac_f32_e32 v8, v25, v25
	v_fmac_f32_e32 v4, v23, v23
	v_add_f32_e32 v8, v8, v4
	v_pk_fma_f32 v[18:19], v[6:7], v[180:181], v[38:39]
	v_cvt_pk_bf16_f32 v4, v16, v17
	global_store_dwordx4 v[26:27], v[16:19], off offset:512 nt
	v_cvt_pk_bf16_f32 v5, v18, v19
	global_store_dwordx2 v[0:1], v[4:5], off offset:256
	v_mul_f32_e32 v4, v17, v17
	v_fmac_f32_e32 v4, v16, v16
	v_fmac_f32_e32 v4, v18, v18
	v_fmac_f32_e32 v4, v19, v19
	v_add_f32_e32 v8, v8, v4
	v_pk_fma_f32 v[14:15], v[2:3], v[180:181], v[34:35]
	v_cvt_pk_bf16_f32 v4, v12, v13
	global_store_dwordx4 v[26:27], v[12:15], off offset:576 nt
	v_cvt_pk_bf16_f32 v5, v14, v15
	global_store_dwordx2 v[0:1], v[4:5], off offset:288
	v_mul_f32_e32 v0, v13, v13
	v_and_b32_e32 v4, 64, v197
	v_fmac_f32_e32 v0, v12, v12
	v_xor_b32_e32 v1, 16, v197
	v_add_u32_e32 v4, 64, v4
	v_fmac_f32_e32 v0, v14, v14
	v_cmp_lt_i32_e32 vcc, v1, v4
	v_fmac_f32_e32 v0, v15, v15
	v_add_f32_e32 v0, v8, v0
	v_cndmask_b32_e32 v1, v197, v1, vcc
	v_lshlrev_b32_e32 v1, 2, v1
	ds_bpermute_b32 v1, v1, v0
	v_readlane_b32 s85, v238, 33
	s_waitcnt lgkmcnt(0)
	v_add_f32_e32 v0, v0, v1
	v_xor_b32_e32 v1, 32, v197
	v_cmp_lt_i32_e32 vcc, v1, v4
	s_nop 1
	v_cndmask_b32_e32 v1, v197, v1, vcc
	v_lshlrev_b32_e32 v1, 2, v1
	ds_bpermute_b32 v1, v1, v0
	s_and_saveexec_b64 s[16:17], s[34:35]
	s_cbranch_execz .LBB0_1888
	v_ashrrev_i32_e32 v71, 31, v70
	s_waitcnt lgkmcnt(0)
	v_add_f32_e32 v4, v0, v1
	v_lshlrev_b64 v[0:1], 7, v[70:71]
	v_lshl_add_u64 v[0:1], s[14:15], 0, v[0:1]
	global_store_dword v[0:1], v4, off

; DEVI unsigned pk_bf16(float lo, float hi) { unsigned r; asm("v_cvt_pk_bf16_f32 %0, %1, %2" : "=v"(r) : "v"(lo), "v"(hi)); return r; }
;     DEVI void operator()(const f32x4 (&acc)[2][2][4][2], const Unit& u, int wr, int wc, int fr, int fq, const LAS float*) const {
;     ...
;         const int row0 = u.pm * BM + wr * 64 + fr, col0 = u.pn * BM + wc * 32 + 4 * fq;
;         f32x4 cur[2][2], nxt[2][2];
;         { const size_t ro = (size_t)row0 * ldc + col0;
; #pragma unroll
;           for (int bj = 0; bj < 2; ++bj)
; #pragma unroll
;               for (int n = 0; n < 2; ++n) cur[bj][n] = *(const f32x4*)(R + ro + bj * HALF + n * 16); }
; #pragma unroll
;         for (int idx = 0; idx < 8; ++idx) {
;             const int ai = idx >> 2, m = idx & 3;
;             const size_t ro = (size_t)(row0 + ai * HALF + m * 16) * ldc + col0;
;             if (idx + 1 < 8) { const int ai2 = (idx + 1) >> 2, m2 = (idx + 1) & 3; const size_t ro2 = (size_t)(row0 + ai2 * HALF + m2 * 16) * ldc + col0;
; #pragma unroll
;                 for (int bj = 0; bj < 2; ++bj)
; #pragma unroll
;                     for (int n = 0; n < 2; ++n) nxt[bj][n] = *(const f32x4*)(R + ro2 + bj * HALF + n * 16); }
;             float ss = 0.f;
; #pragma unroll
;             for (int bj = 0; bj < 2; ++bj)
; #pragma unroll
;                 for (int n = 0; n < 2; ++n) {
;                     const f32x4 hn = cur[bj][n] + acc[ai][bj][m][n] * scale;
;                     *(f32x4*)(C + ro + bj * HALF + n * 16) = hn;
;                     if (HB) { u32x2 w; w.x = pk_bf16(hn[0], hn[1]); w.y = pk_bf16(hn[2], hn[3]); *(u32x2*)(HB + ro + bj * HALF + n * 16) = w;
;                         ss += hn[0] * hn[0] + hn[1] * hn[1] + hn[2] * hn[2] + hn[3] * hn[3]; } }
;             if (HB) { ss += __shfl_xor(ss, 16); ss += __shfl_xor(ss, 32); if (fq == 0) RS[(size_t)(row0 + ai * HALF + m * 16) * 32 + u.pn * 4 + wc] = ss; }
; #pragma unroll
;             for (int bj = 0; bj < 2; ++bj)
; #pragma unroll
;                 for (int n = 0; n < 2; ++n) cur[bj][n] = nxt[bj][n];
;         }
.LBB0_2367:
	v_readlane_b32 s60, v241, 14
	v_readlane_b32 s61, v241, 15
	v_readlane_b32 s62, v241, 16
	v_readlane_b32 s63, v241, 17
	v_lshl_add_u32 v188, s57, 8, v198
	v_lshl_or_b32 v182, s31, 8, v200
	s_mov_b32 s38, s62
	v_readlane_b32 s60, v238, 37
	v_mad_i64_i32 v[128:129], s[14:15], v188, s38, 0
	v_ashrrev_i32_e32 v183, 31, v182
	v_readlane_b32 s66, v238, 43
	v_readlane_b32 s67, v238, 44
	v_lshlrev_b64 v[130:131], 2, v[182:183]
	v_or_b32_e32 v190, 16, v188
	v_lshl_add_u64 v[128:129], v[128:129], 2, s[66:67]
	v_mov_b32_e32 v180, v204
	v_lshl_add_u64 v[128:129], v[128:129], 0, v[130:131]
	v_lshl_add_u64 v[186:187], s[66:67], 0, v[130:131]
	v_mad_i64_i32 v[192:193], s[16:17], v190, s38, 0
	global_load_dwordx4 v[160:163], v[128:129], off
	global_load_dwordx4 v[152:155], v[128:129], off offset:64
	global_load_dwordx4 v[148:151], v[128:129], off offset:512
	global_load_dwordx4 v[144:147], v[128:129], off offset:576
	v_lshl_add_u64 v[128:129], v[192:193], 2, v[186:187]
	global_load_dwordx4 v[140:143], v[128:129], off
	global_load_dwordx4 v[136:139], v[128:129], off offset:64
	global_load_dwordx4 v[132:135], v[128:129], off offset:512
	s_nop 0
	global_load_dwordx4 v[128:131], v[128:129], off offset:576
	s_lshl_b32 s14, s31, 2
	s_ashr_i32 s15, s14, 31
	s_lshl_b64 s[14:15], s[14:15], 2
	v_readlane_b32 s64, v238, 41
	v_readlane_b32 s65, v238, 42
	v_mov_b32_e32 v184, v180
	v_mov_b32_e32 v185, v180
	s_add_u32 s14, s4, s14
	s_waitcnt vmcnt(0)
	v_mad_i64_i32 v[158:159], s[16:17], v188, s38, v[182:183]
	v_ashrrev_i32_e32 v189, 31, v188
	s_addc_u32 s15, s5, s15
	v_lshl_add_u64 v[194:195], v[158:159], 2, s[64:65]
	s_andn2_b64 vcc, exec, s[46:47]
	v_readlane_b32 s61, v238, 38
	v_readlane_b32 s62, v238, 39
	v_readlane_b32 s63, v238, 40
	v_pk_fma_f32 v[164:165], v[126:127], v[180:181], v[162:163] op_sel_hi:[1,0,1]
	v_pk_fma_f32 v[162:163], v[124:125], v[180:181], v[160:161] op_sel_hi:[1,0,1]
	v_cndmask_b32_e64 v124, 0, 1, s[46:47]
	v_cmp_ne_u32_e64 s[38:39], 1, v124
	v_pk_fma_f32 v[160:161], v[120:121], v[184:185], v[152:153]
	v_pk_fma_f32 v[156:157], v[116:117], v[184:185], v[148:149]
	v_pk_fma_f32 v[124:125], v[112:113], v[184:185], v[144:145]
	global_store_dwordx4 v[194:195], v[162:165], off nt
	s_cbranch_vccnz .LBB0_2406
	v_readlane_b32 s60, v238, 45
	v_readlane_b32 s62, v238, 47
	v_readlane_b32 s63, v238, 48
	v_cvt_pk_bf16_f32 v116, v162, v163
	v_mul_f32_e32 v120, v163, v163
	v_mov_b32_e32 v181, v180
	v_lshl_add_u64 v[112:113], v[158:159], 1, s[62:63]
	v_cvt_pk_bf16_f32 v117, v164, v165
	global_store_dwordx2 v[112:113], v[116:117], off
	v_fmac_f32_e32 v120, v162, v162
	v_pk_fma_f32 v[162:163], v[122:123], v[180:181], v[154:155]
	v_cvt_pk_bf16_f32 v116, v160, v161
	global_store_dwordx4 v[194:195], v[160:163], off offset:64 nt
	v_cvt_pk_bf16_f32 v117, v162, v163
	global_store_dwordx2 v[112:113], v[116:117], off offset:32
	v_mul_f32_e32 v116, v161, v161
	v_fmac_f32_e32 v116, v160, v160
	v_fmac_f32_e32 v120, v164, v164
	v_fmac_f32_e32 v116, v162, v162
	v_fmac_f32_e32 v120, v165, v165
	v_fmac_f32_e32 v116, v163, v163
	v_add_f32_e32 v120, v120, v116
	v_pk_fma_f32 v[158:159], v[118:119], v[180:181], v[150:151]
	v_cvt_pk_bf16_f32 v116, v156, v157
	global_store_dwordx4 v[194:195], v[156:159], off offset:512 nt
	v_cvt_pk_bf16_f32 v117, v158, v159
	global_store_dwordx2 v[112:113], v[116:117], off offset:256
	v_mul_f32_e32 v116, v157, v157
	v_fmac_f32_e32 v116, v156, v156
	v_fmac_f32_e32 v116, v158, v158
	v_fmac_f32_e32 v116, v159, v159
	v_add_f32_e32 v120, v116, v120
	v_pk_fma_f32 v[126:127], v[114:115], v[180:181], v[146:147]
	v_cvt_pk_bf16_f32 v116, v124, v125
	global_store_dwordx4 v[194:195], v[124:127], off offset:576 nt
	v_cvt_pk_bf16_f32 v117, v126, v127
	global_store_dwordx2 v[112:113], v[116:117], off offset:288
	v_mul_f32_e32 v112, v125, v125
	v_and_b32_e32 v116, 64, v197
	v_fmac_f32_e32 v112, v124, v124
	v_xor_b32_e32 v113, 16, v197
	v_add_u32_e32 v116, 64, v116
	v_fmac_f32_e32 v112, v126, v126
	v_cmp_lt_i32_e32 vcc, v113, v116
	v_fmac_f32_e32 v112, v127, v127
	v_add_f32_e32 v112, v112, v120
	v_cndmask_b32_e32 v113, v197, v113, vcc
	v_lshlrev_b32_e32 v113, 2, v113
	ds_bpermute_b32 v113, v113, v112
	v_readlane_b32 s61, v238, 46
	s_waitcnt lgkmcnt(0)
	v_add_f32_e32 v112, v112, v113
	v_xor_b32_e32 v113, 32, v197
	v_cmp_lt_i32_e32 vcc, v113, v116
	s_nop 1
	v_cndmask_b32_e32 v113, v197, v113, vcc
	v_lshlrev_b32_e32 v113, 2, v113
	ds_bpermute_b32 v113, v113, v112
	s_and_saveexec_b64 s[16:17], s[34:35]
	s_cbranch_execz .LBB0_2370
	s_waitcnt lgkmcnt(0)
	v_add_f32_e32 v116, v112, v113
	v_lshlrev_b64 v[112:113], 7, v[188:189]
	v_lshl_add_u64 v[112:113], s[14:15], 0, v[112:113]
	global_store_dword v[112:113], v116, off

; DEVI unsigned pk_bf16(float lo, float hi) { unsigned r; asm("v_cvt_pk_bf16_f32 %0, %1, %2" : "=v"(r) : "v"(lo), "v"(hi)); return r; }
;     DEVI void operator()(const f32x4 (&acc)[2][2][4][2], const Unit& u, int wr, int wc, int fr, int fq, const LAS float*) const {
;     ...
;         for (int idx = 0; idx < 8; ++idx) {
;             const int ai = idx >> 2, m = idx & 3;
;             const size_t ro = (size_t)(row0 + ai * HALF + m * 16) * ldc + col0;
;             if (idx + 1 < 8) { const int ai2 = (idx + 1) >> 2, m2 = (idx + 1) & 3; const size_t ro2 = (size_t)(row0 + ai2 * HALF + m2 * 16) * ldc + col0;
; #pragma unroll
;                 for (int bj = 0; bj < 2; ++bj)
; #pragma unroll
;                     for (int n = 0; n < 2; ++n) nxt[bj][n] = *(const f32x4*)(R + ro2 + bj * HALF + n * 16); }
;             float ss = 0.f;
; #pragma unroll
;             for (int bj = 0; bj < 2; ++bj)
; #pragma unroll
;                 for (int n = 0; n < 2; ++n) {
;                     const f32x4 hn = cur[bj][n] + acc[ai][bj][m][n] * scale;
;                     *(f32x4*)(C + ro + bj * HALF + n * 16) = hn;
;                     if (HB) { u32x2 w; w.x = pk_bf16(hn[0], hn[1]); w.y = pk_bf16(hn[2], hn[3]); *(u32x2*)(HB + ro + bj * HALF + n * 16) = w;
;                         ss += hn[0] * hn[0] + hn[1] * hn[1] + hn[2] * hn[2] + hn[3] * hn[3]; } }
;             if (HB) { ss += __shfl_xor(ss, 16); ss += __shfl_xor(ss, 32); if (fq == 0) RS[(size_t)(row0 + ai * HALF + m * 16) * 32 + u.pn * 4 + wc] = ss; }
; #pragma unroll
;             for (int bj = 0; bj < 2; ++bj)
; #pragma unroll
;                 for (int n = 0; n < 2; ++n) cur[bj][n] = nxt[bj][n];
;         }
.LBB0_2372:
	v_readlane_b32 s60, v241, 14
	v_or_b32_e32 v150, 32, v188
	v_readlane_b32 s62, v241, 16
	v_readlane_b32 s61, v241, 15
	v_readlane_b32 s63, v241, 17
	v_mad_i64_i32 v[152:153], s[16:17], v150, s62, 0
	s_waitcnt lgkmcnt(0)
	v_lshl_add_u64 v[112:113], v[152:153], 2, v[186:187]
	global_load_dwordx4 v[124:127], v[112:113], off
	global_load_dwordx4 v[120:123], v[112:113], off offset:64
	global_load_dwordx4 v[116:119], v[112:113], off offset:512
	s_nop 0
	global_load_dwordx4 v[112:115], v[112:113], off offset:576
	v_readlane_b32 s60, v238, 37
	v_lshl_add_u64 v[156:157], v[192:193], 0, v[182:183]
	v_readlane_b32 s64, v238, 41
	v_readlane_b32 s65, v238, 42
	v_mov_b32_e32 v181, v180
	v_pk_fma_f32 v[148:149], v[110:111], v[180:181], v[142:143]
	v_lshl_add_u64 v[154:155], v[156:157], 2, s[64:65]
	v_pk_fma_f32 v[146:147], v[108:109], v[184:185], v[140:141]
	s_and_b64 vcc, exec, s[38:39]
	v_pk_fma_f32 v[144:145], v[104:105], v[184:185], v[136:137]
	v_pk_fma_f32 v[140:141], v[100:101], v[184:185], v[132:133]
	v_pk_fma_f32 v[108:109], v[96:97], v[184:185], v[128:129]
	v_readlane_b32 s61, v238, 38
	v_readlane_b32 s62, v238, 39
	v_readlane_b32 s63, v238, 40
	v_readlane_b32 s66, v238, 43
	v_readlane_b32 s67, v238, 44
	global_store_dwordx4 v[154:155], v[146:149], off nt
	s_cbranch_vccnz .LBB0_2407
	v_readlane_b32 s60, v238, 45
	v_readlane_b32 s62, v238, 47
	v_readlane_b32 s63, v238, 48
	v_cvt_pk_bf16_f32 v100, v146, v147
	v_mul_f32_e32 v104, v147, v147
	v_cvt_pk_bf16_f32 v101, v148, v149
	v_fmac_f32_e32 v104, v146, v146
	v_lshl_add_u64 v[96:97], v[156:157], 1, s[62:63]
	global_store_dwordx2 v[96:97], v[100:101], off
	v_pk_fma_f32 v[146:147], v[106:107], v[180:181], v[138:139]
	v_cvt_pk_bf16_f32 v100, v144, v145
	global_store_dwordx4 v[154:155], v[144:147], off offset:64 nt
	v_cvt_pk_bf16_f32 v101, v146, v147
	global_store_dwordx2 v[96:97], v[100:101], off offset:32
	v_mul_f32_e32 v100, v145, v145
	v_fmac_f32_e32 v100, v144, v144
	v_fmac_f32_e32 v104, v148, v148
	v_fmac_f32_e32 v100, v146, v146
	v_fmac_f32_e32 v104, v149, v149
	v_fmac_f32_e32 v100, v147, v147
	v_add_f32_e32 v104, v104, v100
	v_pk_fma_f32 v[142:143], v[102:103], v[180:181], v[134:135]
	v_cvt_pk_bf16_f32 v100, v140, v141
	global_store_dwordx4 v[154:155], v[140:143], off offset:512 nt
	v_cvt_pk_bf16_f32 v101, v142, v143
	global_store_dwordx2 v[96:97], v[100:101], off offset:256
	v_mul_f32_e32 v100, v141, v141
	v_fmac_f32_e32 v100, v140, v140
	v_fmac_f32_e32 v100, v142, v142
	v_fmac_f32_e32 v100, v143, v143
	v_add_f32_e32 v104, v104, v100
	v_pk_fma_f32 v[110:111], v[98:99], v[180:181], v[130:131]
	v_cvt_pk_bf16_f32 v100, v108, v109
	global_store_dwordx4 v[154:155], v[108:111], off offset:576 nt
	v_cvt_pk_bf16_f32 v101, v110, v111
	global_store_dwordx2 v[96:97], v[100:101], off offset:288
	v_mul_f32_e32 v96, v109, v109
	v_and_b32_e32 v100, 64, v197
	v_fmac_f32_e32 v96, v108, v108
	v_xor_b32_e32 v97, 16, v197
	v_add_u32_e32 v100, 64, v100
	v_fmac_f32_e32 v96, v110, v110
	v_cmp_lt_i32_e32 vcc, v97, v100
	v_fmac_f32_e32 v96, v111, v111
	v_add_f32_e32 v96, v104, v96
	v_cndmask_b32_e32 v97, v197, v97, vcc
	v_lshlrev_b32_e32 v97, 2, v97
	ds_bpermute_b32 v97, v97, v96
	v_readlane_b32 s61, v238, 46
	s_waitcnt lgkmcnt(0)
	v_add_f32_e32 v96, v96, v97
	v_xor_b32_e32 v97, 32, v197
	v_cmp_lt_i32_e32 vcc, v97, v100
	s_nop 1
	v_cndmask_b32_e32 v97, v197, v97, vcc
	v_lshlrev_b32_e32 v97, 2, v97
	ds_bpermute_b32 v97, v97, v96
	s_and_saveexec_b64 s[16:17], s[34:35]
	s_cbranch_execz .LBB0_2375
	v_ashrrev_i32_e32 v191, 31, v190
	s_waitcnt lgkmcnt(0)
	v_add_f32_e32 v100, v96, v97
	v_lshlrev_b64 v[96:97], 7, v[190:191]
	v_lshl_add_u64 v[96:97], s[14:15], 0, v[96:97]
	global_store_dword v[96:97], v100, off

; DEVI unsigned pk_bf16(float lo, float hi) { unsigned r; asm("v_cvt_pk_bf16_f32 %0, %1, %2" : "=v"(r) : "v"(lo), "v"(hi)); return r; }
;     DEVI void operator()(const f32x4 (&acc)[2][2][4][2], const Unit& u, int wr, int wc, int fr, int fq, const LAS float*) const {
;     ...
;         for (int idx = 0; idx < 8; ++idx) {
;             const int ai = idx >> 2, m = idx & 3;
;             const size_t ro = (size_t)(row0 + ai * HALF + m * 16) * ldc + col0;
;             if (idx + 1 < 8) { const int ai2 = (idx + 1) >> 2, m2 = (idx + 1) & 3; const size_t ro2 = (size_t)(row0 + ai2 * HALF + m2 * 16) * ldc + col0;
; #pragma unroll
;                 for (int bj = 0; bj < 2; ++bj)
; #pragma unroll
;                     for (int n = 0; n < 2; ++n) nxt[bj][n] = *(const f32x4*)(R + ro2 + bj * HALF + n * 16); }
;             float ss = 0.f;
; #pragma unroll
;             for (int bj = 0; bj < 2; ++bj)
; #pragma unroll
;                 for (int n = 0; n < 2; ++n) {
;                     const f32x4 hn = cur[bj][n] + acc[ai][bj][m][n] * scale;
;                     *(f32x4*)(C + ro + bj * HALF + n * 16) = hn;
;                     if (HB) { u32x2 w; w.x = pk_bf16(hn[0], hn[1]); w.y = pk_bf16(hn[2], hn[3]); *(u32x2*)(HB + ro + bj * HALF + n * 16) = w;
;                         ss += hn[0] * hn[0] + hn[1] * hn[1] + hn[2] * hn[2] + hn[3] * hn[3]; } }
;             if (HB) { ss += __shfl_xor(ss, 16); ss += __shfl_xor(ss, 32); if (fq == 0) RS[(size_t)(row0 + ai * HALF + m * 16) * 32 + u.pn * 4 + wc] = ss; }
; #pragma unroll
;             for (int bj = 0; bj < 2; ++bj)
; #pragma unroll
;                 for (int n = 0; n < 2; ++n) cur[bj][n] = nxt[bj][n];
;         }
.LBB0_2377:
	v_readlane_b32 s60, v241, 14
	v_or_b32_e32 v134, 48, v188
	v_readlane_b32 s62, v241, 16
	v_readlane_b32 s61, v241, 15
	v_readlane_b32 s63, v241, 17
	v_mad_i64_i32 v[136:137], s[16:17], v134, s62, 0
	s_waitcnt lgkmcnt(0)
	v_lshl_add_u64 v[96:97], v[136:137], 2, v[186:187]
	global_load_dwordx4 v[108:111], v[96:97], off
	global_load_dwordx4 v[104:107], v[96:97], off offset:64
	global_load_dwordx4 v[100:103], v[96:97], off offset:512
	s_nop 0
	global_load_dwordx4 v[96:99], v[96:97], off offset:576
	v_readlane_b32 s60, v238, 37
	v_lshl_add_u64 v[140:141], v[152:153], 0, v[182:183]
	v_readlane_b32 s64, v238, 41
	v_readlane_b32 s65, v238, 42
	v_mov_b32_e32 v181, v180
	s_waitcnt vmcnt(8)
	v_pk_fma_f32 v[132:133], v[94:95], v[180:181], v[126:127]
	v_lshl_add_u64 v[138:139], v[140:141], 2, s[64:65]
	v_pk_fma_f32 v[130:131], v[92:93], v[184:185], v[124:125]
	s_and_b64 vcc, exec, s[38:39]
	s_waitcnt vmcnt(7)
	v_pk_fma_f32 v[128:129], v[88:89], v[184:185], v[120:121]
	s_waitcnt vmcnt(6)
	v_pk_fma_f32 v[124:125], v[84:85], v[184:185], v[116:117]
	s_waitcnt vmcnt(5)
	v_pk_fma_f32 v[92:93], v[80:81], v[184:185], v[112:113]
	v_readlane_b32 s61, v238, 38
	v_readlane_b32 s62, v238, 39
	v_readlane_b32 s63, v238, 40
	v_readlane_b32 s66, v238, 43
	v_readlane_b32 s67, v238, 44
	global_store_dwordx4 v[138:139], v[130:133], off nt
	s_cbranch_vccnz .LBB0_2408
	v_readlane_b32 s60, v238, 45
	v_readlane_b32 s62, v238, 47
	v_readlane_b32 s63, v238, 48
	v_cvt_pk_bf16_f32 v84, v130, v131
	v_mul_f32_e32 v88, v131, v131
	v_cvt_pk_bf16_f32 v85, v132, v133
	v_fmac_f32_e32 v88, v130, v130
	v_lshl_add_u64 v[80:81], v[140:141], 1, s[62:63]
	global_store_dwordx2 v[80:81], v[84:85], off
	v_pk_fma_f32 v[130:131], v[90:91], v[180:181], v[122:123]
	v_cvt_pk_bf16_f32 v84, v128, v129
	global_store_dwordx4 v[138:139], v[128:131], off offset:64 nt
	v_cvt_pk_bf16_f32 v85, v130, v131
	global_store_dwordx2 v[80:81], v[84:85], off offset:32
	v_mul_f32_e32 v84, v129, v129
	v_fmac_f32_e32 v84, v128, v128
	v_fmac_f32_e32 v88, v132, v132
	v_fmac_f32_e32 v84, v130, v130
	v_fmac_f32_e32 v88, v133, v133
	v_fmac_f32_e32 v84, v131, v131
	v_add_f32_e32 v88, v88, v84
	v_pk_fma_f32 v[126:127], v[86:87], v[180:181], v[118:119]
	v_cvt_pk_bf16_f32 v84, v124, v125
	global_store_dwordx4 v[138:139], v[124:127], off offset:512 nt
	v_cvt_pk_bf16_f32 v85, v126, v127
	global_store_dwordx2 v[80:81], v[84:85], off offset:256
	v_mul_f32_e32 v84, v125, v125
	v_fmac_f32_e32 v84, v124, v124
	v_fmac_f32_e32 v84, v126, v126
	v_fmac_f32_e32 v84, v127, v127
	v_add_f32_e32 v88, v88, v84
	v_pk_fma_f32 v[94:95], v[82:83], v[180:181], v[114:115]
	v_cvt_pk_bf16_f32 v84, v92, v93
	global_store_dwordx4 v[138:139], v[92:95], off offset:576 nt
	v_cvt_pk_bf16_f32 v85, v94, v95
	global_store_dwordx2 v[80:81], v[84:85], off offset:288
	v_mul_f32_e32 v80, v93, v93
	v_and_b32_e32 v84, 64, v197
	v_fmac_f32_e32 v80, v92, v92
	v_xor_b32_e32 v81, 16, v197
	v_add_u32_e32 v84, 64, v84
	v_fmac_f32_e32 v80, v94, v94
	v_cmp_lt_i32_e32 vcc, v81, v84
	v_fmac_f32_e32 v80, v95, v95
	v_add_f32_e32 v80, v88, v80
	v_cndmask_b32_e32 v81, v197, v81, vcc
	v_lshlrev_b32_e32 v81, 2, v81
	ds_bpermute_b32 v81, v81, v80
	v_readlane_b32 s61, v238, 46
	s_waitcnt lgkmcnt(0)
	v_add_f32_e32 v80, v80, v81
	v_xor_b32_e32 v81, 32, v197
	v_cmp_lt_i32_e32 vcc, v81, v84
	s_nop 1
	v_cndmask_b32_e32 v81, v197, v81, vcc
	v_lshlrev_b32_e32 v81, 2, v81
	ds_bpermute_b32 v81, v81, v80
	s_and_saveexec_b64 s[16:17], s[34:35]
	s_cbranch_execz .LBB0_2380
	v_ashrrev_i32_e32 v151, 31, v150
	s_waitcnt lgkmcnt(0)
	v_add_f32_e32 v84, v80, v81
	v_lshlrev_b64 v[80:81], 7, v[150:151]
	v_lshl_add_u64 v[80:81], s[14:15], 0, v[80:81]
	global_store_dword v[80:81], v84, off

; DEVI unsigned pk_bf16(float lo, float hi) { unsigned r; asm("v_cvt_pk_bf16_f32 %0, %1, %2" : "=v"(r) : "v"(lo), "v"(hi)); return r; }
;     DEVI void operator()(const f32x4 (&acc)[2][2][4][2], const Unit& u, int wr, int wc, int fr, int fq, const LAS float*) const {
;     ...
;         for (int idx = 0; idx < 8; ++idx) {
;             const int ai = idx >> 2, m = idx & 3;
;             const size_t ro = (size_t)(row0 + ai * HALF + m * 16) * ldc + col0;
;             if (idx + 1 < 8) { const int ai2 = (idx + 1) >> 2, m2 = (idx + 1) & 3; const size_t ro2 = (size_t)(row0 + ai2 * HALF + m2 * 16) * ldc + col0;
; #pragma unroll
;                 for (int bj = 0; bj < 2; ++bj)
; #pragma unroll
;                     for (int n = 0; n < 2; ++n) nxt[bj][n] = *(const f32x4*)(R + ro2 + bj * HALF + n * 16); }
;             float ss = 0.f;
; #pragma unroll
;             for (int bj = 0; bj < 2; ++bj)
; #pragma unroll
;                 for (int n = 0; n < 2; ++n) {
;                     const f32x4 hn = cur[bj][n] + acc[ai][bj][m][n] * scale;
;                     *(f32x4*)(C + ro + bj * HALF + n * 16) = hn;
;                     if (HB) { u32x2 w; w.x = pk_bf16(hn[0], hn[1]); w.y = pk_bf16(hn[2], hn[3]); *(u32x2*)(HB + ro + bj * HALF + n * 16) = w;
;                         ss += hn[0] * hn[0] + hn[1] * hn[1] + hn[2] * hn[2] + hn[3] * hn[3]; } }
;             if (HB) { ss += __shfl_xor(ss, 16); ss += __shfl_xor(ss, 32); if (fq == 0) RS[(size_t)(row0 + ai * HALF + m * 16) * 32 + u.pn * 4 + wc] = ss; }
; #pragma unroll
;             for (int bj = 0; bj < 2; ++bj)
; #pragma unroll
;                 for (int n = 0; n < 2; ++n) cur[bj][n] = nxt[bj][n];
;         }
.LBB0_2382:
	v_readlane_b32 s60, v241, 14
	v_add_u32_e32 v118, 0x80, v188
	v_readlane_b32 s62, v241, 16
	v_readlane_b32 s61, v241, 15
	v_readlane_b32 s63, v241, 17
	v_mad_i64_i32 v[120:121], s[16:17], v118, s62, 0
	s_waitcnt lgkmcnt(0)
	v_lshl_add_u64 v[80:81], v[120:121], 2, v[186:187]
	global_load_dwordx4 v[92:95], v[80:81], off
	global_load_dwordx4 v[88:91], v[80:81], off offset:64
	global_load_dwordx4 v[84:87], v[80:81], off offset:512
	s_nop 0
	global_load_dwordx4 v[80:83], v[80:81], off offset:576
	v_readlane_b32 s60, v238, 37
	v_lshl_add_u64 v[124:125], v[136:137], 0, v[182:183]
	v_readlane_b32 s64, v238, 41
	v_readlane_b32 s65, v238, 42
	v_mov_b32_e32 v181, v180
	s_waitcnt vmcnt(8)
	v_pk_fma_f32 v[116:117], v[78:79], v[180:181], v[110:111]
	v_lshl_add_u64 v[122:123], v[124:125], 2, s[64:65]
	v_pk_fma_f32 v[114:115], v[76:77], v[184:185], v[108:109]
	s_and_b64 vcc, exec, s[38:39]
	s_waitcnt vmcnt(7)
	v_pk_fma_f32 v[112:113], v[72:73], v[184:185], v[104:105]
	s_waitcnt vmcnt(6)
	v_pk_fma_f32 v[108:109], v[68:69], v[184:185], v[100:101]
	s_waitcnt vmcnt(5)
	v_pk_fma_f32 v[76:77], v[64:65], v[184:185], v[96:97]
	v_readlane_b32 s61, v238, 38
	v_readlane_b32 s62, v238, 39
	v_readlane_b32 s63, v238, 40
	v_readlane_b32 s66, v238, 43
	v_readlane_b32 s67, v238, 44
	global_store_dwordx4 v[122:123], v[114:117], off nt
	s_cbranch_vccnz .LBB0_2409
	v_readlane_b32 s60, v238, 45
	v_readlane_b32 s62, v238, 47
	v_readlane_b32 s63, v238, 48
	v_cvt_pk_bf16_f32 v68, v114, v115
	v_mul_f32_e32 v72, v115, v115
	v_cvt_pk_bf16_f32 v69, v116, v117
	v_fmac_f32_e32 v72, v114, v114
	v_lshl_add_u64 v[64:65], v[124:125], 1, s[62:63]
	global_store_dwordx2 v[64:65], v[68:69], off
	v_pk_fma_f32 v[114:115], v[74:75], v[180:181], v[106:107]
	v_cvt_pk_bf16_f32 v68, v112, v113
	global_store_dwordx4 v[122:123], v[112:115], off offset:64 nt
	v_cvt_pk_bf16_f32 v69, v114, v115
	global_store_dwordx2 v[64:65], v[68:69], off offset:32
	v_mul_f32_e32 v68, v113, v113
	v_fmac_f32_e32 v68, v112, v112
	v_fmac_f32_e32 v72, v116, v116
	v_fmac_f32_e32 v68, v114, v114
	v_fmac_f32_e32 v72, v117, v117
	v_fmac_f32_e32 v68, v115, v115
	v_add_f32_e32 v72, v72, v68
	v_pk_fma_f32 v[110:111], v[70:71], v[180:181], v[102:103]
	v_cvt_pk_bf16_f32 v68, v108, v109
	global_store_dwordx4 v[122:123], v[108:111], off offset:512 nt
	v_cvt_pk_bf16_f32 v69, v110, v111
	global_store_dwordx2 v[64:65], v[68:69], off offset:256
	v_mul_f32_e32 v68, v109, v109
	v_fmac_f32_e32 v68, v108, v108
	v_fmac_f32_e32 v68, v110, v110
	v_fmac_f32_e32 v68, v111, v111
	v_add_f32_e32 v72, v72, v68
	v_pk_fma_f32 v[78:79], v[66:67], v[180:181], v[98:99]
	v_cvt_pk_bf16_f32 v68, v76, v77
	global_store_dwordx4 v[122:123], v[76:79], off offset:576 nt
	v_cvt_pk_bf16_f32 v69, v78, v79
	global_store_dwordx2 v[64:65], v[68:69], off offset:288
	v_mul_f32_e32 v64, v77, v77
	v_and_b32_e32 v68, 64, v197
	v_fmac_f32_e32 v64, v76, v76
	v_xor_b32_e32 v65, 16, v197
	v_add_u32_e32 v68, 64, v68
	v_fmac_f32_e32 v64, v78, v78
	v_cmp_lt_i32_e32 vcc, v65, v68
	v_fmac_f32_e32 v64, v79, v79
	v_add_f32_e32 v64, v72, v64
	v_cndmask_b32_e32 v65, v197, v65, vcc
	v_lshlrev_b32_e32 v65, 2, v65
	ds_bpermute_b32 v65, v65, v64
	v_readlane_b32 s61, v238, 46
	s_waitcnt lgkmcnt(0)
	v_add_f32_e32 v64, v64, v65
	v_xor_b32_e32 v65, 32, v197
	v_cmp_lt_i32_e32 vcc, v65, v68
	s_nop 1
	v_cndmask_b32_e32 v65, v197, v65, vcc
	v_lshlrev_b32_e32 v65, 2, v65
	ds_bpermute_b32 v65, v65, v64
	s_and_saveexec_b64 s[16:17], s[34:35]
	s_cbranch_execz .LBB0_2385
	v_ashrrev_i32_e32 v135, 31, v134
	s_waitcnt lgkmcnt(0)
	v_add_f32_e32 v68, v64, v65
	v_lshlrev_b64 v[64:65], 7, v[134:135]
	v_lshl_add_u64 v[64:65], s[14:15], 0, v[64:65]
	global_store_dword v[64:65], v68, off

; DEVI unsigned pk_bf16(float lo, float hi) { unsigned r; asm("v_cvt_pk_bf16_f32 %0, %1, %2" : "=v"(r) : "v"(lo), "v"(hi)); return r; }
;     DEVI void operator()(const f32x4 (&acc)[2][2][4][2], const Unit& u, int wr, int wc, int fr, int fq, const LAS float*) const {
;     ...
;         for (int idx = 0; idx < 8; ++idx) {
;             const int ai = idx >> 2, m = idx & 3;
;             const size_t ro = (size_t)(row0 + ai * HALF + m * 16) * ldc + col0;
;             if (idx + 1 < 8) { const int ai2 = (idx + 1) >> 2, m2 = (idx + 1) & 3; const size_t ro2 = (size_t)(row0 + ai2 * HALF + m2 * 16) * ldc + col0;
; #pragma unroll
;                 for (int bj = 0; bj < 2; ++bj)
; #pragma unroll
;                     for (int n = 0; n < 2; ++n) nxt[bj][n] = *(const f32x4*)(R + ro2 + bj * HALF + n * 16); }
;             float ss = 0.f;
; #pragma unroll
;             for (int bj = 0; bj < 2; ++bj)
; #pragma unroll
;                 for (int n = 0; n < 2; ++n) {
;                     const f32x4 hn = cur[bj][n] + acc[ai][bj][m][n] * scale;
;                     *(f32x4*)(C + ro + bj * HALF + n * 16) = hn;
;                     if (HB) { u32x2 w; w.x = pk_bf16(hn[0], hn[1]); w.y = pk_bf16(hn[2], hn[3]); *(u32x2*)(HB + ro + bj * HALF + n * 16) = w;
;                         ss += hn[0] * hn[0] + hn[1] * hn[1] + hn[2] * hn[2] + hn[3] * hn[3]; } }
;             if (HB) { ss += __shfl_xor(ss, 16); ss += __shfl_xor(ss, 32); if (fq == 0) RS[(size_t)(row0 + ai * HALF + m * 16) * 32 + u.pn * 4 + wc] = ss; }
; #pragma unroll
;             for (int bj = 0; bj < 2; ++bj)
; #pragma unroll
;                 for (int n = 0; n < 2; ++n) cur[bj][n] = nxt[bj][n];
;         }
.LBB0_2387:
	v_readlane_b32 s60, v241, 14
	v_or_b32_e32 v102, 16, v118
	v_readlane_b32 s62, v241, 16
	v_readlane_b32 s61, v241, 15
	v_readlane_b32 s63, v241, 17
	v_mad_i64_i32 v[104:105], s[16:17], v102, s62, 0
	s_waitcnt lgkmcnt(0)
	v_lshl_add_u64 v[64:65], v[104:105], 2, v[186:187]
	global_load_dwordx4 v[76:79], v[64:65], off
	global_load_dwordx4 v[72:75], v[64:65], off offset:64
	global_load_dwordx4 v[68:71], v[64:65], off offset:512
	s_nop 0
	global_load_dwordx4 v[64:67], v[64:65], off offset:576
	v_readlane_b32 s60, v238, 37
	v_lshl_add_u64 v[108:109], v[120:121], 0, v[182:183]
	v_readlane_b32 s64, v238, 41
	v_readlane_b32 s65, v238, 42
	v_mov_b32_e32 v181, v180
	v_ashrrev_i32_e32 v119, 31, v118
	v_lshl_add_u64 v[106:107], v[108:109], 2, s[64:65]
	s_waitcnt vmcnt(8)
	v_pk_fma_f32 v[100:101], v[62:63], v[180:181], v[94:95]
	v_pk_fma_f32 v[98:99], v[60:61], v[184:185], v[92:93]
	s_and_b64 vcc, exec, s[38:39]
	s_waitcnt vmcnt(7)
	v_pk_fma_f32 v[96:97], v[56:57], v[184:185], v[88:89]
	s_waitcnt vmcnt(6)
	v_pk_fma_f32 v[92:93], v[52:53], v[184:185], v[84:85]
	s_waitcnt vmcnt(5)
	v_pk_fma_f32 v[60:61], v[48:49], v[184:185], v[80:81]
	v_readlane_b32 s61, v238, 38
	v_readlane_b32 s62, v238, 39
	v_readlane_b32 s63, v238, 40
	v_readlane_b32 s66, v238, 43
	v_readlane_b32 s67, v238, 44
	global_store_dwordx4 v[106:107], v[98:101], off nt
	s_cbranch_vccnz .LBB0_2410
	v_readlane_b32 s60, v238, 45
	v_readlane_b32 s62, v238, 47
	v_readlane_b32 s63, v238, 48
	v_cvt_pk_bf16_f32 v52, v98, v99
	v_mul_f32_e32 v56, v99, v99
	v_cvt_pk_bf16_f32 v53, v100, v101
	v_fmac_f32_e32 v56, v98, v98
	v_lshl_add_u64 v[48:49], v[108:109], 1, s[62:63]
	global_store_dwordx2 v[48:49], v[52:53], off
	v_pk_fma_f32 v[98:99], v[58:59], v[180:181], v[90:91]
	v_cvt_pk_bf16_f32 v52, v96, v97
	global_store_dwordx4 v[106:107], v[96:99], off offset:64 nt
	v_cvt_pk_bf16_f32 v53, v98, v99
	global_store_dwordx2 v[48:49], v[52:53], off offset:32
	v_mul_f32_e32 v52, v97, v97
	v_fmac_f32_e32 v52, v96, v96
	v_fmac_f32_e32 v56, v100, v100
	v_fmac_f32_e32 v52, v98, v98
	v_fmac_f32_e32 v56, v101, v101
	v_fmac_f32_e32 v52, v99, v99
	v_add_f32_e32 v56, v56, v52
	v_pk_fma_f32 v[94:95], v[54:55], v[180:181], v[86:87]
	v_cvt_pk_bf16_f32 v52, v92, v93
	global_store_dwordx4 v[106:107], v[92:95], off offset:512 nt
	v_cvt_pk_bf16_f32 v53, v94, v95
	global_store_dwordx2 v[48:49], v[52:53], off offset:256
	v_mul_f32_e32 v52, v93, v93
	v_fmac_f32_e32 v52, v92, v92
	v_fmac_f32_e32 v52, v94, v94
	v_fmac_f32_e32 v52, v95, v95
	v_add_f32_e32 v56, v56, v52
	v_pk_fma_f32 v[62:63], v[50:51], v[180:181], v[82:83]
	v_cvt_pk_bf16_f32 v52, v60, v61
	global_store_dwordx4 v[106:107], v[60:63], off offset:576 nt
	v_cvt_pk_bf16_f32 v53, v62, v63
	global_store_dwordx2 v[48:49], v[52:53], off offset:288
	v_mul_f32_e32 v48, v61, v61
	v_and_b32_e32 v52, 64, v197
	v_fmac_f32_e32 v48, v60, v60
	v_xor_b32_e32 v49, 16, v197
	v_add_u32_e32 v52, 64, v52
	v_fmac_f32_e32 v48, v62, v62
	v_cmp_lt_i32_e32 vcc, v49, v52
	v_fmac_f32_e32 v48, v63, v63
	v_add_f32_e32 v48, v56, v48
	v_cndmask_b32_e32 v49, v197, v49, vcc
	v_lshlrev_b32_e32 v49, 2, v49
	ds_bpermute_b32 v49, v49, v48
	v_readlane_b32 s61, v238, 46
	s_waitcnt lgkmcnt(0)
	v_add_f32_e32 v48, v48, v49
	v_xor_b32_e32 v49, 32, v197
	v_cmp_lt_i32_e32 vcc, v49, v52
	s_nop 1
	v_cndmask_b32_e32 v49, v197, v49, vcc
	v_lshlrev_b32_e32 v49, 2, v49
	ds_bpermute_b32 v49, v49, v48
	s_and_saveexec_b64 s[16:17], s[34:35]
	s_cbranch_execz .LBB0_2390
	s_waitcnt lgkmcnt(0)
	v_add_f32_e32 v52, v48, v49
	v_lshlrev_b64 v[48:49], 7, v[118:119]
	v_lshl_add_u64 v[48:49], s[14:15], 0, v[48:49]
	global_store_dword v[48:49], v52, off

; DEVI unsigned pk_bf16(float lo, float hi) { unsigned r; asm("v_cvt_pk_bf16_f32 %0, %1, %2" : "=v"(r) : "v"(lo), "v"(hi)); return r; }
;     DEVI void operator()(const f32x4 (&acc)[2][2][4][2], const Unit& u, int wr, int wc, int fr, int fq, const LAS float*) const {
;     ...
;         for (int idx = 0; idx < 8; ++idx) {
;             const int ai = idx >> 2, m = idx & 3;
;             const size_t ro = (size_t)(row0 + ai * HALF + m * 16) * ldc + col0;
;             if (idx + 1 < 8) { const int ai2 = (idx + 1) >> 2, m2 = (idx + 1) & 3; const size_t ro2 = (size_t)(row0 + ai2 * HALF + m2 * 16) * ldc + col0;
; #pragma unroll
;                 for (int bj = 0; bj < 2; ++bj)
; #pragma unroll
;                     for (int n = 0; n < 2; ++n) nxt[bj][n] = *(const f32x4*)(R + ro2 + bj * HALF + n * 16); }
;             float ss = 0.f;
; #pragma unroll
;             for (int bj = 0; bj < 2; ++bj)
; #pragma unroll
;                 for (int n = 0; n < 2; ++n) {
;                     const f32x4 hn = cur[bj][n] + acc[ai][bj][m][n] * scale;
;                     *(f32x4*)(C + ro + bj * HALF + n * 16) = hn;
;                     if (HB) { u32x2 w; w.x = pk_bf16(hn[0], hn[1]); w.y = pk_bf16(hn[2], hn[3]); *(u32x2*)(HB + ro + bj * HALF + n * 16) = w;
;                         ss += hn[0] * hn[0] + hn[1] * hn[1] + hn[2] * hn[2] + hn[3] * hn[3]; } }
;             if (HB) { ss += __shfl_xor(ss, 16); ss += __shfl_xor(ss, 32); if (fq == 0) RS[(size_t)(row0 + ai * HALF + m * 16) * 32 + u.pn * 4 + wc] = ss; }
; #pragma unroll
;             for (int bj = 0; bj < 2; ++bj)
; #pragma unroll
;                 for (int n = 0; n < 2; ++n) cur[bj][n] = nxt[bj][n];
;         }
.LBB0_2392:
	v_readlane_b32 s60, v241, 14
	v_or_b32_e32 v86, 32, v118
	v_readlane_b32 s62, v241, 16
	v_readlane_b32 s61, v241, 15
	v_readlane_b32 s63, v241, 17
	v_mad_i64_i32 v[88:89], s[16:17], v86, s62, 0
	s_waitcnt lgkmcnt(0)
	v_lshl_add_u64 v[48:49], v[88:89], 2, v[186:187]
	global_load_dwordx4 v[60:63], v[48:49], off
	global_load_dwordx4 v[56:59], v[48:49], off offset:64
	global_load_dwordx4 v[52:55], v[48:49], off offset:512
	s_nop 0
	global_load_dwordx4 v[48:51], v[48:49], off offset:576
	v_readlane_b32 s60, v238, 37
	v_lshl_add_u64 v[92:93], v[104:105], 0, v[182:183]
	v_readlane_b32 s64, v238, 41
	v_readlane_b32 s65, v238, 42
	v_mov_b32_e32 v181, v180
	s_waitcnt vmcnt(8)
	v_pk_fma_f32 v[84:85], v[46:47], v[180:181], v[78:79]
	v_lshl_add_u64 v[90:91], v[92:93], 2, s[64:65]
	v_pk_fma_f32 v[82:83], v[44:45], v[184:185], v[76:77]
	s_and_b64 vcc, exec, s[38:39]
	s_waitcnt vmcnt(7)
	v_pk_fma_f32 v[80:81], v[40:41], v[184:185], v[72:73]
	s_waitcnt vmcnt(6)
	v_pk_fma_f32 v[76:77], v[36:37], v[184:185], v[68:69]
	s_waitcnt vmcnt(5)
	v_pk_fma_f32 v[44:45], v[32:33], v[184:185], v[64:65]
	v_readlane_b32 s61, v238, 38
	v_readlane_b32 s62, v238, 39
	v_readlane_b32 s63, v238, 40
	v_readlane_b32 s66, v238, 43
	v_readlane_b32 s67, v238, 44
	global_store_dwordx4 v[90:91], v[82:85], off nt
	s_cbranch_vccnz .LBB0_2411
	v_readlane_b32 s60, v238, 45
	v_readlane_b32 s62, v238, 47
	v_readlane_b32 s63, v238, 48
	v_cvt_pk_bf16_f32 v36, v82, v83
	v_mul_f32_e32 v40, v83, v83
	v_cvt_pk_bf16_f32 v37, v84, v85
	v_fmac_f32_e32 v40, v82, v82
	v_lshl_add_u64 v[32:33], v[92:93], 1, s[62:63]
	global_store_dwordx2 v[32:33], v[36:37], off
	v_pk_fma_f32 v[82:83], v[42:43], v[180:181], v[74:75]
	v_cvt_pk_bf16_f32 v36, v80, v81
	global_store_dwordx4 v[90:91], v[80:83], off offset:64 nt
	v_cvt_pk_bf16_f32 v37, v82, v83
	global_store_dwordx2 v[32:33], v[36:37], off offset:32
	v_mul_f32_e32 v36, v81, v81
	v_fmac_f32_e32 v36, v80, v80
	v_fmac_f32_e32 v40, v84, v84
	v_fmac_f32_e32 v36, v82, v82
	v_fmac_f32_e32 v40, v85, v85
	v_fmac_f32_e32 v36, v83, v83
	v_add_f32_e32 v40, v40, v36
	v_pk_fma_f32 v[78:79], v[38:39], v[180:181], v[70:71]
	v_cvt_pk_bf16_f32 v36, v76, v77
	global_store_dwordx4 v[90:91], v[76:79], off offset:512 nt
	v_cvt_pk_bf16_f32 v37, v78, v79
	global_store_dwordx2 v[32:33], v[36:37], off offset:256
	v_mul_f32_e32 v36, v77, v77
	v_fmac_f32_e32 v36, v76, v76
	v_fmac_f32_e32 v36, v78, v78
	v_fmac_f32_e32 v36, v79, v79
	v_add_f32_e32 v40, v40, v36
	v_pk_fma_f32 v[46:47], v[34:35], v[180:181], v[66:67]
	v_cvt_pk_bf16_f32 v36, v44, v45
	global_store_dwordx4 v[90:91], v[44:47], off offset:576 nt
	v_cvt_pk_bf16_f32 v37, v46, v47
	global_store_dwordx2 v[32:33], v[36:37], off offset:288
	v_mul_f32_e32 v32, v45, v45
	v_and_b32_e32 v36, 64, v197
	v_fmac_f32_e32 v32, v44, v44
	v_xor_b32_e32 v33, 16, v197
	v_add_u32_e32 v36, 64, v36
	v_fmac_f32_e32 v32, v46, v46
	v_cmp_lt_i32_e32 vcc, v33, v36
	v_fmac_f32_e32 v32, v47, v47
	v_add_f32_e32 v32, v40, v32
	v_cndmask_b32_e32 v33, v197, v33, vcc
	v_lshlrev_b32_e32 v33, 2, v33
	ds_bpermute_b32 v33, v33, v32
	v_readlane_b32 s61, v238, 46
	s_waitcnt lgkmcnt(0)
	v_add_f32_e32 v32, v32, v33
	v_xor_b32_e32 v33, 32, v197
	v_cmp_lt_i32_e32 vcc, v33, v36
	s_nop 1
	v_cndmask_b32_e32 v33, v197, v33, vcc
	v_lshlrev_b32_e32 v33, 2, v33
	ds_bpermute_b32 v33, v33, v32
	s_and_saveexec_b64 s[16:17], s[34:35]
	s_cbranch_execz .LBB0_2395
	v_ashrrev_i32_e32 v103, 31, v102
	s_waitcnt lgkmcnt(0)
	v_add_f32_e32 v36, v32, v33
	v_lshlrev_b64 v[32:33], 7, v[102:103]
	v_lshl_add_u64 v[32:33], s[14:15], 0, v[32:33]
	global_store_dword v[32:33], v36, off

; DEVI unsigned pk_bf16(float lo, float hi) { unsigned r; asm("v_cvt_pk_bf16_f32 %0, %1, %2" : "=v"(r) : "v"(lo), "v"(hi)); return r; }
;     DEVI void operator()(const f32x4 (&acc)[2][2][4][2], const Unit& u, int wr, int wc, int fr, int fq, const LAS float*) const {
;     ...
;         for (int idx = 0; idx < 8; ++idx) {
;             const int ai = idx >> 2, m = idx & 3;
;             const size_t ro = (size_t)(row0 + ai * HALF + m * 16) * ldc + col0;
;             if (idx + 1 < 8) { const int ai2 = (idx + 1) >> 2, m2 = (idx + 1) & 3; const size_t ro2 = (size_t)(row0 + ai2 * HALF + m2 * 16) * ldc + col0;
; #pragma unroll
;                 for (int bj = 0; bj < 2; ++bj)
; #pragma unroll
;                     for (int n = 0; n < 2; ++n) nxt[bj][n] = *(const f32x4*)(R + ro2 + bj * HALF + n * 16); }
;             float ss = 0.f;
; #pragma unroll
;             for (int bj = 0; bj < 2; ++bj)
; #pragma unroll
;                 for (int n = 0; n < 2; ++n) {
;                     const f32x4 hn = cur[bj][n] + acc[ai][bj][m][n] * scale;
;                     *(f32x4*)(C + ro + bj * HALF + n * 16) = hn;
;                     if (HB) { u32x2 w; w.x = pk_bf16(hn[0], hn[1]); w.y = pk_bf16(hn[2], hn[3]); *(u32x2*)(HB + ro + bj * HALF + n * 16) = w;
;                         ss += hn[0] * hn[0] + hn[1] * hn[1] + hn[2] * hn[2] + hn[3] * hn[3]; } }
;             if (HB) { ss += __shfl_xor(ss, 16); ss += __shfl_xor(ss, 32); if (fq == 0) RS[(size_t)(row0 + ai * HALF + m * 16) * 32 + u.pn * 4 + wc] = ss; }
; #pragma unroll
;             for (int bj = 0; bj < 2; ++bj)
; #pragma unroll
;                 for (int n = 0; n < 2; ++n) cur[bj][n] = nxt[bj][n];
;         }
.LBB0_2397:
	v_readlane_b32 s60, v241, 14
	v_or_b32_e32 v70, 48, v118
	v_readlane_b32 s62, v241, 16
	v_readlane_b32 s61, v241, 15
	v_readlane_b32 s63, v241, 17
	v_mad_i64_i32 v[72:73], s[16:17], v70, s62, 0
	s_waitcnt lgkmcnt(0)
	v_lshl_add_u64 v[32:33], v[72:73], 2, v[186:187]
	global_load_dwordx4 v[44:47], v[32:33], off
	global_load_dwordx4 v[40:43], v[32:33], off offset:64
	global_load_dwordx4 v[36:39], v[32:33], off offset:512
	s_nop 0
	global_load_dwordx4 v[32:35], v[32:33], off offset:576
	v_readlane_b32 s60, v238, 37
	v_lshl_add_u64 v[76:77], v[88:89], 0, v[182:183]
	v_readlane_b32 s64, v238, 41
	v_readlane_b32 s65, v238, 42
	v_mov_b32_e32 v181, v180
	s_waitcnt vmcnt(8)
	v_pk_fma_f32 v[68:69], v[30:31], v[180:181], v[62:63]
	v_lshl_add_u64 v[74:75], v[76:77], 2, s[64:65]
	v_pk_fma_f32 v[66:67], v[28:29], v[184:185], v[60:61]
	s_and_b64 vcc, exec, s[38:39]
	s_waitcnt vmcnt(7)
	v_pk_fma_f32 v[64:65], v[24:25], v[184:185], v[56:57]
	s_waitcnt vmcnt(6)
	v_pk_fma_f32 v[60:61], v[20:21], v[184:185], v[52:53]
	s_waitcnt vmcnt(5)
	v_pk_fma_f32 v[28:29], v[16:17], v[184:185], v[48:49]
	v_readlane_b32 s61, v238, 38
	v_readlane_b32 s62, v238, 39
	v_readlane_b32 s63, v238, 40
	v_readlane_b32 s66, v238, 43
	v_readlane_b32 s67, v238, 44
	global_store_dwordx4 v[74:75], v[66:69], off nt
	s_cbranch_vccnz .LBB0_2412
	v_readlane_b32 s60, v238, 45
	v_readlane_b32 s62, v238, 47
	v_readlane_b32 s63, v238, 48
	v_cvt_pk_bf16_f32 v20, v66, v67
	v_mul_f32_e32 v24, v67, v67
	v_cvt_pk_bf16_f32 v21, v68, v69
	v_fmac_f32_e32 v24, v66, v66
	v_lshl_add_u64 v[16:17], v[76:77], 1, s[62:63]
	global_store_dwordx2 v[16:17], v[20:21], off
	v_pk_fma_f32 v[66:67], v[26:27], v[180:181], v[58:59]
	v_cvt_pk_bf16_f32 v20, v64, v65
	global_store_dwordx4 v[74:75], v[64:67], off offset:64 nt
	v_cvt_pk_bf16_f32 v21, v66, v67
	global_store_dwordx2 v[16:17], v[20:21], off offset:32
	v_mul_f32_e32 v20, v65, v65
	v_fmac_f32_e32 v20, v64, v64
	v_fmac_f32_e32 v24, v68, v68
	v_fmac_f32_e32 v20, v66, v66
	v_fmac_f32_e32 v24, v69, v69
	v_fmac_f32_e32 v20, v67, v67
	v_add_f32_e32 v24, v24, v20
	v_pk_fma_f32 v[62:63], v[22:23], v[180:181], v[54:55]
	v_cvt_pk_bf16_f32 v20, v60, v61
	global_store_dwordx4 v[74:75], v[60:63], off offset:512 nt
	v_cvt_pk_bf16_f32 v21, v62, v63
	global_store_dwordx2 v[16:17], v[20:21], off offset:256
	v_mul_f32_e32 v20, v61, v61
	v_fmac_f32_e32 v20, v60, v60
	v_fmac_f32_e32 v20, v62, v62
	v_fmac_f32_e32 v20, v63, v63
	v_add_f32_e32 v24, v24, v20
	v_pk_fma_f32 v[30:31], v[18:19], v[180:181], v[50:51]
	v_cvt_pk_bf16_f32 v20, v28, v29
	global_store_dwordx4 v[74:75], v[28:31], off offset:576 nt
	v_cvt_pk_bf16_f32 v21, v30, v31
	global_store_dwordx2 v[16:17], v[20:21], off offset:288
	v_mul_f32_e32 v16, v29, v29
	v_and_b32_e32 v20, 64, v197
	v_fmac_f32_e32 v16, v28, v28
	v_xor_b32_e32 v17, 16, v197
	v_add_u32_e32 v20, 64, v20
	v_fmac_f32_e32 v16, v30, v30
	v_cmp_lt_i32_e32 vcc, v17, v20
	v_fmac_f32_e32 v16, v31, v31
	v_add_f32_e32 v16, v24, v16
	v_cndmask_b32_e32 v17, v197, v17, vcc
	v_lshlrev_b32_e32 v17, 2, v17
	ds_bpermute_b32 v17, v17, v16
	v_readlane_b32 s61, v238, 46
	s_waitcnt lgkmcnt(0)
	v_add_f32_e32 v16, v16, v17
	v_xor_b32_e32 v17, 32, v197
	v_cmp_lt_i32_e32 vcc, v17, v20
	s_nop 1
	v_cndmask_b32_e32 v17, v197, v17, vcc
	v_lshlrev_b32_e32 v17, 2, v17
	ds_bpermute_b32 v17, v17, v16
	s_and_saveexec_b64 s[16:17], s[34:35]
	s_cbranch_execz .LBB0_2400
	v_ashrrev_i32_e32 v87, 31, v86
	s_waitcnt lgkmcnt(0)
	v_add_f32_e32 v20, v16, v17
	v_lshlrev_b64 v[16:17], 7, v[86:87]
	v_lshl_add_u64 v[16:17], s[14:15], 0, v[16:17]
	global_store_dword v[16:17], v20, off

; DEVI unsigned pk_bf16(float lo, float hi) { unsigned r; asm("v_cvt_pk_bf16_f32 %0, %1, %2" : "=v"(r) : "v"(lo), "v"(hi)); return r; }
;     DEVI void operator()(const f32x4 (&acc)[2][2][4][2], const Unit& u, int wr, int wc, int fr, int fq, const LAS float*) const {
;     ...
;             float ss = 0.f;
; #pragma unroll
;             for (int bj = 0; bj < 2; ++bj)
; #pragma unroll
;                 for (int n = 0; n < 2; ++n) {
;                     const f32x4 hn = cur[bj][n] + acc[ai][bj][m][n] * scale;
;                     *(f32x4*)(C + ro + bj * HALF + n * 16) = hn;
;                     if (HB) { u32x2 w; w.x = pk_bf16(hn[0], hn[1]); w.y = pk_bf16(hn[2], hn[3]); *(u32x2*)(HB + ro + bj * HALF + n * 16) = w;
;                         ss += hn[0] * hn[0] + hn[1] * hn[1] + hn[2] * hn[2] + hn[3] * hn[3]; } }
;             if (HB) { ss += __shfl_xor(ss, 16); ss += __shfl_xor(ss, 32); if (fq == 0) RS[(size_t)(row0 + ai * HALF + m * 16) * 32 + u.pn * 4 + wc] = ss; }
; #pragma unroll
;             for (int bj = 0; bj < 2; ++bj)
; #pragma unroll
;                 for (int n = 0; n < 2; ++n) cur[bj][n] = nxt[bj][n];
;         }
.LBB0_2402:
	v_readlane_b32 s60, v238, 37
	v_lshl_add_u64 v[18:19], v[72:73], 0, v[182:183]
	v_readlane_b32 s64, v238, 41
	v_readlane_b32 s65, v238, 42
	v_mov_b32_e32 v181, v180
	s_waitcnt vmcnt(4)
	v_pk_fma_f32 v[24:25], v[14:15], v[180:181], v[46:47]
	v_lshl_add_u64 v[26:27], v[18:19], 2, s[64:65]
	v_pk_fma_f32 v[22:23], v[12:13], v[184:185], v[44:45]
	s_and_b64 vcc, exec, s[38:39]
	s_waitcnt vmcnt(3)
	v_pk_fma_f32 v[20:21], v[8:9], v[184:185], v[40:41]
	s_waitcnt vmcnt(2) lgkmcnt(0)
	v_pk_fma_f32 v[16:17], v[4:5], v[184:185], v[36:37]
	s_waitcnt vmcnt(1)
	v_pk_fma_f32 v[12:13], v[0:1], v[184:185], v[32:33]
	v_readlane_b32 s61, v238, 38
	v_readlane_b32 s62, v238, 39
	v_readlane_b32 s63, v238, 40
	v_readlane_b32 s66, v238, 43
	v_readlane_b32 s67, v238, 44
	global_store_dwordx4 v[26:27], v[22:25], off nt
	s_cbranch_vccnz .LBB0_2413
	v_readlane_b32 s60, v238, 45
	v_readlane_b32 s62, v238, 47
	v_readlane_b32 s63, v238, 48
	v_cvt_pk_bf16_f32 v4, v22, v23
	v_mul_f32_e32 v8, v23, v23
	v_cvt_pk_bf16_f32 v5, v24, v25
	v_fmac_f32_e32 v8, v22, v22
	v_lshl_add_u64 v[0:1], v[18:19], 1, s[62:63]
	global_store_dwordx2 v[0:1], v[4:5], off
	v_pk_fma_f32 v[22:23], v[10:11], v[180:181], v[42:43]
	v_cvt_pk_bf16_f32 v4, v20, v21
	global_store_dwordx4 v[26:27], v[20:23], off offset:64 nt
	v_cvt_pk_bf16_f32 v5, v22, v23
	global_store_dwordx2 v[0:1], v[4:5], off offset:32
	v_mul_f32_e32 v4, v21, v21
	v_fmac_f32_e32 v4, v20, v20
	v_fmac_f32_e32 v8, v24, v24
	v_fmac_f32_e32 v4, v22, v22
	v_fmac_f32_e32 v8, v25, v25
	v_fmac_f32_e32 v4, v23, v23
	v_add_f32_e32 v8, v8, v4
	v_pk_fma_f32 v[18:19], v[6:7], v[180:181], v[38:39]
	v_cvt_pk_bf16_f32 v4, v16, v17
	global_store_dwordx4 v[26:27], v[16:19], off offset:512 nt
	v_cvt_pk_bf16_f32 v5, v18, v19
	global_store_dwordx2 v[0:1], v[4:5], off offset:256
	v_mul_f32_e32 v4, v17, v17
	v_fmac_f32_e32 v4, v16, v16
	v_fmac_f32_e32 v4, v18, v18
	v_fmac_f32_e32 v4, v19, v19
	v_add_f32_e32 v8, v8, v4
	v_pk_fma_f32 v[14:15], v[2:3], v[180:181], v[34:35]
	v_cvt_pk_bf16_f32 v4, v12, v13
	global_store_dwordx4 v[26:27], v[12:15], off offset:576 nt
	v_cvt_pk_bf16_f32 v5, v14, v15
	global_store_dwordx2 v[0:1], v[4:5], off offset:288
	v_mul_f32_e32 v0, v13, v13
	v_and_b32_e32 v4, 64, v197
	v_fmac_f32_e32 v0, v12, v12
	v_xor_b32_e32 v1, 16, v197
	v_add_u32_e32 v4, 64, v4
	v_fmac_f32_e32 v0, v14, v14
	v_cmp_lt_i32_e32 vcc, v1, v4
	v_fmac_f32_e32 v0, v15, v15
	v_add_f32_e32 v0, v8, v0
	v_cndmask_b32_e32 v1, v197, v1, vcc
	v_lshlrev_b32_e32 v1, 2, v1
	ds_bpermute_b32 v1, v1, v0
	v_readlane_b32 s61, v238, 46
	s_waitcnt lgkmcnt(0)
	v_add_f32_e32 v0, v0, v1
	v_xor_b32_e32 v1, 32, v197
	v_cmp_lt_i32_e32 vcc, v1, v4
	s_nop 1
	v_cndmask_b32_e32 v1, v197, v1, vcc
	v_lshlrev_b32_e32 v1, 2, v1
	ds_bpermute_b32 v1, v1, v0
	s_and_saveexec_b64 s[16:17], s[34:35]
	s_cbranch_execz .LBB0_2405
	v_ashrrev_i32_e32 v71, 31, v70
	s_waitcnt lgkmcnt(0)
	v_add_f32_e32 v4, v0, v1
	v_lshlrev_b64 v[0:1], 7, v[70:71]
	v_lshl_add_u64 v[0:1], s[14:15], 0, v[0:1]
	global_store_dword v[0:1], v4, off

; DEVI float row_rstd(const LAS float* rsl, int r) { return rsqrtf((rsl[r] + rsl[256 + r]) * (1.0f / DM) + 1e-6f); }
;     DEVI void operator()(const f32x4 (&acc)[2][2][4][2], const Unit& u, int wr, int wc, int fr, int fq, const LAS float* rsl) const {
;         bf16_t* const O = O_; const int ldc = ldc_; const float* const rs = rs_; const int rsn = rsn_;
;         const int row0 = u.pm * BM + wr * 64 + fr, col0 = u.pn * BM + wc * 32 + 8 * fq;
; #pragma unroll
;         for (int ai = 0; ai < 2; ++ai)
; #pragma unroll
;             for (int m = 0; m < 4; ++m) { bf16_t* rowp = O + (size_t)(row0 + ai * HALF + m * 16) * ldc + col0;
;                 const float sc = rs ? row_rstd(rsl, wr * 64 + fr + ai * HALF + m * 16) : 1.0f;
; #pragma unroll
;                 for (int bj = 0; bj < 2; ++bj) { const f32x4 v0 = acc[ai][bj][m][0] * sc, v1 = acc[ai][bj][m][1] * sc;
;                     u32x4 w; w.x = pk_bf16(v0[0], v0[1]); w.y = pk_bf16(v0[2], v0[3]); w.z = pk_bf16(v1[0], v1[1]); w.w = pk_bf16(v1[2], v1[3]);
;                     *(u32x4*)(rowp + bj * HALF) = w; } }
;     }
;     DEVI void operator()(const f32x4 (&acc)[2][2][4][2], const Unit& u, int wr, int wc, int fr, int fq, const LAS float* rsl) const {
;         bf16_t* const O = O_; const int ldc = ldc_; const float* const rs = rs_; const int rsn = rsn_;
;         const int row0 = u.pm * BM + wr * 64 + fr, col0 = u.pn * HALF + wc * 32 + 8 * fq;
; #pragma unroll
;         for (int ai = 0; ai < 2; ++ai)
; #pragma unroll
;             for (int m = 0; m < 4; ++m) { bf16_t* rowp = O + (size_t)(row0 + ai * HALF + m * 16) * ldc + col0;
;                 const float sc = row_rstd(rsl, wr * 64 + fr + ai * HALF + m * 16);
;                 const float k1 = -1.4426950408889634f * sc, k2 = sc * sc;
;                 float h[8], tt[8];
;                 const f32x4 guk0 = (acc[ai][0][m][0] * acc[ai][1][m][0]) * k2, guk1 = (acc[ai][0][m][1] * acc[ai][1][m][1]) * k2;
;                 const f32x4 ta = acc[ai][0][m][0] * k1, tb = acc[ai][0][m][1] * k1;
; #pragma unroll
;                 for (int j = 0; j < 4; ++j) { tt[j] = __builtin_amdgcn_exp2f(ta[j]); tt[4 + j] = __builtin_amdgcn_exp2f(tb[j]); }
;                 __builtin_amdgcn_sched_barrier(0);
; #pragma unroll
;                 for (int j = 0; j < 8; ++j) tt[j] = __builtin_amdgcn_rcpf(1.0f + tt[j]);
;                 __builtin_amdgcn_sched_barrier(0);
.LBB0_2511:
	s_lshl_b32 s14, s58, 11
	s_and_b32 s14, s14, 0x800
	v_add_u32_e32 v168, s14, v148
	ds_read2st64_b32 v[144:145], v168 offset1:4
	v_lshl_add_u32 v157, s57, 8, v147
	v_readlane_b32 s14, v239, 48
	v_readlane_b32 s15, v239, 49
	s_waitcnt lgkmcnt(0)
	v_add_f32_e32 v144, v144, v145
	v_fmamk_f32 v144, v144, 0x3a000000, v156
	v_mul_f32_e32 v145, 0x4b800000, v144
	v_cmp_gt_f32_e32 vcc, s52, v144
	s_nop 1
	v_cndmask_b32_e32 v144, v144, v145, vcc
	v_rsq_f32_e32 v158, v144
	v_lshl_or_b32 v144, s56, 7, v150
	v_readlane_b32 s56, v241, 22
	v_ashrrev_i32_e32 v145, 31, v144
	v_mul_f32_e32 v159, 0x45800000, v158
	v_cndmask_b32_e32 v159, v158, v159, vcc
	v_mul_f32_e32 v158, 0xbfb8aa3b, v159
	v_pk_mul_f32 v[160:161], v[122:123], v[158:159] op_sel_hi:[1,0]
	v_pk_mul_f32 v[162:163], v[120:121], v[158:159] op_sel_hi:[1,0]
	v_pk_mul_f32 v[166:167], v[116:117], v[158:159] op_sel_hi:[1,0]
	v_readlane_b32 s58, v241, 24
	v_lshl_add_u64 v[144:145], v[144:145], 1, s[14:15]
	v_pk_mul_f32 v[164:165], v[118:119], v[158:159] op_sel_hi:[1,0]
	v_exp_f32_e32 v158, v162
	v_exp_f32_e32 v162, v166
	v_exp_f32_e32 v166, v167
	v_exp_f32_e32 v167, v160
	v_exp_f32_e32 v169, v161
	v_mad_i64_i32 v[160:161], s[14:15], v157, s58, 0
	v_exp_f32_e32 v163, v163
	v_exp_f32_e32 v164, v164
	v_exp_f32_e32 v165, v165
	v_readlane_b32 s57, v241, 23
	v_readlane_b32 s59, v241, 25
	v_lshl_add_u64 v[160:161], v[160:161], 1, v[144:145]
	v_add_f32_e32 v158, 1.0, v158
	v_rcp_f32_e32 v170, v158
	v_add_f32_e32 v158, 1.0, v163
	v_rcp_f32_e32 v163, v158
	v_add_f32_e32 v158, 1.0, v167
	v_rcp_f32_e32 v167, v158
	v_add_f32_e32 v158, 1.0, v169
	v_rcp_f32_e32 v169, v158
	v_add_f32_e32 v158, 1.0, v162
	v_rcp_f32_e32 v162, v158
	v_add_f32_e32 v158, 1.0, v166
	v_rcp_f32_e32 v166, v158
	v_add_f32_e32 v158, 1.0, v164
	v_rcp_f32_e32 v164, v158
	v_add_f32_e32 v158, 1.0, v165
	v_rcp_f32_e32 v165, v158
	v_mul_f32_e32 v116, v112, v116
	v_mul_f32_e32 v117, v113, v117
	v_mov_b32_e32 v158, v114
	v_mov_b32_e32 v112, v118
	v_mov_b32_e32 v113, v159
	v_pk_mul_f32 v[112:113], v[158:159], v[112:113]
	v_mul_f32_e32 v121, v125, v121
	v_mul_f32_e32 v116, v116, v113
	v_mul_f32_e32 v120, v124, v120
	v_mul_f32_e32 v118, v116, v162
	v_mul_f32_e32 v116, v121, v113
	v_mul_f32_e32 v122, v126, v122
	v_mul_f32_e32 v114, v120, v113
	v_mul_f32_e32 v120, v116, v163
	v_mul_f32_e32 v116, v117, v113
	v_mul_f32_e32 v121, v116, v166
	v_mul_f32_e32 v116, v122, v113
	v_add_u32_e32 v125, 64, v168
	v_mul_f32_e32 v122, v116, v167
	ds_read2st64_b32 v[116:117], v125 offset1:4
	v_mul_f32_e32 v112, v112, v113
	v_mul_f32_e32 v124, v112, v164
	v_mul_f32_e32 v112, v127, v123
	v_mul_f32_e32 v112, v112, v113
	s_waitcnt lgkmcnt(0)
	v_add_f32_e32 v116, v116, v117
	v_fmamk_f32 v116, v116, 0x3a000000, v156
	v_mul_f32_e32 v117, 0x4b800000, v116
	v_cmp_gt_f32_e32 vcc, s52, v116
	v_mul_f32_e32 v123, v112, v169
	v_mul_f32_e32 v112, v115, v119
	v_cndmask_b32_e32 v116, v116, v117, vcc
	v_rsq_f32_e32 v116, v116
	v_mul_f32_e32 v112, v112, v113
	v_mul_f32_e32 v114, v114, v170
	v_mul_f32_e32 v115, v112, v165
	v_cvt_pk_bf16_f32 v112, v114, v120
	v_cvt_pk_bf16_f32 v113, v122, v123
	v_cvt_pk_bf16_f32 v114, v118, v121
	v_cvt_pk_bf16_f32 v115, v124, v115
	global_store_dwordx4 v[160:161], v[112:115], off nt
	v_or_b32_e32 v122, 16, v157
	s_nop 0
	v_mul_f32_e32 v112, 0x45800000, v116
	v_cndmask_b32_e32 v113, v116, v112, vcc
	v_mul_f32_e32 v112, 0xbfb8aa3b, v113
	v_pk_mul_f32 v[114:115], v[110:111], v[112:113] op_sel_hi:[1,0]
	v_pk_mul_f32 v[116:117], v[108:109], v[112:113] op_sel_hi:[1,0]
	v_pk_mul_f32 v[120:121], v[100:101], v[112:113] op_sel_hi:[1,0]
	v_pk_mul_f32 v[118:119], v[102:103], v[112:113] op_sel_hi:[1,0]
	v_exp_f32_e32 v112, v116
	v_exp_f32_e32 v116, v120
	v_exp_f32_e32 v120, v121
	v_exp_f32_e32 v121, v114
	v_exp_f32_e32 v123, v115
	v_mad_i64_i32 v[114:115], s[14:15], v122, s58, 0
	v_exp_f32_e32 v117, v117
	v_exp_f32_e32 v118, v118
	v_exp_f32_e32 v119, v119
	v_lshl_add_u64 v[114:115], v[114:115], 1, v[144:145]
	v_add_f32_e32 v112, 1.0, v112
	v_rcp_f32_e32 v122, v112
	v_add_f32_e32 v112, 1.0, v117
	v_rcp_f32_e32 v117, v112
	v_add_f32_e32 v112, 1.0, v121
	v_rcp_f32_e32 v121, v112
	v_add_f32_e32 v112, 1.0, v123
	v_rcp_f32_e32 v123, v112
	v_add_f32_e32 v112, 1.0, v116
	v_rcp_f32_e32 v116, v112
	v_add_f32_e32 v112, 1.0, v120
	v_rcp_f32_e32 v120, v112
	v_add_f32_e32 v112, 1.0, v118
	v_rcp_f32_e32 v118, v112
	v_add_f32_e32 v112, 1.0, v119
	v_rcp_f32_e32 v119, v112
	v_mul_f32_e32 v100, v96, v100
	v_mul_f32_e32 v101, v97, v101
	v_mov_b32_e32 v112, v98
	v_mov_b32_e32 v96, v102
	v_mov_b32_e32 v97, v113
	v_pk_mul_f32 v[96:97], v[112:113], v[96:97]
	v_mul_f32_e32 v105, v105, v109
	v_mul_f32_e32 v100, v100, v97
	v_mul_f32_e32 v104, v104, v108
	v_mul_f32_e32 v102, v100, v116
	v_mul_f32_e32 v100, v105, v97
	v_mul_f32_e32 v106, v106, v110
	v_mul_f32_e32 v98, v104, v97
	v_mul_f32_e32 v104, v100, v117
	v_mul_f32_e32 v100, v101, v97
	v_mul_f32_e32 v105, v100, v120
	v_mul_f32_e32 v100, v106, v97
	v_add_u32_e32 v109, 0x80, v168
	v_mul_f32_e32 v106, v100, v121
	ds_read2st64_b32 v[100:101], v109 offset1:4
	v_mul_f32_e32 v96, v96, v97
	v_mul_f32_e32 v108, v96, v118
	v_mul_f32_e32 v96, v107, v111
	v_mul_f32_e32 v96, v96, v97
	s_waitcnt lgkmcnt(0)
; #define LAS __attribute__((address_space(3)))
; DEVI u32x4 pack8(const float* f) { u32x4 u; u.x = pk_bf16(f[0], f[1]); u.y = pk_bf16(f[2], f[3]); u.z = pk_bf16(f[4], f[5]); u.w = pk_bf16(f[6], f[7]); return u; }
; DEVI float row_rstd(const LAS float* rsl, int r) { return rsqrtf((rsl[r] + rsl[256 + r]) * (1.0f / DM) + 1e-6f); }
;     DEVI void operator()(const f32x4 (&acc)[2][2][4][2], const Unit& u, int wr, int wc, int fr, int fq, const LAS float* rsl) const {
;         bf16_t* const O = O_; const int ldc = ldc_; const float* const rs = rs_; const int rsn = rsn_;
;         const int row0 = u.pm * BM + wr * 64 + fr, col0 = u.pn * HALF + wc * 32 + 8 * fq;
; #pragma unroll
;         for (int ai = 0; ai < 2; ++ai)
; #pragma unroll
;             for (int m = 0; m < 4; ++m) { bf16_t* rowp = O + (size_t)(row0 + ai * HALF + m * 16) * ldc + col0;
;                 const float sc = row_rstd(rsl, wr * 64 + fr + ai * HALF + m * 16);
;                 const float k1 = -1.4426950408889634f * sc, k2 = sc * sc;
;                 float h[8], tt[8];
;                 const f32x4 guk0 = (acc[ai][0][m][0] * acc[ai][1][m][0]) * k2, guk1 = (acc[ai][0][m][1] * acc[ai][1][m][1]) * k2;
;                 const f32x4 ta = acc[ai][0][m][0] * k1, tb = acc[ai][0][m][1] * k1;
; #pragma unroll
;                 for (int j = 0; j < 4; ++j) { tt[j] = __builtin_amdgcn_exp2f(ta[j]); tt[4 + j] = __builtin_amdgcn_exp2f(tb[j]); }
;                 __builtin_amdgcn_sched_barrier(0);
; #pragma unroll
;                 for (int j = 0; j < 8; ++j) tt[j] = __builtin_amdgcn_rcpf(1.0f + tt[j]);
;                 __builtin_amdgcn_sched_barrier(0);
; #pragma unroll
;                 for (int j = 0; j < 4; ++j) { h[j] = guk0[j] * tt[j]; h[4 + j] = guk1[j] * tt[4 + j]; }
;                 *(u32x4*)rowp = pack8(h); }
	v_add_f32_e32 v100, v100, v101
	v_fmamk_f32 v100, v100, 0x3a000000, v156
	v_mul_f32_e32 v101, 0x4b800000, v100
	v_cmp_gt_f32_e32 vcc, s52, v100
	v_mul_f32_e32 v107, v96, v123
	v_mul_f32_e32 v96, v99, v103
	v_cndmask_b32_e32 v100, v100, v101, vcc
	v_rsq_f32_e32 v100, v100
	v_mul_f32_e32 v96, v96, v97
	v_mul_f32_e32 v98, v98, v122
	v_mul_f32_e32 v99, v96, v119
	v_cvt_pk_bf16_f32 v96, v98, v104
	v_cvt_pk_bf16_f32 v97, v106, v107
	v_cvt_pk_bf16_f32 v98, v102, v105
	v_cvt_pk_bf16_f32 v99, v108, v99
	global_store_dwordx4 v[114:115], v[96:99], off nt
	v_or_b32_e32 v106, 32, v157
	s_nop 0
	v_mul_f32_e32 v96, 0x45800000, v100
	v_cndmask_b32_e32 v97, v100, v96, vcc
	v_mul_f32_e32 v96, 0xbfb8aa3b, v97
	v_pk_mul_f32 v[98:99], v[94:95], v[96:97] op_sel_hi:[1,0]
	v_pk_mul_f32 v[100:101], v[92:93], v[96:97] op_sel_hi:[1,0]
	v_pk_mul_f32 v[104:105], v[84:85], v[96:97] op_sel_hi:[1,0]
	v_pk_mul_f32 v[102:103], v[86:87], v[96:97] op_sel_hi:[1,0]
	v_exp_f32_e32 v96, v100
	v_exp_f32_e32 v100, v104
	v_exp_f32_e32 v104, v105
	v_exp_f32_e32 v105, v98
	v_exp_f32_e32 v107, v99
	v_mad_i64_i32 v[98:99], s[14:15], v106, s58, 0
	v_exp_f32_e32 v101, v101
	v_exp_f32_e32 v102, v102
	v_exp_f32_e32 v103, v103
	v_lshl_add_u64 v[98:99], v[98:99], 1, v[144:145]
	v_add_f32_e32 v96, 1.0, v96
	v_rcp_f32_e32 v106, v96
	v_add_f32_e32 v96, 1.0, v101
	v_rcp_f32_e32 v101, v96
	v_add_f32_e32 v96, 1.0, v105
	v_rcp_f32_e32 v105, v96
	v_add_f32_e32 v96, 1.0, v107
	v_rcp_f32_e32 v107, v96
	v_add_f32_e32 v96, 1.0, v100
	v_rcp_f32_e32 v100, v96
	v_add_f32_e32 v96, 1.0, v104
	v_rcp_f32_e32 v104, v96
	v_add_f32_e32 v96, 1.0, v102
	v_rcp_f32_e32 v102, v96
	v_add_f32_e32 v96, 1.0, v103
	v_rcp_f32_e32 v103, v96
	v_mul_f32_e32 v84, v80, v84
	v_mul_f32_e32 v85, v81, v85
	v_mov_b32_e32 v96, v82
	v_mov_b32_e32 v80, v86
	v_mov_b32_e32 v81, v97
	v_pk_mul_f32 v[80:81], v[96:97], v[80:81]
	v_mul_f32_e32 v89, v89, v93
	v_mul_f32_e32 v84, v84, v81
	v_mul_f32_e32 v88, v88, v92
	v_mul_f32_e32 v86, v84, v100
	v_mul_f32_e32 v84, v89, v81
	v_mul_f32_e32 v90, v90, v94
	v_mul_f32_e32 v82, v88, v81
	v_mul_f32_e32 v88, v84, v101
	v_mul_f32_e32 v84, v85, v81
	v_mul_f32_e32 v89, v84, v104
	v_mul_f32_e32 v84, v90, v81
	v_add_u32_e32 v93, 0xc0, v168
	v_mul_f32_e32 v90, v84, v105
	ds_read2st64_b32 v[84:85], v93 offset1:4
	v_mul_f32_e32 v80, v80, v81
	v_mul_f32_e32 v92, v80, v102
	v_mul_f32_e32 v80, v91, v95
	v_mul_f32_e32 v80, v80, v81
	s_waitcnt lgkmcnt(0)
	v_add_f32_e32 v84, v84, v85
	v_fmamk_f32 v84, v84, 0x3a000000, v156
	v_mul_f32_e32 v85, 0x4b800000, v84
	v_cmp_gt_f32_e32 vcc, s52, v84
	v_mul_f32_e32 v91, v80, v107
	v_mul_f32_e32 v80, v83, v87
	v_cndmask_b32_e32 v84, v84, v85, vcc
	v_rsq_f32_e32 v84, v84
	v_mul_f32_e32 v80, v80, v81
	v_mul_f32_e32 v82, v82, v106
	v_mul_f32_e32 v83, v80, v103
	v_cvt_pk_bf16_f32 v80, v82, v88
	v_cvt_pk_bf16_f32 v81, v90, v91
	v_cvt_pk_bf16_f32 v82, v86, v89
	v_cvt_pk_bf16_f32 v83, v92, v83
	global_store_dwordx4 v[98:99], v[80:83], off nt
	v_or_b32_e32 v90, 48, v157
	s_nop 0
	v_mul_f32_e32 v80, 0x45800000, v84
	v_cndmask_b32_e32 v81, v84, v80, vcc
	v_mul_f32_e32 v80, 0xbfb8aa3b, v81
	v_pk_mul_f32 v[82:83], v[78:79], v[80:81] op_sel_hi:[1,0]
	v_pk_mul_f32 v[84:85], v[76:77], v[80:81] op_sel_hi:[1,0]
	v_pk_mul_f32 v[88:89], v[68:69], v[80:81] op_sel_hi:[1,0]
	v_pk_mul_f32 v[86:87], v[70:71], v[80:81] op_sel_hi:[1,0]
	v_exp_f32_e32 v80, v84
	v_exp_f32_e32 v84, v88
	v_exp_f32_e32 v88, v89
	v_exp_f32_e32 v89, v82
	v_exp_f32_e32 v91, v83
	v_mad_i64_i32 v[82:83], s[14:15], v90, s58, 0
	v_exp_f32_e32 v85, v85
	v_exp_f32_e32 v86, v86
	v_exp_f32_e32 v87, v87
	v_lshl_add_u64 v[82:83], v[82:83], 1, v[144:145]
	v_add_f32_e32 v80, 1.0, v80
	v_rcp_f32_e32 v90, v80
	v_add_f32_e32 v80, 1.0, v85
	v_rcp_f32_e32 v85, v80
	v_add_f32_e32 v80, 1.0, v89
	v_rcp_f32_e32 v89, v80
	v_add_f32_e32 v80, 1.0, v91
	v_rcp_f32_e32 v91, v80
	v_add_f32_e32 v80, 1.0, v84
	v_rcp_f32_e32 v84, v80
	v_add_f32_e32 v80, 1.0, v88
	v_rcp_f32_e32 v88, v80
	v_add_f32_e32 v80, 1.0, v86
	v_rcp_f32_e32 v86, v80
	v_add_f32_e32 v80, 1.0, v87
	v_rcp_f32_e32 v87, v80
	v_mul_f32_e32 v68, v64, v68
	v_mul_f32_e32 v69, v65, v69
	v_mov_b32_e32 v80, v66
	v_mov_b32_e32 v64, v70
	v_mov_b32_e32 v65, v81
	v_pk_mul_f32 v[64:65], v[80:81], v[64:65]
	v_mul_f32_e32 v73, v73, v77
	v_mul_f32_e32 v68, v68, v65
	v_mul_f32_e32 v72, v72, v76
	v_mul_f32_e32 v70, v68, v84
	v_mul_f32_e32 v68, v73, v65
	v_mul_f32_e32 v74, v74, v78
	v_mul_f32_e32 v66, v72, v65
	v_mul_f32_e32 v72, v68, v85
	v_mul_f32_e32 v68, v69, v65
	v_mul_f32_e32 v73, v68, v88
	v_mul_f32_e32 v68, v74, v65
	v_mul_f32_e32 v74, v68, v89
	ds_read2st64_b32 v[68:69], v168 offset0:2 offset1:6
	v_mul_f32_e32 v64, v64, v65
	v_mul_f32_e32 v76, v64, v86
	v_mul_f32_e32 v64, v75, v79
	v_mul_f32_e32 v64, v64, v65
	s_waitcnt lgkmcnt(0)
; #define LAS __attribute__((address_space(3)))
; DEVI u32x4 pack8(const float* f) { u32x4 u; u.x = pk_bf16(f[0], f[1]); u.y = pk_bf16(f[2], f[3]); u.z = pk_bf16(f[4], f[5]); u.w = pk_bf16(f[6], f[7]); return u; }
; DEVI float row_rstd(const LAS float* rsl, int r) { return rsqrtf((rsl[r] + rsl[256 + r]) * (1.0f / DM) + 1e-6f); }
;     DEVI void operator()(const f32x4 (&acc)[2][2][4][2], const Unit& u, int wr, int wc, int fr, int fq, const LAS float* rsl) const {
;         bf16_t* const O = O_; const int ldc = ldc_; const float* const rs = rs_; const int rsn = rsn_;
;         const int row0 = u.pm * BM + wr * 64 + fr, col0 = u.pn * HALF + wc * 32 + 8 * fq;
; #pragma unroll
;         for (int ai = 0; ai < 2; ++ai)
; #pragma unroll
;             for (int m = 0; m < 4; ++m) { bf16_t* rowp = O + (size_t)(row0 + ai * HALF + m * 16) * ldc + col0;
;                 const float sc = row_rstd(rsl, wr * 64 + fr + ai * HALF + m * 16);
;                 const float k1 = -1.4426950408889634f * sc, k2 = sc * sc;
;                 float h[8], tt[8];
;                 const f32x4 guk0 = (acc[ai][0][m][0] * acc[ai][1][m][0]) * k2, guk1 = (acc[ai][0][m][1] * acc[ai][1][m][1]) * k2;
;                 const f32x4 ta = acc[ai][0][m][0] * k1, tb = acc[ai][0][m][1] * k1;
; #pragma unroll
;                 for (int j = 0; j < 4; ++j) { tt[j] = __builtin_amdgcn_exp2f(ta[j]); tt[4 + j] = __builtin_amdgcn_exp2f(tb[j]); }
;                 __builtin_amdgcn_sched_barrier(0);
; #pragma unroll
;                 for (int j = 0; j < 8; ++j) tt[j] = __builtin_amdgcn_rcpf(1.0f + tt[j]);
;                 __builtin_amdgcn_sched_barrier(0);
; #pragma unroll
;                 for (int j = 0; j < 4; ++j) { h[j] = guk0[j] * tt[j]; h[4 + j] = guk1[j] * tt[4 + j]; }
;                 *(u32x4*)rowp = pack8(h); }
	v_add_f32_e32 v68, v68, v69
	v_fmamk_f32 v68, v68, 0x3a000000, v156
	v_mul_f32_e32 v69, 0x4b800000, v68
	v_cmp_gt_f32_e32 vcc, s52, v68
	v_mul_f32_e32 v75, v64, v91
	v_mul_f32_e32 v64, v67, v71
	v_cndmask_b32_e32 v68, v68, v69, vcc
	v_rsq_f32_e32 v68, v68
	v_mul_f32_e32 v64, v64, v65
	v_mul_f32_e32 v66, v66, v90
	v_mul_f32_e32 v67, v64, v87
	v_cvt_pk_bf16_f32 v64, v66, v72
	v_cvt_pk_bf16_f32 v65, v74, v75
	v_cvt_pk_bf16_f32 v66, v70, v73
	v_cvt_pk_bf16_f32 v67, v76, v67
	global_store_dwordx4 v[82:83], v[64:67], off nt
	v_add_u32_e32 v74, 0x80, v157
	s_nop 0
	v_mul_f32_e32 v64, 0x45800000, v68
	v_cndmask_b32_e32 v65, v68, v64, vcc
	v_mul_f32_e32 v64, 0xbfb8aa3b, v65
	v_pk_mul_f32 v[66:67], v[62:63], v[64:65] op_sel_hi:[1,0]
	v_pk_mul_f32 v[68:69], v[60:61], v[64:65] op_sel_hi:[1,0]
	v_pk_mul_f32 v[72:73], v[56:57], v[64:65] op_sel_hi:[1,0]
	v_pk_mul_f32 v[70:71], v[58:59], v[64:65] op_sel_hi:[1,0]
	v_exp_f32_e32 v64, v68
	v_exp_f32_e32 v68, v72
	v_exp_f32_e32 v72, v73
	v_exp_f32_e32 v73, v66
	v_exp_f32_e32 v75, v67
	v_mad_i64_i32 v[66:67], s[14:15], v74, s58, 0
	v_exp_f32_e32 v69, v69
	v_exp_f32_e32 v70, v70
	v_exp_f32_e32 v71, v71
	v_lshl_add_u64 v[66:67], v[66:67], 1, v[144:145]
	v_add_f32_e32 v64, 1.0, v64
	v_rcp_f32_e32 v74, v64
	v_add_f32_e32 v64, 1.0, v69
	v_rcp_f32_e32 v69, v64
	v_add_f32_e32 v64, 1.0, v73
	v_rcp_f32_e32 v73, v64
	v_add_f32_e32 v64, 1.0, v75
	v_rcp_f32_e32 v75, v64
	v_add_f32_e32 v64, 1.0, v68
	v_rcp_f32_e32 v68, v64
	v_add_f32_e32 v64, 1.0, v72
	v_rcp_f32_e32 v72, v64
	v_add_f32_e32 v64, 1.0, v70
	v_rcp_f32_e32 v70, v64
	v_add_f32_e32 v64, 1.0, v71
	v_rcp_f32_e32 v71, v64
	v_mul_f32_e32 v56, v48, v56
	v_mul_f32_e32 v57, v49, v57
	v_mov_b32_e32 v64, v50
	v_mov_b32_e32 v48, v58
	v_mov_b32_e32 v49, v65
	v_mul_f32_e32 v52, v52, v60
	v_pk_mul_f32 v[48:49], v[64:65], v[48:49]
	v_mul_f32_e32 v53, v53, v61
	v_mul_f32_e32 v50, v52, v49
	v_mul_f32_e32 v52, v56, v49
	v_mul_f32_e32 v56, v52, v68
	v_mul_f32_e32 v52, v53, v49
	v_mul_f32_e32 v54, v54, v62
	v_mul_f32_e32 v58, v52, v69
	v_mul_f32_e32 v52, v57, v49
	v_mul_f32_e32 v57, v52, v72
	v_mul_f32_e32 v52, v54, v49
	v_mul_f32_e32 v54, v52, v73
	ds_read2st64_b32 v[52:53], v125 offset0:2 offset1:6
	v_mul_f32_e32 v48, v48, v49
	v_mul_f32_e32 v60, v48, v70
	v_mul_f32_e32 v48, v55, v63
	v_mul_f32_e32 v48, v48, v49
	s_waitcnt lgkmcnt(0)
	v_add_f32_e32 v52, v52, v53
	v_fmamk_f32 v52, v52, 0x3a000000, v156
	v_mul_f32_e32 v53, 0x4b800000, v52
	v_cmp_gt_f32_e32 vcc, s52, v52
	v_mul_f32_e32 v55, v48, v75
	v_mul_f32_e32 v48, v51, v59
	v_cndmask_b32_e32 v52, v52, v53, vcc
	v_rsq_f32_e32 v52, v52
	v_mul_f32_e32 v48, v48, v49
	v_mul_f32_e32 v50, v50, v74
	v_mul_f32_e32 v51, v48, v71
	v_cvt_pk_bf16_f32 v48, v50, v58
	v_cvt_pk_bf16_f32 v49, v54, v55
	v_cvt_pk_bf16_f32 v50, v56, v57
	v_cvt_pk_bf16_f32 v51, v60, v51
	global_store_dwordx4 v[66:67], v[48:51], off nt
	v_add_u32_e32 v58, 0x90, v157
	s_nop 0
	v_mul_f32_e32 v48, 0x45800000, v52
	v_cndmask_b32_e32 v49, v52, v48, vcc
	v_mul_f32_e32 v48, 0xbfb8aa3b, v49
	v_pk_mul_f32 v[50:51], v[46:47], v[48:49] op_sel_hi:[1,0]
	v_pk_mul_f32 v[52:53], v[44:45], v[48:49] op_sel_hi:[1,0]
	v_pk_mul_f32 v[56:57], v[40:41], v[48:49] op_sel_hi:[1,0]
	v_pk_mul_f32 v[54:55], v[42:43], v[48:49] op_sel_hi:[1,0]
	v_exp_f32_e32 v48, v52
	v_exp_f32_e32 v52, v56
	v_exp_f32_e32 v56, v57
	v_exp_f32_e32 v57, v50
	v_exp_f32_e32 v59, v51
	v_mad_i64_i32 v[50:51], s[14:15], v58, s58, 0
	v_exp_f32_e32 v53, v53
	v_exp_f32_e32 v54, v54
	v_exp_f32_e32 v55, v55
	v_lshl_add_u64 v[50:51], v[50:51], 1, v[144:145]
	v_add_f32_e32 v48, 1.0, v48
	v_rcp_f32_e32 v58, v48
	v_add_f32_e32 v48, 1.0, v53
	v_rcp_f32_e32 v53, v48
	v_add_f32_e32 v48, 1.0, v57
	v_rcp_f32_e32 v57, v48
	v_add_f32_e32 v48, 1.0, v59
	v_rcp_f32_e32 v59, v48
	v_add_f32_e32 v48, 1.0, v52
	v_rcp_f32_e32 v52, v48
	v_add_f32_e32 v48, 1.0, v56
	v_rcp_f32_e32 v56, v48
	v_add_f32_e32 v48, 1.0, v54
	v_rcp_f32_e32 v54, v48
	v_add_f32_e32 v48, 1.0, v55
	v_rcp_f32_e32 v55, v48
	v_mul_f32_e32 v40, v32, v40
	v_mul_f32_e32 v41, v33, v41
	v_mov_b32_e32 v48, v34
	v_mov_b32_e32 v32, v42
	v_mov_b32_e32 v33, v49
	v_mul_f32_e32 v36, v36, v44
	v_pk_mul_f32 v[32:33], v[48:49], v[32:33]
	v_mul_f32_e32 v37, v37, v45
	v_mul_f32_e32 v34, v36, v33
	v_mul_f32_e32 v36, v40, v33
	v_mul_f32_e32 v40, v36, v52
	v_mul_f32_e32 v36, v37, v33
	v_mul_f32_e32 v38, v38, v46
	v_mul_f32_e32 v42, v36, v53
	v_mul_f32_e32 v36, v41, v33
	v_mul_f32_e32 v41, v36, v56
	v_mul_f32_e32 v36, v38, v33
	v_mul_f32_e32 v38, v36, v57
	ds_read2st64_b32 v[36:37], v109 offset0:2 offset1:6
	v_mul_f32_e32 v32, v32, v33
	v_mul_f32_e32 v44, v32, v54
	v_mul_f32_e32 v32, v39, v47
	v_mul_f32_e32 v32, v32, v33
	s_waitcnt lgkmcnt(0)
; #define LAS __attribute__((address_space(3)))
; DEVI u32x4 pack8(const float* f) { u32x4 u; u.x = pk_bf16(f[0], f[1]); u.y = pk_bf16(f[2], f[3]); u.z = pk_bf16(f[4], f[5]); u.w = pk_bf16(f[6], f[7]); return u; }
;     DEVI void operator()(const f32x4 (&acc)[2][2][4][2], const Unit& u, int wr, int wc, int fr, int fq, const LAS float* rsl) const {
;     ...
;         for (int ai = 0; ai < 2; ++ai)
; #pragma unroll
;             for (int m = 0; m < 4; ++m) { bf16_t* rowp = O + (size_t)(row0 + ai * HALF + m * 16) * ldc + col0;
;                 const float sc = row_rstd(rsl, wr * 64 + fr + ai * HALF + m * 16);
;                 const float k1 = -1.4426950408889634f * sc, k2 = sc * sc;
;                 float h[8], tt[8];
;                 const f32x4 guk0 = (acc[ai][0][m][0] * acc[ai][1][m][0]) * k2, guk1 = (acc[ai][0][m][1] * acc[ai][1][m][1]) * k2;
;                 const f32x4 ta = acc[ai][0][m][0] * k1, tb = acc[ai][0][m][1] * k1;
; #pragma unroll
;                 for (int j = 0; j < 4; ++j) { tt[j] = __builtin_amdgcn_exp2f(ta[j]); tt[4 + j] = __builtin_amdgcn_exp2f(tb[j]); }
;                 __builtin_amdgcn_sched_barrier(0);
; #pragma unroll
;                 for (int j = 0; j < 8; ++j) tt[j] = __builtin_amdgcn_rcpf(1.0f + tt[j]);
;                 __builtin_amdgcn_sched_barrier(0);
; #pragma unroll
;                 for (int j = 0; j < 4; ++j) { h[j] = guk0[j] * tt[j]; h[4 + j] = guk1[j] * tt[4 + j]; }
;                 *(u32x4*)rowp = pack8(h); }
; template <class Epi>
; DEVI void gemm_phase(LAS unsigned char* lds, const bf16_t* gA, const bf16_t* gBt, const int lda, const int ldb, const int K, const StaticOrder S_, const Epi E) {
;     ...
;     auto rs_prefetch = [&](const Unit& u, int par) {
;         if constexpr (Epi::HAS_RS) { if (E.rs_) {
;             const int r = tid & 255, hf = tid >> 8; float s = 0.f;
;             const float* base = E.rs_ + (size_t)(u.pm * BM + r) * 32 + hf * 16;
;             if (E.rsn_ == 32) {
;                 const f32x4 a = *(const f32x4*)base, b = *(const f32x4*)(base + 4), c = *(const f32x4*)(base + 8), d = *(const f32x4*)(base + 12);
;                 s = ((a[0] + a[1]) + (a[2] + a[3])) + ((b[0] + b[1]) + (b[2] + b[3])) + ((c[0] + c[1]) + (c[2] + c[3])) + ((d[0] + d[1]) + (d[2] + d[3]));
;             } else if (hf == 0) s = base[0];
;             *(LAS float*)(lds + STAGE_BYTES + par * 2048 + hf * 1024 + r * 4) = s; } }
	v_add_f32_e32 v36, v36, v37
	v_fmamk_f32 v36, v36, 0x3a000000, v156
	v_mul_f32_e32 v37, 0x4b800000, v36
	v_cmp_gt_f32_e32 vcc, s52, v36
	v_mul_f32_e32 v39, v32, v59
	v_mul_f32_e32 v32, v35, v43
	v_cndmask_b32_e32 v36, v36, v37, vcc
	v_rsq_f32_e32 v36, v36
	v_mul_f32_e32 v32, v32, v33
	v_mul_f32_e32 v34, v34, v58
	v_mul_f32_e32 v35, v32, v55
	v_cvt_pk_bf16_f32 v32, v34, v42
	v_cvt_pk_bf16_f32 v33, v38, v39
	v_cvt_pk_bf16_f32 v34, v40, v41
	v_cvt_pk_bf16_f32 v35, v44, v35
	global_store_dwordx4 v[50:51], v[32:35], off nt
	v_add_u32_e32 v42, 0xa0, v157
	s_nop 0
	v_mul_f32_e32 v32, 0x45800000, v36
	v_cndmask_b32_e32 v33, v36, v32, vcc
	v_mul_f32_e32 v32, 0xbfb8aa3b, v33
	v_pk_mul_f32 v[34:35], v[30:31], v[32:33] op_sel_hi:[1,0]
	v_pk_mul_f32 v[36:37], v[28:29], v[32:33] op_sel_hi:[1,0]
	v_pk_mul_f32 v[40:41], v[24:25], v[32:33] op_sel_hi:[1,0]
	v_pk_mul_f32 v[38:39], v[26:27], v[32:33] op_sel_hi:[1,0]
	v_exp_f32_e32 v32, v36
	v_exp_f32_e32 v36, v40
	v_exp_f32_e32 v40, v41
	v_exp_f32_e32 v41, v34
	v_exp_f32_e32 v43, v35
	v_mad_i64_i32 v[34:35], s[14:15], v42, s58, 0
	v_exp_f32_e32 v37, v37
	v_exp_f32_e32 v38, v38
	v_exp_f32_e32 v39, v39
	v_lshl_add_u64 v[34:35], v[34:35], 1, v[144:145]
	v_add_f32_e32 v32, 1.0, v32
	v_rcp_f32_e32 v42, v32
	v_add_f32_e32 v32, 1.0, v37
	v_rcp_f32_e32 v37, v32
	v_add_f32_e32 v32, 1.0, v41
	v_rcp_f32_e32 v41, v32
	v_add_f32_e32 v32, 1.0, v43
	v_rcp_f32_e32 v43, v32
	v_add_f32_e32 v32, 1.0, v36
	v_rcp_f32_e32 v36, v32
	v_add_f32_e32 v32, 1.0, v40
	v_rcp_f32_e32 v40, v32
	v_add_f32_e32 v32, 1.0, v38
	v_rcp_f32_e32 v38, v32
	v_add_f32_e32 v32, 1.0, v39
	v_rcp_f32_e32 v39, v32
	v_mul_f32_e32 v24, v16, v24
	v_mul_f32_e32 v25, v17, v25
	v_mov_b32_e32 v32, v18
	v_mov_b32_e32 v16, v26
	v_mov_b32_e32 v17, v33
	v_mul_f32_e32 v20, v20, v28
	v_pk_mul_f32 v[16:17], v[32:33], v[16:17]
	v_mul_f32_e32 v21, v21, v29
	v_mul_f32_e32 v18, v20, v17
	v_mul_f32_e32 v20, v24, v17
	v_mul_f32_e32 v24, v20, v36
	v_mul_f32_e32 v20, v21, v17
	v_mul_f32_e32 v22, v22, v30
	v_mul_f32_e32 v26, v20, v37
	v_mul_f32_e32 v20, v25, v17
	v_mul_f32_e32 v25, v20, v40
	v_mul_f32_e32 v20, v22, v17
	v_mul_f32_e32 v22, v20, v41
	ds_read2st64_b32 v[20:21], v93 offset0:2 offset1:6
	v_mul_f32_e32 v16, v16, v17
	v_mul_f32_e32 v28, v16, v38
	v_mul_f32_e32 v16, v23, v31
	v_mul_f32_e32 v16, v16, v17
	s_waitcnt lgkmcnt(0)
	v_add_f32_e32 v20, v20, v21
	v_fmamk_f32 v20, v20, 0x3a000000, v156
	v_mul_f32_e32 v21, 0x4b800000, v20
	v_cmp_gt_f32_e32 vcc, s52, v20
	v_mul_f32_e32 v23, v16, v43
	v_mul_f32_e32 v16, v19, v27
	v_cndmask_b32_e32 v20, v20, v21, vcc
	v_rsq_f32_e32 v20, v20
	v_mul_f32_e32 v16, v16, v17
	v_mul_f32_e32 v18, v18, v42
	v_mul_f32_e32 v19, v16, v39
	v_cvt_pk_bf16_f32 v16, v18, v26
	v_cvt_pk_bf16_f32 v17, v22, v23
	v_cvt_pk_bf16_f32 v18, v24, v25
	v_cvt_pk_bf16_f32 v19, v28, v19
	global_store_dwordx4 v[34:35], v[16:19], off nt
	v_add_u32_e32 v26, 0xb0, v157
	s_nop 0
	v_mul_f32_e32 v16, 0x45800000, v20
	v_cndmask_b32_e32 v17, v20, v16, vcc
	v_mul_f32_e32 v16, 0xbfb8aa3b, v17
	v_pk_mul_f32 v[18:19], v[14:15], v[16:17] op_sel_hi:[1,0]
	v_pk_mul_f32 v[20:21], v[12:13], v[16:17] op_sel_hi:[1,0]
	v_pk_mul_f32 v[24:25], v[8:9], v[16:17] op_sel_hi:[1,0]
	v_pk_mul_f32 v[22:23], v[10:11], v[16:17] op_sel_hi:[1,0]
	v_exp_f32_e32 v16, v20
	v_exp_f32_e32 v20, v24
	v_exp_f32_e32 v24, v25
	v_exp_f32_e32 v25, v18
	v_exp_f32_e32 v27, v19
	v_mad_i64_i32 v[18:19], s[14:15], v26, s58, 0
	v_exp_f32_e32 v21, v21
	v_exp_f32_e32 v22, v22
	v_exp_f32_e32 v23, v23
	v_lshl_add_u64 v[18:19], v[18:19], 1, v[144:145]
	v_add_f32_e32 v16, 1.0, v16
	v_rcp_f32_e32 v26, v16
	v_add_f32_e32 v16, 1.0, v21
	v_rcp_f32_e32 v21, v16
	v_add_f32_e32 v16, 1.0, v25
	v_rcp_f32_e32 v25, v16
	v_add_f32_e32 v16, 1.0, v27
	v_rcp_f32_e32 v27, v16
	v_add_f32_e32 v16, 1.0, v20
	v_rcp_f32_e32 v20, v16
	v_add_f32_e32 v16, 1.0, v24
	v_rcp_f32_e32 v24, v16
	v_add_f32_e32 v16, 1.0, v22
	v_rcp_f32_e32 v22, v16
	v_add_f32_e32 v16, 1.0, v23
	v_rcp_f32_e32 v23, v16
	v_mul_f32_e32 v8, v0, v8
	v_mul_f32_e32 v9, v1, v9
	v_mov_b32_e32 v16, v2
	v_mov_b32_e32 v0, v10
	v_mov_b32_e32 v1, v17
	v_pk_mul_f32 v[0:1], v[16:17], v[0:1]
	v_mul_f32_e32 v4, v4, v12
	v_mul_f32_e32 v0, v0, v1
	v_mul_f32_e32 v2, v4, v1
	v_mul_f32_e32 v4, v8, v1
	v_mul_f32_e32 v8, v9, v1
	v_mul_f32_e32 v9, v0, v22
	v_mul_f32_e32 v0, v7, v15
	v_mul_f32_e32 v0, v0, v1
	v_mul_f32_e32 v7, v0, v27
	v_mul_f32_e32 v0, v3, v11
	v_mul_f32_e32 v5, v5, v13
	v_mul_f32_e32 v6, v6, v14
	v_mul_f32_e32 v0, v0, v1
	v_mul_f32_e32 v2, v2, v26
	v_mul_f32_e32 v5, v5, v1
	v_mul_f32_e32 v6, v6, v1
	v_mul_f32_e32 v3, v0, v23
	s_and_b64 vcc, exec, s[36:37]
	s_mov_b64 s[14:15], -1
	v_mul_f32_e32 v4, v4, v20
	v_mul_f32_e32 v5, v5, v21
	v_mul_f32_e32 v8, v8, v24
	v_mul_f32_e32 v6, v6, v25
	v_cvt_pk_bf16_f32 v0, v2, v5
	v_cvt_pk_bf16_f32 v1, v6, v7
	v_cvt_pk_bf16_f32 v2, v4, v8
	v_cvt_pk_bf16_f32 v3, v9, v3
	global_store_dwordx4 v[18:19], v[0:3], off nt
	s_cbranch_vccnz .LBB0_2501
	s_and_b64 vcc, exec, s[12:13]
	s_cbranch_vccz .LBB0_2500
	v_lshl_or_b32 v0, s55, 8, v146
	v_ashrrev_i32_e32 v1, 31, v0
	v_lshlrev_b64 v[0:1], 7, v[0:1]
	v_lshl_add_u64 v[0:1], v[136:137], 0, v[0:1]
	s_and_b64 vcc, exec, s[40:41]
	s_cbranch_vccz .LBB0_2517
	v_mov_b32_e32 v2, 0
	s_and_saveexec_b64 s[14:15], s[34:35]
	s_cbranch_execz .LBB0_2516
	global_load_dword v2, v[0:1], off

; DEVI unsigned pk_bf16(float lo, float hi) { unsigned r; asm("v_cvt_pk_bf16_f32 %0, %1, %2" : "=v"(r) : "v"(lo), "v"(hi)); return r; }
;     DEVI void operator()(const f32x4 (&acc)[2][2][4][2], const Unit& u, int wr, int wc, int fr, int fq, const LAS float*) const {
;     ...
;         const int row0 = u.pm * BM + wr * 64 + fr, col0 = u.pn * BM + wc * 32 + 4 * fq;
;         f32x4 cur[2][2], nxt[2][2];
;         { const size_t ro = (size_t)row0 * ldc + col0;
; #pragma unroll
;           for (int bj = 0; bj < 2; ++bj)
; #pragma unroll
;               for (int n = 0; n < 2; ++n) cur[bj][n] = *(const f32x4*)(R + ro + bj * HALF + n * 16); }
; #pragma unroll
;         for (int idx = 0; idx < 8; ++idx) {
;             const int ai = idx >> 2, m = idx & 3;
;             const size_t ro = (size_t)(row0 + ai * HALF + m * 16) * ldc + col0;
;             if (idx + 1 < 8) { const int ai2 = (idx + 1) >> 2, m2 = (idx + 1) & 3; const size_t ro2 = (size_t)(row0 + ai2 * HALF + m2 * 16) * ldc + col0;
; #pragma unroll
;                 for (int bj = 0; bj < 2; ++bj)
; #pragma unroll
;                     for (int n = 0; n < 2; ++n) nxt[bj][n] = *(const f32x4*)(R + ro2 + bj * HALF + n * 16); }
;             float ss = 0.f;
; #pragma unroll
;             for (int bj = 0; bj < 2; ++bj)
; #pragma unroll
;                 for (int n = 0; n < 2; ++n) {
;                     const f32x4 hn = cur[bj][n] + acc[ai][bj][m][n] * scale;
;                     *(f32x4*)(C + ro + bj * HALF + n * 16) = hn;
;                     if (HB) { u32x2 w; w.x = pk_bf16(hn[0], hn[1]); w.y = pk_bf16(hn[2], hn[3]); *(u32x2*)(HB + ro + bj * HALF + n * 16) = w;
;                         ss += hn[0] * hn[0] + hn[1] * hn[1] + hn[2] * hn[2] + hn[3] * hn[3]; } }
;             if (HB) { ss += __shfl_xor(ss, 16); ss += __shfl_xor(ss, 32); if (fq == 0) RS[(size_t)(row0 + ai * HALF + m * 16) * 32 + u.pn * 4 + wc] = ss; }
; #pragma unroll
;             for (int bj = 0; bj < 2; ++bj)
; #pragma unroll
;                 for (int n = 0; n < 2; ++n) cur[bj][n] = nxt[bj][n];
;         }
.LBB0_2591:
	v_lshl_add_u32 v188, s53, 8, v198
	v_lshl_or_b32 v182, s31, 8, v199
	v_mad_i64_i32 v[128:129], s[4:5], v188, s58, 0
	v_ashrrev_i32_e32 v183, 31, v182
	v_lshl_add_u64 v[128:129], v[128:129], 2, s[82:83]
	v_lshlrev_b64 v[130:131], 2, v[182:183]
	v_or_b32_e32 v190, 16, v188
	v_mov_b32_e32 v180, v203
	v_lshl_add_u64 v[128:129], v[128:129], 0, v[130:131]
	v_lshl_add_u64 v[186:187], s[82:83], 0, v[130:131]
	v_mad_i64_i32 v[192:193], s[4:5], v190, s58, 0
	global_load_dwordx4 v[160:163], v[128:129], off
	global_load_dwordx4 v[152:155], v[128:129], off offset:64
	global_load_dwordx4 v[148:151], v[128:129], off offset:512
	global_load_dwordx4 v[144:147], v[128:129], off offset:576
	v_lshl_add_u64 v[128:129], v[192:193], 2, v[186:187]
	global_load_dwordx4 v[140:143], v[128:129], off
	global_load_dwordx4 v[136:139], v[128:129], off offset:64
	global_load_dwordx4 v[132:135], v[128:129], off offset:512
	s_nop 0
	global_load_dwordx4 v[128:131], v[128:129], off offset:576
	s_lshl_b32 s24, s31, 2
	s_ashr_i32 s25, s24, 31
	s_lshl_b64 s[24:25], s[24:25], 2
	v_cndmask_b32_e64 v156, 0, 1, s[20:21]
	v_mov_b32_e32 v184, v180
	v_mov_b32_e32 v185, v180
	v_mad_i64_i32 v[158:159], s[26:27], v188, s58, v[182:183]
	s_add_u32 s24, s44, s24
	v_ashrrev_i32_e32 v189, 31, v188
	v_cmp_ne_u32_e64 s[4:5], 1, v156
	v_lshl_add_u64 v[194:195], v[158:159], 2, s[80:81]
	s_addc_u32 s25, s45, s25
	s_andn2_b64 vcc, exec, s[20:21]
	s_waitcnt vmcnt(0)
	v_pk_fma_f32 v[164:165], v[126:127], v[180:181], v[162:163] op_sel_hi:[1,0,1]
	v_pk_fma_f32 v[162:163], v[124:125], v[180:181], v[160:161] op_sel_hi:[1,0,1]
	v_pk_fma_f32 v[160:161], v[120:121], v[184:185], v[152:153]
	v_pk_fma_f32 v[156:157], v[116:117], v[184:185], v[148:149]
	v_pk_fma_f32 v[124:125], v[112:113], v[184:185], v[144:145]
	global_store_dwordx4 v[194:195], v[162:165], off nt
	s_cbranch_vccnz .LBB0_2630
	v_lshl_add_u64 v[116:117], v[158:159], 1, s[74:75]
	v_cvt_pk_bf16_f32 v112, v162, v163
	v_mul_f32_e32 v120, v163, v163
	v_mov_b32_e32 v181, v180
	v_cvt_pk_bf16_f32 v113, v164, v165
	global_store_dwordx2 v[116:117], v[112:113], off
	v_fmac_f32_e32 v120, v162, v162
	v_pk_fma_f32 v[162:163], v[122:123], v[180:181], v[154:155]
	v_cvt_pk_bf16_f32 v112, v160, v161
	global_store_dwordx4 v[194:195], v[160:163], off offset:64 nt
	v_cvt_pk_bf16_f32 v113, v162, v163
	global_store_dwordx2 v[116:117], v[112:113], off offset:32
	v_mul_f32_e32 v112, v161, v161
	v_fmac_f32_e32 v112, v160, v160
	v_mul_f32_e32 v113, v157, v157
	v_fmac_f32_e32 v120, v164, v164
	v_fmac_f32_e32 v112, v162, v162
	v_pk_fma_f32 v[158:159], v[118:119], v[180:181], v[150:151]
	v_fmac_f32_e32 v113, v156, v156
	v_fmac_f32_e32 v120, v165, v165
	v_fmac_f32_e32 v112, v163, v163
	v_fmac_f32_e32 v113, v158, v158
	v_add_f32_e32 v112, v120, v112
	v_fmac_f32_e32 v113, v159, v159
	v_add_f32_e32 v112, v113, v112
	v_mul_f32_e32 v113, v125, v125
	v_pk_fma_f32 v[126:127], v[114:115], v[180:181], v[146:147]
	v_fmac_f32_e32 v113, v124, v124
	v_fmac_f32_e32 v113, v126, v126
	v_fmac_f32_e32 v113, v127, v127
	v_add_f32_e32 v120, v113, v112
	v_and_b32_e32 v113, 64, v197
	v_xor_b32_e32 v112, 16, v197
	v_add_u32_e32 v121, 64, v113
	v_cmp_lt_i32_e32 vcc, v112, v121
	v_cvt_pk_bf16_f32 v113, v158, v159
	global_store_dwordx4 v[194:195], v[156:159], off offset:512 nt
	s_nop 0
	v_cndmask_b32_e32 v112, v197, v112, vcc
	v_lshlrev_b32_e32 v112, 2, v112
	ds_bpermute_b32 v144, v112, v120
	v_cvt_pk_bf16_f32 v112, v156, v157
	global_store_dwordx2 v[116:117], v[112:113], off offset:256
	v_xor_b32_e32 v113, 32, v197
	v_cmp_lt_i32_e32 vcc, v113, v121
	s_waitcnt lgkmcnt(0)
	v_add_f32_e32 v112, v120, v144
	global_store_dwordx4 v[194:195], v[124:127], off offset:576 nt
	v_cndmask_b32_e32 v113, v197, v113, vcc
	v_lshlrev_b32_e32 v113, 2, v113
	ds_bpermute_b32 v113, v113, v112
	v_cvt_pk_bf16_f32 v120, v124, v125
	v_cvt_pk_bf16_f32 v121, v126, v127
	global_store_dwordx2 v[116:117], v[120:121], off offset:288
	s_and_saveexec_b64 s[26:27], s[0:1]
	s_cbranch_execz .LBB0_2594
	s_waitcnt lgkmcnt(0)
	v_add_f32_e32 v116, v112, v113
	v_lshlrev_b64 v[112:113], 7, v[188:189]
	v_lshl_add_u64 v[112:113], s[24:25], 0, v[112:113]
	global_store_dword v[112:113], v116, off

; DEVI unsigned pk_bf16(float lo, float hi) { unsigned r; asm("v_cvt_pk_bf16_f32 %0, %1, %2" : "=v"(r) : "v"(lo), "v"(hi)); return r; }
;     DEVI void operator()(const f32x4 (&acc)[2][2][4][2], const Unit& u, int wr, int wc, int fr, int fq, const LAS float*) const {
;     ...
;         for (int idx = 0; idx < 8; ++idx) {
;             const int ai = idx >> 2, m = idx & 3;
;             const size_t ro = (size_t)(row0 + ai * HALF + m * 16) * ldc + col0;
;             if (idx + 1 < 8) { const int ai2 = (idx + 1) >> 2, m2 = (idx + 1) & 3; const size_t ro2 = (size_t)(row0 + ai2 * HALF + m2 * 16) * ldc + col0;
; #pragma unroll
;                 for (int bj = 0; bj < 2; ++bj)
; #pragma unroll
;                     for (int n = 0; n < 2; ++n) nxt[bj][n] = *(const f32x4*)(R + ro2 + bj * HALF + n * 16); }
;             float ss = 0.f;
; #pragma unroll
;             for (int bj = 0; bj < 2; ++bj)
; #pragma unroll
;                 for (int n = 0; n < 2; ++n) {
;                     const f32x4 hn = cur[bj][n] + acc[ai][bj][m][n] * scale;
;                     *(f32x4*)(C + ro + bj * HALF + n * 16) = hn;
;                     if (HB) { u32x2 w; w.x = pk_bf16(hn[0], hn[1]); w.y = pk_bf16(hn[2], hn[3]); *(u32x2*)(HB + ro + bj * HALF + n * 16) = w;
;                         ss += hn[0] * hn[0] + hn[1] * hn[1] + hn[2] * hn[2] + hn[3] * hn[3]; } }
;             if (HB) { ss += __shfl_xor(ss, 16); ss += __shfl_xor(ss, 32); if (fq == 0) RS[(size_t)(row0 + ai * HALF + m * 16) * 32 + u.pn * 4 + wc] = ss; }
; #pragma unroll
;             for (int bj = 0; bj < 2; ++bj)
; #pragma unroll
;                 for (int n = 0; n < 2; ++n) cur[bj][n] = nxt[bj][n];
;         }
.LBB0_2596:
	v_or_b32_e32 v150, 32, v188
	v_mad_i64_i32 v[152:153], s[26:27], v150, s58, 0
	s_waitcnt lgkmcnt(0)
	v_lshl_add_u64 v[112:113], v[152:153], 2, v[186:187]
	global_load_dwordx4 v[124:127], v[112:113], off
	global_load_dwordx4 v[120:123], v[112:113], off offset:64
	global_load_dwordx4 v[116:119], v[112:113], off offset:512
	s_nop 0
	global_load_dwordx4 v[112:115], v[112:113], off offset:576
	v_lshl_add_u64 v[156:157], v[192:193], 0, v[182:183]
	v_mov_b32_e32 v181, v180
	v_lshl_add_u64 v[154:155], v[156:157], 2, s[80:81]
	v_pk_fma_f32 v[148:149], v[110:111], v[180:181], v[142:143]
	v_pk_fma_f32 v[146:147], v[108:109], v[184:185], v[140:141]
	s_and_b64 vcc, exec, s[4:5]
	v_pk_fma_f32 v[144:145], v[104:105], v[184:185], v[136:137]
	v_pk_fma_f32 v[140:141], v[100:101], v[184:185], v[132:133]
	v_pk_fma_f32 v[108:109], v[96:97], v[184:185], v[128:129]
	global_store_dwordx4 v[154:155], v[146:149], off nt
	s_cbranch_vccnz .LBB0_2631
	v_lshl_add_u64 v[100:101], v[156:157], 1, s[74:75]
	v_cvt_pk_bf16_f32 v96, v146, v147
	v_mul_f32_e32 v104, v147, v147
	v_cvt_pk_bf16_f32 v97, v148, v149
	global_store_dwordx2 v[100:101], v[96:97], off
	v_fmac_f32_e32 v104, v146, v146
	v_pk_fma_f32 v[146:147], v[106:107], v[180:181], v[138:139]
	v_cvt_pk_bf16_f32 v96, v144, v145
	global_store_dwordx4 v[154:155], v[144:147], off offset:64 nt
	v_cvt_pk_bf16_f32 v97, v146, v147
	global_store_dwordx2 v[100:101], v[96:97], off offset:32
	v_mul_f32_e32 v96, v145, v145
	v_fmac_f32_e32 v96, v144, v144
	v_mul_f32_e32 v97, v141, v141
	v_fmac_f32_e32 v104, v148, v148
	v_fmac_f32_e32 v96, v146, v146
	v_pk_fma_f32 v[142:143], v[102:103], v[180:181], v[134:135]
	v_fmac_f32_e32 v97, v140, v140
	v_fmac_f32_e32 v104, v149, v149
	v_fmac_f32_e32 v96, v147, v147
	v_fmac_f32_e32 v97, v142, v142
	v_add_f32_e32 v96, v104, v96
	v_fmac_f32_e32 v97, v143, v143
	v_add_f32_e32 v96, v96, v97
	v_mul_f32_e32 v97, v109, v109
	v_pk_fma_f32 v[110:111], v[98:99], v[180:181], v[130:131]
	v_fmac_f32_e32 v97, v108, v108
	v_fmac_f32_e32 v97, v110, v110
	v_fmac_f32_e32 v97, v111, v111
	v_add_f32_e32 v104, v96, v97
	v_and_b32_e32 v97, 64, v197
	v_xor_b32_e32 v96, 16, v197
	v_add_u32_e32 v105, 64, v97
	v_cmp_lt_i32_e32 vcc, v96, v105
	v_cvt_pk_bf16_f32 v97, v142, v143
	global_store_dwordx4 v[154:155], v[140:143], off offset:512 nt
	s_nop 0
	v_cndmask_b32_e32 v96, v197, v96, vcc
	v_lshlrev_b32_e32 v96, 2, v96
	ds_bpermute_b32 v128, v96, v104
	v_cvt_pk_bf16_f32 v96, v140, v141
	global_store_dwordx2 v[100:101], v[96:97], off offset:256
	v_xor_b32_e32 v97, 32, v197
	v_cmp_lt_i32_e32 vcc, v97, v105
	s_waitcnt lgkmcnt(0)
	v_add_f32_e32 v96, v104, v128
	global_store_dwordx4 v[154:155], v[108:111], off offset:576 nt
	v_cndmask_b32_e32 v97, v197, v97, vcc
	v_lshlrev_b32_e32 v97, 2, v97
	ds_bpermute_b32 v97, v97, v96
	v_cvt_pk_bf16_f32 v104, v108, v109
	v_cvt_pk_bf16_f32 v105, v110, v111
	global_store_dwordx2 v[100:101], v[104:105], off offset:288
	s_and_saveexec_b64 s[26:27], s[0:1]
	s_cbranch_execz .LBB0_2599
	v_ashrrev_i32_e32 v191, 31, v190
	s_waitcnt lgkmcnt(0)
	v_add_f32_e32 v100, v96, v97
	v_lshlrev_b64 v[96:97], 7, v[190:191]
	v_lshl_add_u64 v[96:97], s[24:25], 0, v[96:97]
	global_store_dword v[96:97], v100, off

; DEVI unsigned pk_bf16(float lo, float hi) { unsigned r; asm("v_cvt_pk_bf16_f32 %0, %1, %2" : "=v"(r) : "v"(lo), "v"(hi)); return r; }
;     DEVI void operator()(const f32x4 (&acc)[2][2][4][2], const Unit& u, int wr, int wc, int fr, int fq, const LAS float*) const {
;     ...
;         for (int idx = 0; idx < 8; ++idx) {
;             const int ai = idx >> 2, m = idx & 3;
;             const size_t ro = (size_t)(row0 + ai * HALF + m * 16) * ldc + col0;
;             if (idx + 1 < 8) { const int ai2 = (idx + 1) >> 2, m2 = (idx + 1) & 3; const size_t ro2 = (size_t)(row0 + ai2 * HALF + m2 * 16) * ldc + col0;
; #pragma unroll
;                 for (int bj = 0; bj < 2; ++bj)
; #pragma unroll
;                     for (int n = 0; n < 2; ++n) nxt[bj][n] = *(const f32x4*)(R + ro2 + bj * HALF + n * 16); }
;             float ss = 0.f;
; #pragma unroll
;             for (int bj = 0; bj < 2; ++bj)
; #pragma unroll
;                 for (int n = 0; n < 2; ++n) {
;                     const f32x4 hn = cur[bj][n] + acc[ai][bj][m][n] * scale;
;                     *(f32x4*)(C + ro + bj * HALF + n * 16) = hn;
;                     if (HB) { u32x2 w; w.x = pk_bf16(hn[0], hn[1]); w.y = pk_bf16(hn[2], hn[3]); *(u32x2*)(HB + ro + bj * HALF + n * 16) = w;
;                         ss += hn[0] * hn[0] + hn[1] * hn[1] + hn[2] * hn[2] + hn[3] * hn[3]; } }
;             if (HB) { ss += __shfl_xor(ss, 16); ss += __shfl_xor(ss, 32); if (fq == 0) RS[(size_t)(row0 + ai * HALF + m * 16) * 32 + u.pn * 4 + wc] = ss; }
; #pragma unroll
;             for (int bj = 0; bj < 2; ++bj)
; #pragma unroll
;                 for (int n = 0; n < 2; ++n) cur[bj][n] = nxt[bj][n];
;         }
.LBB0_2601:
	v_or_b32_e32 v134, 48, v188
	v_mad_i64_i32 v[136:137], s[26:27], v134, s58, 0
	s_waitcnt lgkmcnt(0)
	v_lshl_add_u64 v[96:97], v[136:137], 2, v[186:187]
	global_load_dwordx4 v[108:111], v[96:97], off
	global_load_dwordx4 v[104:107], v[96:97], off offset:64
	global_load_dwordx4 v[100:103], v[96:97], off offset:512
	s_nop 0
	global_load_dwordx4 v[96:99], v[96:97], off offset:576
	v_lshl_add_u64 v[140:141], v[152:153], 0, v[182:183]
	v_mov_b32_e32 v181, v180
	v_lshl_add_u64 v[138:139], v[140:141], 2, s[80:81]
	s_waitcnt vmcnt(8)
	v_pk_fma_f32 v[132:133], v[94:95], v[180:181], v[126:127]
	v_pk_fma_f32 v[130:131], v[92:93], v[184:185], v[124:125]
	s_and_b64 vcc, exec, s[4:5]
	s_waitcnt vmcnt(7)
	v_pk_fma_f32 v[128:129], v[88:89], v[184:185], v[120:121]
	s_waitcnt vmcnt(6)
	v_pk_fma_f32 v[124:125], v[84:85], v[184:185], v[116:117]
	s_waitcnt vmcnt(5)
	v_pk_fma_f32 v[92:93], v[80:81], v[184:185], v[112:113]
	global_store_dwordx4 v[138:139], v[130:133], off nt
	s_cbranch_vccnz .LBB0_2632
	v_lshl_add_u64 v[84:85], v[140:141], 1, s[74:75]
	v_cvt_pk_bf16_f32 v80, v130, v131
	v_mul_f32_e32 v88, v131, v131
	v_cvt_pk_bf16_f32 v81, v132, v133
	global_store_dwordx2 v[84:85], v[80:81], off
	v_fmac_f32_e32 v88, v130, v130
	v_pk_fma_f32 v[130:131], v[90:91], v[180:181], v[122:123]
	v_cvt_pk_bf16_f32 v80, v128, v129
	global_store_dwordx4 v[138:139], v[128:131], off offset:64 nt
	v_cvt_pk_bf16_f32 v81, v130, v131
	global_store_dwordx2 v[84:85], v[80:81], off offset:32
	v_mul_f32_e32 v80, v129, v129
	v_fmac_f32_e32 v80, v128, v128
	v_mul_f32_e32 v81, v125, v125
	v_fmac_f32_e32 v88, v132, v132
	v_fmac_f32_e32 v80, v130, v130
	v_pk_fma_f32 v[126:127], v[86:87], v[180:181], v[118:119]
	v_fmac_f32_e32 v81, v124, v124
	v_fmac_f32_e32 v88, v133, v133
	v_fmac_f32_e32 v80, v131, v131
	v_fmac_f32_e32 v81, v126, v126
	v_add_f32_e32 v80, v88, v80
	v_fmac_f32_e32 v81, v127, v127
	v_add_f32_e32 v80, v80, v81
	v_mul_f32_e32 v81, v93, v93
	v_pk_fma_f32 v[94:95], v[82:83], v[180:181], v[114:115]
	v_fmac_f32_e32 v81, v92, v92
	v_fmac_f32_e32 v81, v94, v94
	v_fmac_f32_e32 v81, v95, v95
	v_add_f32_e32 v88, v80, v81
	v_and_b32_e32 v81, 64, v197
	v_xor_b32_e32 v80, 16, v197
	v_add_u32_e32 v89, 64, v81
	v_cmp_lt_i32_e32 vcc, v80, v89
	v_cvt_pk_bf16_f32 v81, v126, v127
	global_store_dwordx4 v[138:139], v[124:127], off offset:512 nt
	s_nop 0
	v_cndmask_b32_e32 v80, v197, v80, vcc
	v_lshlrev_b32_e32 v80, 2, v80
	ds_bpermute_b32 v112, v80, v88
	v_cvt_pk_bf16_f32 v80, v124, v125
	global_store_dwordx2 v[84:85], v[80:81], off offset:256
	v_xor_b32_e32 v81, 32, v197
	v_cmp_lt_i32_e32 vcc, v81, v89
	s_waitcnt lgkmcnt(0)
	v_add_f32_e32 v80, v88, v112
	global_store_dwordx4 v[138:139], v[92:95], off offset:576 nt
	v_cndmask_b32_e32 v81, v197, v81, vcc
	v_lshlrev_b32_e32 v81, 2, v81
	ds_bpermute_b32 v81, v81, v80
	v_cvt_pk_bf16_f32 v88, v92, v93
	v_cvt_pk_bf16_f32 v89, v94, v95
	global_store_dwordx2 v[84:85], v[88:89], off offset:288
	s_and_saveexec_b64 s[26:27], s[0:1]
	s_cbranch_execz .LBB0_2604
	v_ashrrev_i32_e32 v151, 31, v150
	s_waitcnt lgkmcnt(0)
	v_add_f32_e32 v84, v80, v81
	v_lshlrev_b64 v[80:81], 7, v[150:151]
	v_lshl_add_u64 v[80:81], s[24:25], 0, v[80:81]
	global_store_dword v[80:81], v84, off

; DEVI unsigned pk_bf16(float lo, float hi) { unsigned r; asm("v_cvt_pk_bf16_f32 %0, %1, %2" : "=v"(r) : "v"(lo), "v"(hi)); return r; }
;     DEVI void operator()(const f32x4 (&acc)[2][2][4][2], const Unit& u, int wr, int wc, int fr, int fq, const LAS float*) const {
;     ...
;         for (int idx = 0; idx < 8; ++idx) {
;             const int ai = idx >> 2, m = idx & 3;
;             const size_t ro = (size_t)(row0 + ai * HALF + m * 16) * ldc + col0;
;             if (idx + 1 < 8) { const int ai2 = (idx + 1) >> 2, m2 = (idx + 1) & 3; const size_t ro2 = (size_t)(row0 + ai2 * HALF + m2 * 16) * ldc + col0;
; #pragma unroll
;                 for (int bj = 0; bj < 2; ++bj)
; #pragma unroll
;                     for (int n = 0; n < 2; ++n) nxt[bj][n] = *(const f32x4*)(R + ro2 + bj * HALF + n * 16); }
;             float ss = 0.f;
; #pragma unroll
;             for (int bj = 0; bj < 2; ++bj)
; #pragma unroll
;                 for (int n = 0; n < 2; ++n) {
;                     const f32x4 hn = cur[bj][n] + acc[ai][bj][m][n] * scale;
;                     *(f32x4*)(C + ro + bj * HALF + n * 16) = hn;
;                     if (HB) { u32x2 w; w.x = pk_bf16(hn[0], hn[1]); w.y = pk_bf16(hn[2], hn[3]); *(u32x2*)(HB + ro + bj * HALF + n * 16) = w;
;                         ss += hn[0] * hn[0] + hn[1] * hn[1] + hn[2] * hn[2] + hn[3] * hn[3]; } }
;             if (HB) { ss += __shfl_xor(ss, 16); ss += __shfl_xor(ss, 32); if (fq == 0) RS[(size_t)(row0 + ai * HALF + m * 16) * 32 + u.pn * 4 + wc] = ss; }
; #pragma unroll
;             for (int bj = 0; bj < 2; ++bj)
; #pragma unroll
;                 for (int n = 0; n < 2; ++n) cur[bj][n] = nxt[bj][n];
;         }
.LBB0_2606:
	v_add_u32_e32 v118, 0x80, v188
	v_mad_i64_i32 v[120:121], s[26:27], v118, s58, 0
	s_waitcnt lgkmcnt(0)
	v_lshl_add_u64 v[80:81], v[120:121], 2, v[186:187]
	global_load_dwordx4 v[92:95], v[80:81], off
	global_load_dwordx4 v[88:91], v[80:81], off offset:64
	global_load_dwordx4 v[84:87], v[80:81], off offset:512
	s_nop 0
	global_load_dwordx4 v[80:83], v[80:81], off offset:576
	v_lshl_add_u64 v[124:125], v[136:137], 0, v[182:183]
	v_mov_b32_e32 v181, v180
	v_lshl_add_u64 v[122:123], v[124:125], 2, s[80:81]
	s_waitcnt vmcnt(8)
	v_pk_fma_f32 v[116:117], v[78:79], v[180:181], v[110:111]
	v_pk_fma_f32 v[114:115], v[76:77], v[184:185], v[108:109]
	s_and_b64 vcc, exec, s[4:5]
	s_waitcnt vmcnt(7)
	v_pk_fma_f32 v[112:113], v[72:73], v[184:185], v[104:105]
	s_waitcnt vmcnt(6)
	v_pk_fma_f32 v[108:109], v[68:69], v[184:185], v[100:101]
	s_waitcnt vmcnt(5)
	v_pk_fma_f32 v[76:77], v[64:65], v[184:185], v[96:97]
	global_store_dwordx4 v[122:123], v[114:117], off nt
	s_cbranch_vccnz .LBB0_2633
	v_lshl_add_u64 v[68:69], v[124:125], 1, s[74:75]
	v_cvt_pk_bf16_f32 v64, v114, v115
	v_mul_f32_e32 v72, v115, v115
	v_cvt_pk_bf16_f32 v65, v116, v117
	global_store_dwordx2 v[68:69], v[64:65], off
	v_fmac_f32_e32 v72, v114, v114
	v_pk_fma_f32 v[114:115], v[74:75], v[180:181], v[106:107]
	v_cvt_pk_bf16_f32 v64, v112, v113
	global_store_dwordx4 v[122:123], v[112:115], off offset:64 nt
	v_cvt_pk_bf16_f32 v65, v114, v115
	global_store_dwordx2 v[68:69], v[64:65], off offset:32
	v_mul_f32_e32 v64, v113, v113
	v_fmac_f32_e32 v64, v112, v112
	v_mul_f32_e32 v65, v109, v109
	v_fmac_f32_e32 v72, v116, v116
	v_fmac_f32_e32 v64, v114, v114
	v_pk_fma_f32 v[110:111], v[70:71], v[180:181], v[102:103]
	v_fmac_f32_e32 v65, v108, v108
	v_fmac_f32_e32 v72, v117, v117
	v_fmac_f32_e32 v64, v115, v115
	v_fmac_f32_e32 v65, v110, v110
	v_add_f32_e32 v64, v72, v64
	v_fmac_f32_e32 v65, v111, v111
	v_add_f32_e32 v64, v64, v65
	v_mul_f32_e32 v65, v77, v77
	v_pk_fma_f32 v[78:79], v[66:67], v[180:181], v[98:99]
	v_fmac_f32_e32 v65, v76, v76
	v_fmac_f32_e32 v65, v78, v78
	v_fmac_f32_e32 v65, v79, v79
	v_add_f32_e32 v72, v64, v65
	v_and_b32_e32 v65, 64, v197
	v_xor_b32_e32 v64, 16, v197
	v_add_u32_e32 v73, 64, v65
	v_cmp_lt_i32_e32 vcc, v64, v73
	v_cvt_pk_bf16_f32 v65, v110, v111
	global_store_dwordx4 v[122:123], v[108:111], off offset:512 nt
	s_nop 0
	v_cndmask_b32_e32 v64, v197, v64, vcc
	v_lshlrev_b32_e32 v64, 2, v64
	ds_bpermute_b32 v96, v64, v72
	v_cvt_pk_bf16_f32 v64, v108, v109
	global_store_dwordx2 v[68:69], v[64:65], off offset:256
	v_xor_b32_e32 v65, 32, v197
	v_cmp_lt_i32_e32 vcc, v65, v73
	s_waitcnt lgkmcnt(0)
	v_add_f32_e32 v64, v72, v96
	global_store_dwordx4 v[122:123], v[76:79], off offset:576 nt
	v_cndmask_b32_e32 v65, v197, v65, vcc
	v_lshlrev_b32_e32 v65, 2, v65
	ds_bpermute_b32 v65, v65, v64
	v_cvt_pk_bf16_f32 v72, v76, v77
	v_cvt_pk_bf16_f32 v73, v78, v79
	global_store_dwordx2 v[68:69], v[72:73], off offset:288
	s_and_saveexec_b64 s[26:27], s[0:1]
	s_cbranch_execz .LBB0_2609
	v_ashrrev_i32_e32 v135, 31, v134
	s_waitcnt lgkmcnt(0)
	v_add_f32_e32 v68, v64, v65
	v_lshlrev_b64 v[64:65], 7, v[134:135]
	v_lshl_add_u64 v[64:65], s[24:25], 0, v[64:65]
	global_store_dword v[64:65], v68, off

; DEVI unsigned pk_bf16(float lo, float hi) { unsigned r; asm("v_cvt_pk_bf16_f32 %0, %1, %2" : "=v"(r) : "v"(lo), "v"(hi)); return r; }
;     DEVI void operator()(const f32x4 (&acc)[2][2][4][2], const Unit& u, int wr, int wc, int fr, int fq, const LAS float*) const {
;     ...
;         for (int idx = 0; idx < 8; ++idx) {
;             const int ai = idx >> 2, m = idx & 3;
;             const size_t ro = (size_t)(row0 + ai * HALF + m * 16) * ldc + col0;
;             if (idx + 1 < 8) { const int ai2 = (idx + 1) >> 2, m2 = (idx + 1) & 3; const size_t ro2 = (size_t)(row0 + ai2 * HALF + m2 * 16) * ldc + col0;
; #pragma unroll
;                 for (int bj = 0; bj < 2; ++bj)
; #pragma unroll
;                     for (int n = 0; n < 2; ++n) nxt[bj][n] = *(const f32x4*)(R + ro2 + bj * HALF + n * 16); }
;             float ss = 0.f;
; #pragma unroll
;             for (int bj = 0; bj < 2; ++bj)
; #pragma unroll
;                 for (int n = 0; n < 2; ++n) {
;                     const f32x4 hn = cur[bj][n] + acc[ai][bj][m][n] * scale;
;                     *(f32x4*)(C + ro + bj * HALF + n * 16) = hn;
;                     if (HB) { u32x2 w; w.x = pk_bf16(hn[0], hn[1]); w.y = pk_bf16(hn[2], hn[3]); *(u32x2*)(HB + ro + bj * HALF + n * 16) = w;
;                         ss += hn[0] * hn[0] + hn[1] * hn[1] + hn[2] * hn[2] + hn[3] * hn[3]; } }
;             if (HB) { ss += __shfl_xor(ss, 16); ss += __shfl_xor(ss, 32); if (fq == 0) RS[(size_t)(row0 + ai * HALF + m * 16) * 32 + u.pn * 4 + wc] = ss; }
; #pragma unroll
;             for (int bj = 0; bj < 2; ++bj)
; #pragma unroll
;                 for (int n = 0; n < 2; ++n) cur[bj][n] = nxt[bj][n];
;         }
.LBB0_2611:
	v_or_b32_e32 v102, 16, v118
	v_mad_i64_i32 v[104:105], s[26:27], v102, s58, 0
	s_waitcnt lgkmcnt(0)
	v_lshl_add_u64 v[64:65], v[104:105], 2, v[186:187]
	global_load_dwordx4 v[76:79], v[64:65], off
	global_load_dwordx4 v[72:75], v[64:65], off offset:64
	global_load_dwordx4 v[68:71], v[64:65], off offset:512
	s_nop 0
	global_load_dwordx4 v[64:67], v[64:65], off offset:576
	v_lshl_add_u64 v[108:109], v[120:121], 0, v[182:183]
	v_mov_b32_e32 v181, v180
	v_ashrrev_i32_e32 v119, 31, v118
	v_lshl_add_u64 v[106:107], v[108:109], 2, s[80:81]
	s_waitcnt vmcnt(8)
	v_pk_fma_f32 v[100:101], v[62:63], v[180:181], v[94:95]
	v_pk_fma_f32 v[98:99], v[60:61], v[184:185], v[92:93]
	s_and_b64 vcc, exec, s[4:5]
	s_waitcnt vmcnt(7)
	v_pk_fma_f32 v[96:97], v[56:57], v[184:185], v[88:89]
	s_waitcnt vmcnt(6)
	v_pk_fma_f32 v[92:93], v[52:53], v[184:185], v[84:85]
	s_waitcnt vmcnt(5)
	v_pk_fma_f32 v[60:61], v[48:49], v[184:185], v[80:81]
	global_store_dwordx4 v[106:107], v[98:101], off nt
	s_cbranch_vccnz .LBB0_2634
	v_lshl_add_u64 v[52:53], v[108:109], 1, s[74:75]
	v_cvt_pk_bf16_f32 v48, v98, v99
	v_mul_f32_e32 v56, v99, v99
	v_cvt_pk_bf16_f32 v49, v100, v101
	global_store_dwordx2 v[52:53], v[48:49], off
	v_fmac_f32_e32 v56, v98, v98
	v_pk_fma_f32 v[98:99], v[58:59], v[180:181], v[90:91]
	v_cvt_pk_bf16_f32 v48, v96, v97
	global_store_dwordx4 v[106:107], v[96:99], off offset:64 nt
	v_cvt_pk_bf16_f32 v49, v98, v99
	global_store_dwordx2 v[52:53], v[48:49], off offset:32
	v_mul_f32_e32 v48, v97, v97
	v_fmac_f32_e32 v48, v96, v96
	v_mul_f32_e32 v49, v93, v93
	v_fmac_f32_e32 v56, v100, v100
	v_fmac_f32_e32 v48, v98, v98
	v_pk_fma_f32 v[94:95], v[54:55], v[180:181], v[86:87]
	v_fmac_f32_e32 v49, v92, v92
	v_fmac_f32_e32 v56, v101, v101
	v_fmac_f32_e32 v48, v99, v99
	v_fmac_f32_e32 v49, v94, v94
	v_add_f32_e32 v48, v56, v48
	v_fmac_f32_e32 v49, v95, v95
	v_add_f32_e32 v48, v48, v49
	v_mul_f32_e32 v49, v61, v61
	v_pk_fma_f32 v[62:63], v[50:51], v[180:181], v[82:83]
	v_fmac_f32_e32 v49, v60, v60
	v_fmac_f32_e32 v49, v62, v62
	v_fmac_f32_e32 v49, v63, v63
	v_add_f32_e32 v56, v48, v49
	v_and_b32_e32 v49, 64, v197
	v_xor_b32_e32 v48, 16, v197
	v_add_u32_e32 v57, 64, v49
	v_cmp_lt_i32_e32 vcc, v48, v57
	v_cvt_pk_bf16_f32 v49, v94, v95
	global_store_dwordx4 v[106:107], v[92:95], off offset:512 nt
	s_nop 0
	v_cndmask_b32_e32 v48, v197, v48, vcc
	v_lshlrev_b32_e32 v48, 2, v48
	ds_bpermute_b32 v80, v48, v56
	v_cvt_pk_bf16_f32 v48, v92, v93
	global_store_dwordx2 v[52:53], v[48:49], off offset:256
	v_xor_b32_e32 v49, 32, v197
	v_cmp_lt_i32_e32 vcc, v49, v57
	s_waitcnt lgkmcnt(0)
	v_add_f32_e32 v48, v56, v80
	global_store_dwordx4 v[106:107], v[60:63], off offset:576 nt
	v_cndmask_b32_e32 v49, v197, v49, vcc
	v_lshlrev_b32_e32 v49, 2, v49
	ds_bpermute_b32 v49, v49, v48
	v_cvt_pk_bf16_f32 v56, v60, v61
	v_cvt_pk_bf16_f32 v57, v62, v63
	global_store_dwordx2 v[52:53], v[56:57], off offset:288
	s_and_saveexec_b64 s[26:27], s[0:1]
	s_cbranch_execz .LBB0_2614
	s_waitcnt lgkmcnt(0)
	v_add_f32_e32 v52, v48, v49
	v_lshlrev_b64 v[48:49], 7, v[118:119]
	v_lshl_add_u64 v[48:49], s[24:25], 0, v[48:49]
	global_store_dword v[48:49], v52, off

; DEVI unsigned pk_bf16(float lo, float hi) { unsigned r; asm("v_cvt_pk_bf16_f32 %0, %1, %2" : "=v"(r) : "v"(lo), "v"(hi)); return r; }
;     DEVI void operator()(const f32x4 (&acc)[2][2][4][2], const Unit& u, int wr, int wc, int fr, int fq, const LAS float*) const {
;     ...
;         for (int idx = 0; idx < 8; ++idx) {
;             const int ai = idx >> 2, m = idx & 3;
;             const size_t ro = (size_t)(row0 + ai * HALF + m * 16) * ldc + col0;
;             if (idx + 1 < 8) { const int ai2 = (idx + 1) >> 2, m2 = (idx + 1) & 3; const size_t ro2 = (size_t)(row0 + ai2 * HALF + m2 * 16) * ldc + col0;
; #pragma unroll
;                 for (int bj = 0; bj < 2; ++bj)
; #pragma unroll
;                     for (int n = 0; n < 2; ++n) nxt[bj][n] = *(const f32x4*)(R + ro2 + bj * HALF + n * 16); }
;             float ss = 0.f;
; #pragma unroll
;             for (int bj = 0; bj < 2; ++bj)
; #pragma unroll
;                 for (int n = 0; n < 2; ++n) {
;                     const f32x4 hn = cur[bj][n] + acc[ai][bj][m][n] * scale;
;                     *(f32x4*)(C + ro + bj * HALF + n * 16) = hn;
;                     if (HB) { u32x2 w; w.x = pk_bf16(hn[0], hn[1]); w.y = pk_bf16(hn[2], hn[3]); *(u32x2*)(HB + ro + bj * HALF + n * 16) = w;
;                         ss += hn[0] * hn[0] + hn[1] * hn[1] + hn[2] * hn[2] + hn[3] * hn[3]; } }
;             if (HB) { ss += __shfl_xor(ss, 16); ss += __shfl_xor(ss, 32); if (fq == 0) RS[(size_t)(row0 + ai * HALF + m * 16) * 32 + u.pn * 4 + wc] = ss; }
; #pragma unroll
;             for (int bj = 0; bj < 2; ++bj)
; #pragma unroll
;                 for (int n = 0; n < 2; ++n) cur[bj][n] = nxt[bj][n];
;         }
.LBB0_2616:
	v_or_b32_e32 v86, 32, v118
	v_mad_i64_i32 v[88:89], s[26:27], v86, s58, 0
	s_waitcnt lgkmcnt(0)
	v_lshl_add_u64 v[48:49], v[88:89], 2, v[186:187]
	global_load_dwordx4 v[60:63], v[48:49], off
	global_load_dwordx4 v[56:59], v[48:49], off offset:64
	global_load_dwordx4 v[52:55], v[48:49], off offset:512
	s_nop 0
	global_load_dwordx4 v[48:51], v[48:49], off offset:576
	v_lshl_add_u64 v[92:93], v[104:105], 0, v[182:183]
	v_mov_b32_e32 v181, v180
	v_lshl_add_u64 v[90:91], v[92:93], 2, s[80:81]
	s_waitcnt vmcnt(8)
	v_pk_fma_f32 v[84:85], v[46:47], v[180:181], v[78:79]
	v_pk_fma_f32 v[82:83], v[44:45], v[184:185], v[76:77]
	s_and_b64 vcc, exec, s[4:5]
	s_waitcnt vmcnt(7)
	v_pk_fma_f32 v[80:81], v[40:41], v[184:185], v[72:73]
	s_waitcnt vmcnt(6)
	v_pk_fma_f32 v[76:77], v[36:37], v[184:185], v[68:69]
	s_waitcnt vmcnt(5)
	v_pk_fma_f32 v[44:45], v[32:33], v[184:185], v[64:65]
	global_store_dwordx4 v[90:91], v[82:85], off nt
	s_cbranch_vccnz .LBB0_2635
	v_lshl_add_u64 v[36:37], v[92:93], 1, s[74:75]
	v_cvt_pk_bf16_f32 v32, v82, v83
	v_mul_f32_e32 v40, v83, v83
	v_cvt_pk_bf16_f32 v33, v84, v85
	global_store_dwordx2 v[36:37], v[32:33], off
	v_fmac_f32_e32 v40, v82, v82
	v_pk_fma_f32 v[82:83], v[42:43], v[180:181], v[74:75]
	v_cvt_pk_bf16_f32 v32, v80, v81
	global_store_dwordx4 v[90:91], v[80:83], off offset:64 nt
	v_cvt_pk_bf16_f32 v33, v82, v83
	global_store_dwordx2 v[36:37], v[32:33], off offset:32
	v_mul_f32_e32 v32, v81, v81
	v_fmac_f32_e32 v32, v80, v80
	v_mul_f32_e32 v33, v77, v77
	v_fmac_f32_e32 v40, v84, v84
	v_fmac_f32_e32 v32, v82, v82
	v_pk_fma_f32 v[78:79], v[38:39], v[180:181], v[70:71]
	v_fmac_f32_e32 v33, v76, v76
	v_fmac_f32_e32 v40, v85, v85
	v_fmac_f32_e32 v32, v83, v83
	v_fmac_f32_e32 v33, v78, v78
	v_add_f32_e32 v32, v40, v32
	v_fmac_f32_e32 v33, v79, v79
	v_add_f32_e32 v32, v32, v33
	v_mul_f32_e32 v33, v45, v45
	v_pk_fma_f32 v[46:47], v[34:35], v[180:181], v[66:67]
	v_fmac_f32_e32 v33, v44, v44
	v_fmac_f32_e32 v33, v46, v46
	v_fmac_f32_e32 v33, v47, v47
	v_add_f32_e32 v40, v32, v33
	v_and_b32_e32 v33, 64, v197
	v_xor_b32_e32 v32, 16, v197
	v_add_u32_e32 v41, 64, v33
	v_cmp_lt_i32_e32 vcc, v32, v41
	v_cvt_pk_bf16_f32 v33, v78, v79
	global_store_dwordx4 v[90:91], v[76:79], off offset:512 nt
	s_nop 0
	v_cndmask_b32_e32 v32, v197, v32, vcc
	v_lshlrev_b32_e32 v32, 2, v32
	ds_bpermute_b32 v64, v32, v40
	v_cvt_pk_bf16_f32 v32, v76, v77
	global_store_dwordx2 v[36:37], v[32:33], off offset:256
	v_xor_b32_e32 v33, 32, v197
	v_cmp_lt_i32_e32 vcc, v33, v41
	s_waitcnt lgkmcnt(0)
	v_add_f32_e32 v32, v40, v64
	global_store_dwordx4 v[90:91], v[44:47], off offset:576 nt
	v_cndmask_b32_e32 v33, v197, v33, vcc
	v_lshlrev_b32_e32 v33, 2, v33
	ds_bpermute_b32 v33, v33, v32
	v_cvt_pk_bf16_f32 v40, v44, v45
	v_cvt_pk_bf16_f32 v41, v46, v47
	global_store_dwordx2 v[36:37], v[40:41], off offset:288
	s_and_saveexec_b64 s[26:27], s[0:1]
	s_cbranch_execz .LBB0_2619
	v_ashrrev_i32_e32 v103, 31, v102
	s_waitcnt lgkmcnt(0)
	v_add_f32_e32 v36, v32, v33
	v_lshlrev_b64 v[32:33], 7, v[102:103]
	v_lshl_add_u64 v[32:33], s[24:25], 0, v[32:33]
	global_store_dword v[32:33], v36, off

; DEVI unsigned pk_bf16(float lo, float hi) { unsigned r; asm("v_cvt_pk_bf16_f32 %0, %1, %2" : "=v"(r) : "v"(lo), "v"(hi)); return r; }
;     DEVI void operator()(const f32x4 (&acc)[2][2][4][2], const Unit& u, int wr, int wc, int fr, int fq, const LAS float*) const {
;     ...
;         for (int idx = 0; idx < 8; ++idx) {
;             const int ai = idx >> 2, m = idx & 3;
;             const size_t ro = (size_t)(row0 + ai * HALF + m * 16) * ldc + col0;
;             if (idx + 1 < 8) { const int ai2 = (idx + 1) >> 2, m2 = (idx + 1) & 3; const size_t ro2 = (size_t)(row0 + ai2 * HALF + m2 * 16) * ldc + col0;
; #pragma unroll
;                 for (int bj = 0; bj < 2; ++bj)
; #pragma unroll
;                     for (int n = 0; n < 2; ++n) nxt[bj][n] = *(const f32x4*)(R + ro2 + bj * HALF + n * 16); }
;             float ss = 0.f;
; #pragma unroll
;             for (int bj = 0; bj < 2; ++bj)
; #pragma unroll
;                 for (int n = 0; n < 2; ++n) {
;                     const f32x4 hn = cur[bj][n] + acc[ai][bj][m][n] * scale;
;                     *(f32x4*)(C + ro + bj * HALF + n * 16) = hn;
;                     if (HB) { u32x2 w; w.x = pk_bf16(hn[0], hn[1]); w.y = pk_bf16(hn[2], hn[3]); *(u32x2*)(HB + ro + bj * HALF + n * 16) = w;
;                         ss += hn[0] * hn[0] + hn[1] * hn[1] + hn[2] * hn[2] + hn[3] * hn[3]; } }
;             if (HB) { ss += __shfl_xor(ss, 16); ss += __shfl_xor(ss, 32); if (fq == 0) RS[(size_t)(row0 + ai * HALF + m * 16) * 32 + u.pn * 4 + wc] = ss; }
; #pragma unroll
;             for (int bj = 0; bj < 2; ++bj)
; #pragma unroll
;                 for (int n = 0; n < 2; ++n) cur[bj][n] = nxt[bj][n];
;         }
.LBB0_2621:
	v_or_b32_e32 v70, 48, v118
	v_mad_i64_i32 v[72:73], s[26:27], v70, s58, 0
	s_waitcnt lgkmcnt(0)
	v_lshl_add_u64 v[32:33], v[72:73], 2, v[186:187]
	global_load_dwordx4 v[44:47], v[32:33], off
	global_load_dwordx4 v[40:43], v[32:33], off offset:64
	global_load_dwordx4 v[36:39], v[32:33], off offset:512
	s_nop 0
	global_load_dwordx4 v[32:35], v[32:33], off offset:576
	v_lshl_add_u64 v[76:77], v[88:89], 0, v[182:183]
	v_mov_b32_e32 v181, v180
	v_lshl_add_u64 v[74:75], v[76:77], 2, s[80:81]
	s_waitcnt vmcnt(8)
	v_pk_fma_f32 v[68:69], v[30:31], v[180:181], v[62:63]
	v_pk_fma_f32 v[66:67], v[28:29], v[184:185], v[60:61]
	s_and_b64 vcc, exec, s[4:5]
	s_waitcnt vmcnt(7)
	v_pk_fma_f32 v[64:65], v[24:25], v[184:185], v[56:57]
	s_waitcnt vmcnt(6)
	v_pk_fma_f32 v[60:61], v[20:21], v[184:185], v[52:53]
	s_waitcnt vmcnt(5)
	v_pk_fma_f32 v[28:29], v[16:17], v[184:185], v[48:49]
	global_store_dwordx4 v[74:75], v[66:69], off nt
	s_cbranch_vccnz .LBB0_2636
	v_lshl_add_u64 v[20:21], v[76:77], 1, s[74:75]
	v_cvt_pk_bf16_f32 v16, v66, v67
	v_mul_f32_e32 v24, v67, v67
	v_cvt_pk_bf16_f32 v17, v68, v69
	global_store_dwordx2 v[20:21], v[16:17], off
	v_fmac_f32_e32 v24, v66, v66
	v_pk_fma_f32 v[66:67], v[26:27], v[180:181], v[58:59]
	v_cvt_pk_bf16_f32 v16, v64, v65
	global_store_dwordx4 v[74:75], v[64:67], off offset:64 nt
	v_cvt_pk_bf16_f32 v17, v66, v67
	global_store_dwordx2 v[20:21], v[16:17], off offset:32
	v_mul_f32_e32 v16, v65, v65
	v_fmac_f32_e32 v16, v64, v64
	v_mul_f32_e32 v17, v61, v61
	v_fmac_f32_e32 v24, v68, v68
	v_fmac_f32_e32 v16, v66, v66
	v_pk_fma_f32 v[62:63], v[22:23], v[180:181], v[54:55]
	v_fmac_f32_e32 v17, v60, v60
	v_fmac_f32_e32 v24, v69, v69
	v_fmac_f32_e32 v16, v67, v67
	v_fmac_f32_e32 v17, v62, v62
	v_add_f32_e32 v16, v24, v16
	v_fmac_f32_e32 v17, v63, v63
	v_add_f32_e32 v16, v16, v17
	v_mul_f32_e32 v17, v29, v29
	v_pk_fma_f32 v[30:31], v[18:19], v[180:181], v[50:51]
	v_fmac_f32_e32 v17, v28, v28
	v_fmac_f32_e32 v17, v30, v30
	v_fmac_f32_e32 v17, v31, v31
	v_add_f32_e32 v24, v16, v17
	v_and_b32_e32 v17, 64, v197
	v_xor_b32_e32 v16, 16, v197
	v_add_u32_e32 v25, 64, v17
	v_cmp_lt_i32_e32 vcc, v16, v25
	v_cvt_pk_bf16_f32 v17, v62, v63
	global_store_dwordx4 v[74:75], v[60:63], off offset:512 nt
	s_nop 0
	v_cndmask_b32_e32 v16, v197, v16, vcc
	v_lshlrev_b32_e32 v16, 2, v16
	ds_bpermute_b32 v48, v16, v24
	v_cvt_pk_bf16_f32 v16, v60, v61
	global_store_dwordx2 v[20:21], v[16:17], off offset:256
	v_xor_b32_e32 v17, 32, v197
	v_cmp_lt_i32_e32 vcc, v17, v25
	s_waitcnt lgkmcnt(0)
	v_add_f32_e32 v16, v24, v48
	global_store_dwordx4 v[74:75], v[28:31], off offset:576 nt
	v_cndmask_b32_e32 v17, v197, v17, vcc
	v_lshlrev_b32_e32 v17, 2, v17
	ds_bpermute_b32 v17, v17, v16
	v_cvt_pk_bf16_f32 v24, v28, v29
	v_cvt_pk_bf16_f32 v25, v30, v31
	global_store_dwordx2 v[20:21], v[24:25], off offset:288
	s_and_saveexec_b64 s[26:27], s[0:1]
	s_cbranch_execz .LBB0_2624
	v_ashrrev_i32_e32 v87, 31, v86
	s_waitcnt lgkmcnt(0)
	v_add_f32_e32 v20, v16, v17
	v_lshlrev_b64 v[16:17], 7, v[86:87]
	v_lshl_add_u64 v[16:17], s[24:25], 0, v[16:17]
	global_store_dword v[16:17], v20, off

; DEVI unsigned pk_bf16(float lo, float hi) { unsigned r; asm("v_cvt_pk_bf16_f32 %0, %1, %2" : "=v"(r) : "v"(lo), "v"(hi)); return r; }
;     DEVI void operator()(const f32x4 (&acc)[2][2][4][2], const Unit& u, int wr, int wc, int fr, int fq, const LAS float*) const {
;     ...
;             float ss = 0.f;
; #pragma unroll
;             for (int bj = 0; bj < 2; ++bj)
; #pragma unroll
;                 for (int n = 0; n < 2; ++n) {
;                     const f32x4 hn = cur[bj][n] + acc[ai][bj][m][n] * scale;
;                     *(f32x4*)(C + ro + bj * HALF + n * 16) = hn;
;                     if (HB) { u32x2 w; w.x = pk_bf16(hn[0], hn[1]); w.y = pk_bf16(hn[2], hn[3]); *(u32x2*)(HB + ro + bj * HALF + n * 16) = w;
;                         ss += hn[0] * hn[0] + hn[1] * hn[1] + hn[2] * hn[2] + hn[3] * hn[3]; } }
;             if (HB) { ss += __shfl_xor(ss, 16); ss += __shfl_xor(ss, 32); if (fq == 0) RS[(size_t)(row0 + ai * HALF + m * 16) * 32 + u.pn * 4 + wc] = ss; }
; #pragma unroll
;             for (int bj = 0; bj < 2; ++bj)
; #pragma unroll
;                 for (int n = 0; n < 2; ++n) cur[bj][n] = nxt[bj][n];
;         }
.LBB0_2626:
	v_lshl_add_u64 v[18:19], v[72:73], 0, v[182:183]
	v_mov_b32_e32 v181, v180
	v_lshl_add_u64 v[26:27], v[18:19], 2, s[80:81]
	s_waitcnt vmcnt(4)
	v_pk_fma_f32 v[24:25], v[14:15], v[180:181], v[46:47]
	v_pk_fma_f32 v[22:23], v[12:13], v[184:185], v[44:45]
	s_and_b64 vcc, exec, s[4:5]
	s_waitcnt vmcnt(3)
	v_pk_fma_f32 v[20:21], v[8:9], v[184:185], v[40:41]
	s_waitcnt vmcnt(2) lgkmcnt(0)
	v_pk_fma_f32 v[16:17], v[4:5], v[184:185], v[36:37]
	s_waitcnt vmcnt(1)
	v_pk_fma_f32 v[12:13], v[0:1], v[184:185], v[32:33]
	global_store_dwordx4 v[26:27], v[22:25], off nt
	s_cbranch_vccnz .LBB0_2637
	v_lshl_add_u64 v[4:5], v[18:19], 1, s[74:75]
	v_cvt_pk_bf16_f32 v0, v22, v23
	v_mul_f32_e32 v8, v23, v23
	v_cvt_pk_bf16_f32 v1, v24, v25
	global_store_dwordx2 v[4:5], v[0:1], off
	v_fmac_f32_e32 v8, v22, v22
	v_pk_fma_f32 v[22:23], v[10:11], v[180:181], v[42:43]
	v_cvt_pk_bf16_f32 v0, v20, v21
	global_store_dwordx4 v[26:27], v[20:23], off offset:64 nt
	v_cvt_pk_bf16_f32 v1, v22, v23
	global_store_dwordx2 v[4:5], v[0:1], off offset:32
	v_mul_f32_e32 v0, v21, v21
	v_fmac_f32_e32 v0, v20, v20
	v_mul_f32_e32 v1, v17, v17
	v_fmac_f32_e32 v8, v24, v24
	v_fmac_f32_e32 v0, v22, v22
	v_pk_fma_f32 v[18:19], v[6:7], v[180:181], v[38:39]
	v_fmac_f32_e32 v1, v16, v16
	v_fmac_f32_e32 v8, v25, v25
	v_fmac_f32_e32 v0, v23, v23
	v_fmac_f32_e32 v1, v18, v18
	v_add_f32_e32 v0, v8, v0
	v_fmac_f32_e32 v1, v19, v19
	v_add_f32_e32 v0, v0, v1
	v_mul_f32_e32 v1, v13, v13
	v_pk_fma_f32 v[14:15], v[2:3], v[180:181], v[34:35]
	v_fmac_f32_e32 v1, v12, v12
	v_fmac_f32_e32 v1, v14, v14
	v_fmac_f32_e32 v1, v15, v15
	v_add_f32_e32 v8, v0, v1
	v_and_b32_e32 v1, 64, v197
	v_xor_b32_e32 v0, 16, v197
	v_add_u32_e32 v9, 64, v1
	v_cmp_lt_i32_e32 vcc, v0, v9
	v_cvt_pk_bf16_f32 v1, v18, v19
	global_store_dwordx4 v[26:27], v[16:19], off offset:512 nt
	s_nop 0
	v_cndmask_b32_e32 v0, v197, v0, vcc
	v_lshlrev_b32_e32 v0, 2, v0
	ds_bpermute_b32 v22, v0, v8
	v_cvt_pk_bf16_f32 v0, v16, v17
	global_store_dwordx2 v[4:5], v[0:1], off offset:256
	v_xor_b32_e32 v1, 32, v197
	v_cmp_lt_i32_e32 vcc, v1, v9
	s_waitcnt lgkmcnt(0)
	v_add_f32_e32 v0, v8, v22
	global_store_dwordx4 v[26:27], v[12:15], off offset:576 nt
	v_cndmask_b32_e32 v1, v197, v1, vcc
	v_lshlrev_b32_e32 v1, 2, v1
	ds_bpermute_b32 v1, v1, v0
	v_cvt_pk_bf16_f32 v8, v12, v13
	v_cvt_pk_bf16_f32 v9, v14, v15
	global_store_dwordx2 v[4:5], v[8:9], off offset:288
	s_and_saveexec_b64 s[4:5], s[0:1]
	s_cbranch_execz .LBB0_2629
	v_ashrrev_i32_e32 v71, 31, v70
	s_waitcnt lgkmcnt(0)
	v_add_f32_e32 v4, v0, v1
	v_lshlrev_b64 v[0:1], 7, v[70:71]
	v_lshl_add_u64 v[0:1], s[24:25], 0, v[0:1]
	global_store_dword v[0:1], v4, off
